# v35
# speedup vs baseline: 1.0145x; 1.0046x over previous
.LBB0_189:
	s_add_u32 s36, s34, 0xfffc0080
	s_addc_u32 s37, s35, -1
	s_add_i32 s75, 0, 0x10000
	v_add_u32_e32 v140, s75, v161
	ds_read_b128 v[164:167], v140
	ds_read_b128 v[168:171], v140 offset:1024
	ds_read_b128 v[172:175], v140 offset:2048
	ds_read_b128 v[176:179], v140 offset:3072
	s_cmp_eq_u32 s74, 12
	s_cselect_b32 s39, s25, s37
	s_cselect_b32 s38, s69, s36
	s_cselect_b32 s37, s23, s73
	s_cselect_b32 s36, s70, s71
	s_add_i32 m0, s31, 0xc000
	ds_read_b128 v[180:183], v163
	ds_read_b128 v[184:187], v163 offset:1024
	ds_read_b128 v[188:191], v163 offset:2048
	ds_read_b128 v[192:195], v163 offset:3072
	ds_read_b128 v[196:199], v163 offset:4096
	ds_read_b128 v[200:203], v163 offset:5120
	ds_read_b128 v[204:207], v163 offset:6144
	ds_read_b128 v[208:211], v163 offset:7168
	global_load_lds_dwordx4 v136, s[34:35]
	s_add_i32 m0, s31, 0xe000
	s_nop 0
	global_load_lds_dwordx4 v138, s[34:35]
	s_waitcnt lgkmcnt(8)
	s_barrier
	s_waitcnt lgkmcnt(0)
	v_mfma_f32_16x16x32_bf16 v[124:127], v[164:167], v[180:183], v[124:127]
	v_mfma_f32_16x16x32_bf16 v[120:123], v[172:175], v[180:183], v[120:123]
	v_mfma_f32_16x16x32_bf16 v[116:119], v[164:167], v[188:191], v[116:119]
	v_mfma_f32_16x16x32_bf16 v[108:111], v[172:175], v[188:191], v[108:111]
	v_mfma_f32_16x16x32_bf16 v[100:103], v[164:167], v[196:199], v[100:103]
	v_mfma_f32_16x16x32_bf16 v[92:95], v[172:175], v[196:199], v[92:95]
	v_mfma_f32_16x16x32_bf16 v[84:87], v[164:167], v[204:207], v[84:87]
	v_mfma_f32_16x16x32_bf16 v[76:79], v[172:175], v[204:207], v[76:79]
	v_mfma_f32_16x16x32_bf16 v[124:127], v[168:171], v[184:187], v[124:127]
	v_mfma_f32_16x16x32_bf16 v[120:123], v[176:179], v[184:187], v[120:123]
	v_mfma_f32_16x16x32_bf16 v[116:119], v[168:171], v[192:195], v[116:119]
	v_mfma_f32_16x16x32_bf16 v[108:111], v[176:179], v[192:195], v[108:111]
	v_mfma_f32_16x16x32_bf16 v[100:103], v[168:171], v[200:203], v[100:103]
	v_mfma_f32_16x16x32_bf16 v[92:95], v[176:179], v[200:203], v[92:95]
	v_mfma_f32_16x16x32_bf16 v[84:87], v[168:171], v[208:211], v[84:87]
	v_mfma_f32_16x16x32_bf16 v[76:79], v[176:179], v[208:211], v[76:79]
	s_barrier
	s_add_i32 s78, 0, 0x14000
	v_add_u32_e32 v140, s78, v161
	s_add_i32 s75, s75, s57
	ds_read_b128 v[212:215], v140
	ds_read_b128 v[216:219], v140 offset:1024
	ds_read_b128 v[220:223], v140 offset:2048
	ds_read_b128 v[224:227], v140 offset:3072
	s_add_u32 s98, s36, s14
	s_addc_u32 s99, s37, s15
	s_mov_b32 m0, s75
	s_nop 0
	global_load_lds_dwordx4 v128, s[36:37]
	s_add_i32 m0, s75, 0x2000
	s_nop 0
	global_load_lds_dwordx4 v130, s[36:37]
	s_barrier
	s_waitcnt lgkmcnt(0)
	v_mfma_f32_16x16x32_bf16 v[112:115], v[212:215], v[180:183], v[112:115]
	v_mfma_f32_16x16x32_bf16 v[104:107], v[220:223], v[180:183], v[104:107]
	v_mfma_f32_16x16x32_bf16 v[96:99], v[212:215], v[188:191], v[96:99]
	v_mfma_f32_16x16x32_bf16 v[88:91], v[220:223], v[188:191], v[88:91]
	v_mfma_f32_16x16x32_bf16 v[80:83], v[212:215], v[196:199], v[80:83]
	v_mfma_f32_16x16x32_bf16 v[72:75], v[220:223], v[196:199], v[72:75]
	v_mfma_f32_16x16x32_bf16 v[68:71], v[212:215], v[204:207], v[68:71]
	v_mfma_f32_16x16x32_bf16 v[64:67], v[220:223], v[204:207], v[64:67]
	v_mfma_f32_16x16x32_bf16 v[112:115], v[216:219], v[184:187], v[112:115]
	v_mfma_f32_16x16x32_bf16 v[104:107], v[224:227], v[184:187], v[104:107]
	v_mfma_f32_16x16x32_bf16 v[96:99], v[216:219], v[192:195], v[96:99]
	v_mfma_f32_16x16x32_bf16 v[88:91], v[224:227], v[192:195], v[88:91]
	v_mfma_f32_16x16x32_bf16 v[80:83], v[216:219], v[200:203], v[80:83]
	v_mfma_f32_16x16x32_bf16 v[72:75], v[224:227], v[200:203], v[72:75]
	v_mfma_f32_16x16x32_bf16 v[68:71], v[216:219], v[208:211], v[68:71]
	v_mfma_f32_16x16x32_bf16 v[64:67], v[224:227], v[208:211], v[64:67]
	s_mov_b32 m0, s31
	s_add_u32 s100, s38, s14
	s_addc_u32 s101, s39, s15
	s_barrier
	ds_read_b128 v[180:183], v163 offset:16384
	ds_read_b128 v[184:187], v163 offset:17408
	ds_read_b128 v[188:191], v163 offset:18432
	ds_read_b128 v[192:195], v163 offset:19456
	ds_read_b128 v[196:199], v163 offset:20480
	ds_read_b128 v[200:203], v163 offset:21504
	ds_read_b128 v[204:207], v163 offset:22528
	ds_read_b128 v[208:211], v163 offset:23552
	global_load_lds_dwordx4 v134, s[38:39]
	s_mov_b32 m0, s60
	s_nop 0
	global_load_lds_dwordx4 v132, s[38:39]
	s_barrier
	s_waitcnt lgkmcnt(0)
	v_mfma_f32_16x16x32_bf16 v[60:63], v[164:167], v[180:183], v[60:63]
	v_mfma_f32_16x16x32_bf16 v[56:59], v[172:175], v[180:183], v[56:59]
	v_mfma_f32_16x16x32_bf16 v[52:55], v[164:167], v[188:191], v[52:55]
	v_mfma_f32_16x16x32_bf16 v[44:47], v[172:175], v[188:191], v[44:47]
	v_mfma_f32_16x16x32_bf16 v[36:39], v[164:167], v[196:199], v[36:39]
	v_mfma_f32_16x16x32_bf16 v[28:31], v[172:175], v[196:199], v[28:31]
	v_mfma_f32_16x16x32_bf16 v[20:23], v[164:167], v[204:207], v[20:23]
	v_mfma_f32_16x16x32_bf16 v[12:15], v[172:175], v[204:207], v[12:15]
	v_mfma_f32_16x16x32_bf16 v[60:63], v[168:171], v[184:187], v[60:63]
	v_mfma_f32_16x16x32_bf16 v[56:59], v[176:179], v[184:187], v[56:59]
	v_mfma_f32_16x16x32_bf16 v[52:55], v[168:171], v[192:195], v[52:55]
	v_mfma_f32_16x16x32_bf16 v[44:47], v[176:179], v[192:195], v[44:47]
	v_mfma_f32_16x16x32_bf16 v[36:39], v[168:171], v[200:203], v[36:39]
	v_mfma_f32_16x16x32_bf16 v[28:31], v[176:179], v[200:203], v[28:31]
	v_mfma_f32_16x16x32_bf16 v[20:23], v[168:171], v[208:211], v[20:23]
	v_mfma_f32_16x16x32_bf16 v[12:15], v[176:179], v[208:211], v[12:15]
	s_barrier
	s_add_u32 s76, s36, 0x40000
	s_addc_u32 s77, s37, 0
	s_add_i32 s75, s78, s57
	s_mov_b32 m0, s75
	s_nop 0
	global_load_lds_dwordx4 v128, s[76:77]
	s_add_i32 m0, s75, 0x2000
	s_nop 0
	global_load_lds_dwordx4 v130, s[76:77]
	s_waitcnt vmcnt(6)
	s_barrier
	v_mfma_f32_16x16x32_bf16 v[48:51], v[212:215], v[180:183], v[48:51]
	v_mfma_f32_16x16x32_bf16 v[40:43], v[220:223], v[180:183], v[40:43]
	v_mfma_f32_16x16x32_bf16 v[32:35], v[212:215], v[188:191], v[32:35]
	v_mfma_f32_16x16x32_bf16 v[24:27], v[220:223], v[188:191], v[24:27]
	v_mfma_f32_16x16x32_bf16 v[16:19], v[212:215], v[196:199], v[16:19]
	v_mfma_f32_16x16x32_bf16 v[8:11], v[220:223], v[196:199], v[8:11]
	v_mfma_f32_16x16x32_bf16 v[4:7], v[212:215], v[204:207], v[4:7]
	v_mfma_f32_16x16x32_bf16 v[0:3], v[220:223], v[204:207], v[0:3]
	v_mfma_f32_16x16x32_bf16 v[48:51], v[216:219], v[184:187], v[48:51]
	v_mfma_f32_16x16x32_bf16 v[40:43], v[224:227], v[184:187], v[40:43]
	v_mfma_f32_16x16x32_bf16 v[32:35], v[216:219], v[192:195], v[32:35]
	v_mfma_f32_16x16x32_bf16 v[24:27], v[224:227], v[192:195], v[24:27]
	v_mfma_f32_16x16x32_bf16 v[16:19], v[216:219], v[200:203], v[16:19]
	v_mfma_f32_16x16x32_bf16 v[8:11], v[224:227], v[200:203], v[8:11]
	v_mfma_f32_16x16x32_bf16 v[4:7], v[216:219], v[208:211], v[4:7]
	v_mfma_f32_16x16x32_bf16 v[0:3], v[224:227], v[208:211], v[0:3]
	s_add_i32 s75, 0, 0x18000
	v_add_u32_e32 v176, s75, v161
	s_barrier
	ds_read_b128 v[164:167], v176
	ds_read_b128 v[168:171], v176 offset:1024
	ds_read_b128 v[172:175], v176 offset:2048
	ds_read_b128 v[176:179], v176 offset:3072
	s_add_u32 s38, s38, 0x40000
	s_addc_u32 s39, s39, 0
	s_mov_b32 m0, s61
	ds_read_b128 v[180:183], v163 offset:32768
	ds_read_b128 v[184:187], v163 offset:33792
	ds_read_b128 v[188:191], v163 offset:34816
	ds_read_b128 v[192:195], v163 offset:35840
	ds_read_b128 v[196:199], v163 offset:36864
	ds_read_b128 v[200:203], v163 offset:37888
	ds_read_b128 v[204:207], v163 offset:38912
	ds_read_b128 v[208:211], v163 offset:39936
	global_load_lds_dwordx4 v134, s[38:39]
	s_mov_b32 m0, s62
	s_nop 0
	global_load_lds_dwordx4 v132, s[38:39]
	s_waitcnt lgkmcnt(8)
	s_barrier
	s_waitcnt lgkmcnt(0)
	v_mfma_f32_16x16x32_bf16 v[124:127], v[164:167], v[180:183], v[124:127]
	v_mfma_f32_16x16x32_bf16 v[120:123], v[172:175], v[180:183], v[120:123]
	v_mfma_f32_16x16x32_bf16 v[116:119], v[164:167], v[188:191], v[116:119]
	v_mfma_f32_16x16x32_bf16 v[108:111], v[172:175], v[188:191], v[108:111]
	v_mfma_f32_16x16x32_bf16 v[100:103], v[164:167], v[196:199], v[100:103]
	v_mfma_f32_16x16x32_bf16 v[92:95], v[172:175], v[196:199], v[92:95]
	v_mfma_f32_16x16x32_bf16 v[84:87], v[164:167], v[204:207], v[84:87]
	v_mfma_f32_16x16x32_bf16 v[76:79], v[172:175], v[204:207], v[76:79]
	v_mfma_f32_16x16x32_bf16 v[124:127], v[168:171], v[184:187], v[124:127]
	v_mfma_f32_16x16x32_bf16 v[120:123], v[176:179], v[184:187], v[120:123]
	v_mfma_f32_16x16x32_bf16 v[116:119], v[168:171], v[192:195], v[116:119]
	v_mfma_f32_16x16x32_bf16 v[108:111], v[176:179], v[192:195], v[108:111]
	v_mfma_f32_16x16x32_bf16 v[100:103], v[168:171], v[200:203], v[100:103]
	v_mfma_f32_16x16x32_bf16 v[92:95], v[176:179], v[200:203], v[92:95]
	v_mfma_f32_16x16x32_bf16 v[84:87], v[168:171], v[208:211], v[84:87]
	v_mfma_f32_16x16x32_bf16 v[76:79], v[176:179], v[208:211], v[76:79]
	s_barrier
	s_add_i32 s38, 0, 0x1c000
	s_add_i32 s39, s75, s57
	v_add_u32_e32 v224, s38, v161
	s_mov_b32 m0, s39
	ds_read_b128 v[212:215], v224
	ds_read_b128 v[216:219], v224 offset:1024
	ds_read_b128 v[220:223], v224 offset:2048
	ds_read_b128 v[224:227], v224 offset:3072
	global_load_lds_dwordx4 v128, s[98:99]
	s_add_i32 m0, s39, 0x2000
	s_nop 0
	global_load_lds_dwordx4 v130, s[98:99]
	s_barrier
	s_waitcnt lgkmcnt(0)
	v_mfma_f32_16x16x32_bf16 v[112:115], v[212:215], v[180:183], v[112:115]
	v_mfma_f32_16x16x32_bf16 v[104:107], v[220:223], v[180:183], v[104:107]
	v_mfma_f32_16x16x32_bf16 v[96:99], v[212:215], v[188:191], v[96:99]
	v_mfma_f32_16x16x32_bf16 v[88:91], v[220:223], v[188:191], v[88:91]
	v_mfma_f32_16x16x32_bf16 v[80:83], v[212:215], v[196:199], v[80:83]
	v_mfma_f32_16x16x32_bf16 v[72:75], v[220:223], v[196:199], v[72:75]
	v_mfma_f32_16x16x32_bf16 v[68:71], v[212:215], v[204:207], v[68:71]
	v_mfma_f32_16x16x32_bf16 v[64:67], v[220:223], v[204:207], v[64:67]
	v_mfma_f32_16x16x32_bf16 v[112:115], v[216:219], v[184:187], v[112:115]
	v_mfma_f32_16x16x32_bf16 v[104:107], v[224:227], v[184:187], v[104:107]
	v_mfma_f32_16x16x32_bf16 v[96:99], v[216:219], v[192:195], v[96:99]
	v_mfma_f32_16x16x32_bf16 v[88:91], v[224:227], v[192:195], v[88:91]
	v_mfma_f32_16x16x32_bf16 v[80:83], v[216:219], v[200:203], v[80:83]
	v_mfma_f32_16x16x32_bf16 v[72:75], v[224:227], v[200:203], v[72:75]
	v_mfma_f32_16x16x32_bf16 v[68:71], v[216:219], v[208:211], v[68:71]
	v_mfma_f32_16x16x32_bf16 v[64:67], v[224:227], v[208:211], v[64:67]
	s_mov_b32 m0, s63
	s_barrier
	ds_read_b128 v[180:183], v163 offset:49152
	ds_read_b128 v[184:187], v163 offset:50176
	ds_read_b128 v[188:191], v163 offset:51200
	ds_read_b128 v[192:195], v163 offset:52224
	ds_read_b128 v[196:199], v163 offset:53248
	ds_read_b128 v[200:203], v163 offset:54272
	ds_read_b128 v[204:207], v163 offset:55296
	ds_read_b128 v[208:211], v163 offset:56320
	global_load_lds_dwordx4 v134, s[100:101]
	s_mov_b32 m0, s64
	s_nop 0
	global_load_lds_dwordx4 v132, s[100:101]
	s_barrier
	s_waitcnt lgkmcnt(0)
	v_mfma_f32_16x16x32_bf16 v[60:63], v[164:167], v[180:183], v[60:63]
	v_mfma_f32_16x16x32_bf16 v[56:59], v[172:175], v[180:183], v[56:59]
	v_mfma_f32_16x16x32_bf16 v[52:55], v[164:167], v[188:191], v[52:55]
	v_mfma_f32_16x16x32_bf16 v[44:47], v[172:175], v[188:191], v[44:47]
	v_mfma_f32_16x16x32_bf16 v[36:39], v[164:167], v[196:199], v[36:39]
	v_mfma_f32_16x16x32_bf16 v[28:31], v[172:175], v[196:199], v[28:31]
	v_mfma_f32_16x16x32_bf16 v[20:23], v[164:167], v[204:207], v[20:23]
	v_mfma_f32_16x16x32_bf16 v[12:15], v[172:175], v[204:207], v[12:15]
	v_mfma_f32_16x16x32_bf16 v[60:63], v[168:171], v[184:187], v[60:63]
	v_mfma_f32_16x16x32_bf16 v[56:59], v[176:179], v[184:187], v[56:59]
	v_mfma_f32_16x16x32_bf16 v[52:55], v[168:171], v[192:195], v[52:55]
	v_mfma_f32_16x16x32_bf16 v[44:47], v[176:179], v[192:195], v[44:47]
	v_mfma_f32_16x16x32_bf16 v[36:39], v[168:171], v[200:203], v[36:39]
	v_mfma_f32_16x16x32_bf16 v[28:31], v[176:179], v[200:203], v[28:31]
	v_mfma_f32_16x16x32_bf16 v[20:23], v[168:171], v[208:211], v[20:23]
	v_mfma_f32_16x16x32_bf16 v[12:15], v[176:179], v[208:211], v[12:15]
	s_barrier
	s_add_u32 s36, s36, 0x40080
	s_addc_u32 s37, s37, 0
	s_add_i32 s38, s38, s57
	s_mov_b32 m0, s38
	s_nop 0
	global_load_lds_dwordx4 v128, s[36:37]
	s_add_i32 m0, s38, 0x2000
	s_nop 0
	global_load_lds_dwordx4 v130, s[36:37]
	s_waitcnt vmcnt(6)
	s_barrier
	v_mfma_f32_16x16x32_bf16 v[48:51], v[212:215], v[180:183], v[48:51]
	v_mfma_f32_16x16x32_bf16 v[40:43], v[220:223], v[180:183], v[40:43]
	v_mfma_f32_16x16x32_bf16 v[32:35], v[212:215], v[188:191], v[32:35]
	v_mfma_f32_16x16x32_bf16 v[24:27], v[220:223], v[188:191], v[24:27]
	v_mfma_f32_16x16x32_bf16 v[16:19], v[212:215], v[196:199], v[16:19]
	v_mfma_f32_16x16x32_bf16 v[8:11], v[220:223], v[196:199], v[8:11]
	v_mfma_f32_16x16x32_bf16 v[4:7], v[212:215], v[204:207], v[4:7]
	v_mfma_f32_16x16x32_bf16 v[0:3], v[220:223], v[204:207], v[0:3]
	v_mfma_f32_16x16x32_bf16 v[48:51], v[216:219], v[184:187], v[48:51]
	v_mfma_f32_16x16x32_bf16 v[40:43], v[224:227], v[184:187], v[40:43]
	v_mfma_f32_16x16x32_bf16 v[32:35], v[216:219], v[192:195], v[32:35]
	v_mfma_f32_16x16x32_bf16 v[24:27], v[224:227], v[192:195], v[24:27]
	v_mfma_f32_16x16x32_bf16 v[16:19], v[216:219], v[200:203], v[16:19]
	v_mfma_f32_16x16x32_bf16 v[8:11], v[224:227], v[200:203], v[8:11]
	v_mfma_f32_16x16x32_bf16 v[4:7], v[216:219], v[208:211], v[4:7]
	v_mfma_f32_16x16x32_bf16 v[0:3], v[224:227], v[208:211], v[0:3]
	s_add_i32 s74, s74, 2
	s_add_u32 s34, s34, 0x100
	s_addc_u32 s35, s35, 0
	s_add_u32 s71, s71, 0x100
	s_addc_u32 s73, s73, 0
	s_cmp_gt_u32 s74, 13
	s_barrier
	s_cbranch_scc0 .LBB0_189
	v_lshl_or_b32 v140, s68, 8, v162
	v_lshl_add_u32 v166, s30, 8, v159
	v_ashrrev_i32_e32 v141, 31, v140
	v_lshl_add_u64 v[140:141], v[140:141], 1, s[20:21]
	v_mad_i64_i32 v[164:165], s[34:35], v166, s52, 0
	v_lshl_add_u64 v[164:165], v[164:165], 1, v[140:141]
	v_cvt_pk_bf16_f32 v124, v124, v125
	v_cvt_pk_bf16_f32 v125, v126, v127
	v_cvt_pk_bf16_f32 v126, v120, v121
	v_cvt_pk_bf16_f32 v127, v122, v123
	global_store_dwordx4 v[164:165], v[124:127], off
	v_cvt_pk_bf16_f32 v112, v112, v113
	v_cvt_pk_bf16_f32 v113, v114, v115
	v_cvt_pk_bf16_f32 v114, v104, v105
	v_or_b32_e32 v104, 16, v166
	v_mad_i64_i32 v[104:105], s[34:35], v104, s52, 0
	v_cvt_pk_bf16_f32 v115, v106, v107
	global_store_dwordx4 v[164:165], v[112:115], off offset:256
	s_and_b64 vcc, exec, s[4:5]
	s_mov_b32 s68, s22
	v_lshl_add_u64 v[112:113], v[104:105], 1, v[140:141]
	v_cvt_pk_bf16_f32 v104, v116, v117
	v_cvt_pk_bf16_f32 v105, v118, v119
	v_cvt_pk_bf16_f32 v106, v108, v109
	v_cvt_pk_bf16_f32 v107, v110, v111
	global_store_dwordx4 v[112:113], v[104:107], off
	v_cvt_pk_bf16_f32 v96, v96, v97
	v_cvt_pk_bf16_f32 v97, v98, v99
	v_cvt_pk_bf16_f32 v98, v88, v89
	v_or_b32_e32 v88, 32, v166
	v_mad_i64_i32 v[88:89], s[34:35], v88, s52, 0
	v_cvt_pk_bf16_f32 v99, v90, v91
	global_store_dwordx4 v[112:113], v[96:99], off offset:256
	s_mov_b32 s30, s24
	s_mov_b64 s[36:37], s[28:29]
	v_lshl_add_u64 v[96:97], v[88:89], 1, v[140:141]
	v_cvt_pk_bf16_f32 v88, v100, v101
	v_cvt_pk_bf16_f32 v89, v102, v103
	v_cvt_pk_bf16_f32 v90, v92, v93
	v_cvt_pk_bf16_f32 v91, v94, v95
	global_store_dwordx4 v[96:97], v[88:91], off
	v_cvt_pk_bf16_f32 v80, v80, v81
	v_cvt_pk_bf16_f32 v81, v82, v83
	v_cvt_pk_bf16_f32 v82, v72, v73
	v_or_b32_e32 v72, 48, v166
	v_mad_i64_i32 v[72:73], s[34:35], v72, s52, 0
	v_cvt_pk_bf16_f32 v83, v74, v75
	global_store_dwordx4 v[96:97], v[80:83], off offset:256
	s_nop 1
	v_lshl_add_u64 v[80:81], v[72:73], 1, v[140:141]
	v_cvt_pk_bf16_f32 v72, v84, v85
	v_cvt_pk_bf16_f32 v73, v86, v87
	v_cvt_pk_bf16_f32 v74, v76, v77
	v_cvt_pk_bf16_f32 v75, v78, v79
	global_store_dwordx4 v[80:81], v[72:75], off
	v_cvt_pk_bf16_f32 v68, v68, v69
	v_cvt_pk_bf16_f32 v69, v70, v71
	v_cvt_pk_bf16_f32 v70, v64, v65
	v_add_u32_e32 v64, 0x80, v166
	v_mad_i64_i32 v[64:65], s[34:35], v64, s52, 0
	v_lshl_add_u64 v[64:65], v[64:65], 1, v[140:141]
	v_cvt_pk_bf16_f32 v71, v66, v67
	global_store_dwordx4 v[80:81], v[68:71], off offset:256
	v_cvt_pk_bf16_f32 v60, v60, v61
	v_cvt_pk_bf16_f32 v61, v62, v63
	v_cvt_pk_bf16_f32 v62, v56, v57
	v_cvt_pk_bf16_f32 v63, v58, v59
	global_store_dwordx4 v[64:65], v[60:63], off
	v_cvt_pk_bf16_f32 v48, v48, v49
	v_cvt_pk_bf16_f32 v49, v50, v51
	v_cvt_pk_bf16_f32 v50, v40, v41
	v_add_u32_e32 v40, 0x90, v166
	v_mad_i64_i32 v[40:41], s[34:35], v40, s52, 0
	v_cvt_pk_bf16_f32 v51, v42, v43
	global_store_dwordx4 v[64:65], v[48:51], off offset:256
	s_nop 1
	v_lshl_add_u64 v[48:49], v[40:41], 1, v[140:141]
	v_cvt_pk_bf16_f32 v40, v52, v53
	v_cvt_pk_bf16_f32 v41, v54, v55
	v_cvt_pk_bf16_f32 v42, v44, v45
	v_cvt_pk_bf16_f32 v43, v46, v47
	global_store_dwordx4 v[48:49], v[40:43], off
	v_cvt_pk_bf16_f32 v32, v32, v33
	v_cvt_pk_bf16_f32 v33, v34, v35
	v_cvt_pk_bf16_f32 v34, v24, v25
	v_add_u32_e32 v24, 0xa0, v166
	v_mad_i64_i32 v[24:25], s[34:35], v24, s52, 0
	v_cvt_pk_bf16_f32 v35, v26, v27
	global_store_dwordx4 v[48:49], v[32:35], off offset:256
	s_nop 1
	v_lshl_add_u64 v[32:33], v[24:25], 1, v[140:141]
	v_cvt_pk_bf16_f32 v24, v36, v37
	v_cvt_pk_bf16_f32 v25, v38, v39
	v_cvt_pk_bf16_f32 v26, v28, v29
	v_cvt_pk_bf16_f32 v27, v30, v31
	global_store_dwordx4 v[32:33], v[24:27], off
	v_cvt_pk_bf16_f32 v16, v16, v17
	v_cvt_pk_bf16_f32 v17, v18, v19
	v_cvt_pk_bf16_f32 v18, v8, v9
	v_add_u32_e32 v8, 0xb0, v166
	v_mad_i64_i32 v[8:9], s[34:35], v8, s52, 0
	v_cvt_pk_bf16_f32 v19, v10, v11
	global_store_dwordx4 v[32:33], v[16:19], off offset:256
	s_mov_b64 s[34:35], s[26:27]
	s_nop 0
	v_lshl_add_u64 v[16:17], v[8:9], 1, v[140:141]
	v_cvt_pk_bf16_f32 v8, v20, v21
	v_cvt_pk_bf16_f32 v9, v22, v23
	v_cvt_pk_bf16_f32 v10, v12, v13
	v_cvt_pk_bf16_f32 v11, v14, v15
	global_store_dwordx4 v[16:17], v[8:11], off
	v_cvt_pk_bf16_f32 v4, v4, v5
	v_cvt_pk_bf16_f32 v5, v6, v7
	v_cvt_pk_bf16_f32 v6, v0, v1
	v_cvt_pk_bf16_f32 v7, v2, v3
	global_store_dwordx4 v[16:17], v[4:7], off offset:256
	s_cbranch_vccz .LBB0_186
	s_waitcnt vmcnt(0)
	s_cmpk_gt_u32 s56, 0xff
	s_cbranch_scc1 .LBB0_174
	s_barrier
	s_branch .LBB0_174

.LBB0_203:
	ds_read_b128 v[144:147], v153
	ds_read_b128 v[156:159], v153 offset:1024
	ds_read_b128 v[162:165], v153 offset:2048
	ds_read_b128 v[166:169], v153 offset:3072
	s_add_u32 s26, s24, 0xfffc0080
	s_addc_u32 s27, s25, -1
	s_cmp_eq_u32 s54, 12
	s_cselect_b32 s29, s5, s27
	s_cselect_b32 s28, s17, s26
	s_cselect_b32 s27, s15, s53
	s_cselect_b32 s26, s23, s52
	s_add_i32 m0, s36, 0xc000
	ds_read_b128 v[170:173], v154
	ds_read_b128 v[174:177], v154 offset:1024
	ds_read_b128 v[178:181], v154 offset:2048
	ds_read_b128 v[182:185], v154 offset:3072
	ds_read_b128 v[186:189], v154 offset:4096
	ds_read_b128 v[190:193], v154 offset:5120
	ds_read_b128 v[194:197], v154 offset:6144
	ds_read_b128 v[198:201], v154 offset:7168
	global_load_lds_dwordx4 v136, s[24:25]
	s_add_i32 m0, s36, 0xe000
	s_nop 0
	global_load_lds_dwordx4 v138, s[24:25]
	s_waitcnt lgkmcnt(8)
	s_barrier
	s_waitcnt lgkmcnt(0)
	v_mfma_f32_16x16x32_bf16 v[124:127], v[144:147], v[170:173], v[124:127]
	v_mfma_f32_16x16x32_bf16 v[120:123], v[162:165], v[170:173], v[120:123]
	v_mfma_f32_16x16x32_bf16 v[108:111], v[144:147], v[178:181], v[108:111]
	v_mfma_f32_16x16x32_bf16 v[104:107], v[162:165], v[178:181], v[104:107]
	v_mfma_f32_16x16x32_bf16 v[92:95], v[144:147], v[186:189], v[92:95]
	v_mfma_f32_16x16x32_bf16 v[88:91], v[162:165], v[186:189], v[88:91]
	v_mfma_f32_16x16x32_bf16 v[76:79], v[144:147], v[194:197], v[76:79]
	v_mfma_f32_16x16x32_bf16 v[72:75], v[162:165], v[194:197], v[72:75]
	v_mfma_f32_16x16x32_bf16 v[124:127], v[156:159], v[174:177], v[124:127]
	v_mfma_f32_16x16x32_bf16 v[120:123], v[166:169], v[174:177], v[120:123]
	v_mfma_f32_16x16x32_bf16 v[108:111], v[156:159], v[182:185], v[108:111]
	v_mfma_f32_16x16x32_bf16 v[104:107], v[166:169], v[182:185], v[104:107]
	v_mfma_f32_16x16x32_bf16 v[92:95], v[156:159], v[190:193], v[92:95]
	v_mfma_f32_16x16x32_bf16 v[88:91], v[166:169], v[190:193], v[88:91]
	v_mfma_f32_16x16x32_bf16 v[76:79], v[156:159], v[198:201], v[76:79]
	v_mfma_f32_16x16x32_bf16 v[72:75], v[166:169], v[198:201], v[72:75]
	s_barrier
	s_add_i32 s55, s48, s35
	s_add_u32 s98, s26, s12
	s_addc_u32 s99, s27, s13
	s_mov_b32 m0, s55
	ds_read_b128 v[202:205], v155
	ds_read_b128 v[206:209], v155 offset:1024
	ds_read_b128 v[210:213], v155 offset:2048
	ds_read_b128 v[214:217], v155 offset:3072
	global_load_lds_dwordx4 v130, s[26:27]
	s_add_i32 m0, s55, 0x2000
	s_nop 0
	global_load_lds_dwordx4 v134, s[26:27]
	s_barrier
	s_waitcnt lgkmcnt(0)
	v_mfma_f32_16x16x32_bf16 v[116:119], v[202:205], v[170:173], v[116:119]
	v_mfma_f32_16x16x32_bf16 v[112:115], v[210:213], v[170:173], v[112:115]
	v_mfma_f32_16x16x32_bf16 v[100:103], v[202:205], v[178:181], v[100:103]
	v_mfma_f32_16x16x32_bf16 v[96:99], v[210:213], v[178:181], v[96:99]
	v_mfma_f32_16x16x32_bf16 v[84:87], v[202:205], v[186:189], v[84:87]
	v_mfma_f32_16x16x32_bf16 v[80:83], v[210:213], v[186:189], v[80:83]
	v_mfma_f32_16x16x32_bf16 v[68:71], v[202:205], v[194:197], v[68:71]
	v_mfma_f32_16x16x32_bf16 v[64:67], v[210:213], v[194:197], v[64:67]
	v_mfma_f32_16x16x32_bf16 v[116:119], v[206:209], v[174:177], v[116:119]
	v_mfma_f32_16x16x32_bf16 v[112:115], v[214:217], v[174:177], v[112:115]
	v_mfma_f32_16x16x32_bf16 v[100:103], v[206:209], v[182:185], v[100:103]
	v_mfma_f32_16x16x32_bf16 v[96:99], v[214:217], v[182:185], v[96:99]
	v_mfma_f32_16x16x32_bf16 v[84:87], v[206:209], v[190:193], v[84:87]
	v_mfma_f32_16x16x32_bf16 v[80:83], v[214:217], v[190:193], v[80:83]
	v_mfma_f32_16x16x32_bf16 v[68:71], v[206:209], v[198:201], v[68:71]
	v_mfma_f32_16x16x32_bf16 v[64:67], v[214:217], v[198:201], v[64:67]
	s_mov_b32 m0, s36
	s_add_u32 s100, s28, s12
	s_addc_u32 s101, s29, s13
	s_barrier
	ds_read_b128 v[170:173], v154 offset:16384
	ds_read_b128 v[174:177], v154 offset:17408
	ds_read_b128 v[178:181], v154 offset:18432
	ds_read_b128 v[182:185], v154 offset:19456
	ds_read_b128 v[186:189], v154 offset:20480
	ds_read_b128 v[190:193], v154 offset:21504
	ds_read_b128 v[194:197], v154 offset:22528
	ds_read_b128 v[198:201], v154 offset:23552
	global_load_lds_dwordx4 v128, s[28:29]
	s_mov_b32 m0, s37
	s_nop 0
	global_load_lds_dwordx4 v132, s[28:29]
	s_barrier
	s_waitcnt lgkmcnt(0)
	v_mfma_f32_16x16x32_bf16 v[60:63], v[144:147], v[170:173], v[60:63]
	v_mfma_f32_16x16x32_bf16 v[56:59], v[162:165], v[170:173], v[56:59]
	v_mfma_f32_16x16x32_bf16 v[44:47], v[144:147], v[178:181], v[44:47]
	v_mfma_f32_16x16x32_bf16 v[40:43], v[162:165], v[178:181], v[40:43]
	v_mfma_f32_16x16x32_bf16 v[28:31], v[144:147], v[186:189], v[28:31]
	v_mfma_f32_16x16x32_bf16 v[24:27], v[162:165], v[186:189], v[24:27]
	v_mfma_f32_16x16x32_bf16 v[12:15], v[144:147], v[194:197], v[12:15]
	v_mfma_f32_16x16x32_bf16 v[8:11], v[162:165], v[194:197], v[8:11]
	v_mfma_f32_16x16x32_bf16 v[60:63], v[156:159], v[174:177], v[60:63]
	v_mfma_f32_16x16x32_bf16 v[56:59], v[166:169], v[174:177], v[56:59]
	v_mfma_f32_16x16x32_bf16 v[44:47], v[156:159], v[182:185], v[44:47]
	v_mfma_f32_16x16x32_bf16 v[40:43], v[166:169], v[182:185], v[40:43]
	v_mfma_f32_16x16x32_bf16 v[28:31], v[156:159], v[190:193], v[28:31]
	v_mfma_f32_16x16x32_bf16 v[24:27], v[166:169], v[190:193], v[24:27]
	v_mfma_f32_16x16x32_bf16 v[12:15], v[156:159], v[198:201], v[12:15]
	v_mfma_f32_16x16x32_bf16 v[8:11], v[166:169], v[198:201], v[8:11]
	s_barrier
	s_add_u32 s56, s26, 0x40000
	s_addc_u32 s57, s27, 0
	s_add_i32 s55, s49, s35
	s_mov_b32 m0, s55
	s_nop 0
	global_load_lds_dwordx4 v130, s[56:57]
	s_add_i32 m0, s55, 0x2000
	s_nop 0
	global_load_lds_dwordx4 v134, s[56:57]
	s_waitcnt vmcnt(6)
	s_barrier
	v_mfma_f32_16x16x32_bf16 v[52:55], v[202:205], v[170:173], v[52:55]
	v_mfma_f32_16x16x32_bf16 v[48:51], v[210:213], v[170:173], v[48:51]
	v_mfma_f32_16x16x32_bf16 v[36:39], v[202:205], v[178:181], v[36:39]
	v_mfma_f32_16x16x32_bf16 v[32:35], v[210:213], v[178:181], v[32:35]
	v_mfma_f32_16x16x32_bf16 v[20:23], v[202:205], v[186:189], v[20:23]
	v_mfma_f32_16x16x32_bf16 v[16:19], v[210:213], v[186:189], v[16:19]
	v_mfma_f32_16x16x32_bf16 v[4:7], v[202:205], v[194:197], v[4:7]
	v_mfma_f32_16x16x32_bf16 v[0:3], v[210:213], v[194:197], v[0:3]
	v_mfma_f32_16x16x32_bf16 v[52:55], v[206:209], v[174:177], v[52:55]
	v_mfma_f32_16x16x32_bf16 v[48:51], v[214:217], v[174:177], v[48:51]
	v_mfma_f32_16x16x32_bf16 v[36:39], v[206:209], v[182:185], v[36:39]
	v_mfma_f32_16x16x32_bf16 v[32:35], v[214:217], v[182:185], v[32:35]
	v_mfma_f32_16x16x32_bf16 v[20:23], v[206:209], v[190:193], v[20:23]
	v_mfma_f32_16x16x32_bf16 v[16:19], v[214:217], v[190:193], v[16:19]
	v_mfma_f32_16x16x32_bf16 v[4:7], v[206:209], v[198:201], v[4:7]
	v_mfma_f32_16x16x32_bf16 v[0:3], v[214:217], v[198:201], v[0:3]
	s_add_i32 s55, 0, 0x18000
	v_add_u32_e32 v161, s55, v151
	s_barrier
	ds_read_b128 v[144:147], v161
	ds_read_b128 v[156:159], v161 offset:1024
	ds_read_b128 v[162:165], v161 offset:2048
	ds_read_b128 v[166:169], v161 offset:3072
	s_add_u32 s28, s28, 0x40000
	s_addc_u32 s29, s29, 0
	s_mov_b32 m0, s38
	ds_read_b128 v[170:173], v154 offset:32768
	ds_read_b128 v[174:177], v154 offset:33792
	ds_read_b128 v[178:181], v154 offset:34816
	ds_read_b128 v[182:185], v154 offset:35840
	ds_read_b128 v[186:189], v154 offset:36864
	ds_read_b128 v[190:193], v154 offset:37888
	ds_read_b128 v[194:197], v154 offset:38912
	ds_read_b128 v[198:201], v154 offset:39936
	global_load_lds_dwordx4 v128, s[28:29]
	s_mov_b32 m0, s39
	s_nop 0
	global_load_lds_dwordx4 v132, s[28:29]
	s_waitcnt lgkmcnt(8)
	s_barrier
	s_waitcnt lgkmcnt(0)
	v_mfma_f32_16x16x32_bf16 v[124:127], v[144:147], v[170:173], v[124:127]
	v_mfma_f32_16x16x32_bf16 v[120:123], v[162:165], v[170:173], v[120:123]
	v_mfma_f32_16x16x32_bf16 v[108:111], v[144:147], v[178:181], v[108:111]
	v_mfma_f32_16x16x32_bf16 v[104:107], v[162:165], v[178:181], v[104:107]
	v_mfma_f32_16x16x32_bf16 v[92:95], v[144:147], v[186:189], v[92:95]
	v_mfma_f32_16x16x32_bf16 v[88:91], v[162:165], v[186:189], v[88:91]
	v_mfma_f32_16x16x32_bf16 v[76:79], v[144:147], v[194:197], v[76:79]
	v_mfma_f32_16x16x32_bf16 v[72:75], v[162:165], v[194:197], v[72:75]
	v_mfma_f32_16x16x32_bf16 v[124:127], v[156:159], v[174:177], v[124:127]
	v_mfma_f32_16x16x32_bf16 v[120:123], v[166:169], v[174:177], v[120:123]
	v_mfma_f32_16x16x32_bf16 v[108:111], v[156:159], v[182:185], v[108:111]
	v_mfma_f32_16x16x32_bf16 v[104:107], v[166:169], v[182:185], v[104:107]
	v_mfma_f32_16x16x32_bf16 v[92:95], v[156:159], v[190:193], v[92:95]
	v_mfma_f32_16x16x32_bf16 v[88:91], v[166:169], v[190:193], v[88:91]
	v_mfma_f32_16x16x32_bf16 v[76:79], v[156:159], v[198:201], v[76:79]
	v_mfma_f32_16x16x32_bf16 v[72:75], v[166:169], v[198:201], v[72:75]
	s_barrier
	s_add_i32 s28, 0, 0x1c000
	s_add_i32 s29, s55, s35
	v_add_u32_e32 v161, s28, v151
	s_mov_b32 m0, s29
	ds_read_b128 v[202:205], v161
	ds_read_b128 v[206:209], v161 offset:1024
	ds_read_b128 v[210:213], v161 offset:2048
	ds_read_b128 v[214:217], v161 offset:3072
	global_load_lds_dwordx4 v130, s[98:99]
	s_add_i32 m0, s29, 0x2000
	s_nop 0
	global_load_lds_dwordx4 v134, s[98:99]
	s_barrier
	s_waitcnt lgkmcnt(0)
	v_mfma_f32_16x16x32_bf16 v[116:119], v[202:205], v[170:173], v[116:119]
	v_mfma_f32_16x16x32_bf16 v[112:115], v[210:213], v[170:173], v[112:115]
	v_mfma_f32_16x16x32_bf16 v[100:103], v[202:205], v[178:181], v[100:103]
	v_mfma_f32_16x16x32_bf16 v[96:99], v[210:213], v[178:181], v[96:99]
	v_mfma_f32_16x16x32_bf16 v[84:87], v[202:205], v[186:189], v[84:87]
	v_mfma_f32_16x16x32_bf16 v[80:83], v[210:213], v[186:189], v[80:83]
	v_mfma_f32_16x16x32_bf16 v[68:71], v[202:205], v[194:197], v[68:71]
	v_mfma_f32_16x16x32_bf16 v[64:67], v[210:213], v[194:197], v[64:67]
	v_mfma_f32_16x16x32_bf16 v[116:119], v[206:209], v[174:177], v[116:119]
	v_mfma_f32_16x16x32_bf16 v[112:115], v[214:217], v[174:177], v[112:115]
	v_mfma_f32_16x16x32_bf16 v[100:103], v[206:209], v[182:185], v[100:103]
	v_mfma_f32_16x16x32_bf16 v[96:99], v[214:217], v[182:185], v[96:99]
	v_mfma_f32_16x16x32_bf16 v[84:87], v[206:209], v[190:193], v[84:87]
	v_mfma_f32_16x16x32_bf16 v[80:83], v[214:217], v[190:193], v[80:83]
	v_mfma_f32_16x16x32_bf16 v[68:71], v[206:209], v[198:201], v[68:71]
	v_mfma_f32_16x16x32_bf16 v[64:67], v[214:217], v[198:201], v[64:67]
	s_mov_b32 m0, s44
	s_barrier
	ds_read_b128 v[170:173], v154 offset:49152
	ds_read_b128 v[174:177], v154 offset:50176
	ds_read_b128 v[178:181], v154 offset:51200
	ds_read_b128 v[182:185], v154 offset:52224
	ds_read_b128 v[186:189], v154 offset:53248
	ds_read_b128 v[190:193], v154 offset:54272
	ds_read_b128 v[194:197], v154 offset:55296
	ds_read_b128 v[198:201], v154 offset:56320
	global_load_lds_dwordx4 v128, s[100:101]
	s_mov_b32 m0, s46
	s_nop 0
	global_load_lds_dwordx4 v132, s[100:101]
	s_barrier
	s_waitcnt lgkmcnt(0)
	v_mfma_f32_16x16x32_bf16 v[60:63], v[144:147], v[170:173], v[60:63]
	v_mfma_f32_16x16x32_bf16 v[56:59], v[162:165], v[170:173], v[56:59]
	v_mfma_f32_16x16x32_bf16 v[44:47], v[144:147], v[178:181], v[44:47]
	v_mfma_f32_16x16x32_bf16 v[40:43], v[162:165], v[178:181], v[40:43]
	v_mfma_f32_16x16x32_bf16 v[28:31], v[144:147], v[186:189], v[28:31]
	v_mfma_f32_16x16x32_bf16 v[24:27], v[162:165], v[186:189], v[24:27]
	v_mfma_f32_16x16x32_bf16 v[12:15], v[144:147], v[194:197], v[12:15]
	v_mfma_f32_16x16x32_bf16 v[8:11], v[162:165], v[194:197], v[8:11]
	v_mfma_f32_16x16x32_bf16 v[60:63], v[156:159], v[174:177], v[60:63]
	v_mfma_f32_16x16x32_bf16 v[56:59], v[166:169], v[174:177], v[56:59]
	v_mfma_f32_16x16x32_bf16 v[44:47], v[156:159], v[182:185], v[44:47]
	v_mfma_f32_16x16x32_bf16 v[40:43], v[166:169], v[182:185], v[40:43]
	v_mfma_f32_16x16x32_bf16 v[28:31], v[156:159], v[190:193], v[28:31]
	v_mfma_f32_16x16x32_bf16 v[24:27], v[166:169], v[190:193], v[24:27]
	v_mfma_f32_16x16x32_bf16 v[12:15], v[156:159], v[198:201], v[12:15]
	v_mfma_f32_16x16x32_bf16 v[8:11], v[166:169], v[198:201], v[8:11]
	s_barrier
	s_add_u32 s26, s26, 0x40080
	s_addc_u32 s27, s27, 0
	s_add_i32 s28, s28, s35
	s_mov_b32 m0, s28
	s_nop 0
	global_load_lds_dwordx4 v130, s[26:27]
	s_add_i32 m0, s28, 0x2000
	s_nop 0
	global_load_lds_dwordx4 v134, s[26:27]
	s_waitcnt vmcnt(6)
	s_barrier
	v_mfma_f32_16x16x32_bf16 v[52:55], v[202:205], v[170:173], v[52:55]
	v_mfma_f32_16x16x32_bf16 v[48:51], v[210:213], v[170:173], v[48:51]
	v_mfma_f32_16x16x32_bf16 v[36:39], v[202:205], v[178:181], v[36:39]
	v_mfma_f32_16x16x32_bf16 v[32:35], v[210:213], v[178:181], v[32:35]
	v_mfma_f32_16x16x32_bf16 v[20:23], v[202:205], v[186:189], v[20:23]
	v_mfma_f32_16x16x32_bf16 v[16:19], v[210:213], v[186:189], v[16:19]
	v_mfma_f32_16x16x32_bf16 v[4:7], v[202:205], v[194:197], v[4:7]
	v_mfma_f32_16x16x32_bf16 v[0:3], v[210:213], v[194:197], v[0:3]
	v_mfma_f32_16x16x32_bf16 v[52:55], v[206:209], v[174:177], v[52:55]
	v_mfma_f32_16x16x32_bf16 v[48:51], v[214:217], v[174:177], v[48:51]
	v_mfma_f32_16x16x32_bf16 v[36:39], v[206:209], v[182:185], v[36:39]
	v_mfma_f32_16x16x32_bf16 v[32:35], v[214:217], v[182:185], v[32:35]
	v_mfma_f32_16x16x32_bf16 v[20:23], v[206:209], v[190:193], v[20:23]
	v_mfma_f32_16x16x32_bf16 v[16:19], v[214:217], v[190:193], v[16:19]
	v_mfma_f32_16x16x32_bf16 v[4:7], v[206:209], v[198:201], v[4:7]
	v_mfma_f32_16x16x32_bf16 v[0:3], v[214:217], v[198:201], v[0:3]
	s_add_i32 s54, s54, 2
	s_add_u32 s24, s24, 0x100
	s_addc_u32 s25, s25, 0
	s_add_u32 s52, s52, 0x100
	s_addc_u32 s53, s53, 0
	s_cmp_gt_u32 s54, 13
	s_barrier
	s_cbranch_scc0 .LBB0_203
	v_lshl_or_b32 v148, s22, 8, v152
	v_cmp_lt_i32_e32 vcc, s50, v148
	s_and_saveexec_b64 s[22:23], vcc
	s_cbranch_execz .LBB0_206
	v_mul_f32_e32 v149, 0x3d372713, v126
	v_mul_f32_e32 v145, 0x3d372713, v120
	v_mul_f32_e32 v149, v126, v149
	v_mul_f32_e32 v156, 0x3d372713, v122
	v_mul_f32_e32 v145, v120, v145
	v_mul_f32_e32 v146, 0x3d372713, v125
	v_fma_f32 v149, v126, v149, v126
	v_mul_f32_e32 v156, v122, v156
	v_fma_f32 v145, v120, v145, v120
	v_mul_f32_e32 v146, v125, v146
	v_mul_f32_e32 v149, 0xc0135761, v149
	v_fma_f32 v156, v122, v156, v122
	v_mul_f32_e32 v145, 0xc0135761, v145
	v_fma_f32 v146, v125, v146, v125
	v_exp_f32_e32 v149, v149
	v_mul_f32_e32 v156, 0xc0135761, v156
	v_exp_f32_e32 v145, v145
	v_mul_f32_e32 v146, 0xc0135761, v146
	v_exp_f32_e32 v157, v156
	v_exp_f32_e32 v147, v146
	v_add_f32_e32 v149, 1.0, v149
	v_add_f32_e32 v145, 1.0, v145
	v_rcp_f32_e32 v156, v149
	v_add_f32_e32 v149, 1.0, v157
	v_mul_f32_e32 v157, 0x3d372713, v127
	v_mul_f32_e32 v144, 0x3d372713, v124
	v_rcp_f32_e32 v146, v145
	v_add_f32_e32 v145, 1.0, v147
	v_mul_f32_e32 v147, 0x3d372713, v121
	v_mul_f32_e32 v157, v127, v157
	v_mul_f32_e32 v158, 0x3d372713, v123
	v_mul_f32_e32 v144, v124, v144
	v_mul_f32_e32 v147, v121, v147
	v_fma_f32 v157, v127, v157, v127
	v_mul_f32_e32 v158, v123, v158
	v_fma_f32 v144, v124, v144, v124
	v_fma_f32 v147, v121, v147, v121
	v_mul_f32_e32 v157, 0xc0135761, v157
	v_fma_f32 v158, v123, v158, v123
	v_mul_f32_e32 v144, 0xc0135761, v144
	v_mul_f32_e32 v147, 0xc0135761, v147
	v_exp_f32_e32 v157, v157
	v_mul_f32_e32 v158, 0xc0135761, v158
	v_exp_f32_e32 v144, v144
	v_exp_f32_e32 v147, v147
	v_exp_f32_e32 v159, v158
	v_rcp_f32_e32 v158, v149
	v_add_f32_e32 v149, 1.0, v157
	v_add_f32_e32 v144, 1.0, v144
	v_add_f32_e32 v147, 1.0, v147
	v_rcp_f32_e32 v157, v149
	v_add_f32_e32 v149, 1.0, v159
	v_rcp_f32_e32 v144, v144
	v_rcp_f32_e32 v145, v145
	v_rcp_f32_e32 v159, v149
	v_rcp_f32_e32 v147, v147
	v_pk_mul_f32 v[126:127], v[126:127], v[156:157]
	v_pk_mul_f32 v[124:125], v[124:125], v[144:145]
	v_pk_mul_f32 v[122:123], v[122:123], v[158:159]
	v_pk_mul_f32 v[120:121], v[120:121], v[146:147]

.LBB0_321:
	ds_read_b128 v[144:147], v157
	ds_read_b128 v[148:151], v157 offset:1024
	ds_read_b128 v[164:167], v157 offset:2048
	ds_read_b128 v[168:171], v157 offset:3072
	s_add_u32 s4, s8, 0x100
	s_addc_u32 s5, s9, 0
	s_cmp_eq_u32 s60, 2
	s_cselect_b32 s11, s29, s5
	s_cselect_b32 s10, s28, s4
	s_cselect_b32 s7, s31, s37
	s_cselect_b32 s6, s30, s35
	v_lshl_add_u64 v[152:153], s[8:9], 0, v[136:137]
	s_add_i32 m0, s46, 0xc000
	ds_read_b128 v[172:175], v158
	ds_read_b128 v[176:179], v158 offset:1024
	ds_read_b128 v[180:183], v158 offset:2048
	ds_read_b128 v[184:187], v158 offset:3072
	ds_read_b128 v[188:191], v158 offset:4096
	ds_read_b128 v[192:195], v158 offset:5120
	ds_read_b128 v[196:199], v158 offset:6144
	ds_read_b128 v[200:203], v158 offset:7168
	global_load_lds_dwordx4 v[152:153], off
	v_lshl_add_u64 v[152:153], s[8:9], 0, v[138:139]
	s_add_i32 m0, s46, 0xe000
	s_nop 0
	global_load_lds_dwordx4 v[152:153], off
	s_waitcnt lgkmcnt(8)
	s_barrier
	s_waitcnt lgkmcnt(0)
	v_mfma_f32_16x16x32_bf16 v[124:127], v[144:147], v[172:175], v[124:127]
	v_mfma_f32_16x16x32_bf16 v[120:123], v[164:167], v[172:175], v[120:123]
	v_mfma_f32_16x16x32_bf16 v[116:119], v[144:147], v[180:183], v[116:119]
	v_mfma_f32_16x16x32_bf16 v[112:115], v[164:167], v[180:183], v[112:115]
	v_mfma_f32_16x16x32_bf16 v[108:111], v[144:147], v[188:191], v[108:111]
	v_mfma_f32_16x16x32_bf16 v[104:107], v[164:167], v[188:191], v[104:107]
	v_mfma_f32_16x16x32_bf16 v[100:103], v[144:147], v[196:199], v[100:103]
	v_mfma_f32_16x16x32_bf16 v[96:99], v[164:167], v[196:199], v[96:99]
	v_mfma_f32_16x16x32_bf16 v[124:127], v[148:151], v[176:179], v[124:127]
	v_mfma_f32_16x16x32_bf16 v[120:123], v[168:171], v[176:179], v[120:123]
	v_mfma_f32_16x16x32_bf16 v[116:119], v[148:151], v[184:187], v[116:119]
	v_mfma_f32_16x16x32_bf16 v[112:115], v[168:171], v[184:187], v[112:115]
	v_mfma_f32_16x16x32_bf16 v[108:111], v[148:151], v[192:195], v[108:111]
	v_mfma_f32_16x16x32_bf16 v[104:107], v[168:171], v[192:195], v[104:107]
	v_mfma_f32_16x16x32_bf16 v[100:103], v[148:151], v[200:203], v[100:103]
	v_mfma_f32_16x16x32_bf16 v[96:99], v[168:171], v[200:203], v[96:99]
	s_barrier
	s_add_i32 s8, s54, s44
	s_add_u32 s98, s6, s26
	s_addc_u32 s99, s7, s27
	s_mov_b32 m0, s8
	ds_read_b128 v[204:207], v159
	ds_read_b128 v[208:211], v159 offset:1024
	ds_read_b128 v[212:215], v159 offset:2048
	ds_read_b128 v[216:219], v159 offset:3072
	global_load_lds_dwordx4 v130, s[6:7]
	s_add_i32 m0, s8, 0x2000
	s_nop 0
	global_load_lds_dwordx4 v134, s[6:7]
	s_barrier
	s_waitcnt lgkmcnt(0)
	v_mfma_f32_16x16x32_bf16 v[60:63], v[204:207], v[172:175], v[60:63]
	v_mfma_f32_16x16x32_bf16 v[56:59], v[212:215], v[172:175], v[56:59]
	v_mfma_f32_16x16x32_bf16 v[52:55], v[204:207], v[180:183], v[52:55]
	v_mfma_f32_16x16x32_bf16 v[48:51], v[212:215], v[180:183], v[48:51]
	v_mfma_f32_16x16x32_bf16 v[44:47], v[204:207], v[188:191], v[44:47]
	v_mfma_f32_16x16x32_bf16 v[40:43], v[212:215], v[188:191], v[40:43]
	v_mfma_f32_16x16x32_bf16 v[36:39], v[204:207], v[196:199], v[36:39]
	v_mfma_f32_16x16x32_bf16 v[32:35], v[212:215], v[196:199], v[32:35]
	v_mfma_f32_16x16x32_bf16 v[60:63], v[208:211], v[176:179], v[60:63]
	v_mfma_f32_16x16x32_bf16 v[56:59], v[216:219], v[176:179], v[56:59]
	v_mfma_f32_16x16x32_bf16 v[52:55], v[208:211], v[184:187], v[52:55]
	v_mfma_f32_16x16x32_bf16 v[48:51], v[216:219], v[184:187], v[48:51]
	v_mfma_f32_16x16x32_bf16 v[44:47], v[208:211], v[192:195], v[44:47]
	v_mfma_f32_16x16x32_bf16 v[40:43], v[216:219], v[192:195], v[40:43]
	v_mfma_f32_16x16x32_bf16 v[36:39], v[208:211], v[200:203], v[36:39]
	v_mfma_f32_16x16x32_bf16 v[32:35], v[216:219], v[200:203], v[32:35]
	s_mov_b32 m0, s46
	s_add_u32 s100, s10, s26
	s_addc_u32 s101, s11, s27
	s_barrier
	ds_read_b128 v[172:175], v158 offset:16384
	ds_read_b128 v[176:179], v158 offset:17408
	ds_read_b128 v[180:183], v158 offset:18432
	ds_read_b128 v[184:187], v158 offset:19456
	ds_read_b128 v[188:191], v158 offset:20480
	ds_read_b128 v[192:195], v158 offset:21504
	ds_read_b128 v[196:199], v158 offset:22528
	ds_read_b128 v[200:203], v158 offset:23552
	global_load_lds_dwordx4 v128, s[10:11]
	s_mov_b32 m0, s47
	s_nop 0
	global_load_lds_dwordx4 v132, s[10:11]
	s_barrier
	s_waitcnt lgkmcnt(0)
	v_mfma_f32_16x16x32_bf16 v[92:95], v[144:147], v[172:175], v[92:95]
	v_mfma_f32_16x16x32_bf16 v[88:91], v[164:167], v[172:175], v[88:91]
	v_mfma_f32_16x16x32_bf16 v[84:87], v[144:147], v[180:183], v[84:87]
	v_mfma_f32_16x16x32_bf16 v[80:83], v[164:167], v[180:183], v[80:83]
	v_mfma_f32_16x16x32_bf16 v[76:79], v[144:147], v[188:191], v[76:79]
	v_mfma_f32_16x16x32_bf16 v[72:75], v[164:167], v[188:191], v[72:75]
	v_mfma_f32_16x16x32_bf16 v[68:71], v[144:147], v[196:199], v[68:71]
	v_mfma_f32_16x16x32_bf16 v[64:67], v[164:167], v[196:199], v[64:67]
	v_mfma_f32_16x16x32_bf16 v[92:95], v[148:151], v[176:179], v[92:95]
	v_mfma_f32_16x16x32_bf16 v[88:91], v[168:171], v[176:179], v[88:91]
	v_mfma_f32_16x16x32_bf16 v[84:87], v[148:151], v[184:187], v[84:87]
	v_mfma_f32_16x16x32_bf16 v[80:83], v[168:171], v[184:187], v[80:83]
	v_mfma_f32_16x16x32_bf16 v[76:79], v[148:151], v[192:195], v[76:79]
	v_mfma_f32_16x16x32_bf16 v[72:75], v[168:171], v[192:195], v[72:75]
	v_mfma_f32_16x16x32_bf16 v[68:71], v[148:151], v[200:203], v[68:71]
	v_mfma_f32_16x16x32_bf16 v[64:67], v[168:171], v[200:203], v[64:67]
	s_barrier
	s_add_u32 s8, s6, 0x18000
	s_addc_u32 s9, s7, 0
	s_add_i32 s61, s55, s44
	s_mov_b32 m0, s61
	s_nop 0
	global_load_lds_dwordx4 v130, s[8:9]
	s_add_i32 m0, s61, 0x2000
	s_nop 0
	global_load_lds_dwordx4 v134, s[8:9]
	s_waitcnt vmcnt(6)
	s_barrier
	v_mfma_f32_16x16x32_bf16 v[28:31], v[204:207], v[172:175], v[28:31]
	v_mfma_f32_16x16x32_bf16 v[24:27], v[212:215], v[172:175], v[24:27]
	v_mfma_f32_16x16x32_bf16 v[20:23], v[204:207], v[180:183], v[20:23]
	v_mfma_f32_16x16x32_bf16 v[16:19], v[212:215], v[180:183], v[16:19]
	v_mfma_f32_16x16x32_bf16 v[12:15], v[204:207], v[188:191], v[12:15]
	v_mfma_f32_16x16x32_bf16 v[8:11], v[212:215], v[188:191], v[8:11]
	v_mfma_f32_16x16x32_bf16 v[4:7], v[204:207], v[196:199], v[4:7]
	v_mfma_f32_16x16x32_bf16 v[0:3], v[212:215], v[196:199], v[0:3]
	v_mfma_f32_16x16x32_bf16 v[28:31], v[208:211], v[176:179], v[28:31]
	v_mfma_f32_16x16x32_bf16 v[24:27], v[216:219], v[176:179], v[24:27]
	v_mfma_f32_16x16x32_bf16 v[20:23], v[208:211], v[184:187], v[20:23]
	v_mfma_f32_16x16x32_bf16 v[16:19], v[216:219], v[184:187], v[16:19]
	v_mfma_f32_16x16x32_bf16 v[12:15], v[208:211], v[192:195], v[12:15]
	v_mfma_f32_16x16x32_bf16 v[8:11], v[216:219], v[192:195], v[8:11]
	v_mfma_f32_16x16x32_bf16 v[4:7], v[208:211], v[200:203], v[4:7]
	v_mfma_f32_16x16x32_bf16 v[0:3], v[216:219], v[200:203], v[0:3]
	s_add_i32 s61, 0, 0x18000
	v_add_u32_e32 v163, s61, v155
	s_barrier
	ds_read_b128 v[144:147], v163
	ds_read_b128 v[148:151], v163 offset:1024
	ds_read_b128 v[164:167], v163 offset:2048
	ds_read_b128 v[168:171], v163 offset:3072
	s_add_u32 s8, s10, 0x18000
	s_addc_u32 s9, s11, 0
	s_mov_b32 m0, s48
	ds_read_b128 v[172:175], v158 offset:32768
	ds_read_b128 v[176:179], v158 offset:33792
	ds_read_b128 v[180:183], v158 offset:34816
	ds_read_b128 v[184:187], v158 offset:35840
	ds_read_b128 v[188:191], v158 offset:36864
	ds_read_b128 v[192:195], v158 offset:37888
	ds_read_b128 v[196:199], v158 offset:38912
	ds_read_b128 v[200:203], v158 offset:39936
	global_load_lds_dwordx4 v128, s[8:9]
	s_mov_b32 m0, s49
	s_nop 0
	global_load_lds_dwordx4 v132, s[8:9]
	s_waitcnt lgkmcnt(8)
	s_barrier
	s_waitcnt lgkmcnt(0)
	v_mfma_f32_16x16x32_bf16 v[124:127], v[144:147], v[172:175], v[124:127]
	v_mfma_f32_16x16x32_bf16 v[120:123], v[164:167], v[172:175], v[120:123]
	v_mfma_f32_16x16x32_bf16 v[116:119], v[144:147], v[180:183], v[116:119]
	v_mfma_f32_16x16x32_bf16 v[112:115], v[164:167], v[180:183], v[112:115]
	v_mfma_f32_16x16x32_bf16 v[108:111], v[144:147], v[188:191], v[108:111]
	v_mfma_f32_16x16x32_bf16 v[104:107], v[164:167], v[188:191], v[104:107]
	v_mfma_f32_16x16x32_bf16 v[100:103], v[144:147], v[196:199], v[100:103]
	v_mfma_f32_16x16x32_bf16 v[96:99], v[164:167], v[196:199], v[96:99]
	v_mfma_f32_16x16x32_bf16 v[124:127], v[148:151], v[176:179], v[124:127]
	v_mfma_f32_16x16x32_bf16 v[120:123], v[168:171], v[176:179], v[120:123]
	v_mfma_f32_16x16x32_bf16 v[116:119], v[148:151], v[184:187], v[116:119]
	v_mfma_f32_16x16x32_bf16 v[112:115], v[168:171], v[184:187], v[112:115]
	v_mfma_f32_16x16x32_bf16 v[108:111], v[148:151], v[192:195], v[108:111]
	v_mfma_f32_16x16x32_bf16 v[104:107], v[168:171], v[192:195], v[104:107]
	v_mfma_f32_16x16x32_bf16 v[100:103], v[148:151], v[200:203], v[100:103]
	v_mfma_f32_16x16x32_bf16 v[96:99], v[168:171], v[200:203], v[96:99]
	s_barrier
	s_add_i32 s8, 0, 0x1c000
	s_add_i32 s9, s61, s44
	v_add_u32_e32 v163, s8, v155
	s_mov_b32 m0, s9
	ds_read_b128 v[204:207], v163
	ds_read_b128 v[208:211], v163 offset:1024
	ds_read_b128 v[212:215], v163 offset:2048
	ds_read_b128 v[216:219], v163 offset:3072
	global_load_lds_dwordx4 v130, s[98:99]
	s_add_i32 m0, s9, 0x2000
	s_nop 0
	global_load_lds_dwordx4 v134, s[98:99]
	s_barrier
	s_waitcnt lgkmcnt(0)
	v_mfma_f32_16x16x32_bf16 v[60:63], v[204:207], v[172:175], v[60:63]
	v_mfma_f32_16x16x32_bf16 v[56:59], v[212:215], v[172:175], v[56:59]
	v_mfma_f32_16x16x32_bf16 v[52:55], v[204:207], v[180:183], v[52:55]
	v_mfma_f32_16x16x32_bf16 v[48:51], v[212:215], v[180:183], v[48:51]
	v_mfma_f32_16x16x32_bf16 v[44:47], v[204:207], v[188:191], v[44:47]
	v_mfma_f32_16x16x32_bf16 v[40:43], v[212:215], v[188:191], v[40:43]
	v_mfma_f32_16x16x32_bf16 v[36:39], v[204:207], v[196:199], v[36:39]
	v_mfma_f32_16x16x32_bf16 v[32:35], v[212:215], v[196:199], v[32:35]
	v_mfma_f32_16x16x32_bf16 v[60:63], v[208:211], v[176:179], v[60:63]
	v_mfma_f32_16x16x32_bf16 v[56:59], v[216:219], v[176:179], v[56:59]
	v_mfma_f32_16x16x32_bf16 v[52:55], v[208:211], v[184:187], v[52:55]
	v_mfma_f32_16x16x32_bf16 v[48:51], v[216:219], v[184:187], v[48:51]
	v_mfma_f32_16x16x32_bf16 v[44:47], v[208:211], v[192:195], v[44:47]
	v_mfma_f32_16x16x32_bf16 v[40:43], v[216:219], v[192:195], v[40:43]
	v_mfma_f32_16x16x32_bf16 v[36:39], v[208:211], v[200:203], v[36:39]
	v_mfma_f32_16x16x32_bf16 v[32:35], v[216:219], v[200:203], v[32:35]
	s_mov_b32 m0, s51
	s_barrier
	ds_read_b128 v[172:175], v158 offset:49152
	ds_read_b128 v[176:179], v158 offset:50176
	ds_read_b128 v[180:183], v158 offset:51200
	ds_read_b128 v[184:187], v158 offset:52224
	ds_read_b128 v[188:191], v158 offset:53248
	ds_read_b128 v[192:195], v158 offset:54272
	ds_read_b128 v[196:199], v158 offset:55296
	ds_read_b128 v[200:203], v158 offset:56320
	global_load_lds_dwordx4 v128, s[100:101]
	s_mov_b32 m0, s52
	s_nop 0
	global_load_lds_dwordx4 v132, s[100:101]
	s_barrier
	s_waitcnt lgkmcnt(0)
	v_mfma_f32_16x16x32_bf16 v[92:95], v[144:147], v[172:175], v[92:95]
	v_mfma_f32_16x16x32_bf16 v[88:91], v[164:167], v[172:175], v[88:91]
	v_mfma_f32_16x16x32_bf16 v[84:87], v[144:147], v[180:183], v[84:87]
	v_mfma_f32_16x16x32_bf16 v[80:83], v[164:167], v[180:183], v[80:83]
	v_mfma_f32_16x16x32_bf16 v[76:79], v[144:147], v[188:191], v[76:79]
	v_mfma_f32_16x16x32_bf16 v[72:75], v[164:167], v[188:191], v[72:75]
	v_mfma_f32_16x16x32_bf16 v[68:71], v[144:147], v[196:199], v[68:71]
	v_mfma_f32_16x16x32_bf16 v[64:67], v[164:167], v[196:199], v[64:67]
	v_mfma_f32_16x16x32_bf16 v[92:95], v[148:151], v[176:179], v[92:95]
	v_mfma_f32_16x16x32_bf16 v[88:91], v[168:171], v[176:179], v[88:91]
	v_mfma_f32_16x16x32_bf16 v[84:87], v[148:151], v[184:187], v[84:87]
	v_mfma_f32_16x16x32_bf16 v[80:83], v[168:171], v[184:187], v[80:83]
	v_mfma_f32_16x16x32_bf16 v[76:79], v[148:151], v[192:195], v[76:79]
	v_mfma_f32_16x16x32_bf16 v[72:75], v[168:171], v[192:195], v[72:75]
	v_mfma_f32_16x16x32_bf16 v[68:71], v[148:151], v[200:203], v[68:71]
	v_mfma_f32_16x16x32_bf16 v[64:67], v[168:171], v[200:203], v[64:67]
	s_barrier
	s_add_u32 s6, s6, 0x18080
	s_addc_u32 s7, s7, 0
	s_add_i32 s8, s8, s44
	s_mov_b32 m0, s8
	s_nop 0
	global_load_lds_dwordx4 v130, s[6:7]
	s_add_i32 m0, s8, 0x2000
	s_nop 0
	global_load_lds_dwordx4 v134, s[6:7]
	s_waitcnt vmcnt(6)
	s_barrier
	v_mfma_f32_16x16x32_bf16 v[28:31], v[204:207], v[172:175], v[28:31]
	v_mfma_f32_16x16x32_bf16 v[24:27], v[212:215], v[172:175], v[24:27]
	v_mfma_f32_16x16x32_bf16 v[20:23], v[204:207], v[180:183], v[20:23]
	v_mfma_f32_16x16x32_bf16 v[16:19], v[212:215], v[180:183], v[16:19]
	v_mfma_f32_16x16x32_bf16 v[12:15], v[204:207], v[188:191], v[12:15]
	v_mfma_f32_16x16x32_bf16 v[8:11], v[212:215], v[188:191], v[8:11]
	v_mfma_f32_16x16x32_bf16 v[4:7], v[204:207], v[196:199], v[4:7]
	v_mfma_f32_16x16x32_bf16 v[0:3], v[212:215], v[196:199], v[0:3]
	v_mfma_f32_16x16x32_bf16 v[28:31], v[208:211], v[176:179], v[28:31]
	v_mfma_f32_16x16x32_bf16 v[24:27], v[216:219], v[176:179], v[24:27]
	v_mfma_f32_16x16x32_bf16 v[20:23], v[208:211], v[184:187], v[20:23]
	v_mfma_f32_16x16x32_bf16 v[16:19], v[216:219], v[184:187], v[16:19]
	v_mfma_f32_16x16x32_bf16 v[12:15], v[208:211], v[192:195], v[12:15]
	v_mfma_f32_16x16x32_bf16 v[8:11], v[216:219], v[192:195], v[8:11]
	v_mfma_f32_16x16x32_bf16 v[4:7], v[208:211], v[200:203], v[4:7]
	v_mfma_f32_16x16x32_bf16 v[0:3], v[216:219], v[200:203], v[0:3]
	s_add_i32 s60, s60, 2
	s_add_u32 s35, s35, 0x100
	s_addc_u32 s37, s37, 0
	s_cmp_gt_u32 s60, 3
	s_mov_b64 s[8:9], s[4:5]
	s_barrier
	s_cbranch_scc0 .LBB0_321
	s_lshl_b32 s37, s34, 8
	s_ashr_i32 s6, s34, 1
	s_cmp_lt_i32 s6, 2
	s_cselect_b64 s[8:9], -1, 0
	s_cmp_gt_i32 s6, 1
	s_cselect_b64 s[34:35], -1, 0
	s_lshl_b32 s60, s6, 9
	s_add_i32 s61, s60, 0xfffffc00
	v_bitop3_b32 v144, s37, v161, v156 bitop3:0xc8
	v_or_b32_e32 v146, s61, v144
	v_or_b32_e32 v144, s60, v144
	v_mov_b32_e32 v145, 0
	s_cmp_lt_i32 s6, 4
	v_cndmask_b32_e64 v152, v146, v144, s[8:9]
	s_cselect_b64 s[4:5], -1, 0
	s_cmp_gt_i32 s6, 3
	v_ashrrev_i32_e32 v153, 31, v152
	v_mov_b32_e32 v144, v145
	s_cbranch_scc1 .LBB0_330
	s_and_b64 s[10:11], s[8:9], exec
	s_cselect_b32 s7, s21, s23
	s_cselect_b32 s10, s20, s22
	v_mov_b32_e32 v146, s10
	v_mov_b32_e32 v147, s7
	v_lshl_add_u64 v[146:147], v[152:153], 2, v[146:147]
	global_load_dword v144, v[146:147], off
	v_cndmask_b32_e64 v146, 0, 1, s[4:5]
	v_cmp_ne_u32_e64 s[10:11], 1, v146
	s_andn2_b64 vcc, exec, s[4:5]
	s_cbranch_vccz .LBB0_331

.LBB0_583:
	ds_read_b128 v[128:131], v164
	ds_read_b128 v[132:135], v164 offset:1024
	ds_read_b128 v[152:155], v164 offset:2048
	ds_read_b128 v[156:159], v164 offset:3072
	s_add_u32 s38, s36, 0xfffc0080
	s_addc_u32 s39, s37, -1
	s_cmp_eq_u32 s63, 12
	s_cselect_b32 s41, s9, s39
	s_cselect_b32 s40, s29, s38
	s_cselect_b32 s39, s27, s62
	s_cselect_b32 s38, s60, s61
	s_add_i32 m0, s50, 0xc000
	ds_read_b128 v[168:171], v165
	ds_read_b128 v[172:175], v165 offset:1024
	ds_read_b128 v[176:179], v165 offset:2048
	ds_read_b128 v[180:183], v165 offset:3072
	ds_read_b128 v[184:187], v165 offset:4096
	ds_read_b128 v[188:191], v165 offset:5120
	ds_read_b128 v[192:195], v165 offset:6144
	ds_read_b128 v[196:199], v165 offset:7168
	global_load_lds_dwordx4 v144, s[36:37]
	s_add_i32 m0, s50, 0xe000
	s_nop 0
	global_load_lds_dwordx4 v146, s[36:37]
	s_waitcnt lgkmcnt(8)
	s_barrier
	s_waitcnt lgkmcnt(0)
	v_mfma_f32_16x16x32_bf16 v[120:123], v[128:131], v[168:171], v[120:123]
	v_mfma_f32_16x16x32_bf16 v[124:127], v[152:155], v[168:171], v[124:127]
	v_mfma_f32_16x16x32_bf16 v[104:107], v[128:131], v[176:179], v[104:107]
	v_mfma_f32_16x16x32_bf16 v[108:111], v[152:155], v[176:179], v[108:111]
	v_mfma_f32_16x16x32_bf16 v[88:91], v[128:131], v[184:187], v[88:91]
	v_mfma_f32_16x16x32_bf16 v[92:95], v[152:155], v[184:187], v[92:95]
	v_mfma_f32_16x16x32_bf16 v[72:75], v[128:131], v[192:195], v[72:75]
	v_mfma_f32_16x16x32_bf16 v[76:79], v[152:155], v[192:195], v[76:79]
	v_mfma_f32_16x16x32_bf16 v[120:123], v[132:135], v[172:175], v[120:123]
	v_mfma_f32_16x16x32_bf16 v[124:127], v[156:159], v[172:175], v[124:127]
	v_mfma_f32_16x16x32_bf16 v[104:107], v[132:135], v[180:183], v[104:107]
	v_mfma_f32_16x16x32_bf16 v[108:111], v[156:159], v[180:183], v[108:111]
	v_mfma_f32_16x16x32_bf16 v[88:91], v[132:135], v[188:191], v[88:91]
	v_mfma_f32_16x16x32_bf16 v[92:95], v[156:159], v[188:191], v[92:95]
	v_mfma_f32_16x16x32_bf16 v[72:75], v[132:135], v[196:199], v[72:75]
	v_mfma_f32_16x16x32_bf16 v[76:79], v[156:159], v[196:199], v[76:79]
	s_barrier
	s_add_i32 s64, s57, s49
	s_add_u32 s98, s38, s22
	s_addc_u32 s99, s39, s23
	s_mov_b32 m0, s64
	ds_read_b128 v[200:203], v166
	ds_read_b128 v[204:207], v166 offset:1024
	ds_read_b128 v[208:211], v166 offset:2048
	ds_read_b128 v[212:215], v166 offset:3072
	global_load_lds_dwordx4 v138, s[38:39]
	s_add_i32 m0, s64, 0x2000
	s_nop 0
	global_load_lds_dwordx4 v142, s[38:39]
	s_barrier
	s_waitcnt lgkmcnt(0)
	v_mfma_f32_16x16x32_bf16 v[112:115], v[200:203], v[168:171], v[112:115]
	v_mfma_f32_16x16x32_bf16 v[116:119], v[208:211], v[168:171], v[116:119]
	v_mfma_f32_16x16x32_bf16 v[96:99], v[200:203], v[176:179], v[96:99]
	v_mfma_f32_16x16x32_bf16 v[100:103], v[208:211], v[176:179], v[100:103]
	v_mfma_f32_16x16x32_bf16 v[80:83], v[200:203], v[184:187], v[80:83]
	v_mfma_f32_16x16x32_bf16 v[84:87], v[208:211], v[184:187], v[84:87]
	v_mfma_f32_16x16x32_bf16 v[64:67], v[200:203], v[192:195], v[64:67]
	v_mfma_f32_16x16x32_bf16 v[68:71], v[208:211], v[192:195], v[68:71]
	v_mfma_f32_16x16x32_bf16 v[112:115], v[204:207], v[172:175], v[112:115]
	v_mfma_f32_16x16x32_bf16 v[116:119], v[212:215], v[172:175], v[116:119]
	v_mfma_f32_16x16x32_bf16 v[96:99], v[204:207], v[180:183], v[96:99]
	v_mfma_f32_16x16x32_bf16 v[100:103], v[212:215], v[180:183], v[100:103]
	v_mfma_f32_16x16x32_bf16 v[80:83], v[204:207], v[188:191], v[80:83]
	v_mfma_f32_16x16x32_bf16 v[84:87], v[212:215], v[188:191], v[84:87]
	v_mfma_f32_16x16x32_bf16 v[64:67], v[204:207], v[196:199], v[64:67]
	v_mfma_f32_16x16x32_bf16 v[68:71], v[212:215], v[196:199], v[68:71]
	s_mov_b32 m0, s50
	s_add_u32 s100, s40, s22
	s_addc_u32 s101, s41, s23
	s_barrier
	ds_read_b128 v[168:171], v165 offset:16384
	ds_read_b128 v[172:175], v165 offset:17408
	ds_read_b128 v[176:179], v165 offset:18432
	ds_read_b128 v[180:183], v165 offset:19456
	ds_read_b128 v[184:187], v165 offset:20480
	ds_read_b128 v[188:191], v165 offset:21504
	ds_read_b128 v[192:195], v165 offset:22528
	ds_read_b128 v[196:199], v165 offset:23552
	global_load_lds_dwordx4 v136, s[40:41]
	s_mov_b32 m0, s51
	s_nop 0
	global_load_lds_dwordx4 v140, s[40:41]
	s_barrier
	s_waitcnt lgkmcnt(0)
	v_mfma_f32_16x16x32_bf16 v[56:59], v[128:131], v[168:171], v[56:59]
	v_mfma_f32_16x16x32_bf16 v[60:63], v[152:155], v[168:171], v[60:63]
	v_mfma_f32_16x16x32_bf16 v[40:43], v[128:131], v[176:179], v[40:43]
	v_mfma_f32_16x16x32_bf16 v[44:47], v[152:155], v[176:179], v[44:47]
	v_mfma_f32_16x16x32_bf16 v[24:27], v[128:131], v[184:187], v[24:27]
	v_mfma_f32_16x16x32_bf16 v[28:31], v[152:155], v[184:187], v[28:31]
	v_mfma_f32_16x16x32_bf16 v[8:11], v[128:131], v[192:195], v[8:11]
	v_mfma_f32_16x16x32_bf16 v[12:15], v[152:155], v[192:195], v[12:15]
	v_mfma_f32_16x16x32_bf16 v[56:59], v[132:135], v[172:175], v[56:59]
	v_mfma_f32_16x16x32_bf16 v[60:63], v[156:159], v[172:175], v[60:63]
	v_mfma_f32_16x16x32_bf16 v[40:43], v[132:135], v[180:183], v[40:43]
	v_mfma_f32_16x16x32_bf16 v[44:47], v[156:159], v[180:183], v[44:47]
	v_mfma_f32_16x16x32_bf16 v[24:27], v[132:135], v[188:191], v[24:27]
	v_mfma_f32_16x16x32_bf16 v[28:31], v[156:159], v[188:191], v[28:31]
	v_mfma_f32_16x16x32_bf16 v[8:11], v[132:135], v[196:199], v[8:11]
	v_mfma_f32_16x16x32_bf16 v[12:15], v[156:159], v[196:199], v[12:15]
	s_barrier
	s_add_u32 s64, s38, 0x40000
	s_addc_u32 s65, s39, 0
	s_add_i32 s66, s58, s49
	s_mov_b32 m0, s66
	s_nop 0
	global_load_lds_dwordx4 v138, s[64:65]
	s_add_i32 m0, s66, 0x2000
	s_nop 0
	global_load_lds_dwordx4 v142, s[64:65]
	s_waitcnt vmcnt(6)
	s_barrier
	v_mfma_f32_16x16x32_bf16 v[48:51], v[200:203], v[168:171], v[48:51]
	v_mfma_f32_16x16x32_bf16 v[52:55], v[208:211], v[168:171], v[52:55]
	v_mfma_f32_16x16x32_bf16 v[32:35], v[200:203], v[176:179], v[32:35]
	v_mfma_f32_16x16x32_bf16 v[36:39], v[208:211], v[176:179], v[36:39]
	v_mfma_f32_16x16x32_bf16 v[16:19], v[200:203], v[184:187], v[16:19]
	v_mfma_f32_16x16x32_bf16 v[20:23], v[208:211], v[184:187], v[20:23]
	v_mfma_f32_16x16x32_bf16 v[4:7], v[200:203], v[192:195], v[4:7]
	v_mfma_f32_16x16x32_bf16 v[0:3], v[208:211], v[192:195], v[0:3]
	v_mfma_f32_16x16x32_bf16 v[48:51], v[204:207], v[172:175], v[48:51]
	v_mfma_f32_16x16x32_bf16 v[52:55], v[212:215], v[172:175], v[52:55]
	v_mfma_f32_16x16x32_bf16 v[32:35], v[204:207], v[180:183], v[32:35]
	v_mfma_f32_16x16x32_bf16 v[36:39], v[212:215], v[180:183], v[36:39]
	v_mfma_f32_16x16x32_bf16 v[16:19], v[204:207], v[188:191], v[16:19]
	v_mfma_f32_16x16x32_bf16 v[20:23], v[212:215], v[188:191], v[20:23]
	v_mfma_f32_16x16x32_bf16 v[4:7], v[204:207], v[196:199], v[4:7]
	v_mfma_f32_16x16x32_bf16 v[0:3], v[212:215], v[196:199], v[0:3]
	s_add_i32 s64, 0, 0x18000
	v_add_u32_e32 v156, s64, v162
	s_barrier
	ds_read_b128 v[128:131], v156
	ds_read_b128 v[132:135], v156 offset:1024
	ds_read_b128 v[152:155], v156 offset:2048
	ds_read_b128 v[156:159], v156 offset:3072
	s_add_u32 s40, s40, 0x40000
	s_addc_u32 s41, s41, 0
	s_mov_b32 m0, s52
	ds_read_b128 v[168:171], v165 offset:32768
	ds_read_b128 v[172:175], v165 offset:33792
	ds_read_b128 v[176:179], v165 offset:34816
	ds_read_b128 v[180:183], v165 offset:35840
	ds_read_b128 v[184:187], v165 offset:36864
	ds_read_b128 v[188:191], v165 offset:37888
	ds_read_b128 v[192:195], v165 offset:38912
	ds_read_b128 v[196:199], v165 offset:39936
	global_load_lds_dwordx4 v136, s[40:41]
	s_mov_b32 m0, s53
	s_nop 0
	global_load_lds_dwordx4 v140, s[40:41]
	s_waitcnt lgkmcnt(8)
	s_barrier
	s_waitcnt lgkmcnt(0)
	v_mfma_f32_16x16x32_bf16 v[120:123], v[128:131], v[168:171], v[120:123]
	v_mfma_f32_16x16x32_bf16 v[124:127], v[152:155], v[168:171], v[124:127]
	v_mfma_f32_16x16x32_bf16 v[104:107], v[128:131], v[176:179], v[104:107]
	v_mfma_f32_16x16x32_bf16 v[108:111], v[152:155], v[176:179], v[108:111]
	v_mfma_f32_16x16x32_bf16 v[88:91], v[128:131], v[184:187], v[88:91]
	v_mfma_f32_16x16x32_bf16 v[92:95], v[152:155], v[184:187], v[92:95]
	v_mfma_f32_16x16x32_bf16 v[72:75], v[128:131], v[192:195], v[72:75]
	v_mfma_f32_16x16x32_bf16 v[76:79], v[152:155], v[192:195], v[76:79]
	v_mfma_f32_16x16x32_bf16 v[120:123], v[132:135], v[172:175], v[120:123]
	v_mfma_f32_16x16x32_bf16 v[124:127], v[156:159], v[172:175], v[124:127]
	v_mfma_f32_16x16x32_bf16 v[104:107], v[132:135], v[180:183], v[104:107]
	v_mfma_f32_16x16x32_bf16 v[108:111], v[156:159], v[180:183], v[108:111]
	v_mfma_f32_16x16x32_bf16 v[88:91], v[132:135], v[188:191], v[88:91]
	v_mfma_f32_16x16x32_bf16 v[92:95], v[156:159], v[188:191], v[92:95]
	v_mfma_f32_16x16x32_bf16 v[72:75], v[132:135], v[196:199], v[72:75]
	v_mfma_f32_16x16x32_bf16 v[76:79], v[156:159], v[196:199], v[76:79]
	s_barrier
	s_add_i32 s40, 0, 0x1c000
	s_add_i32 s41, s64, s49
	v_add_u32_e32 v212, s40, v162
	s_mov_b32 m0, s41
	ds_read_b128 v[200:203], v212
	ds_read_b128 v[204:207], v212 offset:1024
	ds_read_b128 v[208:211], v212 offset:2048
	ds_read_b128 v[212:215], v212 offset:3072
	global_load_lds_dwordx4 v138, s[98:99]
	s_add_i32 m0, s41, 0x2000
	s_nop 0
	global_load_lds_dwordx4 v142, s[98:99]
	s_barrier
	s_waitcnt lgkmcnt(0)
	v_mfma_f32_16x16x32_bf16 v[112:115], v[200:203], v[168:171], v[112:115]
	v_mfma_f32_16x16x32_bf16 v[116:119], v[208:211], v[168:171], v[116:119]
	v_mfma_f32_16x16x32_bf16 v[96:99], v[200:203], v[176:179], v[96:99]
	v_mfma_f32_16x16x32_bf16 v[100:103], v[208:211], v[176:179], v[100:103]
	v_mfma_f32_16x16x32_bf16 v[80:83], v[200:203], v[184:187], v[80:83]
	v_mfma_f32_16x16x32_bf16 v[84:87], v[208:211], v[184:187], v[84:87]
	v_mfma_f32_16x16x32_bf16 v[64:67], v[200:203], v[192:195], v[64:67]
	v_mfma_f32_16x16x32_bf16 v[68:71], v[208:211], v[192:195], v[68:71]
	v_mfma_f32_16x16x32_bf16 v[112:115], v[204:207], v[172:175], v[112:115]
	v_mfma_f32_16x16x32_bf16 v[116:119], v[212:215], v[172:175], v[116:119]
	v_mfma_f32_16x16x32_bf16 v[96:99], v[204:207], v[180:183], v[96:99]
	v_mfma_f32_16x16x32_bf16 v[100:103], v[212:215], v[180:183], v[100:103]
	v_mfma_f32_16x16x32_bf16 v[80:83], v[204:207], v[188:191], v[80:83]
	v_mfma_f32_16x16x32_bf16 v[84:87], v[212:215], v[188:191], v[84:87]
	v_mfma_f32_16x16x32_bf16 v[64:67], v[204:207], v[196:199], v[64:67]
	v_mfma_f32_16x16x32_bf16 v[68:71], v[212:215], v[196:199], v[68:71]
	s_mov_b32 m0, s55
	s_barrier
	ds_read_b128 v[168:171], v165 offset:49152
	ds_read_b128 v[172:175], v165 offset:50176
	ds_read_b128 v[176:179], v165 offset:51200
	ds_read_b128 v[180:183], v165 offset:52224
	ds_read_b128 v[184:187], v165 offset:53248
	ds_read_b128 v[188:191], v165 offset:54272
	ds_read_b128 v[192:195], v165 offset:55296
	ds_read_b128 v[196:199], v165 offset:56320
	global_load_lds_dwordx4 v136, s[100:101]
	s_mov_b32 m0, s56
	s_nop 0
	global_load_lds_dwordx4 v140, s[100:101]
	s_barrier
	s_waitcnt lgkmcnt(0)
	v_mfma_f32_16x16x32_bf16 v[56:59], v[128:131], v[168:171], v[56:59]
	v_mfma_f32_16x16x32_bf16 v[60:63], v[152:155], v[168:171], v[60:63]
	v_mfma_f32_16x16x32_bf16 v[40:43], v[128:131], v[176:179], v[40:43]
	v_mfma_f32_16x16x32_bf16 v[44:47], v[152:155], v[176:179], v[44:47]
	v_mfma_f32_16x16x32_bf16 v[24:27], v[128:131], v[184:187], v[24:27]
	v_mfma_f32_16x16x32_bf16 v[28:31], v[152:155], v[184:187], v[28:31]
	v_mfma_f32_16x16x32_bf16 v[8:11], v[128:131], v[192:195], v[8:11]
	v_mfma_f32_16x16x32_bf16 v[12:15], v[152:155], v[192:195], v[12:15]
	v_mfma_f32_16x16x32_bf16 v[56:59], v[132:135], v[172:175], v[56:59]
	v_mfma_f32_16x16x32_bf16 v[60:63], v[156:159], v[172:175], v[60:63]
	v_mfma_f32_16x16x32_bf16 v[40:43], v[132:135], v[180:183], v[40:43]
	v_mfma_f32_16x16x32_bf16 v[44:47], v[156:159], v[180:183], v[44:47]
	v_mfma_f32_16x16x32_bf16 v[24:27], v[132:135], v[188:191], v[24:27]
	v_mfma_f32_16x16x32_bf16 v[28:31], v[156:159], v[188:191], v[28:31]
	v_mfma_f32_16x16x32_bf16 v[8:11], v[132:135], v[196:199], v[8:11]
	v_mfma_f32_16x16x32_bf16 v[12:15], v[156:159], v[196:199], v[12:15]
	s_barrier
	s_add_u32 s38, s38, 0x40080
	s_addc_u32 s39, s39, 0
	s_add_i32 s40, s40, s49
	s_mov_b32 m0, s40
	s_nop 0
	global_load_lds_dwordx4 v138, s[38:39]
	s_add_i32 m0, s40, 0x2000
	s_nop 0
	global_load_lds_dwordx4 v142, s[38:39]
	s_waitcnt vmcnt(6)
	s_barrier
	v_mfma_f32_16x16x32_bf16 v[48:51], v[200:203], v[168:171], v[48:51]
	v_mfma_f32_16x16x32_bf16 v[52:55], v[208:211], v[168:171], v[52:55]
	v_mfma_f32_16x16x32_bf16 v[32:35], v[200:203], v[176:179], v[32:35]
	v_mfma_f32_16x16x32_bf16 v[36:39], v[208:211], v[176:179], v[36:39]
	v_mfma_f32_16x16x32_bf16 v[16:19], v[200:203], v[184:187], v[16:19]
	v_mfma_f32_16x16x32_bf16 v[20:23], v[208:211], v[184:187], v[20:23]
	v_mfma_f32_16x16x32_bf16 v[4:7], v[200:203], v[192:195], v[4:7]
	v_mfma_f32_16x16x32_bf16 v[0:3], v[208:211], v[192:195], v[0:3]
	v_mfma_f32_16x16x32_bf16 v[48:51], v[204:207], v[172:175], v[48:51]
	v_mfma_f32_16x16x32_bf16 v[52:55], v[212:215], v[172:175], v[52:55]
	v_mfma_f32_16x16x32_bf16 v[32:35], v[204:207], v[180:183], v[32:35]
	v_mfma_f32_16x16x32_bf16 v[36:39], v[212:215], v[180:183], v[36:39]
	v_mfma_f32_16x16x32_bf16 v[16:19], v[204:207], v[188:191], v[16:19]
	v_mfma_f32_16x16x32_bf16 v[20:23], v[212:215], v[188:191], v[20:23]
	v_mfma_f32_16x16x32_bf16 v[4:7], v[204:207], v[196:199], v[4:7]
	v_mfma_f32_16x16x32_bf16 v[0:3], v[212:215], v[196:199], v[0:3]
	s_add_i32 s63, s63, 2
	s_add_u32 s36, s36, 0x100
	s_addc_u32 s37, s37, 0
	s_add_u32 s61, s61, 0x100
	s_addc_u32 s62, s62, 0
	s_cmp_gt_u32 s63, 13
	s_barrier
	s_cbranch_scc0 .LBB0_583
	v_lshl_add_u32 v152, s8, 8, v161
	v_lshl_or_b32 v153, s16, 8, v163
	s_lshl_b32 s36, s16, 2
	s_ashr_i32 s37, s36, 31
	s_lshl_b32 s16, s54, 2
	v_lshl_add_u32 v154, v152, 10, v153
	v_lshl_add_u32 v156, v152, 6, s16
	v_lshl_add_u32 v156, s36, 2, v156
	v_lshlrev_b32_e32 v155, 1, v154
	v_lshlrev_b32_e32 v154, 2, v154
	global_load_dwordx4 v[168:171], v154, s[14:15]
	global_load_dwordx4 v[172:175], v154, s[14:15] offset:16
	global_load_dwordx4 v[176:179], v154, s[14:15] offset:512
	global_load_dwordx4 v[180:183], v154, s[14:15] offset:528
	v_add_u32_e32 v154, 0x10000, v154
	global_load_dwordx4 v[184:187], v154, s[14:15]
	global_load_dwordx4 v[188:191], v154, s[14:15] offset:16
	global_load_dwordx4 v[192:195], v154, s[14:15] offset:512
	global_load_dwordx4 v[196:199], v154, s[14:15] offset:528
	v_add_u32_e32 v154, 0x10000, v154
	global_load_dwordx4 v[200:203], v154, s[14:15]
	global_load_dwordx4 v[204:207], v154, s[14:15] offset:16
	global_load_dwordx4 v[208:211], v154, s[14:15] offset:512
	global_load_dwordx4 v[212:215], v154, s[14:15] offset:528
	v_add_u32_e32 v154, 0x10000, v154
	global_load_dwordx4 v[216:219], v154, s[14:15]
	global_load_dwordx4 v[220:223], v154, s[14:15] offset:16
	global_load_dwordx4 v[128:131], v154, s[14:15] offset:512
	global_load_dwordx4 v[132:135], v154, s[14:15] offset:528
	v_add_u32_e32 v154, 0x50000, v154
	s_waitcnt vmcnt(12)
	v_pk_add_f32 v[120:121], v[120:121], v[168:169]
	v_pk_add_f32 v[122:123], v[122:123], v[170:171]
	v_pk_add_f32 v[124:125], v[124:125], v[172:173]
	v_pk_add_f32 v[126:127], v[126:127], v[174:175]
	v_cvt_pk_bf16_f32 v168, v120, v121
	v_cvt_pk_bf16_f32 v169, v122, v123
	v_cvt_pk_bf16_f32 v170, v124, v125
	v_cvt_pk_bf16_f32 v171, v126, v127
	v_pk_mul_f32 v[172:173], v[120:121], v[120:121]
	global_store_dwordx4 v155, v[168:171], s[18:19]
	v_pk_fma_f32 v[172:173], v[122:123], v[122:123], v[172:173]
	v_pk_fma_f32 v[172:173], v[124:125], v[124:125], v[172:173]
	v_pk_fma_f32 v[172:173], v[126:127], v[126:127], v[172:173]
	v_pk_add_f32 v[112:113], v[112:113], v[176:177]
	v_pk_add_f32 v[114:115], v[114:115], v[178:179]
	v_pk_add_f32 v[116:117], v[116:117], v[180:181]
	v_pk_add_f32 v[118:119], v[118:119], v[182:183]
	v_cvt_pk_bf16_f32 v176, v112, v113
	v_cvt_pk_bf16_f32 v177, v114, v115
	v_cvt_pk_bf16_f32 v178, v116, v117
	v_cvt_pk_bf16_f32 v179, v118, v119
	v_pk_fma_f32 v[172:173], v[112:113], v[112:113], v[172:173]
	global_store_dwordx4 v155, v[176:179], s[18:19] offset:256
	v_pk_fma_f32 v[172:173], v[114:115], v[114:115], v[172:173]
	v_pk_fma_f32 v[172:173], v[116:117], v[116:117], v[172:173]
	v_pk_fma_f32 v[172:173], v[118:119], v[118:119], v[172:173]
	v_add_f32_e32 v157, v172, v173
	v_add_u32_e32 v155, 0x8000, v155
	v_mov_b32_e32 v158, v157
	s_nop 1
	v_permlane16_swap_b32_e32 v157, v158
	s_nop 0
	v_add_f32_e32 v157, v157, v158
	v_mov_b32_e32 v158, v157
	s_nop 1
	v_permlane32_swap_b32_e32 v157, v158
	s_nop 0
	v_add_f32_e32 v157, v157, v158
	s_and_saveexec_b64 s[38:39], s[4:5]
	global_store_dword v156, v157, s[20:21]
	s_mov_b64 exec, s[38:39]
	global_load_dwordx4 v[168:171], v154, s[14:15]
	global_load_dwordx4 v[172:175], v154, s[14:15] offset:16
	global_load_dwordx4 v[176:179], v154, s[14:15] offset:512
	global_load_dwordx4 v[180:183], v154, s[14:15] offset:528
	v_add_u32_e32 v154, 0x10000, v154
	s_waitcnt vmcnt(15)
	v_pk_add_f32 v[104:105], v[104:105], v[184:185]
	v_pk_add_f32 v[106:107], v[106:107], v[186:187]
	v_pk_add_f32 v[108:109], v[108:109], v[188:189]
	v_pk_add_f32 v[110:111], v[110:111], v[190:191]
	v_cvt_pk_bf16_f32 v184, v104, v105
	v_cvt_pk_bf16_f32 v185, v106, v107
	v_cvt_pk_bf16_f32 v186, v108, v109
	v_cvt_pk_bf16_f32 v187, v110, v111
	v_pk_mul_f32 v[188:189], v[104:105], v[104:105]
	global_store_dwordx4 v155, v[184:187], s[18:19]
	v_pk_fma_f32 v[188:189], v[106:107], v[106:107], v[188:189]
	v_pk_fma_f32 v[188:189], v[108:109], v[108:109], v[188:189]
	v_pk_fma_f32 v[188:189], v[110:111], v[110:111], v[188:189]
	v_pk_add_f32 v[96:97], v[96:97], v[192:193]
	v_pk_add_f32 v[98:99], v[98:99], v[194:195]
	v_pk_add_f32 v[100:101], v[100:101], v[196:197]
	v_pk_add_f32 v[102:103], v[102:103], v[198:199]
	v_cvt_pk_bf16_f32 v192, v96, v97
	v_cvt_pk_bf16_f32 v193, v98, v99
	v_cvt_pk_bf16_f32 v194, v100, v101
	v_cvt_pk_bf16_f32 v195, v102, v103
	v_pk_fma_f32 v[188:189], v[96:97], v[96:97], v[188:189]
	global_store_dwordx4 v155, v[192:195], s[18:19] offset:256
	v_pk_fma_f32 v[188:189], v[98:99], v[98:99], v[188:189]
	v_pk_fma_f32 v[188:189], v[100:101], v[100:101], v[188:189]
	v_pk_fma_f32 v[188:189], v[102:103], v[102:103], v[188:189]
	v_add_f32_e32 v157, v188, v189
	v_add_u32_e32 v155, 0x8000, v155
	v_mov_b32_e32 v158, v157
	s_nop 1
	v_permlane16_swap_b32_e32 v157, v158
	s_nop 0
	v_add_f32_e32 v157, v157, v158
	v_mov_b32_e32 v158, v157
	s_nop 1
	v_permlane32_swap_b32_e32 v157, v158
	s_nop 0
	v_add_f32_e32 v157, v157, v158
	s_and_saveexec_b64 s[38:39], s[4:5]
	global_store_dword v156, v157, s[20:21] offset:1024
	s_mov_b64 exec, s[38:39]
	global_load_dwordx4 v[184:187], v154, s[14:15]
	global_load_dwordx4 v[188:191], v154, s[14:15] offset:16
	global_load_dwordx4 v[192:195], v154, s[14:15] offset:512
	global_load_dwordx4 v[196:199], v154, s[14:15] offset:528
	v_add_u32_e32 v154, 0x10000, v154
	s_waitcnt vmcnt(18)
	v_pk_add_f32 v[88:89], v[88:89], v[200:201]
	v_pk_add_f32 v[90:91], v[90:91], v[202:203]
	v_pk_add_f32 v[92:93], v[92:93], v[204:205]
	v_pk_add_f32 v[94:95], v[94:95], v[206:207]
	v_cvt_pk_bf16_f32 v200, v88, v89
	v_cvt_pk_bf16_f32 v201, v90, v91
	v_cvt_pk_bf16_f32 v202, v92, v93
	v_cvt_pk_bf16_f32 v203, v94, v95
	v_pk_mul_f32 v[204:205], v[88:89], v[88:89]
	global_store_dwordx4 v155, v[200:203], s[18:19]
	v_pk_fma_f32 v[204:205], v[90:91], v[90:91], v[204:205]
	v_pk_fma_f32 v[204:205], v[92:93], v[92:93], v[204:205]
	v_pk_fma_f32 v[204:205], v[94:95], v[94:95], v[204:205]
	v_pk_add_f32 v[80:81], v[80:81], v[208:209]
	v_pk_add_f32 v[82:83], v[82:83], v[210:211]
	v_pk_add_f32 v[84:85], v[84:85], v[212:213]
	v_pk_add_f32 v[86:87], v[86:87], v[214:215]
	v_cvt_pk_bf16_f32 v208, v80, v81
	v_cvt_pk_bf16_f32 v209, v82, v83
	v_cvt_pk_bf16_f32 v210, v84, v85
	v_cvt_pk_bf16_f32 v211, v86, v87
	v_pk_fma_f32 v[204:205], v[80:81], v[80:81], v[204:205]
	global_store_dwordx4 v155, v[208:211], s[18:19] offset:256
	v_pk_fma_f32 v[204:205], v[82:83], v[82:83], v[204:205]
	v_pk_fma_f32 v[204:205], v[84:85], v[84:85], v[204:205]
	v_pk_fma_f32 v[204:205], v[86:87], v[86:87], v[204:205]
	v_add_f32_e32 v157, v204, v205
	v_add_u32_e32 v155, 0x8000, v155
	v_mov_b32_e32 v158, v157
	s_nop 1
	v_permlane16_swap_b32_e32 v157, v158
	s_nop 0
	v_add_f32_e32 v157, v157, v158
	v_mov_b32_e32 v158, v157
	s_nop 1
	v_permlane32_swap_b32_e32 v157, v158
	s_nop 0
	v_add_f32_e32 v157, v157, v158
	s_and_saveexec_b64 s[38:39], s[4:5]
	global_store_dword v156, v157, s[20:21] offset:2048
	s_mov_b64 exec, s[38:39]
	global_load_dwordx4 v[200:203], v154, s[14:15]
	global_load_dwordx4 v[204:207], v154, s[14:15] offset:16
	global_load_dwordx4 v[208:211], v154, s[14:15] offset:512
	global_load_dwordx4 v[212:215], v154, s[14:15] offset:528
	v_add_u32_e32 v154, 0x10000, v154
	s_waitcnt vmcnt(21)
	v_pk_add_f32 v[72:73], v[72:73], v[216:217]
	v_pk_add_f32 v[74:75], v[74:75], v[218:219]
	v_pk_add_f32 v[76:77], v[76:77], v[220:221]
	v_pk_add_f32 v[78:79], v[78:79], v[222:223]
	v_cvt_pk_bf16_f32 v216, v72, v73
	v_cvt_pk_bf16_f32 v217, v74, v75
	v_cvt_pk_bf16_f32 v218, v76, v77
	v_cvt_pk_bf16_f32 v219, v78, v79
	v_pk_mul_f32 v[220:221], v[72:73], v[72:73]
	global_store_dwordx4 v155, v[216:219], s[18:19]
	v_pk_fma_f32 v[220:221], v[74:75], v[74:75], v[220:221]
	v_pk_fma_f32 v[220:221], v[76:77], v[76:77], v[220:221]
	v_pk_fma_f32 v[220:221], v[78:79], v[78:79], v[220:221]
	v_pk_add_f32 v[64:65], v[64:65], v[128:129]
	v_pk_add_f32 v[66:67], v[66:67], v[130:131]
	v_pk_add_f32 v[68:69], v[68:69], v[132:133]
	v_pk_add_f32 v[70:71], v[70:71], v[134:135]
	v_cvt_pk_bf16_f32 v128, v64, v65
	v_cvt_pk_bf16_f32 v129, v66, v67
	v_cvt_pk_bf16_f32 v130, v68, v69
	v_cvt_pk_bf16_f32 v131, v70, v71
	v_pk_fma_f32 v[220:221], v[64:65], v[64:65], v[220:221]
	global_store_dwordx4 v155, v[128:131], s[18:19] offset:256
	v_pk_fma_f32 v[220:221], v[66:67], v[66:67], v[220:221]
	v_pk_fma_f32 v[220:221], v[68:69], v[68:69], v[220:221]
	v_pk_fma_f32 v[220:221], v[70:71], v[70:71], v[220:221]
	v_add_f32_e32 v157, v220, v221
	v_add_u32_e32 v155, 0x28000, v155
	v_mov_b32_e32 v158, v157
	s_nop 1
	v_permlane16_swap_b32_e32 v157, v158
	s_nop 0
	v_add_f32_e32 v157, v157, v158
	v_mov_b32_e32 v158, v157
	s_nop 1
	v_permlane32_swap_b32_e32 v157, v158
	s_nop 0
	v_add_f32_e32 v157, v157, v158
	s_and_saveexec_b64 s[38:39], s[4:5]
	global_store_dword v156, v157, s[20:21] offset:3072
	s_mov_b64 exec, s[38:39]
	v_add_u32_e32 v156, 0x2000, v156
	global_load_dwordx4 v[216:219], v154, s[14:15]
	global_load_dwordx4 v[220:223], v154, s[14:15] offset:16
	global_load_dwordx4 v[128:131], v154, s[14:15] offset:512
	global_load_dwordx4 v[132:135], v154, s[14:15] offset:528
	s_waitcnt vmcnt(21)
	v_pk_add_f32 v[56:57], v[56:57], v[168:169]
	v_pk_add_f32 v[58:59], v[58:59], v[170:171]
	v_pk_add_f32 v[60:61], v[60:61], v[172:173]
	v_pk_add_f32 v[62:63], v[62:63], v[174:175]
	v_cvt_pk_bf16_f32 v168, v56, v57
	v_cvt_pk_bf16_f32 v169, v58, v59
	v_cvt_pk_bf16_f32 v170, v60, v61
	v_cvt_pk_bf16_f32 v171, v62, v63
	v_pk_mul_f32 v[172:173], v[56:57], v[56:57]
	global_store_dwordx4 v155, v[168:171], s[18:19]
	v_pk_fma_f32 v[172:173], v[58:59], v[58:59], v[172:173]
	v_pk_fma_f32 v[172:173], v[60:61], v[60:61], v[172:173]
	v_pk_fma_f32 v[172:173], v[62:63], v[62:63], v[172:173]
	v_pk_add_f32 v[48:49], v[48:49], v[176:177]
	v_pk_add_f32 v[50:51], v[50:51], v[178:179]
	v_pk_add_f32 v[52:53], v[52:53], v[180:181]
	v_pk_add_f32 v[54:55], v[54:55], v[182:183]
	v_cvt_pk_bf16_f32 v176, v48, v49
	v_cvt_pk_bf16_f32 v177, v50, v51
	v_cvt_pk_bf16_f32 v178, v52, v53
	v_cvt_pk_bf16_f32 v179, v54, v55
	v_pk_fma_f32 v[172:173], v[48:49], v[48:49], v[172:173]
	global_store_dwordx4 v155, v[176:179], s[18:19] offset:256
	v_pk_fma_f32 v[172:173], v[50:51], v[50:51], v[172:173]
	v_pk_fma_f32 v[172:173], v[52:53], v[52:53], v[172:173]
	v_pk_fma_f32 v[172:173], v[54:55], v[54:55], v[172:173]
	v_add_f32_e32 v157, v172, v173
	v_add_u32_e32 v155, 0x8000, v155
	v_mov_b32_e32 v158, v157
	s_nop 1
	v_permlane16_swap_b32_e32 v157, v158
	s_nop 0
	v_add_f32_e32 v157, v157, v158
	v_mov_b32_e32 v158, v157
	s_nop 1
	v_permlane32_swap_b32_e32 v157, v158
	s_nop 0
	v_add_f32_e32 v157, v157, v158
	s_and_saveexec_b64 s[38:39], s[4:5]
	global_store_dword v156, v157, s[20:21]
	s_mov_b64 exec, s[38:39]
	s_waitcnt vmcnt(17)
	v_pk_add_f32 v[40:41], v[40:41], v[184:185]
	v_pk_add_f32 v[42:43], v[42:43], v[186:187]
	v_pk_add_f32 v[44:45], v[44:45], v[188:189]
	v_pk_add_f32 v[46:47], v[46:47], v[190:191]
	v_cvt_pk_bf16_f32 v184, v40, v41
	v_cvt_pk_bf16_f32 v185, v42, v43
	v_cvt_pk_bf16_f32 v186, v44, v45
	v_cvt_pk_bf16_f32 v187, v46, v47
	v_pk_mul_f32 v[188:189], v[40:41], v[40:41]
	global_store_dwordx4 v155, v[184:187], s[18:19]
	v_pk_fma_f32 v[188:189], v[42:43], v[42:43], v[188:189]
	v_pk_fma_f32 v[188:189], v[44:45], v[44:45], v[188:189]
	v_pk_fma_f32 v[188:189], v[46:47], v[46:47], v[188:189]
	v_pk_add_f32 v[32:33], v[32:33], v[192:193]
	v_pk_add_f32 v[34:35], v[34:35], v[194:195]
	v_pk_add_f32 v[36:37], v[36:37], v[196:197]
	v_pk_add_f32 v[38:39], v[38:39], v[198:199]
	v_cvt_pk_bf16_f32 v192, v32, v33
	v_cvt_pk_bf16_f32 v193, v34, v35
	v_cvt_pk_bf16_f32 v194, v36, v37
	v_cvt_pk_bf16_f32 v195, v38, v39
	v_pk_fma_f32 v[188:189], v[32:33], v[32:33], v[188:189]
	global_store_dwordx4 v155, v[192:195], s[18:19] offset:256
	v_pk_fma_f32 v[188:189], v[34:35], v[34:35], v[188:189]
	v_pk_fma_f32 v[188:189], v[36:37], v[36:37], v[188:189]
	v_pk_fma_f32 v[188:189], v[38:39], v[38:39], v[188:189]
	v_add_f32_e32 v157, v188, v189
	v_add_u32_e32 v155, 0x8000, v155
	v_mov_b32_e32 v158, v157
	s_nop 1
	v_permlane16_swap_b32_e32 v157, v158
	s_nop 0
	v_add_f32_e32 v157, v157, v158
	v_mov_b32_e32 v158, v157
	s_nop 1
	v_permlane32_swap_b32_e32 v157, v158
	s_nop 0
	v_add_f32_e32 v157, v157, v158
	s_and_saveexec_b64 s[38:39], s[4:5]
	global_store_dword v156, v157, s[20:21] offset:1024
	s_mov_b64 exec, s[38:39]
	s_waitcnt vmcnt(13)
	v_pk_add_f32 v[24:25], v[24:25], v[200:201]
	v_pk_add_f32 v[26:27], v[26:27], v[202:203]
	v_pk_add_f32 v[28:29], v[28:29], v[204:205]
	v_pk_add_f32 v[30:31], v[30:31], v[206:207]
	v_cvt_pk_bf16_f32 v200, v24, v25
	v_cvt_pk_bf16_f32 v201, v26, v27
	v_cvt_pk_bf16_f32 v202, v28, v29
	v_cvt_pk_bf16_f32 v203, v30, v31
	v_pk_mul_f32 v[204:205], v[24:25], v[24:25]
	global_store_dwordx4 v155, v[200:203], s[18:19]
	v_pk_fma_f32 v[204:205], v[26:27], v[26:27], v[204:205]
	v_pk_fma_f32 v[204:205], v[28:29], v[28:29], v[204:205]
	v_pk_fma_f32 v[204:205], v[30:31], v[30:31], v[204:205]
	v_pk_add_f32 v[16:17], v[16:17], v[208:209]
	v_pk_add_f32 v[18:19], v[18:19], v[210:211]
	v_pk_add_f32 v[20:21], v[20:21], v[212:213]
	v_pk_add_f32 v[22:23], v[22:23], v[214:215]
	v_cvt_pk_bf16_f32 v208, v16, v17
	v_cvt_pk_bf16_f32 v209, v18, v19
	v_cvt_pk_bf16_f32 v210, v20, v21
	v_cvt_pk_bf16_f32 v211, v22, v23
	v_pk_fma_f32 v[204:205], v[16:17], v[16:17], v[204:205]
	global_store_dwordx4 v155, v[208:211], s[18:19] offset:256
	v_pk_fma_f32 v[204:205], v[18:19], v[18:19], v[204:205]
	v_pk_fma_f32 v[204:205], v[20:21], v[20:21], v[204:205]
	v_pk_fma_f32 v[204:205], v[22:23], v[22:23], v[204:205]
	v_add_f32_e32 v157, v204, v205
	v_add_u32_e32 v155, 0x8000, v155
	v_mov_b32_e32 v158, v157
	s_nop 1
	v_permlane16_swap_b32_e32 v157, v158
	s_nop 0
	v_add_f32_e32 v157, v157, v158
	v_mov_b32_e32 v158, v157
	s_nop 1
	v_permlane32_swap_b32_e32 v157, v158
	s_nop 0
	v_add_f32_e32 v157, v157, v158
	s_and_saveexec_b64 s[38:39], s[4:5]
	global_store_dword v156, v157, s[20:21] offset:2048
	s_mov_b64 exec, s[38:39]
	s_waitcnt vmcnt(9)
	v_pk_add_f32 v[8:9], v[8:9], v[216:217]
	v_pk_add_f32 v[10:11], v[10:11], v[218:219]
	v_pk_add_f32 v[12:13], v[12:13], v[220:221]
	v_pk_add_f32 v[14:15], v[14:15], v[222:223]
	v_cvt_pk_bf16_f32 v216, v8, v9
	v_cvt_pk_bf16_f32 v217, v10, v11
	v_cvt_pk_bf16_f32 v218, v12, v13
	v_cvt_pk_bf16_f32 v219, v14, v15
	v_pk_mul_f32 v[220:221], v[8:9], v[8:9]
	global_store_dwordx4 v155, v[216:219], s[18:19]
	v_pk_fma_f32 v[220:221], v[10:11], v[10:11], v[220:221]
	v_pk_fma_f32 v[220:221], v[12:13], v[12:13], v[220:221]
	v_pk_fma_f32 v[220:221], v[14:15], v[14:15], v[220:221]
	v_pk_add_f32 v[4:5], v[4:5], v[128:129]
	v_pk_add_f32 v[6:7], v[6:7], v[130:131]
	v_pk_add_f32 v[0:1], v[0:1], v[132:133]
	v_pk_add_f32 v[2:3], v[2:3], v[134:135]
	v_cvt_pk_bf16_f32 v128, v4, v5
	v_cvt_pk_bf16_f32 v129, v6, v7
	v_cvt_pk_bf16_f32 v130, v0, v1
	v_cvt_pk_bf16_f32 v131, v2, v3
	v_pk_fma_f32 v[220:221], v[4:5], v[4:5], v[220:221]
	global_store_dwordx4 v155, v[128:131], s[18:19] offset:256
	v_pk_fma_f32 v[220:221], v[6:7], v[6:7], v[220:221]
	v_pk_fma_f32 v[220:221], v[0:1], v[0:1], v[220:221]
	v_pk_fma_f32 v[220:221], v[2:3], v[2:3], v[220:221]
	v_add_f32_e32 v157, v220, v221
	v_add_u32_e32 v155, 0x8000, v155
	v_mov_b32_e32 v158, v157
	s_nop 1
	v_permlane16_swap_b32_e32 v157, v158
	s_nop 0
	v_add_f32_e32 v157, v157, v158
	v_mov_b32_e32 v158, v157
	s_nop 1
	v_permlane32_swap_b32_e32 v157, v158
	s_nop 0
	v_add_f32_e32 v157, v157, v158
	s_and_saveexec_b64 s[38:39], s[4:5]
	global_store_dword v156, v157, s[20:21] offset:3072
	s_mov_b64 exec, s[38:39]
	s_branch .LBB0_575

.LBB0_698:
	s_add_u32 s28, s26, 0xfffc0080
	s_addc_u32 s29, s27, -1
	s_add_i32 s68, 0, 0x10000
	v_add_u32_e32 v155, s68, v153
	ds_read_b128 v[138:141], v155
	ds_read_b128 v[142:145], v155 offset:1024
	ds_read_b128 v[146:149], v155 offset:2048
	ds_read_b128 v[156:159], v155 offset:3072
	s_cmp_eq_u32 s51, 12
	s_cselect_b32 s31, s21, s29
	s_cselect_b32 s30, s38, s28
	s_cselect_b32 s29, s7, s50
	s_cselect_b32 s28, s39, s46
	s_add_i32 m0, s58, 0xc000
	ds_read_b128 v[160:163], v154
	ds_read_b128 v[164:167], v154 offset:1024
	ds_read_b128 v[168:171], v154 offset:2048
	ds_read_b128 v[172:175], v154 offset:3072
	ds_read_b128 v[176:179], v154 offset:4096
	ds_read_b128 v[180:183], v154 offset:5120
	ds_read_b128 v[184:187], v154 offset:6144
	ds_read_b128 v[188:191], v154 offset:7168
	global_load_lds_dwordx4 v134, s[26:27]
	s_add_i32 m0, s58, 0xe000
	s_nop 0
	global_load_lds_dwordx4 v136, s[26:27]
	s_waitcnt lgkmcnt(8)
	s_barrier
	s_waitcnt lgkmcnt(0)
	v_mfma_f32_16x16x32_bf16 v[124:127], v[138:141], v[160:163], v[124:127]
	v_mfma_f32_16x16x32_bf16 v[120:123], v[146:149], v[160:163], v[120:123]
	v_mfma_f32_16x16x32_bf16 v[108:111], v[138:141], v[168:171], v[108:111]
	v_mfma_f32_16x16x32_bf16 v[104:107], v[146:149], v[168:171], v[104:107]
	v_mfma_f32_16x16x32_bf16 v[92:95], v[138:141], v[176:179], v[92:95]
	v_mfma_f32_16x16x32_bf16 v[88:91], v[146:149], v[176:179], v[88:91]
	v_mfma_f32_16x16x32_bf16 v[76:79], v[138:141], v[184:187], v[76:79]
	v_mfma_f32_16x16x32_bf16 v[72:75], v[146:149], v[184:187], v[72:75]
	v_mfma_f32_16x16x32_bf16 v[124:127], v[142:145], v[164:167], v[124:127]
	v_mfma_f32_16x16x32_bf16 v[120:123], v[156:159], v[164:167], v[120:123]
	v_mfma_f32_16x16x32_bf16 v[108:111], v[142:145], v[172:175], v[108:111]
	v_mfma_f32_16x16x32_bf16 v[104:107], v[156:159], v[172:175], v[104:107]
	v_mfma_f32_16x16x32_bf16 v[92:95], v[142:145], v[180:183], v[92:95]
	v_mfma_f32_16x16x32_bf16 v[88:91], v[156:159], v[180:183], v[88:91]
	v_mfma_f32_16x16x32_bf16 v[76:79], v[142:145], v[188:191], v[76:79]
	v_mfma_f32_16x16x32_bf16 v[72:75], v[156:159], v[188:191], v[72:75]
	s_barrier
	s_add_i32 s70, 0, 0x14000
	s_add_i32 s68, s68, s57
	v_add_u32_e32 v155, s70, v153
	s_add_u32 s98, s28, s40
	s_addc_u32 s99, s29, s41
	s_mov_b32 m0, s68
	ds_read_b128 v[192:195], v155
	ds_read_b128 v[196:199], v155 offset:1024
	ds_read_b128 v[200:203], v155 offset:2048
	ds_read_b128 v[204:207], v155 offset:3072
	global_load_lds_dwordx4 v208, s[28:29]
	s_add_i32 m0, s68, 0x2000
	s_nop 0
	global_load_lds_dwordx4 v128, s[28:29]
	s_barrier
	s_waitcnt lgkmcnt(0)
	v_mfma_f32_16x16x32_bf16 v[116:119], v[192:195], v[160:163], v[116:119]
	v_mfma_f32_16x16x32_bf16 v[112:115], v[200:203], v[160:163], v[112:115]
	v_mfma_f32_16x16x32_bf16 v[100:103], v[192:195], v[168:171], v[100:103]
	v_mfma_f32_16x16x32_bf16 v[96:99], v[200:203], v[168:171], v[96:99]
	v_mfma_f32_16x16x32_bf16 v[84:87], v[192:195], v[176:179], v[84:87]
	v_mfma_f32_16x16x32_bf16 v[80:83], v[200:203], v[176:179], v[80:83]
	v_mfma_f32_16x16x32_bf16 v[68:71], v[192:195], v[184:187], v[68:71]
	v_mfma_f32_16x16x32_bf16 v[64:67], v[200:203], v[184:187], v[64:67]
	v_mfma_f32_16x16x32_bf16 v[116:119], v[196:199], v[164:167], v[116:119]
	v_mfma_f32_16x16x32_bf16 v[112:115], v[204:207], v[164:167], v[112:115]
	v_mfma_f32_16x16x32_bf16 v[100:103], v[196:199], v[172:175], v[100:103]
	v_mfma_f32_16x16x32_bf16 v[96:99], v[204:207], v[172:175], v[96:99]
	v_mfma_f32_16x16x32_bf16 v[84:87], v[196:199], v[180:183], v[84:87]
	v_mfma_f32_16x16x32_bf16 v[80:83], v[204:207], v[180:183], v[80:83]
	v_mfma_f32_16x16x32_bf16 v[68:71], v[196:199], v[188:191], v[68:71]
	v_mfma_f32_16x16x32_bf16 v[64:67], v[204:207], v[188:191], v[64:67]
	s_mov_b32 m0, s58
	s_add_u32 s100, s30, s40
	s_addc_u32 s101, s31, s41
	s_barrier
	ds_read_b128 v[160:163], v154 offset:16384
	ds_read_b128 v[164:167], v154 offset:17408
	ds_read_b128 v[168:171], v154 offset:18432
	ds_read_b128 v[172:175], v154 offset:19456
	ds_read_b128 v[176:179], v154 offset:20480
	ds_read_b128 v[180:183], v154 offset:21504
	ds_read_b128 v[184:187], v154 offset:22528
	ds_read_b128 v[188:191], v154 offset:23552
	global_load_lds_dwordx4 v132, s[30:31]
	s_mov_b32 m0, s59
	s_nop 0
	global_load_lds_dwordx4 v130, s[30:31]
	s_barrier
	s_waitcnt lgkmcnt(0)
	v_mfma_f32_16x16x32_bf16 v[60:63], v[138:141], v[160:163], v[60:63]
	v_mfma_f32_16x16x32_bf16 v[56:59], v[146:149], v[160:163], v[56:59]
	v_mfma_f32_16x16x32_bf16 v[44:47], v[138:141], v[168:171], v[44:47]
	v_mfma_f32_16x16x32_bf16 v[40:43], v[146:149], v[168:171], v[40:43]
	v_mfma_f32_16x16x32_bf16 v[28:31], v[138:141], v[176:179], v[28:31]
	v_mfma_f32_16x16x32_bf16 v[24:27], v[146:149], v[176:179], v[24:27]
	v_mfma_f32_16x16x32_bf16 v[12:15], v[138:141], v[184:187], v[12:15]
	v_mfma_f32_16x16x32_bf16 v[8:11], v[146:149], v[184:187], v[8:11]
	v_mfma_f32_16x16x32_bf16 v[60:63], v[142:145], v[164:167], v[60:63]
	v_mfma_f32_16x16x32_bf16 v[56:59], v[156:159], v[164:167], v[56:59]
	v_mfma_f32_16x16x32_bf16 v[44:47], v[142:145], v[172:175], v[44:47]
	v_mfma_f32_16x16x32_bf16 v[40:43], v[156:159], v[172:175], v[40:43]
	v_mfma_f32_16x16x32_bf16 v[28:31], v[142:145], v[180:183], v[28:31]
	v_mfma_f32_16x16x32_bf16 v[24:27], v[156:159], v[180:183], v[24:27]
	v_mfma_f32_16x16x32_bf16 v[12:15], v[142:145], v[188:191], v[12:15]
	v_mfma_f32_16x16x32_bf16 v[8:11], v[156:159], v[188:191], v[8:11]
	s_barrier
	s_add_u32 s68, s28, 0x40000
	s_addc_u32 s69, s29, 0
	s_add_i32 s70, s70, s57
	s_mov_b32 m0, s70
	s_nop 0
	global_load_lds_dwordx4 v208, s[68:69]
	s_add_i32 m0, s70, 0x2000
	s_nop 0
	global_load_lds_dwordx4 v128, s[68:69]
	s_waitcnt vmcnt(6)
	s_barrier
	v_mfma_f32_16x16x32_bf16 v[52:55], v[192:195], v[160:163], v[52:55]
	v_mfma_f32_16x16x32_bf16 v[48:51], v[200:203], v[160:163], v[48:51]
	v_mfma_f32_16x16x32_bf16 v[36:39], v[192:195], v[168:171], v[36:39]
	v_mfma_f32_16x16x32_bf16 v[32:35], v[200:203], v[168:171], v[32:35]
	v_mfma_f32_16x16x32_bf16 v[20:23], v[192:195], v[176:179], v[20:23]
	v_mfma_f32_16x16x32_bf16 v[16:19], v[200:203], v[176:179], v[16:19]
	v_mfma_f32_16x16x32_bf16 v[4:7], v[192:195], v[184:187], v[4:7]
	v_mfma_f32_16x16x32_bf16 v[0:3], v[200:203], v[184:187], v[0:3]
	v_mfma_f32_16x16x32_bf16 v[52:55], v[196:199], v[164:167], v[52:55]
	v_mfma_f32_16x16x32_bf16 v[48:51], v[204:207], v[164:167], v[48:51]
	v_mfma_f32_16x16x32_bf16 v[36:39], v[196:199], v[172:175], v[36:39]
	v_mfma_f32_16x16x32_bf16 v[32:35], v[204:207], v[172:175], v[32:35]
	v_mfma_f32_16x16x32_bf16 v[20:23], v[196:199], v[180:183], v[20:23]
	v_mfma_f32_16x16x32_bf16 v[16:19], v[204:207], v[180:183], v[16:19]
	v_mfma_f32_16x16x32_bf16 v[4:7], v[196:199], v[188:191], v[4:7]
	v_mfma_f32_16x16x32_bf16 v[0:3], v[204:207], v[188:191], v[0:3]
	s_add_i32 s68, 0, 0x18000
	v_add_u32_e32 v155, s68, v153
	s_barrier
	ds_read_b128 v[138:141], v155
	ds_read_b128 v[142:145], v155 offset:1024
	ds_read_b128 v[146:149], v155 offset:2048
	ds_read_b128 v[156:159], v155 offset:3072
	s_add_u32 s30, s30, 0x40000
	s_addc_u32 s31, s31, 0
	s_mov_b32 m0, s60
	ds_read_b128 v[160:163], v154 offset:32768
	ds_read_b128 v[164:167], v154 offset:33792
	ds_read_b128 v[168:171], v154 offset:34816
	ds_read_b128 v[172:175], v154 offset:35840
	ds_read_b128 v[176:179], v154 offset:36864
	ds_read_b128 v[180:183], v154 offset:37888
	ds_read_b128 v[184:187], v154 offset:38912
	ds_read_b128 v[188:191], v154 offset:39936
	global_load_lds_dwordx4 v132, s[30:31]
	s_mov_b32 m0, s61
	s_nop 0
	global_load_lds_dwordx4 v130, s[30:31]
	s_waitcnt lgkmcnt(8)
	s_barrier
	s_waitcnt lgkmcnt(0)
	v_mfma_f32_16x16x32_bf16 v[124:127], v[138:141], v[160:163], v[124:127]
	v_mfma_f32_16x16x32_bf16 v[120:123], v[146:149], v[160:163], v[120:123]
	v_mfma_f32_16x16x32_bf16 v[108:111], v[138:141], v[168:171], v[108:111]
	v_mfma_f32_16x16x32_bf16 v[104:107], v[146:149], v[168:171], v[104:107]
	v_mfma_f32_16x16x32_bf16 v[92:95], v[138:141], v[176:179], v[92:95]
	v_mfma_f32_16x16x32_bf16 v[88:91], v[146:149], v[176:179], v[88:91]
	v_mfma_f32_16x16x32_bf16 v[76:79], v[138:141], v[184:187], v[76:79]
	v_mfma_f32_16x16x32_bf16 v[72:75], v[146:149], v[184:187], v[72:75]
	v_mfma_f32_16x16x32_bf16 v[124:127], v[142:145], v[164:167], v[124:127]
	v_mfma_f32_16x16x32_bf16 v[120:123], v[156:159], v[164:167], v[120:123]
	v_mfma_f32_16x16x32_bf16 v[108:111], v[142:145], v[172:175], v[108:111]
	v_mfma_f32_16x16x32_bf16 v[104:107], v[156:159], v[172:175], v[104:107]
	v_mfma_f32_16x16x32_bf16 v[92:95], v[142:145], v[180:183], v[92:95]
	v_mfma_f32_16x16x32_bf16 v[88:91], v[156:159], v[180:183], v[88:91]
	v_mfma_f32_16x16x32_bf16 v[76:79], v[142:145], v[188:191], v[76:79]
	v_mfma_f32_16x16x32_bf16 v[72:75], v[156:159], v[188:191], v[72:75]
	s_barrier
	s_add_i32 s30, 0, 0x1c000
	s_add_i32 s31, s68, s57
	v_add_u32_e32 v155, s30, v153
	s_mov_b32 m0, s31
	ds_read_b128 v[192:195], v155
	ds_read_b128 v[196:199], v155 offset:1024
	ds_read_b128 v[200:203], v155 offset:2048
	ds_read_b128 v[204:207], v155 offset:3072
	global_load_lds_dwordx4 v208, s[98:99]
	s_add_i32 m0, s31, 0x2000
	s_nop 0
	global_load_lds_dwordx4 v128, s[98:99]
	s_barrier
	s_waitcnt lgkmcnt(0)
	v_mfma_f32_16x16x32_bf16 v[116:119], v[192:195], v[160:163], v[116:119]
	v_mfma_f32_16x16x32_bf16 v[112:115], v[200:203], v[160:163], v[112:115]
	v_mfma_f32_16x16x32_bf16 v[100:103], v[192:195], v[168:171], v[100:103]
	v_mfma_f32_16x16x32_bf16 v[96:99], v[200:203], v[168:171], v[96:99]
	v_mfma_f32_16x16x32_bf16 v[84:87], v[192:195], v[176:179], v[84:87]
	v_mfma_f32_16x16x32_bf16 v[80:83], v[200:203], v[176:179], v[80:83]
	v_mfma_f32_16x16x32_bf16 v[68:71], v[192:195], v[184:187], v[68:71]
	v_mfma_f32_16x16x32_bf16 v[64:67], v[200:203], v[184:187], v[64:67]
	v_mfma_f32_16x16x32_bf16 v[116:119], v[196:199], v[164:167], v[116:119]
	v_mfma_f32_16x16x32_bf16 v[112:115], v[204:207], v[164:167], v[112:115]
	v_mfma_f32_16x16x32_bf16 v[100:103], v[196:199], v[172:175], v[100:103]
	v_mfma_f32_16x16x32_bf16 v[96:99], v[204:207], v[172:175], v[96:99]
	v_mfma_f32_16x16x32_bf16 v[84:87], v[196:199], v[180:183], v[84:87]
	v_mfma_f32_16x16x32_bf16 v[80:83], v[204:207], v[180:183], v[80:83]
	v_mfma_f32_16x16x32_bf16 v[68:71], v[196:199], v[188:191], v[68:71]
	v_mfma_f32_16x16x32_bf16 v[64:67], v[204:207], v[188:191], v[64:67]
	s_mov_b32 m0, s64
	s_barrier
	ds_read_b128 v[160:163], v154 offset:49152
	ds_read_b128 v[164:167], v154 offset:50176
	ds_read_b128 v[168:171], v154 offset:51200
	ds_read_b128 v[172:175], v154 offset:52224
	ds_read_b128 v[176:179], v154 offset:53248
	ds_read_b128 v[180:183], v154 offset:54272
	ds_read_b128 v[184:187], v154 offset:55296
	ds_read_b128 v[188:191], v154 offset:56320
	global_load_lds_dwordx4 v132, s[100:101]
	s_mov_b32 m0, s65
	s_nop 0
	global_load_lds_dwordx4 v130, s[100:101]
	s_barrier
	s_waitcnt lgkmcnt(0)
	v_mfma_f32_16x16x32_bf16 v[60:63], v[138:141], v[160:163], v[60:63]
	v_mfma_f32_16x16x32_bf16 v[56:59], v[146:149], v[160:163], v[56:59]
	v_mfma_f32_16x16x32_bf16 v[44:47], v[138:141], v[168:171], v[44:47]
	v_mfma_f32_16x16x32_bf16 v[40:43], v[146:149], v[168:171], v[40:43]
	v_mfma_f32_16x16x32_bf16 v[28:31], v[138:141], v[176:179], v[28:31]
	v_mfma_f32_16x16x32_bf16 v[24:27], v[146:149], v[176:179], v[24:27]
	v_mfma_f32_16x16x32_bf16 v[12:15], v[138:141], v[184:187], v[12:15]
	v_mfma_f32_16x16x32_bf16 v[8:11], v[146:149], v[184:187], v[8:11]
	v_mfma_f32_16x16x32_bf16 v[60:63], v[142:145], v[164:167], v[60:63]
	v_mfma_f32_16x16x32_bf16 v[56:59], v[156:159], v[164:167], v[56:59]
	v_mfma_f32_16x16x32_bf16 v[44:47], v[142:145], v[172:175], v[44:47]
	v_mfma_f32_16x16x32_bf16 v[40:43], v[156:159], v[172:175], v[40:43]
	v_mfma_f32_16x16x32_bf16 v[28:31], v[142:145], v[180:183], v[28:31]
	v_mfma_f32_16x16x32_bf16 v[24:27], v[156:159], v[180:183], v[24:27]
	v_mfma_f32_16x16x32_bf16 v[12:15], v[142:145], v[188:191], v[12:15]
	v_mfma_f32_16x16x32_bf16 v[8:11], v[156:159], v[188:191], v[8:11]
	s_barrier
	s_add_u32 s28, s28, 0x40080
	s_addc_u32 s29, s29, 0
	s_add_i32 s30, s30, s57
	s_mov_b32 m0, s30
	s_nop 0
	global_load_lds_dwordx4 v208, s[28:29]
	s_add_i32 m0, s30, 0x2000
	s_nop 0
	global_load_lds_dwordx4 v128, s[28:29]
	s_waitcnt vmcnt(6)
	s_barrier
	v_mfma_f32_16x16x32_bf16 v[52:55], v[192:195], v[160:163], v[52:55]
	v_mfma_f32_16x16x32_bf16 v[48:51], v[200:203], v[160:163], v[48:51]
	v_mfma_f32_16x16x32_bf16 v[36:39], v[192:195], v[168:171], v[36:39]
	v_mfma_f32_16x16x32_bf16 v[32:35], v[200:203], v[168:171], v[32:35]
	v_mfma_f32_16x16x32_bf16 v[20:23], v[192:195], v[176:179], v[20:23]
	v_mfma_f32_16x16x32_bf16 v[16:19], v[200:203], v[176:179], v[16:19]
	v_mfma_f32_16x16x32_bf16 v[4:7], v[192:195], v[184:187], v[4:7]
	v_mfma_f32_16x16x32_bf16 v[0:3], v[200:203], v[184:187], v[0:3]
	v_mfma_f32_16x16x32_bf16 v[52:55], v[196:199], v[164:167], v[52:55]
	v_mfma_f32_16x16x32_bf16 v[48:51], v[204:207], v[164:167], v[48:51]
	v_mfma_f32_16x16x32_bf16 v[36:39], v[196:199], v[172:175], v[36:39]
	v_mfma_f32_16x16x32_bf16 v[32:35], v[204:207], v[172:175], v[32:35]
	v_mfma_f32_16x16x32_bf16 v[20:23], v[196:199], v[180:183], v[20:23]
	v_mfma_f32_16x16x32_bf16 v[16:19], v[204:207], v[180:183], v[16:19]
	v_mfma_f32_16x16x32_bf16 v[4:7], v[196:199], v[188:191], v[4:7]
	v_mfma_f32_16x16x32_bf16 v[0:3], v[204:207], v[188:191], v[0:3]
	s_add_i32 s51, s51, 2
	s_add_u32 s26, s26, 0x100
	s_addc_u32 s27, s27, 0
	s_add_u32 s46, s46, 0x100
	s_addc_u32 s50, s50, 0
	s_cmp_gt_u32 s51, 13
	s_barrier
	s_cbranch_scc0 .LBB0_698
	s_cmp_lt_i32 s34, 4
	s_cselect_b64 vcc, -1, 0
	v_mov_b32_e32 v138, 0x3e38aa3b
	s_nop 0
	v_cndmask_b32_e32 v155, 1.0, v138, vcc
	s_and_b64 s[26:27], vcc, exec
	v_lshl_add_u32 v140, s35, 8, v152
	s_cselect_b32 s7, s9, s11
	s_cselect_b32 s21, s8, s10
	v_mov_b32_e32 v138, s21
	v_mov_b32_e32 v139, s7
	v_lshlrev_b32_e32 v142, 3, v151
	v_mov_b32_e32 v143, 0
	v_lshl_add_u64 v[138:139], v[142:143], 2, v[138:139]
	global_load_dwordx4 v[188:191], v[138:139], off
	global_load_dwordx4 v[192:195], v[138:139], off offset:16
	global_load_dwordx4 v[196:199], v[138:139], off offset:128
	global_load_dwordx4 v[200:203], v[138:139], off offset:144
	s_lshl_b32 s7, s34, 8
	s_or_b32 s26, s7, s66
	s_ashr_i32 s27, s26, 31
	s_lshl_b64 s[26:27], s[26:27], 1
	s_add_u32 s26, s62, s26
	s_addc_u32 s27, s63, s27
	s_mov_b32 s34, s6
	s_mov_b32 s35, s20
	s_mov_b64 s[28:29], s[24:25]
	v_mbcnt_lo_u32_b32 v210, -1, 0
	v_mbcnt_hi_u32_b32 v210, -1, v210
	v_and_b32_e32 v210, 48, v210
	v_lshl_add_u32 v210, v140, 6, v210
	v_lshlrev_b32_e32 v211, 12, v140
	v_lshl_add_u32 v211, v151, 4, v211
	global_load_dwordx4 v[156:159], v210, s[18:19]
	global_load_dwordx4 v[160:163], v210, s[18:19] offset:1024
	global_load_dwordx4 v[164:167], v210, s[18:19] offset:2048
	global_load_dwordx4 v[168:171], v210, s[18:19] offset:3072
	v_add_u32_e32 v210, 0x2000, v210
	global_load_dwordx4 v[172:175], v210, s[18:19]
	global_load_dwordx4 v[176:179], v210, s[18:19] offset:1024
	global_load_dwordx4 v[180:183], v210, s[18:19] offset:2048
	global_load_dwordx4 v[184:187], v210, s[18:19] offset:3072
	s_waitcnt vmcnt(7)
	v_pk_add_f32 v[156:157], v[156:157], v[158:159]
	s_nop 0
	v_add_f32_e32 v214, v156, v157
	v_mov_b32_e32 v215, v214
	s_nop 1
	v_permlane16_swap_b32_e32 v214, v215
	s_nop 0
	v_add_f32_e32 v214, v214, v215
	v_mov_b32_e32 v215, v214
	s_nop 1
	v_permlane32_swap_b32_e32 v214, v215
	s_nop 0
	v_add_f32_e32 v214, v214, v215
	v_fmamk_f32 v214, v214, 0x3a800000, v248
	v_rsq_f32_e32 v216, v214
	s_nop 0
	v_pk_mul_f32 v[124:125], v[124:125], v[216:217] op_sel_hi:[1,0]
	v_pk_mul_f32 v[126:127], v[126:127], v[216:217] op_sel_hi:[1,0]
	v_pk_mul_f32 v[120:121], v[120:121], v[216:217] op_sel_hi:[1,0]
	v_pk_mul_f32 v[122:123], v[122:123], v[216:217] op_sel_hi:[1,0]
	v_pk_mul_f32 v[116:117], v[116:117], v[216:217] op_sel_hi:[1,0]
	v_pk_mul_f32 v[118:119], v[118:119], v[216:217] op_sel_hi:[1,0]
	v_pk_mul_f32 v[112:113], v[112:113], v[216:217] op_sel_hi:[1,0]
	v_pk_mul_f32 v[114:115], v[114:115], v[216:217] op_sel_hi:[1,0]
	v_pk_mul_f32 v[148:149], v[124:125], v[124:125]
	v_pk_fma_f32 v[148:149], v[126:127], v[126:127], v[148:149]
	v_pk_fma_f32 v[148:149], v[120:121], v[120:121], v[148:149]
	v_pk_fma_f32 v[148:149], v[122:123], v[122:123], v[148:149]
	v_pk_fma_f32 v[148:149], v[116:117], v[116:117], v[148:149]
	v_pk_fma_f32 v[148:149], v[118:119], v[118:119], v[148:149]
	v_pk_fma_f32 v[148:149], v[112:113], v[112:113], v[148:149]
	v_pk_fma_f32 v[148:149], v[114:115], v[114:115], v[148:149]
	v_add_f32_e32 v214, v148, v149
	v_mov_b32_e32 v215, v214
	s_nop 1
	v_permlane16_swap_b32_e32 v214, v215
	s_nop 0
	v_add_f32_e32 v214, v214, v215
	v_mov_b32_e32 v215, v214
	s_nop 1
	v_permlane32_swap_b32_e32 v214, v215
	s_nop 0
	v_add_f32_e32 v214, v214, v215
	v_fmamk_f32 v214, v214, 0x3c800000, v248
	v_rsq_f32_e32 v214, v214
	s_nop 0
	v_mul_f32_e32 v218, v155, v214
	v_pk_mul_f32 v[156:157], v[188:189], v[218:219] op_sel_hi:[1,0]
	v_pk_mul_f32 v[124:125], v[124:125], v[156:157]
	v_pk_mul_f32 v[156:157], v[190:191], v[218:219] op_sel_hi:[1,0]
	v_pk_mul_f32 v[126:127], v[126:127], v[156:157]
	v_pk_mul_f32 v[156:157], v[192:193], v[218:219] op_sel_hi:[1,0]
	v_pk_mul_f32 v[120:121], v[120:121], v[156:157]
	v_pk_mul_f32 v[156:157], v[194:195], v[218:219] op_sel_hi:[1,0]
	v_pk_mul_f32 v[122:123], v[122:123], v[156:157]
	v_cvt_pk_bf16_f32 v204, v124, v125
	v_cvt_pk_bf16_f32 v205, v126, v127
	v_cvt_pk_bf16_f32 v206, v120, v121
	v_cvt_pk_bf16_f32 v207, v122, v123
	global_store_dwordx4 v211, v[204:207], s[26:27]
	v_pk_mul_f32 v[156:157], v[196:197], v[218:219] op_sel_hi:[1,0]
	v_pk_mul_f32 v[116:117], v[116:117], v[156:157]
	v_pk_mul_f32 v[156:157], v[198:199], v[218:219] op_sel_hi:[1,0]
	v_pk_mul_f32 v[118:119], v[118:119], v[156:157]
	v_pk_mul_f32 v[156:157], v[200:201], v[218:219] op_sel_hi:[1,0]
	v_pk_mul_f32 v[112:113], v[112:113], v[156:157]
	v_pk_mul_f32 v[156:157], v[202:203], v[218:219] op_sel_hi:[1,0]
	v_pk_mul_f32 v[114:115], v[114:115], v[156:157]
	v_cvt_pk_bf16_f32 v144, v116, v117
	v_cvt_pk_bf16_f32 v145, v118, v119
	v_cvt_pk_bf16_f32 v146, v112, v113
	v_cvt_pk_bf16_f32 v147, v114, v115
	global_store_dwordx4 v211, v[144:147], s[26:27] offset:64
	v_add_u32_e32 v211, 0x10000, v211
	s_waitcnt vmcnt(8)
	v_pk_add_f32 v[160:161], v[160:161], v[162:163]
	s_nop 0
	v_add_f32_e32 v214, v160, v161
	v_mov_b32_e32 v215, v214
	s_nop 1
	v_permlane16_swap_b32_e32 v214, v215
	s_nop 0
	v_add_f32_e32 v214, v214, v215
	v_mov_b32_e32 v215, v214
	s_nop 1
	v_permlane32_swap_b32_e32 v214, v215
	s_nop 0
	v_add_f32_e32 v214, v214, v215
	v_fmamk_f32 v214, v214, 0x3a800000, v248
	v_rsq_f32_e32 v216, v214
	s_nop 0
	v_pk_mul_f32 v[108:109], v[108:109], v[216:217] op_sel_hi:[1,0]
	v_pk_mul_f32 v[110:111], v[110:111], v[216:217] op_sel_hi:[1,0]
	v_pk_mul_f32 v[104:105], v[104:105], v[216:217] op_sel_hi:[1,0]
	v_pk_mul_f32 v[106:107], v[106:107], v[216:217] op_sel_hi:[1,0]
	v_pk_mul_f32 v[100:101], v[100:101], v[216:217] op_sel_hi:[1,0]
	v_pk_mul_f32 v[102:103], v[102:103], v[216:217] op_sel_hi:[1,0]
	v_pk_mul_f32 v[96:97], v[96:97], v[216:217] op_sel_hi:[1,0]
	v_pk_mul_f32 v[98:99], v[98:99], v[216:217] op_sel_hi:[1,0]
	v_pk_mul_f32 v[148:149], v[108:109], v[108:109]
	v_pk_fma_f32 v[148:149], v[110:111], v[110:111], v[148:149]
	v_pk_fma_f32 v[148:149], v[104:105], v[104:105], v[148:149]
	v_pk_fma_f32 v[148:149], v[106:107], v[106:107], v[148:149]
	v_pk_fma_f32 v[148:149], v[100:101], v[100:101], v[148:149]
	v_pk_fma_f32 v[148:149], v[102:103], v[102:103], v[148:149]
	v_pk_fma_f32 v[148:149], v[96:97], v[96:97], v[148:149]
	v_pk_fma_f32 v[148:149], v[98:99], v[98:99], v[148:149]
	v_add_f32_e32 v214, v148, v149
	v_mov_b32_e32 v215, v214
	s_nop 1
	v_permlane16_swap_b32_e32 v214, v215
	s_nop 0
	v_add_f32_e32 v214, v214, v215
	v_mov_b32_e32 v215, v214
	s_nop 1
	v_permlane32_swap_b32_e32 v214, v215
	s_nop 0
	v_add_f32_e32 v214, v214, v215
	v_fmamk_f32 v214, v214, 0x3c800000, v248
	v_rsq_f32_e32 v214, v214
	s_nop 0
	v_mul_f32_e32 v218, v155, v214
	v_pk_mul_f32 v[160:161], v[188:189], v[218:219] op_sel_hi:[1,0]
	v_pk_mul_f32 v[108:109], v[108:109], v[160:161]
	v_pk_mul_f32 v[160:161], v[190:191], v[218:219] op_sel_hi:[1,0]
	v_pk_mul_f32 v[110:111], v[110:111], v[160:161]
	v_pk_mul_f32 v[160:161], v[192:193], v[218:219] op_sel_hi:[1,0]
	v_pk_mul_f32 v[104:105], v[104:105], v[160:161]
	v_pk_mul_f32 v[160:161], v[194:195], v[218:219] op_sel_hi:[1,0]
	v_pk_mul_f32 v[106:107], v[106:107], v[160:161]
	v_cvt_pk_bf16_f32 v204, v108, v109
	v_cvt_pk_bf16_f32 v205, v110, v111
	v_cvt_pk_bf16_f32 v206, v104, v105
	v_cvt_pk_bf16_f32 v207, v106, v107
	global_store_dwordx4 v211, v[204:207], s[26:27]
	v_pk_mul_f32 v[160:161], v[196:197], v[218:219] op_sel_hi:[1,0]
	v_pk_mul_f32 v[100:101], v[100:101], v[160:161]
	v_pk_mul_f32 v[160:161], v[198:199], v[218:219] op_sel_hi:[1,0]
	v_pk_mul_f32 v[102:103], v[102:103], v[160:161]
	v_pk_mul_f32 v[160:161], v[200:201], v[218:219] op_sel_hi:[1,0]
	v_pk_mul_f32 v[96:97], v[96:97], v[160:161]
	v_pk_mul_f32 v[160:161], v[202:203], v[218:219] op_sel_hi:[1,0]
	v_pk_mul_f32 v[98:99], v[98:99], v[160:161]
	v_cvt_pk_bf16_f32 v144, v100, v101
	v_cvt_pk_bf16_f32 v145, v102, v103
	v_cvt_pk_bf16_f32 v146, v96, v97
	v_cvt_pk_bf16_f32 v147, v98, v99
	global_store_dwordx4 v211, v[144:147], s[26:27] offset:64
	v_add_u32_e32 v211, 0x10000, v211
	s_waitcnt vmcnt(9)
	v_pk_add_f32 v[164:165], v[164:165], v[166:167]
	s_nop 0
	v_add_f32_e32 v214, v164, v165
	v_mov_b32_e32 v215, v214
	s_nop 1
	v_permlane16_swap_b32_e32 v214, v215
	s_nop 0
	v_add_f32_e32 v214, v214, v215
	v_mov_b32_e32 v215, v214
	s_nop 1
	v_permlane32_swap_b32_e32 v214, v215
	s_nop 0
	v_add_f32_e32 v214, v214, v215
	v_fmamk_f32 v214, v214, 0x3a800000, v248
	v_rsq_f32_e32 v216, v214
	s_nop 0
	v_pk_mul_f32 v[92:93], v[92:93], v[216:217] op_sel_hi:[1,0]
	v_pk_mul_f32 v[94:95], v[94:95], v[216:217] op_sel_hi:[1,0]
	v_pk_mul_f32 v[88:89], v[88:89], v[216:217] op_sel_hi:[1,0]
	v_pk_mul_f32 v[90:91], v[90:91], v[216:217] op_sel_hi:[1,0]
	v_pk_mul_f32 v[84:85], v[84:85], v[216:217] op_sel_hi:[1,0]
	v_pk_mul_f32 v[86:87], v[86:87], v[216:217] op_sel_hi:[1,0]
	v_pk_mul_f32 v[80:81], v[80:81], v[216:217] op_sel_hi:[1,0]
	v_pk_mul_f32 v[82:83], v[82:83], v[216:217] op_sel_hi:[1,0]
	v_pk_mul_f32 v[148:149], v[92:93], v[92:93]
	v_pk_fma_f32 v[148:149], v[94:95], v[94:95], v[148:149]
	v_pk_fma_f32 v[148:149], v[88:89], v[88:89], v[148:149]
	v_pk_fma_f32 v[148:149], v[90:91], v[90:91], v[148:149]
	v_pk_fma_f32 v[148:149], v[84:85], v[84:85], v[148:149]
	v_pk_fma_f32 v[148:149], v[86:87], v[86:87], v[148:149]
	v_pk_fma_f32 v[148:149], v[80:81], v[80:81], v[148:149]
	v_pk_fma_f32 v[148:149], v[82:83], v[82:83], v[148:149]
	v_add_f32_e32 v214, v148, v149
	v_mov_b32_e32 v215, v214
	s_nop 1
	v_permlane16_swap_b32_e32 v214, v215
	s_nop 0
	v_add_f32_e32 v214, v214, v215
	v_mov_b32_e32 v215, v214
	s_nop 1
	v_permlane32_swap_b32_e32 v214, v215
	s_nop 0
	v_add_f32_e32 v214, v214, v215
	v_fmamk_f32 v214, v214, 0x3c800000, v248
	v_rsq_f32_e32 v214, v214
	s_nop 0
	v_mul_f32_e32 v218, v155, v214
	v_pk_mul_f32 v[164:165], v[188:189], v[218:219] op_sel_hi:[1,0]
	v_pk_mul_f32 v[92:93], v[92:93], v[164:165]
	v_pk_mul_f32 v[164:165], v[190:191], v[218:219] op_sel_hi:[1,0]
	v_pk_mul_f32 v[94:95], v[94:95], v[164:165]
	v_pk_mul_f32 v[164:165], v[192:193], v[218:219] op_sel_hi:[1,0]
	v_pk_mul_f32 v[88:89], v[88:89], v[164:165]
	v_pk_mul_f32 v[164:165], v[194:195], v[218:219] op_sel_hi:[1,0]
	v_pk_mul_f32 v[90:91], v[90:91], v[164:165]
	v_cvt_pk_bf16_f32 v204, v92, v93
	v_cvt_pk_bf16_f32 v205, v94, v95
	v_cvt_pk_bf16_f32 v206, v88, v89
	v_cvt_pk_bf16_f32 v207, v90, v91
	global_store_dwordx4 v211, v[204:207], s[26:27]
	v_pk_mul_f32 v[164:165], v[196:197], v[218:219] op_sel_hi:[1,0]
	v_pk_mul_f32 v[84:85], v[84:85], v[164:165]
	v_pk_mul_f32 v[164:165], v[198:199], v[218:219] op_sel_hi:[1,0]
	v_pk_mul_f32 v[86:87], v[86:87], v[164:165]
	v_pk_mul_f32 v[164:165], v[200:201], v[218:219] op_sel_hi:[1,0]
	v_pk_mul_f32 v[80:81], v[80:81], v[164:165]
	v_pk_mul_f32 v[164:165], v[202:203], v[218:219] op_sel_hi:[1,0]
	v_pk_mul_f32 v[82:83], v[82:83], v[164:165]
	v_cvt_pk_bf16_f32 v144, v84, v85
	v_cvt_pk_bf16_f32 v145, v86, v87
	v_cvt_pk_bf16_f32 v146, v80, v81
	v_cvt_pk_bf16_f32 v147, v82, v83
	global_store_dwordx4 v211, v[144:147], s[26:27] offset:64
	v_add_u32_e32 v211, 0x10000, v211
	s_waitcnt vmcnt(10)
	v_pk_add_f32 v[168:169], v[168:169], v[170:171]
	s_nop 0
	v_add_f32_e32 v214, v168, v169
	v_mov_b32_e32 v215, v214
	s_nop 1
	v_permlane16_swap_b32_e32 v214, v215
	s_nop 0
	v_add_f32_e32 v214, v214, v215
	v_mov_b32_e32 v215, v214
	s_nop 1
	v_permlane32_swap_b32_e32 v214, v215
	s_nop 0
	v_add_f32_e32 v214, v214, v215
	v_fmamk_f32 v214, v214, 0x3a800000, v248
	v_rsq_f32_e32 v216, v214
	s_nop 0
	v_pk_mul_f32 v[76:77], v[76:77], v[216:217] op_sel_hi:[1,0]
	v_pk_mul_f32 v[78:79], v[78:79], v[216:217] op_sel_hi:[1,0]
	v_pk_mul_f32 v[72:73], v[72:73], v[216:217] op_sel_hi:[1,0]
	v_pk_mul_f32 v[74:75], v[74:75], v[216:217] op_sel_hi:[1,0]
	v_pk_mul_f32 v[68:69], v[68:69], v[216:217] op_sel_hi:[1,0]
	v_pk_mul_f32 v[70:71], v[70:71], v[216:217] op_sel_hi:[1,0]
	v_pk_mul_f32 v[64:65], v[64:65], v[216:217] op_sel_hi:[1,0]
	v_pk_mul_f32 v[66:67], v[66:67], v[216:217] op_sel_hi:[1,0]
	v_pk_mul_f32 v[148:149], v[76:77], v[76:77]
	v_pk_fma_f32 v[148:149], v[78:79], v[78:79], v[148:149]
	v_pk_fma_f32 v[148:149], v[72:73], v[72:73], v[148:149]
	v_pk_fma_f32 v[148:149], v[74:75], v[74:75], v[148:149]
	v_pk_fma_f32 v[148:149], v[68:69], v[68:69], v[148:149]
	v_pk_fma_f32 v[148:149], v[70:71], v[70:71], v[148:149]
	v_pk_fma_f32 v[148:149], v[64:65], v[64:65], v[148:149]
	v_pk_fma_f32 v[148:149], v[66:67], v[66:67], v[148:149]
	v_add_f32_e32 v214, v148, v149
	v_mov_b32_e32 v215, v214
	s_nop 1
	v_permlane16_swap_b32_e32 v214, v215
	s_nop 0
	v_add_f32_e32 v214, v214, v215
	v_mov_b32_e32 v215, v214
	s_nop 1
	v_permlane32_swap_b32_e32 v214, v215
	s_nop 0
	v_add_f32_e32 v214, v214, v215
	v_fmamk_f32 v214, v214, 0x3c800000, v248
	v_rsq_f32_e32 v214, v214
	s_nop 0
	v_mul_f32_e32 v218, v155, v214
	v_pk_mul_f32 v[168:169], v[188:189], v[218:219] op_sel_hi:[1,0]
	v_pk_mul_f32 v[76:77], v[76:77], v[168:169]
	v_pk_mul_f32 v[168:169], v[190:191], v[218:219] op_sel_hi:[1,0]
	v_pk_mul_f32 v[78:79], v[78:79], v[168:169]
	v_pk_mul_f32 v[168:169], v[192:193], v[218:219] op_sel_hi:[1,0]
	v_pk_mul_f32 v[72:73], v[72:73], v[168:169]
	v_pk_mul_f32 v[168:169], v[194:195], v[218:219] op_sel_hi:[1,0]
	v_pk_mul_f32 v[74:75], v[74:75], v[168:169]
	v_cvt_pk_bf16_f32 v204, v76, v77
	v_cvt_pk_bf16_f32 v205, v78, v79
	v_cvt_pk_bf16_f32 v206, v72, v73
	v_cvt_pk_bf16_f32 v207, v74, v75
	global_store_dwordx4 v211, v[204:207], s[26:27]
	v_pk_mul_f32 v[168:169], v[196:197], v[218:219] op_sel_hi:[1,0]
	v_pk_mul_f32 v[68:69], v[68:69], v[168:169]
	v_pk_mul_f32 v[168:169], v[198:199], v[218:219] op_sel_hi:[1,0]
	v_pk_mul_f32 v[70:71], v[70:71], v[168:169]
	v_pk_mul_f32 v[168:169], v[200:201], v[218:219] op_sel_hi:[1,0]
	v_pk_mul_f32 v[64:65], v[64:65], v[168:169]
	v_pk_mul_f32 v[168:169], v[202:203], v[218:219] op_sel_hi:[1,0]
	v_pk_mul_f32 v[66:67], v[66:67], v[168:169]
	v_cvt_pk_bf16_f32 v144, v68, v69
	v_cvt_pk_bf16_f32 v145, v70, v71
	v_cvt_pk_bf16_f32 v146, v64, v65
	v_cvt_pk_bf16_f32 v147, v66, v67
	global_store_dwordx4 v211, v[144:147], s[26:27] offset:64
	v_add_u32_e32 v211, 0x50000, v211
	s_waitcnt vmcnt(11)
	v_pk_add_f32 v[172:173], v[172:173], v[174:175]
	s_nop 0
	v_add_f32_e32 v214, v172, v173
	v_mov_b32_e32 v215, v214
	s_nop 1
	v_permlane16_swap_b32_e32 v214, v215
	s_nop 0
	v_add_f32_e32 v214, v214, v215
	v_mov_b32_e32 v215, v214
	s_nop 1
	v_permlane32_swap_b32_e32 v214, v215
	s_nop 0
	v_add_f32_e32 v214, v214, v215
	v_fmamk_f32 v214, v214, 0x3a800000, v248
	v_rsq_f32_e32 v216, v214
	s_nop 0
	v_pk_mul_f32 v[60:61], v[60:61], v[216:217] op_sel_hi:[1,0]
	v_pk_mul_f32 v[62:63], v[62:63], v[216:217] op_sel_hi:[1,0]
	v_pk_mul_f32 v[56:57], v[56:57], v[216:217] op_sel_hi:[1,0]
	v_pk_mul_f32 v[58:59], v[58:59], v[216:217] op_sel_hi:[1,0]
	v_pk_mul_f32 v[52:53], v[52:53], v[216:217] op_sel_hi:[1,0]
	v_pk_mul_f32 v[54:55], v[54:55], v[216:217] op_sel_hi:[1,0]
	v_pk_mul_f32 v[48:49], v[48:49], v[216:217] op_sel_hi:[1,0]
	v_pk_mul_f32 v[50:51], v[50:51], v[216:217] op_sel_hi:[1,0]
	v_pk_mul_f32 v[148:149], v[60:61], v[60:61]
	v_pk_fma_f32 v[148:149], v[62:63], v[62:63], v[148:149]
	v_pk_fma_f32 v[148:149], v[56:57], v[56:57], v[148:149]
	v_pk_fma_f32 v[148:149], v[58:59], v[58:59], v[148:149]
	v_pk_fma_f32 v[148:149], v[52:53], v[52:53], v[148:149]
	v_pk_fma_f32 v[148:149], v[54:55], v[54:55], v[148:149]
	v_pk_fma_f32 v[148:149], v[48:49], v[48:49], v[148:149]
	v_pk_fma_f32 v[148:149], v[50:51], v[50:51], v[148:149]
	v_add_f32_e32 v214, v148, v149
	v_mov_b32_e32 v215, v214
	s_nop 1
	v_permlane16_swap_b32_e32 v214, v215
	s_nop 0
	v_add_f32_e32 v214, v214, v215
	v_mov_b32_e32 v215, v214
	s_nop 1
	v_permlane32_swap_b32_e32 v214, v215
	s_nop 0
	v_add_f32_e32 v214, v214, v215
	v_fmamk_f32 v214, v214, 0x3c800000, v248
	v_rsq_f32_e32 v214, v214
	s_nop 0
	v_mul_f32_e32 v218, v155, v214
	v_pk_mul_f32 v[172:173], v[188:189], v[218:219] op_sel_hi:[1,0]
	v_pk_mul_f32 v[60:61], v[60:61], v[172:173]
	v_pk_mul_f32 v[172:173], v[190:191], v[218:219] op_sel_hi:[1,0]
	v_pk_mul_f32 v[62:63], v[62:63], v[172:173]
	v_pk_mul_f32 v[172:173], v[192:193], v[218:219] op_sel_hi:[1,0]
	v_pk_mul_f32 v[56:57], v[56:57], v[172:173]
	v_pk_mul_f32 v[172:173], v[194:195], v[218:219] op_sel_hi:[1,0]
	v_pk_mul_f32 v[58:59], v[58:59], v[172:173]
	v_cvt_pk_bf16_f32 v204, v60, v61
	v_cvt_pk_bf16_f32 v205, v62, v63
	v_cvt_pk_bf16_f32 v206, v56, v57
	v_cvt_pk_bf16_f32 v207, v58, v59
	global_store_dwordx4 v211, v[204:207], s[26:27]
	v_pk_mul_f32 v[172:173], v[196:197], v[218:219] op_sel_hi:[1,0]
	v_pk_mul_f32 v[52:53], v[52:53], v[172:173]
	v_pk_mul_f32 v[172:173], v[198:199], v[218:219] op_sel_hi:[1,0]
	v_pk_mul_f32 v[54:55], v[54:55], v[172:173]
	v_pk_mul_f32 v[172:173], v[200:201], v[218:219] op_sel_hi:[1,0]
	v_pk_mul_f32 v[48:49], v[48:49], v[172:173]
	v_pk_mul_f32 v[172:173], v[202:203], v[218:219] op_sel_hi:[1,0]
	v_pk_mul_f32 v[50:51], v[50:51], v[172:173]
	v_cvt_pk_bf16_f32 v144, v52, v53
	v_cvt_pk_bf16_f32 v145, v54, v55
	v_cvt_pk_bf16_f32 v146, v48, v49
	v_cvt_pk_bf16_f32 v147, v50, v51
	global_store_dwordx4 v211, v[144:147], s[26:27] offset:64
	v_add_u32_e32 v211, 0x10000, v211
	s_waitcnt vmcnt(12)
	v_pk_add_f32 v[176:177], v[176:177], v[178:179]
	s_nop 0
	v_add_f32_e32 v214, v176, v177
	v_mov_b32_e32 v215, v214
	s_nop 1
	v_permlane16_swap_b32_e32 v214, v215
	s_nop 0
	v_add_f32_e32 v214, v214, v215
	v_mov_b32_e32 v215, v214
	s_nop 1
	v_permlane32_swap_b32_e32 v214, v215
	s_nop 0
	v_add_f32_e32 v214, v214, v215
	v_fmamk_f32 v214, v214, 0x3a800000, v248
	v_rsq_f32_e32 v216, v214
	s_nop 0
	v_pk_mul_f32 v[44:45], v[44:45], v[216:217] op_sel_hi:[1,0]
	v_pk_mul_f32 v[46:47], v[46:47], v[216:217] op_sel_hi:[1,0]
	v_pk_mul_f32 v[40:41], v[40:41], v[216:217] op_sel_hi:[1,0]
	v_pk_mul_f32 v[42:43], v[42:43], v[216:217] op_sel_hi:[1,0]
	v_pk_mul_f32 v[36:37], v[36:37], v[216:217] op_sel_hi:[1,0]
	v_pk_mul_f32 v[38:39], v[38:39], v[216:217] op_sel_hi:[1,0]
	v_pk_mul_f32 v[32:33], v[32:33], v[216:217] op_sel_hi:[1,0]
	v_pk_mul_f32 v[34:35], v[34:35], v[216:217] op_sel_hi:[1,0]
	v_pk_mul_f32 v[148:149], v[44:45], v[44:45]
	v_pk_fma_f32 v[148:149], v[46:47], v[46:47], v[148:149]
	v_pk_fma_f32 v[148:149], v[40:41], v[40:41], v[148:149]
	v_pk_fma_f32 v[148:149], v[42:43], v[42:43], v[148:149]
	v_pk_fma_f32 v[148:149], v[36:37], v[36:37], v[148:149]
	v_pk_fma_f32 v[148:149], v[38:39], v[38:39], v[148:149]
	v_pk_fma_f32 v[148:149], v[32:33], v[32:33], v[148:149]
	v_pk_fma_f32 v[148:149], v[34:35], v[34:35], v[148:149]
	v_add_f32_e32 v214, v148, v149
	v_mov_b32_e32 v215, v214
	s_nop 1
	v_permlane16_swap_b32_e32 v214, v215
	s_nop 0
	v_add_f32_e32 v214, v214, v215
	v_mov_b32_e32 v215, v214
	s_nop 1
	v_permlane32_swap_b32_e32 v214, v215
	s_nop 0
	v_add_f32_e32 v214, v214, v215
	v_fmamk_f32 v214, v214, 0x3c800000, v248
	v_rsq_f32_e32 v214, v214
	s_nop 0
	v_mul_f32_e32 v218, v155, v214
	v_pk_mul_f32 v[176:177], v[188:189], v[218:219] op_sel_hi:[1,0]
	v_pk_mul_f32 v[44:45], v[44:45], v[176:177]
	v_pk_mul_f32 v[176:177], v[190:191], v[218:219] op_sel_hi:[1,0]
	v_pk_mul_f32 v[46:47], v[46:47], v[176:177]
	v_pk_mul_f32 v[176:177], v[192:193], v[218:219] op_sel_hi:[1,0]
	v_pk_mul_f32 v[40:41], v[40:41], v[176:177]
	v_pk_mul_f32 v[176:177], v[194:195], v[218:219] op_sel_hi:[1,0]
	v_pk_mul_f32 v[42:43], v[42:43], v[176:177]
	v_cvt_pk_bf16_f32 v204, v44, v45
	v_cvt_pk_bf16_f32 v205, v46, v47
	v_cvt_pk_bf16_f32 v206, v40, v41
	v_cvt_pk_bf16_f32 v207, v42, v43
	global_store_dwordx4 v211, v[204:207], s[26:27]
	v_pk_mul_f32 v[176:177], v[196:197], v[218:219] op_sel_hi:[1,0]
	v_pk_mul_f32 v[36:37], v[36:37], v[176:177]
	v_pk_mul_f32 v[176:177], v[198:199], v[218:219] op_sel_hi:[1,0]
	v_pk_mul_f32 v[38:39], v[38:39], v[176:177]
	v_pk_mul_f32 v[176:177], v[200:201], v[218:219] op_sel_hi:[1,0]
	v_pk_mul_f32 v[32:33], v[32:33], v[176:177]
	v_pk_mul_f32 v[176:177], v[202:203], v[218:219] op_sel_hi:[1,0]
	v_pk_mul_f32 v[34:35], v[34:35], v[176:177]
	v_cvt_pk_bf16_f32 v144, v36, v37
	v_cvt_pk_bf16_f32 v145, v38, v39
	v_cvt_pk_bf16_f32 v146, v32, v33
	v_cvt_pk_bf16_f32 v147, v34, v35
	global_store_dwordx4 v211, v[144:147], s[26:27] offset:64
	v_add_u32_e32 v211, 0x10000, v211
	s_waitcnt vmcnt(13)
	v_pk_add_f32 v[180:181], v[180:181], v[182:183]
	s_nop 0
	v_add_f32_e32 v214, v180, v181
	v_mov_b32_e32 v215, v214
	s_nop 1
	v_permlane16_swap_b32_e32 v214, v215
	s_nop 0
	v_add_f32_e32 v214, v214, v215
	v_mov_b32_e32 v215, v214
	s_nop 1
	v_permlane32_swap_b32_e32 v214, v215
	s_nop 0
	v_add_f32_e32 v214, v214, v215
	v_fmamk_f32 v214, v214, 0x3a800000, v248
	v_rsq_f32_e32 v216, v214
	s_nop 0
	v_pk_mul_f32 v[28:29], v[28:29], v[216:217] op_sel_hi:[1,0]
	v_pk_mul_f32 v[30:31], v[30:31], v[216:217] op_sel_hi:[1,0]
	v_pk_mul_f32 v[24:25], v[24:25], v[216:217] op_sel_hi:[1,0]
	v_pk_mul_f32 v[26:27], v[26:27], v[216:217] op_sel_hi:[1,0]
	v_pk_mul_f32 v[20:21], v[20:21], v[216:217] op_sel_hi:[1,0]
	v_pk_mul_f32 v[22:23], v[22:23], v[216:217] op_sel_hi:[1,0]
	v_pk_mul_f32 v[16:17], v[16:17], v[216:217] op_sel_hi:[1,0]
	v_pk_mul_f32 v[18:19], v[18:19], v[216:217] op_sel_hi:[1,0]
	v_pk_mul_f32 v[148:149], v[28:29], v[28:29]
	v_pk_fma_f32 v[148:149], v[30:31], v[30:31], v[148:149]
	v_pk_fma_f32 v[148:149], v[24:25], v[24:25], v[148:149]
	v_pk_fma_f32 v[148:149], v[26:27], v[26:27], v[148:149]
	v_pk_fma_f32 v[148:149], v[20:21], v[20:21], v[148:149]
	v_pk_fma_f32 v[148:149], v[22:23], v[22:23], v[148:149]
	v_pk_fma_f32 v[148:149], v[16:17], v[16:17], v[148:149]
	v_pk_fma_f32 v[148:149], v[18:19], v[18:19], v[148:149]
	v_add_f32_e32 v214, v148, v149
	v_mov_b32_e32 v215, v214
	s_nop 1
	v_permlane16_swap_b32_e32 v214, v215
	s_nop 0
	v_add_f32_e32 v214, v214, v215
	v_mov_b32_e32 v215, v214
	s_nop 1
	v_permlane32_swap_b32_e32 v214, v215
	s_nop 0
	v_add_f32_e32 v214, v214, v215
	v_fmamk_f32 v214, v214, 0x3c800000, v248
	v_rsq_f32_e32 v214, v214
	s_nop 0
	v_mul_f32_e32 v218, v155, v214
	v_pk_mul_f32 v[180:181], v[188:189], v[218:219] op_sel_hi:[1,0]
	v_pk_mul_f32 v[28:29], v[28:29], v[180:181]
	v_pk_mul_f32 v[180:181], v[190:191], v[218:219] op_sel_hi:[1,0]
	v_pk_mul_f32 v[30:31], v[30:31], v[180:181]
	v_pk_mul_f32 v[180:181], v[192:193], v[218:219] op_sel_hi:[1,0]
	v_pk_mul_f32 v[24:25], v[24:25], v[180:181]
	v_pk_mul_f32 v[180:181], v[194:195], v[218:219] op_sel_hi:[1,0]
	v_pk_mul_f32 v[26:27], v[26:27], v[180:181]
	v_cvt_pk_bf16_f32 v204, v28, v29
	v_cvt_pk_bf16_f32 v205, v30, v31
	v_cvt_pk_bf16_f32 v206, v24, v25
	v_cvt_pk_bf16_f32 v207, v26, v27
	global_store_dwordx4 v211, v[204:207], s[26:27]
	v_pk_mul_f32 v[180:181], v[196:197], v[218:219] op_sel_hi:[1,0]
	v_pk_mul_f32 v[20:21], v[20:21], v[180:181]
	v_pk_mul_f32 v[180:181], v[198:199], v[218:219] op_sel_hi:[1,0]
	v_pk_mul_f32 v[22:23], v[22:23], v[180:181]
	v_pk_mul_f32 v[180:181], v[200:201], v[218:219] op_sel_hi:[1,0]
	v_pk_mul_f32 v[16:17], v[16:17], v[180:181]
	v_pk_mul_f32 v[180:181], v[202:203], v[218:219] op_sel_hi:[1,0]
	v_pk_mul_f32 v[18:19], v[18:19], v[180:181]
	v_cvt_pk_bf16_f32 v144, v20, v21
	v_cvt_pk_bf16_f32 v145, v22, v23
	v_cvt_pk_bf16_f32 v146, v16, v17
	v_cvt_pk_bf16_f32 v147, v18, v19
	global_store_dwordx4 v211, v[144:147], s[26:27] offset:64
	v_add_u32_e32 v211, 0x10000, v211
	s_waitcnt vmcnt(14)
	v_pk_add_f32 v[184:185], v[184:185], v[186:187]
	s_nop 0
	v_add_f32_e32 v214, v184, v185
	v_mov_b32_e32 v215, v214
	s_nop 1
	v_permlane16_swap_b32_e32 v214, v215
	s_nop 0
	v_add_f32_e32 v214, v214, v215
	v_mov_b32_e32 v215, v214
	s_nop 1
	v_permlane32_swap_b32_e32 v214, v215
	s_nop 0
	v_add_f32_e32 v214, v214, v215
	v_fmamk_f32 v214, v214, 0x3a800000, v248
	v_rsq_f32_e32 v216, v214
	s_nop 0
	v_pk_mul_f32 v[12:13], v[12:13], v[216:217] op_sel_hi:[1,0]
	v_pk_mul_f32 v[14:15], v[14:15], v[216:217] op_sel_hi:[1,0]
	v_pk_mul_f32 v[8:9], v[8:9], v[216:217] op_sel_hi:[1,0]
	v_pk_mul_f32 v[10:11], v[10:11], v[216:217] op_sel_hi:[1,0]
	v_pk_mul_f32 v[4:5], v[4:5], v[216:217] op_sel_hi:[1,0]
	v_pk_mul_f32 v[6:7], v[6:7], v[216:217] op_sel_hi:[1,0]
	v_pk_mul_f32 v[0:1], v[0:1], v[216:217] op_sel_hi:[1,0]
	v_pk_mul_f32 v[2:3], v[2:3], v[216:217] op_sel_hi:[1,0]
	v_pk_mul_f32 v[148:149], v[12:13], v[12:13]
	v_pk_fma_f32 v[148:149], v[14:15], v[14:15], v[148:149]
	v_pk_fma_f32 v[148:149], v[8:9], v[8:9], v[148:149]
	v_pk_fma_f32 v[148:149], v[10:11], v[10:11], v[148:149]
	v_pk_fma_f32 v[148:149], v[4:5], v[4:5], v[148:149]
	v_pk_fma_f32 v[148:149], v[6:7], v[6:7], v[148:149]
	v_pk_fma_f32 v[148:149], v[0:1], v[0:1], v[148:149]
	v_pk_fma_f32 v[148:149], v[2:3], v[2:3], v[148:149]
	v_add_f32_e32 v214, v148, v149
	v_mov_b32_e32 v215, v214
	s_nop 1
	v_permlane16_swap_b32_e32 v214, v215
	s_nop 0
	v_add_f32_e32 v214, v214, v215
	v_mov_b32_e32 v215, v214
	s_nop 1
	v_permlane32_swap_b32_e32 v214, v215
	s_nop 0
	v_add_f32_e32 v214, v214, v215
	v_fmamk_f32 v214, v214, 0x3c800000, v248
	v_rsq_f32_e32 v214, v214
	s_nop 0
	v_mul_f32_e32 v218, v155, v214
	v_pk_mul_f32 v[184:185], v[188:189], v[218:219] op_sel_hi:[1,0]
	v_pk_mul_f32 v[12:13], v[12:13], v[184:185]
	v_pk_mul_f32 v[184:185], v[190:191], v[218:219] op_sel_hi:[1,0]
	v_pk_mul_f32 v[14:15], v[14:15], v[184:185]
	v_pk_mul_f32 v[184:185], v[192:193], v[218:219] op_sel_hi:[1,0]
	v_pk_mul_f32 v[8:9], v[8:9], v[184:185]
	v_pk_mul_f32 v[184:185], v[194:195], v[218:219] op_sel_hi:[1,0]
	v_pk_mul_f32 v[10:11], v[10:11], v[184:185]
	v_cvt_pk_bf16_f32 v204, v12, v13
	v_cvt_pk_bf16_f32 v205, v14, v15
	v_cvt_pk_bf16_f32 v206, v8, v9
	v_cvt_pk_bf16_f32 v207, v10, v11
	global_store_dwordx4 v211, v[204:207], s[26:27]
	v_pk_mul_f32 v[184:185], v[196:197], v[218:219] op_sel_hi:[1,0]
	v_pk_mul_f32 v[4:5], v[4:5], v[184:185]
	v_pk_mul_f32 v[184:185], v[198:199], v[218:219] op_sel_hi:[1,0]
	v_pk_mul_f32 v[6:7], v[6:7], v[184:185]
	v_pk_mul_f32 v[184:185], v[200:201], v[218:219] op_sel_hi:[1,0]
	v_pk_mul_f32 v[0:1], v[0:1], v[184:185]
	v_pk_mul_f32 v[184:185], v[202:203], v[218:219] op_sel_hi:[1,0]
	v_pk_mul_f32 v[2:3], v[2:3], v[184:185]
	v_cvt_pk_bf16_f32 v144, v4, v5
	v_cvt_pk_bf16_f32 v145, v6, v7
	v_cvt_pk_bf16_f32 v146, v0, v1
	v_cvt_pk_bf16_f32 v147, v2, v3
	global_store_dwordx4 v211, v[144:147], s[26:27] offset:64
	s_and_b64 vcc, exec, s[4:5]
	s_mov_b64 s[26:27], s[22:23]
	s_cbranch_vccz .LBB0_691
	s_waitcnt vmcnt(0)
	s_cmpk_gt_u32 s54, 0xff
	s_cbranch_scc1 .LBB0_702
	s_barrier

.LBB0_714:
	s_add_u32 s26, s6, 0xfffc0080
	s_addc_u32 s27, s7, -1
	s_add_i32 s63, 0, 0x10000
	v_add_u32_e32 v140, s63, v165
	ds_read_b128 v[128:131], v140
	ds_read_b128 v[132:135], v140 offset:1024
	ds_read_b128 v[136:139], v140 offset:2048
	ds_read_b128 v[140:143], v140 offset:3072
	s_cmp_eq_u32 s51, 12
	s_cselect_b32 s29, s21, s27
	s_cselect_b32 s28, s38, s26
	s_cselect_b32 s27, s11, s50
	s_cselect_b32 s26, s39, s46
	s_add_i32 m0, s56, 0xc000
	ds_read_b128 v[154:157], v167
	ds_read_b128 v[158:161], v167 offset:1024
	ds_read_b128 v[168:171], v167 offset:2048
	ds_read_b128 v[172:175], v167 offset:3072
	ds_read_b128 v[176:179], v167 offset:4096
	ds_read_b128 v[180:183], v167 offset:5120
	ds_read_b128 v[184:187], v167 offset:6144
	ds_read_b128 v[188:191], v167 offset:7168
	global_load_lds_dwordx4 v150, s[6:7]
	s_add_i32 m0, s56, 0xe000
	s_nop 0
	global_load_lds_dwordx4 v152, s[6:7]
	s_waitcnt lgkmcnt(8)
	s_barrier
	s_waitcnt lgkmcnt(0)
	v_mfma_f32_16x16x32_bf16 v[124:127], v[128:131], v[154:157], v[124:127]
	v_mfma_f32_16x16x32_bf16 v[120:123], v[136:139], v[154:157], v[120:123]
	v_mfma_f32_16x16x32_bf16 v[116:119], v[128:131], v[168:171], v[116:119]
	v_mfma_f32_16x16x32_bf16 v[112:115], v[136:139], v[168:171], v[112:115]
	v_mfma_f32_16x16x32_bf16 v[108:111], v[128:131], v[176:179], v[108:111]
	v_mfma_f32_16x16x32_bf16 v[104:107], v[136:139], v[176:179], v[104:107]
	v_mfma_f32_16x16x32_bf16 v[100:103], v[128:131], v[184:187], v[100:103]
	v_mfma_f32_16x16x32_bf16 v[96:99], v[136:139], v[184:187], v[96:99]
	v_mfma_f32_16x16x32_bf16 v[124:127], v[132:135], v[158:161], v[124:127]
	v_mfma_f32_16x16x32_bf16 v[120:123], v[140:143], v[158:161], v[120:123]
	v_mfma_f32_16x16x32_bf16 v[116:119], v[132:135], v[172:175], v[116:119]
	v_mfma_f32_16x16x32_bf16 v[112:115], v[140:143], v[172:175], v[112:115]
	v_mfma_f32_16x16x32_bf16 v[108:111], v[132:135], v[180:183], v[108:111]
	v_mfma_f32_16x16x32_bf16 v[104:107], v[140:143], v[180:183], v[104:107]
	v_mfma_f32_16x16x32_bf16 v[100:103], v[132:135], v[188:191], v[100:103]
	v_mfma_f32_16x16x32_bf16 v[96:99], v[140:143], v[188:191], v[96:99]
	s_barrier
	s_add_i32 s66, 0, 0x14000
	v_add_u32_e32 v162, s66, v165
	s_add_i32 s63, s63, s55
	ds_read_b128 v[192:195], v162
	ds_read_b128 v[196:199], v162 offset:1024
	ds_read_b128 v[200:203], v162 offset:2048
	ds_read_b128 v[204:207], v162 offset:3072
	s_add_u32 s98, s26, s40
	s_addc_u32 s99, s27, s41
	s_mov_b32 m0, s63
	s_nop 0
	global_load_lds_dwordx4 v208, s[26:27]
	s_add_i32 m0, s63, 0x2000
	s_nop 0
	global_load_lds_dwordx4 v144, s[26:27]
	s_barrier
	s_waitcnt lgkmcnt(0)
	v_mfma_f32_16x16x32_bf16 v[60:63], v[192:195], v[154:157], v[60:63]
	v_mfma_f32_16x16x32_bf16 v[56:59], v[200:203], v[154:157], v[56:59]
	v_mfma_f32_16x16x32_bf16 v[52:55], v[192:195], v[168:171], v[52:55]
	v_mfma_f32_16x16x32_bf16 v[48:51], v[200:203], v[168:171], v[48:51]
	v_mfma_f32_16x16x32_bf16 v[44:47], v[192:195], v[176:179], v[44:47]
	v_mfma_f32_16x16x32_bf16 v[40:43], v[200:203], v[176:179], v[40:43]
	v_mfma_f32_16x16x32_bf16 v[36:39], v[192:195], v[184:187], v[36:39]
	v_mfma_f32_16x16x32_bf16 v[32:35], v[200:203], v[184:187], v[32:35]
	v_mfma_f32_16x16x32_bf16 v[60:63], v[196:199], v[158:161], v[60:63]
	v_mfma_f32_16x16x32_bf16 v[56:59], v[204:207], v[158:161], v[56:59]
	v_mfma_f32_16x16x32_bf16 v[52:55], v[196:199], v[172:175], v[52:55]
	v_mfma_f32_16x16x32_bf16 v[48:51], v[204:207], v[172:175], v[48:51]
	v_mfma_f32_16x16x32_bf16 v[44:47], v[196:199], v[180:183], v[44:47]
	v_mfma_f32_16x16x32_bf16 v[40:43], v[204:207], v[180:183], v[40:43]
	v_mfma_f32_16x16x32_bf16 v[36:39], v[196:199], v[188:191], v[36:39]
	v_mfma_f32_16x16x32_bf16 v[32:35], v[204:207], v[188:191], v[32:35]
	s_mov_b32 m0, s56
	s_add_u32 s100, s28, s40
	s_addc_u32 s101, s29, s41
	s_barrier
	ds_read_b128 v[154:157], v167 offset:16384
	ds_read_b128 v[158:161], v167 offset:17408
	ds_read_b128 v[168:171], v167 offset:18432
	ds_read_b128 v[172:175], v167 offset:19456
	ds_read_b128 v[176:179], v167 offset:20480
	ds_read_b128 v[180:183], v167 offset:21504
	ds_read_b128 v[184:187], v167 offset:22528
	ds_read_b128 v[188:191], v167 offset:23552
	global_load_lds_dwordx4 v148, s[28:29]
	s_mov_b32 m0, s57
	s_nop 0
	global_load_lds_dwordx4 v146, s[28:29]
	s_barrier
	s_waitcnt lgkmcnt(0)
	v_mfma_f32_16x16x32_bf16 v[92:95], v[128:131], v[154:157], v[92:95]
	v_mfma_f32_16x16x32_bf16 v[88:91], v[136:139], v[154:157], v[88:91]
	v_mfma_f32_16x16x32_bf16 v[84:87], v[128:131], v[168:171], v[84:87]
	v_mfma_f32_16x16x32_bf16 v[80:83], v[136:139], v[168:171], v[80:83]
	v_mfma_f32_16x16x32_bf16 v[76:79], v[128:131], v[176:179], v[76:79]
	v_mfma_f32_16x16x32_bf16 v[72:75], v[136:139], v[176:179], v[72:75]
	v_mfma_f32_16x16x32_bf16 v[68:71], v[128:131], v[184:187], v[68:71]
	v_mfma_f32_16x16x32_bf16 v[64:67], v[136:139], v[184:187], v[64:67]
	v_mfma_f32_16x16x32_bf16 v[92:95], v[132:135], v[158:161], v[92:95]
	v_mfma_f32_16x16x32_bf16 v[88:91], v[140:143], v[158:161], v[88:91]
	v_mfma_f32_16x16x32_bf16 v[84:87], v[132:135], v[172:175], v[84:87]
	v_mfma_f32_16x16x32_bf16 v[80:83], v[140:143], v[172:175], v[80:83]
	v_mfma_f32_16x16x32_bf16 v[76:79], v[132:135], v[180:183], v[76:79]
	v_mfma_f32_16x16x32_bf16 v[72:75], v[140:143], v[180:183], v[72:75]
	v_mfma_f32_16x16x32_bf16 v[68:71], v[132:135], v[188:191], v[68:71]
	v_mfma_f32_16x16x32_bf16 v[64:67], v[140:143], v[188:191], v[64:67]
	s_barrier
	s_add_u32 s64, s26, 0x40000
	s_addc_u32 s65, s27, 0
	s_add_i32 s63, s66, s55
	s_mov_b32 m0, s63
	s_nop 0
	global_load_lds_dwordx4 v208, s[64:65]
	s_add_i32 m0, s63, 0x2000
	s_nop 0
	global_load_lds_dwordx4 v144, s[64:65]
	s_waitcnt vmcnt(6)
	s_barrier
	v_mfma_f32_16x16x32_bf16 v[28:31], v[192:195], v[154:157], v[28:31]
	v_mfma_f32_16x16x32_bf16 v[24:27], v[200:203], v[154:157], v[24:27]
	v_mfma_f32_16x16x32_bf16 v[20:23], v[192:195], v[168:171], v[20:23]
	v_mfma_f32_16x16x32_bf16 v[16:19], v[200:203], v[168:171], v[16:19]
	v_mfma_f32_16x16x32_bf16 v[12:15], v[192:195], v[176:179], v[12:15]
	v_mfma_f32_16x16x32_bf16 v[8:11], v[200:203], v[176:179], v[8:11]
	v_mfma_f32_16x16x32_bf16 v[4:7], v[192:195], v[184:187], v[4:7]
	v_mfma_f32_16x16x32_bf16 v[0:3], v[200:203], v[184:187], v[0:3]
	v_mfma_f32_16x16x32_bf16 v[28:31], v[196:199], v[158:161], v[28:31]
	v_mfma_f32_16x16x32_bf16 v[24:27], v[204:207], v[158:161], v[24:27]
	v_mfma_f32_16x16x32_bf16 v[20:23], v[196:199], v[172:175], v[20:23]
	v_mfma_f32_16x16x32_bf16 v[16:19], v[204:207], v[172:175], v[16:19]
	v_mfma_f32_16x16x32_bf16 v[12:15], v[196:199], v[180:183], v[12:15]
	v_mfma_f32_16x16x32_bf16 v[8:11], v[204:207], v[180:183], v[8:11]
	v_mfma_f32_16x16x32_bf16 v[4:7], v[196:199], v[188:191], v[4:7]
	v_mfma_f32_16x16x32_bf16 v[0:3], v[204:207], v[188:191], v[0:3]
	s_add_i32 s63, 0, 0x18000
	v_add_u32_e32 v140, s63, v165
	s_barrier
	ds_read_b128 v[128:131], v140
	ds_read_b128 v[132:135], v140 offset:1024
	ds_read_b128 v[136:139], v140 offset:2048
	ds_read_b128 v[140:143], v140 offset:3072
	s_add_u32 s28, s28, 0x40000
	s_addc_u32 s29, s29, 0
	s_mov_b32 m0, s58
	ds_read_b128 v[154:157], v167 offset:32768
	ds_read_b128 v[158:161], v167 offset:33792
	ds_read_b128 v[168:171], v167 offset:34816
	ds_read_b128 v[172:175], v167 offset:35840
	ds_read_b128 v[176:179], v167 offset:36864
	ds_read_b128 v[180:183], v167 offset:37888
	ds_read_b128 v[184:187], v167 offset:38912
	ds_read_b128 v[188:191], v167 offset:39936
	global_load_lds_dwordx4 v148, s[28:29]
	s_mov_b32 m0, s59
	s_nop 0
	global_load_lds_dwordx4 v146, s[28:29]
	s_waitcnt lgkmcnt(8)
	s_barrier
	s_waitcnt lgkmcnt(0)
	v_mfma_f32_16x16x32_bf16 v[124:127], v[128:131], v[154:157], v[124:127]
	v_mfma_f32_16x16x32_bf16 v[120:123], v[136:139], v[154:157], v[120:123]
	v_mfma_f32_16x16x32_bf16 v[116:119], v[128:131], v[168:171], v[116:119]
	v_mfma_f32_16x16x32_bf16 v[112:115], v[136:139], v[168:171], v[112:115]
	v_mfma_f32_16x16x32_bf16 v[108:111], v[128:131], v[176:179], v[108:111]
	v_mfma_f32_16x16x32_bf16 v[104:107], v[136:139], v[176:179], v[104:107]
	v_mfma_f32_16x16x32_bf16 v[100:103], v[128:131], v[184:187], v[100:103]
	v_mfma_f32_16x16x32_bf16 v[96:99], v[136:139], v[184:187], v[96:99]
	v_mfma_f32_16x16x32_bf16 v[124:127], v[132:135], v[158:161], v[124:127]
	v_mfma_f32_16x16x32_bf16 v[120:123], v[140:143], v[158:161], v[120:123]
	v_mfma_f32_16x16x32_bf16 v[116:119], v[132:135], v[172:175], v[116:119]
	v_mfma_f32_16x16x32_bf16 v[112:115], v[140:143], v[172:175], v[112:115]
	v_mfma_f32_16x16x32_bf16 v[108:111], v[132:135], v[180:183], v[108:111]
	v_mfma_f32_16x16x32_bf16 v[104:107], v[140:143], v[180:183], v[104:107]
	v_mfma_f32_16x16x32_bf16 v[100:103], v[132:135], v[188:191], v[100:103]
	v_mfma_f32_16x16x32_bf16 v[96:99], v[140:143], v[188:191], v[96:99]
	s_barrier
	s_add_i32 s28, 0, 0x1c000
	s_add_i32 s29, s63, s55
	v_add_u32_e32 v204, s28, v165
	s_mov_b32 m0, s29
	ds_read_b128 v[192:195], v204
	ds_read_b128 v[196:199], v204 offset:1024
	ds_read_b128 v[200:203], v204 offset:2048
	ds_read_b128 v[204:207], v204 offset:3072
	global_load_lds_dwordx4 v208, s[98:99]
	s_add_i32 m0, s29, 0x2000
	s_nop 0
	global_load_lds_dwordx4 v144, s[98:99]
	s_barrier
	s_waitcnt lgkmcnt(0)
	v_mfma_f32_16x16x32_bf16 v[60:63], v[192:195], v[154:157], v[60:63]
	v_mfma_f32_16x16x32_bf16 v[56:59], v[200:203], v[154:157], v[56:59]
	v_mfma_f32_16x16x32_bf16 v[52:55], v[192:195], v[168:171], v[52:55]
	v_mfma_f32_16x16x32_bf16 v[48:51], v[200:203], v[168:171], v[48:51]
	v_mfma_f32_16x16x32_bf16 v[44:47], v[192:195], v[176:179], v[44:47]
	v_mfma_f32_16x16x32_bf16 v[40:43], v[200:203], v[176:179], v[40:43]
	v_mfma_f32_16x16x32_bf16 v[36:39], v[192:195], v[184:187], v[36:39]
	v_mfma_f32_16x16x32_bf16 v[32:35], v[200:203], v[184:187], v[32:35]
	v_mfma_f32_16x16x32_bf16 v[60:63], v[196:199], v[158:161], v[60:63]
	v_mfma_f32_16x16x32_bf16 v[56:59], v[204:207], v[158:161], v[56:59]
	v_mfma_f32_16x16x32_bf16 v[52:55], v[196:199], v[172:175], v[52:55]
	v_mfma_f32_16x16x32_bf16 v[48:51], v[204:207], v[172:175], v[48:51]
	v_mfma_f32_16x16x32_bf16 v[44:47], v[196:199], v[180:183], v[44:47]
	v_mfma_f32_16x16x32_bf16 v[40:43], v[204:207], v[180:183], v[40:43]
	v_mfma_f32_16x16x32_bf16 v[36:39], v[196:199], v[188:191], v[36:39]
	v_mfma_f32_16x16x32_bf16 v[32:35], v[204:207], v[188:191], v[32:35]
	s_mov_b32 m0, s60
	s_barrier
	ds_read_b128 v[154:157], v167 offset:49152
	ds_read_b128 v[158:161], v167 offset:50176
	ds_read_b128 v[168:171], v167 offset:51200
	ds_read_b128 v[172:175], v167 offset:52224
	ds_read_b128 v[176:179], v167 offset:53248
	ds_read_b128 v[180:183], v167 offset:54272
	ds_read_b128 v[184:187], v167 offset:55296
	ds_read_b128 v[188:191], v167 offset:56320
	global_load_lds_dwordx4 v148, s[100:101]
	s_mov_b32 m0, s61
	s_nop 0
	global_load_lds_dwordx4 v146, s[100:101]
	s_barrier
	s_waitcnt lgkmcnt(0)
	v_mfma_f32_16x16x32_bf16 v[92:95], v[128:131], v[154:157], v[92:95]
	v_mfma_f32_16x16x32_bf16 v[88:91], v[136:139], v[154:157], v[88:91]
	v_mfma_f32_16x16x32_bf16 v[84:87], v[128:131], v[168:171], v[84:87]
	v_mfma_f32_16x16x32_bf16 v[80:83], v[136:139], v[168:171], v[80:83]
	v_mfma_f32_16x16x32_bf16 v[76:79], v[128:131], v[176:179], v[76:79]
	v_mfma_f32_16x16x32_bf16 v[72:75], v[136:139], v[176:179], v[72:75]
	v_mfma_f32_16x16x32_bf16 v[68:71], v[128:131], v[184:187], v[68:71]
	v_mfma_f32_16x16x32_bf16 v[64:67], v[136:139], v[184:187], v[64:67]
	v_mfma_f32_16x16x32_bf16 v[92:95], v[132:135], v[158:161], v[92:95]
	v_mfma_f32_16x16x32_bf16 v[88:91], v[140:143], v[158:161], v[88:91]
	v_mfma_f32_16x16x32_bf16 v[84:87], v[132:135], v[172:175], v[84:87]
	v_mfma_f32_16x16x32_bf16 v[80:83], v[140:143], v[172:175], v[80:83]
	v_mfma_f32_16x16x32_bf16 v[76:79], v[132:135], v[180:183], v[76:79]
	v_mfma_f32_16x16x32_bf16 v[72:75], v[140:143], v[180:183], v[72:75]
	v_mfma_f32_16x16x32_bf16 v[68:71], v[132:135], v[188:191], v[68:71]
	v_mfma_f32_16x16x32_bf16 v[64:67], v[140:143], v[188:191], v[64:67]
	s_barrier
	s_add_u32 s26, s26, 0x40080
	s_addc_u32 s27, s27, 0
	s_add_i32 s28, s28, s55
	s_mov_b32 m0, s28
	s_nop 0
	global_load_lds_dwordx4 v208, s[26:27]
	s_add_i32 m0, s28, 0x2000
	s_nop 0
	global_load_lds_dwordx4 v144, s[26:27]
	s_waitcnt vmcnt(6)
	s_barrier
	v_mfma_f32_16x16x32_bf16 v[28:31], v[192:195], v[154:157], v[28:31]
	v_mfma_f32_16x16x32_bf16 v[24:27], v[200:203], v[154:157], v[24:27]
	v_mfma_f32_16x16x32_bf16 v[20:23], v[192:195], v[168:171], v[20:23]
	v_mfma_f32_16x16x32_bf16 v[16:19], v[200:203], v[168:171], v[16:19]
	v_mfma_f32_16x16x32_bf16 v[12:15], v[192:195], v[176:179], v[12:15]
	v_mfma_f32_16x16x32_bf16 v[8:11], v[200:203], v[176:179], v[8:11]
	v_mfma_f32_16x16x32_bf16 v[4:7], v[192:195], v[184:187], v[4:7]
	v_mfma_f32_16x16x32_bf16 v[0:3], v[200:203], v[184:187], v[0:3]
	v_mfma_f32_16x16x32_bf16 v[28:31], v[196:199], v[158:161], v[28:31]
	v_mfma_f32_16x16x32_bf16 v[24:27], v[204:207], v[158:161], v[24:27]
	v_mfma_f32_16x16x32_bf16 v[20:23], v[196:199], v[172:175], v[20:23]
	v_mfma_f32_16x16x32_bf16 v[16:19], v[204:207], v[172:175], v[16:19]
	v_mfma_f32_16x16x32_bf16 v[12:15], v[196:199], v[180:183], v[12:15]
	v_mfma_f32_16x16x32_bf16 v[8:11], v[204:207], v[180:183], v[8:11]
	v_mfma_f32_16x16x32_bf16 v[4:7], v[196:199], v[188:191], v[4:7]
	v_mfma_f32_16x16x32_bf16 v[0:3], v[204:207], v[188:191], v[0:3]
	s_add_i32 s51, s51, 2
	s_add_u32 s6, s6, 0x100
	s_addc_u32 s7, s7, 0
	s_add_u32 s46, s46, 0x100
	s_addc_u32 s50, s50, 0
	s_cmp_gt_u32 s51, 13
	s_barrier
	s_cbranch_scc0 .LBB0_714
	v_lshl_or_b32 v158, s34, 8, v166
	v_lshl_add_u32 v159, s35, 8, v164
	s_mov_b32 s34, s10
	s_mov_b32 s35, s20
	s_mov_b64 s[26:27], s[24:25]
	v_mbcnt_lo_u32_b32 v160, -1, 0
	v_mbcnt_hi_u32_b32 v160, -1, v160
	v_and_b32_e32 v157, 7, v160
	v_and_b32_e32 v160, 8, v160
	v_add_u32_e32 v157, v158, v157
	v_lshlrev_b32_e32 v157, 6, v157
	v_lshl_add_u32 v157, v160, 2, v157
	v_add_u32_e32 v161, 0x2000, v157
	global_load_dwordx4 v[128:131], v157, s[18:19]
	global_load_dwordx4 v[132:135], v157, s[18:19] offset:16
	global_load_dwordx4 v[136:139], v161, s[18:19]
	global_load_dwordx4 v[140:143], v161, s[18:19] offset:16
	v_mov_b32_e32 v155, 0x358637bd
	v_lshlrev_b32_e32 v156, 17, v159
	v_lshl_add_u32 v156, v158, 1, v156
	s_waitcnt vmcnt(0)
	v_pk_add_f32 v[128:129], v[128:129], v[130:131]
	v_pk_add_f32 v[132:133], v[132:133], v[134:135]
	v_pk_add_f32 v[128:129], v[128:129], v[132:133]
	s_nop 0
	v_add_f32_e32 v154, v128, v129
	s_nop 1
	v_add_f32_dpp v154, v154, v154 row_ror:8 row_mask:0xf bank_mask:0xf
	s_nop 0
	v_fmamk_f32 v154, v154, 0x3a800000, v155
	v_rsq_f32_e32 v154, v154
	s_nop 1
	v_mov_b32_dpp v168, v154 row_newbcast:0 row_mask:0xf bank_mask:0xf
	v_mov_b32_dpp v169, v154 row_newbcast:1 row_mask:0xf bank_mask:0xf
	v_mov_b32_dpp v170, v154 row_newbcast:2 row_mask:0xf bank_mask:0xf
	v_mov_b32_dpp v171, v154 row_newbcast:3 row_mask:0xf bank_mask:0xf
	v_mov_b32_dpp v172, v154 row_newbcast:4 row_mask:0xf bank_mask:0xf
	v_mov_b32_dpp v173, v154 row_newbcast:5 row_mask:0xf bank_mask:0xf
	v_mov_b32_dpp v174, v154 row_newbcast:6 row_mask:0xf bank_mask:0xf
	v_mov_b32_dpp v175, v154 row_newbcast:7 row_mask:0xf bank_mask:0xf
	v_pk_add_f32 v[136:137], v[136:137], v[138:139]
	v_pk_add_f32 v[140:141], v[140:141], v[142:143]
	v_pk_add_f32 v[136:137], v[136:137], v[140:141]
	s_nop 0
	v_add_f32_e32 v154, v136, v137
	s_nop 1
	v_add_f32_dpp v154, v154, v154 row_ror:8 row_mask:0xf bank_mask:0xf
	s_nop 0
	v_fmamk_f32 v154, v154, 0x3a800000, v155
	v_rsq_f32_e32 v154, v154
	s_nop 1
	v_mov_b32_dpp v176, v154 row_newbcast:0 row_mask:0xf bank_mask:0xf
	v_mov_b32_dpp v177, v154 row_newbcast:1 row_mask:0xf bank_mask:0xf
	v_mov_b32_dpp v178, v154 row_newbcast:2 row_mask:0xf bank_mask:0xf
	v_mov_b32_dpp v179, v154 row_newbcast:3 row_mask:0xf bank_mask:0xf
	v_mov_b32_dpp v180, v154 row_newbcast:4 row_mask:0xf bank_mask:0xf
	v_mov_b32_dpp v181, v154 row_newbcast:5 row_mask:0xf bank_mask:0xf
	v_mov_b32_dpp v182, v154 row_newbcast:6 row_mask:0xf bank_mask:0xf
	v_mov_b32_dpp v183, v154 row_newbcast:7 row_mask:0xf bank_mask:0xf
	v_pk_mul_f32 v[124:125], v[124:125], v[168:169]
	v_pk_mul_f32 v[126:127], v[126:127], v[170:171]
	v_pk_mul_f32 v[120:121], v[120:121], v[172:173]
	v_pk_mul_f32 v[122:123], v[122:123], v[174:175]
	v_cvt_pk_bf16_f32 v184, v124, v125
	v_cvt_pk_bf16_f32 v185, v126, v127
	v_cvt_pk_bf16_f32 v186, v120, v121
	v_cvt_pk_bf16_f32 v187, v122, v123
	global_store_dwordx4 v156, v[184:187], s[8:9]
	v_pk_mul_f32 v[60:61], v[60:61], v[176:177]
	v_pk_mul_f32 v[62:63], v[62:63], v[178:179]
	v_pk_mul_f32 v[56:57], v[56:57], v[180:181]
	v_pk_mul_f32 v[58:59], v[58:59], v[182:183]
	v_cvt_pk_bf16_f32 v188, v60, v61
	v_cvt_pk_bf16_f32 v189, v62, v63
	v_cvt_pk_bf16_f32 v190, v56, v57
	v_cvt_pk_bf16_f32 v191, v58, v59
	global_store_dwordx4 v156, v[188:191], s[8:9] offset:256
	v_add_u32_e32 v156, 0x200000, v156
	v_pk_mul_f32 v[116:117], v[116:117], v[168:169]
	v_pk_mul_f32 v[118:119], v[118:119], v[170:171]
	v_pk_mul_f32 v[112:113], v[112:113], v[172:173]
	v_pk_mul_f32 v[114:115], v[114:115], v[174:175]
	v_cvt_pk_bf16_f32 v184, v116, v117
	v_cvt_pk_bf16_f32 v185, v118, v119
	v_cvt_pk_bf16_f32 v186, v112, v113
	v_cvt_pk_bf16_f32 v187, v114, v115
	global_store_dwordx4 v156, v[184:187], s[8:9]
	v_pk_mul_f32 v[52:53], v[52:53], v[176:177]
	v_pk_mul_f32 v[54:55], v[54:55], v[178:179]
	v_pk_mul_f32 v[48:49], v[48:49], v[180:181]
	v_pk_mul_f32 v[50:51], v[50:51], v[182:183]
	v_cvt_pk_bf16_f32 v188, v52, v53
	v_cvt_pk_bf16_f32 v189, v54, v55
	v_cvt_pk_bf16_f32 v190, v48, v49
	v_cvt_pk_bf16_f32 v191, v50, v51
	global_store_dwordx4 v156, v[188:191], s[8:9] offset:256
	v_add_u32_e32 v156, 0x200000, v156
	v_pk_mul_f32 v[108:109], v[108:109], v[168:169]
	v_pk_mul_f32 v[110:111], v[110:111], v[170:171]
	v_pk_mul_f32 v[104:105], v[104:105], v[172:173]
	v_pk_mul_f32 v[106:107], v[106:107], v[174:175]
	v_cvt_pk_bf16_f32 v184, v108, v109
	v_cvt_pk_bf16_f32 v185, v110, v111
	v_cvt_pk_bf16_f32 v186, v104, v105
	v_cvt_pk_bf16_f32 v187, v106, v107
	global_store_dwordx4 v156, v[184:187], s[8:9]
	v_pk_mul_f32 v[44:45], v[44:45], v[176:177]
	v_pk_mul_f32 v[46:47], v[46:47], v[178:179]
	v_pk_mul_f32 v[40:41], v[40:41], v[180:181]
	v_pk_mul_f32 v[42:43], v[42:43], v[182:183]
	v_cvt_pk_bf16_f32 v188, v44, v45
	v_cvt_pk_bf16_f32 v189, v46, v47
	v_cvt_pk_bf16_f32 v190, v40, v41
	v_cvt_pk_bf16_f32 v191, v42, v43
	global_store_dwordx4 v156, v[188:191], s[8:9] offset:256
	v_add_u32_e32 v156, 0x200000, v156
	v_pk_mul_f32 v[100:101], v[100:101], v[168:169]
	v_pk_mul_f32 v[102:103], v[102:103], v[170:171]
	v_pk_mul_f32 v[96:97], v[96:97], v[172:173]
	v_pk_mul_f32 v[98:99], v[98:99], v[174:175]
	v_cvt_pk_bf16_f32 v184, v100, v101
	v_cvt_pk_bf16_f32 v185, v102, v103
	v_cvt_pk_bf16_f32 v186, v96, v97
	v_cvt_pk_bf16_f32 v187, v98, v99
	global_store_dwordx4 v156, v[184:187], s[8:9]
	v_pk_mul_f32 v[36:37], v[36:37], v[176:177]
	v_pk_mul_f32 v[38:39], v[38:39], v[178:179]
	v_pk_mul_f32 v[32:33], v[32:33], v[180:181]
	v_pk_mul_f32 v[34:35], v[34:35], v[182:183]
	v_cvt_pk_bf16_f32 v188, v36, v37
	v_cvt_pk_bf16_f32 v189, v38, v39
	v_cvt_pk_bf16_f32 v190, v32, v33
	v_cvt_pk_bf16_f32 v191, v34, v35
	global_store_dwordx4 v156, v[188:191], s[8:9] offset:256
	v_add_u32_e32 v156, 0xa00000, v156
	v_pk_mul_f32 v[92:93], v[92:93], v[168:169]
	v_pk_mul_f32 v[94:95], v[94:95], v[170:171]
	v_pk_mul_f32 v[88:89], v[88:89], v[172:173]
	v_pk_mul_f32 v[90:91], v[90:91], v[174:175]
	v_cvt_pk_bf16_f32 v184, v92, v93
	v_cvt_pk_bf16_f32 v185, v94, v95
	v_cvt_pk_bf16_f32 v186, v88, v89
	v_cvt_pk_bf16_f32 v187, v90, v91
	global_store_dwordx4 v156, v[184:187], s[8:9]
	v_pk_mul_f32 v[28:29], v[28:29], v[176:177]
	v_pk_mul_f32 v[30:31], v[30:31], v[178:179]
	v_pk_mul_f32 v[24:25], v[24:25], v[180:181]
	v_pk_mul_f32 v[26:27], v[26:27], v[182:183]
	v_cvt_pk_bf16_f32 v188, v28, v29
	v_cvt_pk_bf16_f32 v189, v30, v31
	v_cvt_pk_bf16_f32 v190, v24, v25
	v_cvt_pk_bf16_f32 v191, v26, v27
	global_store_dwordx4 v156, v[188:191], s[8:9] offset:256
	v_add_u32_e32 v156, 0x200000, v156
	v_pk_mul_f32 v[84:85], v[84:85], v[168:169]
	v_pk_mul_f32 v[86:87], v[86:87], v[170:171]
	v_pk_mul_f32 v[80:81], v[80:81], v[172:173]
	v_pk_mul_f32 v[82:83], v[82:83], v[174:175]
	v_cvt_pk_bf16_f32 v184, v84, v85
	v_cvt_pk_bf16_f32 v185, v86, v87
	v_cvt_pk_bf16_f32 v186, v80, v81
	v_cvt_pk_bf16_f32 v187, v82, v83
	global_store_dwordx4 v156, v[184:187], s[8:9]
	v_pk_mul_f32 v[20:21], v[20:21], v[176:177]
	v_pk_mul_f32 v[22:23], v[22:23], v[178:179]
	v_pk_mul_f32 v[16:17], v[16:17], v[180:181]
	v_pk_mul_f32 v[18:19], v[18:19], v[182:183]
	v_cvt_pk_bf16_f32 v188, v20, v21
	v_cvt_pk_bf16_f32 v189, v22, v23
	v_cvt_pk_bf16_f32 v190, v16, v17
	v_cvt_pk_bf16_f32 v191, v18, v19
	global_store_dwordx4 v156, v[188:191], s[8:9] offset:256
	v_add_u32_e32 v156, 0x200000, v156
	v_pk_mul_f32 v[76:77], v[76:77], v[168:169]
	v_pk_mul_f32 v[78:79], v[78:79], v[170:171]
	v_pk_mul_f32 v[72:73], v[72:73], v[172:173]
	v_pk_mul_f32 v[74:75], v[74:75], v[174:175]
	v_cvt_pk_bf16_f32 v184, v76, v77
	v_cvt_pk_bf16_f32 v185, v78, v79
	v_cvt_pk_bf16_f32 v186, v72, v73
	v_cvt_pk_bf16_f32 v187, v74, v75
	global_store_dwordx4 v156, v[184:187], s[8:9]
	v_pk_mul_f32 v[12:13], v[12:13], v[176:177]
	v_pk_mul_f32 v[14:15], v[14:15], v[178:179]
	v_pk_mul_f32 v[8:9], v[8:9], v[180:181]
	v_pk_mul_f32 v[10:11], v[10:11], v[182:183]
	v_cvt_pk_bf16_f32 v188, v12, v13
	v_cvt_pk_bf16_f32 v189, v14, v15
	v_cvt_pk_bf16_f32 v190, v8, v9
	v_cvt_pk_bf16_f32 v191, v10, v11
	global_store_dwordx4 v156, v[188:191], s[8:9] offset:256
	v_add_u32_e32 v156, 0x200000, v156
	v_pk_mul_f32 v[68:69], v[68:69], v[168:169]
	v_pk_mul_f32 v[70:71], v[70:71], v[170:171]
	v_pk_mul_f32 v[64:65], v[64:65], v[172:173]
	v_pk_mul_f32 v[66:67], v[66:67], v[174:175]
	v_cvt_pk_bf16_f32 v184, v68, v69
	v_cvt_pk_bf16_f32 v185, v70, v71
	v_cvt_pk_bf16_f32 v186, v64, v65
	v_cvt_pk_bf16_f32 v187, v66, v67
	global_store_dwordx4 v156, v[184:187], s[8:9]
	v_pk_mul_f32 v[4:5], v[4:5], v[176:177]
	v_pk_mul_f32 v[6:7], v[6:7], v[178:179]
	v_pk_mul_f32 v[0:1], v[0:1], v[180:181]
	v_pk_mul_f32 v[2:3], v[2:3], v[182:183]
	v_cvt_pk_bf16_f32 v188, v4, v5
	v_cvt_pk_bf16_f32 v189, v6, v7
	v_cvt_pk_bf16_f32 v190, v0, v1
	v_cvt_pk_bf16_f32 v191, v2, v3
	global_store_dwordx4 v156, v[188:191], s[8:9] offset:256
	s_mov_b64 s[6:7], s[22:23]
	s_and_b64 vcc, exec, s[4:5]
	s_cbranch_vccz .LBB0_707
	s_waitcnt vmcnt(0)
	s_cmpk_gt_u32 s30, 0xff
	s_cbranch_scc1 .LBB0_718
	s_barrier

.LBB0_776:
	s_add_u32 s28, s26, 0xfffc0080
	s_addc_u32 s29, s27, -1
	s_add_i32 s66, 0, 0x10000
	v_add_u32_e32 v154, s66, v143
	ds_read_b128 v[138:141], v154
	ds_read_b128 v[146:149], v154 offset:1024
	ds_read_b128 v[150:153], v154 offset:2048
	ds_read_b128 v[154:157], v154 offset:3072
	s_cmp_eq_u32 s65, 12
	s_cselect_b32 s31, s21, s29
	s_cselect_b32 s30, s39, s28
	s_cselect_b32 s29, s19, s64
	s_cselect_b32 s28, s62, s63
	s_add_i32 m0, s54, 0xc000
	ds_read_b128 v[158:161], v145
	ds_read_b128 v[162:165], v145 offset:1024
	ds_read_b128 v[166:169], v145 offset:2048
	ds_read_b128 v[170:173], v145 offset:3072
	ds_read_b128 v[174:177], v145 offset:4096
	ds_read_b128 v[178:181], v145 offset:5120
	ds_read_b128 v[182:185], v145 offset:6144
	ds_read_b128 v[186:189], v145 offset:7168
	global_load_lds_dwordx4 v134, s[26:27]
	s_add_i32 m0, s54, 0xe000
	s_nop 0
	global_load_lds_dwordx4 v136, s[26:27]
	s_waitcnt lgkmcnt(8)
	s_barrier
	s_waitcnt lgkmcnt(0)
	v_mfma_f32_16x16x32_bf16 v[124:127], v[138:141], v[158:161], v[124:127]
	v_mfma_f32_16x16x32_bf16 v[120:123], v[150:153], v[158:161], v[120:123]
	v_mfma_f32_16x16x32_bf16 v[108:111], v[138:141], v[166:169], v[108:111]
	v_mfma_f32_16x16x32_bf16 v[104:107], v[150:153], v[166:169], v[104:107]
	v_mfma_f32_16x16x32_bf16 v[92:95], v[138:141], v[174:177], v[92:95]
	v_mfma_f32_16x16x32_bf16 v[88:91], v[150:153], v[174:177], v[88:91]
	v_mfma_f32_16x16x32_bf16 v[76:79], v[138:141], v[182:185], v[76:79]
	v_mfma_f32_16x16x32_bf16 v[72:75], v[150:153], v[182:185], v[72:75]
	v_mfma_f32_16x16x32_bf16 v[124:127], v[146:149], v[162:165], v[124:127]
	v_mfma_f32_16x16x32_bf16 v[120:123], v[154:157], v[162:165], v[120:123]
	v_mfma_f32_16x16x32_bf16 v[108:111], v[146:149], v[170:173], v[108:111]
	v_mfma_f32_16x16x32_bf16 v[104:107], v[154:157], v[170:173], v[104:107]
	v_mfma_f32_16x16x32_bf16 v[92:95], v[146:149], v[178:181], v[92:95]
	v_mfma_f32_16x16x32_bf16 v[88:91], v[154:157], v[178:181], v[88:91]
	v_mfma_f32_16x16x32_bf16 v[76:79], v[146:149], v[186:189], v[76:79]
	v_mfma_f32_16x16x32_bf16 v[72:75], v[154:157], v[186:189], v[72:75]
	s_barrier
	s_add_i32 s68, 0, 0x14000
	s_add_i32 s66, s66, s53
	v_add_u32_e32 v202, s68, v143
	s_add_u32 s98, s28, s40
	s_addc_u32 s99, s29, s41
	s_mov_b32 m0, s66
	ds_read_b128 v[190:193], v202
	ds_read_b128 v[194:197], v202 offset:1024
	ds_read_b128 v[198:201], v202 offset:2048
	ds_read_b128 v[202:205], v202 offset:3072
	global_load_lds_dwordx4 v208, s[28:29]
	s_add_i32 m0, s66, 0x2000
	s_nop 0
	global_load_lds_dwordx4 v128, s[28:29]
	s_barrier
	s_waitcnt lgkmcnt(0)
	v_mfma_f32_16x16x32_bf16 v[116:119], v[190:193], v[158:161], v[116:119]
	v_mfma_f32_16x16x32_bf16 v[112:115], v[198:201], v[158:161], v[112:115]
	v_mfma_f32_16x16x32_bf16 v[100:103], v[190:193], v[166:169], v[100:103]
	v_mfma_f32_16x16x32_bf16 v[96:99], v[198:201], v[166:169], v[96:99]
	v_mfma_f32_16x16x32_bf16 v[84:87], v[190:193], v[174:177], v[84:87]
	v_mfma_f32_16x16x32_bf16 v[80:83], v[198:201], v[174:177], v[80:83]
	v_mfma_f32_16x16x32_bf16 v[68:71], v[190:193], v[182:185], v[68:71]
	v_mfma_f32_16x16x32_bf16 v[64:67], v[198:201], v[182:185], v[64:67]
	v_mfma_f32_16x16x32_bf16 v[116:119], v[194:197], v[162:165], v[116:119]
	v_mfma_f32_16x16x32_bf16 v[112:115], v[202:205], v[162:165], v[112:115]
	v_mfma_f32_16x16x32_bf16 v[100:103], v[194:197], v[170:173], v[100:103]
	v_mfma_f32_16x16x32_bf16 v[96:99], v[202:205], v[170:173], v[96:99]
	v_mfma_f32_16x16x32_bf16 v[84:87], v[194:197], v[178:181], v[84:87]
	v_mfma_f32_16x16x32_bf16 v[80:83], v[202:205], v[178:181], v[80:83]
	v_mfma_f32_16x16x32_bf16 v[68:71], v[194:197], v[186:189], v[68:71]
	v_mfma_f32_16x16x32_bf16 v[64:67], v[202:205], v[186:189], v[64:67]
	s_mov_b32 m0, s54
	s_add_u32 s100, s30, s40
	s_addc_u32 s101, s31, s41
	s_barrier
	ds_read_b128 v[158:161], v145 offset:16384
	ds_read_b128 v[162:165], v145 offset:17408
	ds_read_b128 v[166:169], v145 offset:18432
	ds_read_b128 v[170:173], v145 offset:19456
	ds_read_b128 v[174:177], v145 offset:20480
	ds_read_b128 v[178:181], v145 offset:21504
	ds_read_b128 v[182:185], v145 offset:22528
	ds_read_b128 v[186:189], v145 offset:23552
	global_load_lds_dwordx4 v132, s[30:31]
	s_mov_b32 m0, s55
	s_nop 0
	global_load_lds_dwordx4 v130, s[30:31]
	s_barrier
	s_waitcnt lgkmcnt(0)
	v_mfma_f32_16x16x32_bf16 v[60:63], v[138:141], v[158:161], v[60:63]
	v_mfma_f32_16x16x32_bf16 v[56:59], v[150:153], v[158:161], v[56:59]
	v_mfma_f32_16x16x32_bf16 v[44:47], v[138:141], v[166:169], v[44:47]
	v_mfma_f32_16x16x32_bf16 v[40:43], v[150:153], v[166:169], v[40:43]
	v_mfma_f32_16x16x32_bf16 v[28:31], v[138:141], v[174:177], v[28:31]
	v_mfma_f32_16x16x32_bf16 v[24:27], v[150:153], v[174:177], v[24:27]
	v_mfma_f32_16x16x32_bf16 v[12:15], v[138:141], v[182:185], v[12:15]
	v_mfma_f32_16x16x32_bf16 v[8:11], v[150:153], v[182:185], v[8:11]
	v_mfma_f32_16x16x32_bf16 v[60:63], v[146:149], v[162:165], v[60:63]
	v_mfma_f32_16x16x32_bf16 v[56:59], v[154:157], v[162:165], v[56:59]
	v_mfma_f32_16x16x32_bf16 v[44:47], v[146:149], v[170:173], v[44:47]
	v_mfma_f32_16x16x32_bf16 v[40:43], v[154:157], v[170:173], v[40:43]
	v_mfma_f32_16x16x32_bf16 v[28:31], v[146:149], v[178:181], v[28:31]
	v_mfma_f32_16x16x32_bf16 v[24:27], v[154:157], v[178:181], v[24:27]
	v_mfma_f32_16x16x32_bf16 v[12:15], v[146:149], v[186:189], v[12:15]
	v_mfma_f32_16x16x32_bf16 v[8:11], v[154:157], v[186:189], v[8:11]
	s_barrier
	s_add_u32 s66, s28, 0x40000
	s_addc_u32 s67, s29, 0
	s_add_i32 s68, s68, s53
	s_mov_b32 m0, s68
	s_nop 0
	global_load_lds_dwordx4 v208, s[66:67]
	s_add_i32 m0, s68, 0x2000
	s_nop 0
	global_load_lds_dwordx4 v128, s[66:67]
	s_waitcnt vmcnt(6)
	s_barrier
	v_mfma_f32_16x16x32_bf16 v[52:55], v[190:193], v[158:161], v[52:55]
	v_mfma_f32_16x16x32_bf16 v[48:51], v[198:201], v[158:161], v[48:51]
	v_mfma_f32_16x16x32_bf16 v[36:39], v[190:193], v[166:169], v[36:39]
	v_mfma_f32_16x16x32_bf16 v[32:35], v[198:201], v[166:169], v[32:35]
	v_mfma_f32_16x16x32_bf16 v[20:23], v[190:193], v[174:177], v[20:23]
	v_mfma_f32_16x16x32_bf16 v[16:19], v[198:201], v[174:177], v[16:19]
	v_mfma_f32_16x16x32_bf16 v[4:7], v[190:193], v[182:185], v[4:7]
	v_mfma_f32_16x16x32_bf16 v[0:3], v[198:201], v[182:185], v[0:3]
	v_mfma_f32_16x16x32_bf16 v[52:55], v[194:197], v[162:165], v[52:55]
	v_mfma_f32_16x16x32_bf16 v[48:51], v[202:205], v[162:165], v[48:51]
	v_mfma_f32_16x16x32_bf16 v[36:39], v[194:197], v[170:173], v[36:39]
	v_mfma_f32_16x16x32_bf16 v[32:35], v[202:205], v[170:173], v[32:35]
	v_mfma_f32_16x16x32_bf16 v[20:23], v[194:197], v[178:181], v[20:23]
	v_mfma_f32_16x16x32_bf16 v[16:19], v[202:205], v[178:181], v[16:19]
	v_mfma_f32_16x16x32_bf16 v[4:7], v[194:197], v[186:189], v[4:7]
	v_mfma_f32_16x16x32_bf16 v[0:3], v[202:205], v[186:189], v[0:3]
	s_add_i32 s66, 0, 0x18000
	v_add_u32_e32 v154, s66, v143
	s_barrier
	ds_read_b128 v[138:141], v154
	ds_read_b128 v[146:149], v154 offset:1024
	ds_read_b128 v[150:153], v154 offset:2048
	ds_read_b128 v[154:157], v154 offset:3072
	s_add_u32 s30, s30, 0x40000
	s_addc_u32 s31, s31, 0
	s_mov_b32 m0, s56
	ds_read_b128 v[158:161], v145 offset:32768
	ds_read_b128 v[162:165], v145 offset:33792
	ds_read_b128 v[166:169], v145 offset:34816
	ds_read_b128 v[170:173], v145 offset:35840
	ds_read_b128 v[174:177], v145 offset:36864
	ds_read_b128 v[178:181], v145 offset:37888
	ds_read_b128 v[182:185], v145 offset:38912
	ds_read_b128 v[186:189], v145 offset:39936
	global_load_lds_dwordx4 v132, s[30:31]
	s_mov_b32 m0, s57
	s_nop 0
	global_load_lds_dwordx4 v130, s[30:31]
	s_waitcnt lgkmcnt(8)
	s_barrier
	s_waitcnt lgkmcnt(0)
	v_mfma_f32_16x16x32_bf16 v[124:127], v[138:141], v[158:161], v[124:127]
	v_mfma_f32_16x16x32_bf16 v[120:123], v[150:153], v[158:161], v[120:123]
	v_mfma_f32_16x16x32_bf16 v[108:111], v[138:141], v[166:169], v[108:111]
	v_mfma_f32_16x16x32_bf16 v[104:107], v[150:153], v[166:169], v[104:107]
	v_mfma_f32_16x16x32_bf16 v[92:95], v[138:141], v[174:177], v[92:95]
	v_mfma_f32_16x16x32_bf16 v[88:91], v[150:153], v[174:177], v[88:91]
	v_mfma_f32_16x16x32_bf16 v[76:79], v[138:141], v[182:185], v[76:79]
	v_mfma_f32_16x16x32_bf16 v[72:75], v[150:153], v[182:185], v[72:75]
	v_mfma_f32_16x16x32_bf16 v[124:127], v[146:149], v[162:165], v[124:127]
	v_mfma_f32_16x16x32_bf16 v[120:123], v[154:157], v[162:165], v[120:123]
	v_mfma_f32_16x16x32_bf16 v[108:111], v[146:149], v[170:173], v[108:111]
	v_mfma_f32_16x16x32_bf16 v[104:107], v[154:157], v[170:173], v[104:107]
	v_mfma_f32_16x16x32_bf16 v[92:95], v[146:149], v[178:181], v[92:95]
	v_mfma_f32_16x16x32_bf16 v[88:91], v[154:157], v[178:181], v[88:91]
	v_mfma_f32_16x16x32_bf16 v[76:79], v[146:149], v[186:189], v[76:79]
	v_mfma_f32_16x16x32_bf16 v[72:75], v[154:157], v[186:189], v[72:75]
	s_barrier
	s_add_i32 s30, 0, 0x1c000
	s_add_i32 s31, s66, s53
	v_add_u32_e32 v202, s30, v143
	s_mov_b32 m0, s31
	ds_read_b128 v[190:193], v202
	ds_read_b128 v[194:197], v202 offset:1024
	ds_read_b128 v[198:201], v202 offset:2048
	ds_read_b128 v[202:205], v202 offset:3072
	global_load_lds_dwordx4 v208, s[98:99]
	s_add_i32 m0, s31, 0x2000
	s_nop 0
	global_load_lds_dwordx4 v128, s[98:99]
	s_barrier
	s_waitcnt lgkmcnt(0)
	v_mfma_f32_16x16x32_bf16 v[116:119], v[190:193], v[158:161], v[116:119]
	v_mfma_f32_16x16x32_bf16 v[112:115], v[198:201], v[158:161], v[112:115]
	v_mfma_f32_16x16x32_bf16 v[100:103], v[190:193], v[166:169], v[100:103]
	v_mfma_f32_16x16x32_bf16 v[96:99], v[198:201], v[166:169], v[96:99]
	v_mfma_f32_16x16x32_bf16 v[84:87], v[190:193], v[174:177], v[84:87]
	v_mfma_f32_16x16x32_bf16 v[80:83], v[198:201], v[174:177], v[80:83]
	v_mfma_f32_16x16x32_bf16 v[68:71], v[190:193], v[182:185], v[68:71]
	v_mfma_f32_16x16x32_bf16 v[64:67], v[198:201], v[182:185], v[64:67]
	v_mfma_f32_16x16x32_bf16 v[116:119], v[194:197], v[162:165], v[116:119]
	v_mfma_f32_16x16x32_bf16 v[112:115], v[202:205], v[162:165], v[112:115]
	v_mfma_f32_16x16x32_bf16 v[100:103], v[194:197], v[170:173], v[100:103]
	v_mfma_f32_16x16x32_bf16 v[96:99], v[202:205], v[170:173], v[96:99]
	v_mfma_f32_16x16x32_bf16 v[84:87], v[194:197], v[178:181], v[84:87]
	v_mfma_f32_16x16x32_bf16 v[80:83], v[202:205], v[178:181], v[80:83]
	v_mfma_f32_16x16x32_bf16 v[68:71], v[194:197], v[186:189], v[68:71]
	v_mfma_f32_16x16x32_bf16 v[64:67], v[202:205], v[186:189], v[64:67]
	s_mov_b32 m0, s59
	s_barrier
	ds_read_b128 v[158:161], v145 offset:49152
	ds_read_b128 v[162:165], v145 offset:50176
	ds_read_b128 v[166:169], v145 offset:51200
	ds_read_b128 v[170:173], v145 offset:52224
	ds_read_b128 v[174:177], v145 offset:53248
	ds_read_b128 v[178:181], v145 offset:54272
	ds_read_b128 v[182:185], v145 offset:55296
	ds_read_b128 v[186:189], v145 offset:56320
	global_load_lds_dwordx4 v132, s[100:101]
	s_mov_b32 m0, s60
	s_nop 0
	global_load_lds_dwordx4 v130, s[100:101]
	s_barrier
	s_waitcnt lgkmcnt(0)
	v_mfma_f32_16x16x32_bf16 v[60:63], v[138:141], v[158:161], v[60:63]
	v_mfma_f32_16x16x32_bf16 v[56:59], v[150:153], v[158:161], v[56:59]
	v_mfma_f32_16x16x32_bf16 v[44:47], v[138:141], v[166:169], v[44:47]
	v_mfma_f32_16x16x32_bf16 v[40:43], v[150:153], v[166:169], v[40:43]
	v_mfma_f32_16x16x32_bf16 v[28:31], v[138:141], v[174:177], v[28:31]
	v_mfma_f32_16x16x32_bf16 v[24:27], v[150:153], v[174:177], v[24:27]
	v_mfma_f32_16x16x32_bf16 v[12:15], v[138:141], v[182:185], v[12:15]
	v_mfma_f32_16x16x32_bf16 v[8:11], v[150:153], v[182:185], v[8:11]
	v_mfma_f32_16x16x32_bf16 v[60:63], v[146:149], v[162:165], v[60:63]
	v_mfma_f32_16x16x32_bf16 v[56:59], v[154:157], v[162:165], v[56:59]
	v_mfma_f32_16x16x32_bf16 v[44:47], v[146:149], v[170:173], v[44:47]
	v_mfma_f32_16x16x32_bf16 v[40:43], v[154:157], v[170:173], v[40:43]
	v_mfma_f32_16x16x32_bf16 v[28:31], v[146:149], v[178:181], v[28:31]
	v_mfma_f32_16x16x32_bf16 v[24:27], v[154:157], v[178:181], v[24:27]
	v_mfma_f32_16x16x32_bf16 v[12:15], v[146:149], v[186:189], v[12:15]
	v_mfma_f32_16x16x32_bf16 v[8:11], v[154:157], v[186:189], v[8:11]
	s_barrier
	s_add_u32 s28, s28, 0x40080
	s_addc_u32 s29, s29, 0
	s_add_i32 s30, s30, s53
	s_mov_b32 m0, s30
	s_nop 0
	global_load_lds_dwordx4 v208, s[28:29]
	s_add_i32 m0, s30, 0x2000
	s_nop 0
	global_load_lds_dwordx4 v128, s[28:29]
	s_waitcnt vmcnt(6)
	s_barrier
	v_mfma_f32_16x16x32_bf16 v[52:55], v[190:193], v[158:161], v[52:55]
	v_mfma_f32_16x16x32_bf16 v[48:51], v[198:201], v[158:161], v[48:51]
	v_mfma_f32_16x16x32_bf16 v[36:39], v[190:193], v[166:169], v[36:39]
	v_mfma_f32_16x16x32_bf16 v[32:35], v[198:201], v[166:169], v[32:35]
	v_mfma_f32_16x16x32_bf16 v[20:23], v[190:193], v[174:177], v[20:23]
	v_mfma_f32_16x16x32_bf16 v[16:19], v[198:201], v[174:177], v[16:19]
	v_mfma_f32_16x16x32_bf16 v[4:7], v[190:193], v[182:185], v[4:7]
	v_mfma_f32_16x16x32_bf16 v[0:3], v[198:201], v[182:185], v[0:3]
	v_mfma_f32_16x16x32_bf16 v[52:55], v[194:197], v[162:165], v[52:55]
	v_mfma_f32_16x16x32_bf16 v[48:51], v[202:205], v[162:165], v[48:51]
	v_mfma_f32_16x16x32_bf16 v[36:39], v[194:197], v[170:173], v[36:39]
	v_mfma_f32_16x16x32_bf16 v[32:35], v[202:205], v[170:173], v[32:35]
	v_mfma_f32_16x16x32_bf16 v[20:23], v[194:197], v[178:181], v[20:23]
	v_mfma_f32_16x16x32_bf16 v[16:19], v[202:205], v[178:181], v[16:19]
	v_mfma_f32_16x16x32_bf16 v[4:7], v[194:197], v[186:189], v[4:7]
	v_mfma_f32_16x16x32_bf16 v[0:3], v[202:205], v[186:189], v[0:3]
	s_add_i32 s65, s65, 2
	s_add_u32 s26, s26, 0x100
	s_addc_u32 s27, s27, 0
	s_add_u32 s63, s63, 0x100
	s_addc_u32 s64, s64, 0
	s_cmp_gt_u32 s65, 13
	s_barrier
	s_cbranch_scc0 .LBB0_776
	v_lshl_add_u32 v140, s38, 8, v142
	v_lshl_or_b32 v141, s36, 8, v144
	s_lshl_b32 s26, s36, 2
	s_ashr_i32 s27, s26, 31
	s_lshl_b32 s36, s58, 2
	v_lshlrev_b32_e32 v206, 11, v140
	v_lshl_add_u32 v206, v141, 1, v206
	v_lshl_add_u32 v210, v140, 6, s36
	v_lshl_add_u32 v210, s26, 2, v210
	v_mov_b32_e32 v207, v206
	global_load_dwordx4 v[146:149], v206, s[10:11]
	global_load_dwordx4 v[150:153], v206, s[10:11] offset:256
	v_add_u32_e32 v206, 0x8000, v206
	global_load_dwordx4 v[154:157], v206, s[10:11]
	global_load_dwordx4 v[158:161], v206, s[10:11] offset:256
	v_add_u32_e32 v206, 0x8000, v206
	global_load_dwordx4 v[162:165], v206, s[10:11]
	global_load_dwordx4 v[166:169], v206, s[10:11] offset:256
	v_add_u32_e32 v206, 0x8000, v206
	global_load_dwordx4 v[170:173], v206, s[10:11]
	global_load_dwordx4 v[174:177], v206, s[10:11] offset:256
	v_add_u32_e32 v206, 0x28000, v206
	global_load_dwordx4 v[178:181], v206, s[10:11]
	global_load_dwordx4 v[182:185], v206, s[10:11] offset:256
	v_add_u32_e32 v206, 0x8000, v206
	global_load_dwordx4 v[186:189], v206, s[10:11]
	global_load_dwordx4 v[190:193], v206, s[10:11] offset:256
	v_add_u32_e32 v206, 0x8000, v206
	global_load_dwordx4 v[194:197], v206, s[10:11]
	global_load_dwordx4 v[198:201], v206, s[10:11] offset:256
	v_add_u32_e32 v206, 0x8000, v206
	s_waitcnt vmcnt(12)
	v_lshlrev_b32_e32 v202, 16, v146
	v_and_b32_e32 v203, 0xffff0000, v146
	v_lshlrev_b32_e32 v204, 16, v147
	v_and_b32_e32 v205, 0xffff0000, v147
	v_pk_add_f32 v[124:125], v[124:125], v[202:203]
	v_pk_add_f32 v[126:127], v[126:127], v[204:205]
	v_lshlrev_b32_e32 v202, 16, v148
	v_and_b32_e32 v203, 0xffff0000, v148
	v_lshlrev_b32_e32 v204, 16, v149
	v_and_b32_e32 v205, 0xffff0000, v149
	v_pk_add_f32 v[120:121], v[120:121], v[202:203]
	v_pk_add_f32 v[122:123], v[122:123], v[204:205]
	v_cvt_pk_bf16_f32 v146, v124, v125
	v_cvt_pk_bf16_f32 v147, v126, v127
	v_cvt_pk_bf16_f32 v148, v120, v121
	v_cvt_pk_bf16_f32 v149, v122, v123
	v_pk_mul_f32 v[138:139], v[124:125], v[124:125]
	global_store_dwordx4 v207, v[146:149], s[10:11]
	v_pk_fma_f32 v[138:139], v[126:127], v[126:127], v[138:139]
	v_pk_fma_f32 v[138:139], v[120:121], v[120:121], v[138:139]
	v_pk_fma_f32 v[138:139], v[122:123], v[122:123], v[138:139]
	v_lshlrev_b32_e32 v202, 16, v150
	v_and_b32_e32 v203, 0xffff0000, v150
	v_lshlrev_b32_e32 v204, 16, v151
	v_and_b32_e32 v205, 0xffff0000, v151
	v_pk_add_f32 v[116:117], v[116:117], v[202:203]
	v_pk_add_f32 v[118:119], v[118:119], v[204:205]
	v_lshlrev_b32_e32 v202, 16, v152
	v_and_b32_e32 v203, 0xffff0000, v152
	v_lshlrev_b32_e32 v204, 16, v153
	v_and_b32_e32 v205, 0xffff0000, v153
	v_pk_add_f32 v[112:113], v[112:113], v[202:203]
	v_pk_add_f32 v[114:115], v[114:115], v[204:205]
	v_cvt_pk_bf16_f32 v150, v116, v117
	v_cvt_pk_bf16_f32 v151, v118, v119
	v_cvt_pk_bf16_f32 v152, v112, v113
	v_cvt_pk_bf16_f32 v153, v114, v115
	v_pk_fma_f32 v[138:139], v[116:117], v[116:117], v[138:139]
	global_store_dwordx4 v207, v[150:153], s[10:11] offset:256
	v_pk_fma_f32 v[138:139], v[118:119], v[118:119], v[138:139]
	v_pk_fma_f32 v[138:139], v[112:113], v[112:113], v[138:139]
	v_pk_fma_f32 v[138:139], v[114:115], v[114:115], v[138:139]
	v_add_f32_e32 v214, v138, v139
	v_add_u32_e32 v207, 0x8000, v207
	v_mov_b32_e32 v215, v214
	s_nop 1
	v_permlane16_swap_b32_e32 v214, v215
	s_nop 0
	v_add_f32_e32 v214, v214, v215
	v_mov_b32_e32 v215, v214
	s_nop 1
	v_permlane32_swap_b32_e32 v214, v215
	s_nop 0
	v_add_f32_e32 v214, v214, v215
	s_and_saveexec_b64 s[28:29], s[4:5]
	global_store_dword v210, v214, s[16:17]
	s_mov_b64 exec, s[28:29]
	global_load_dwordx4 v[146:149], v206, s[10:11]
	global_load_dwordx4 v[150:153], v206, s[10:11] offset:256
	s_waitcnt vmcnt(15)
	v_lshlrev_b32_e32 v202, 16, v154
	v_and_b32_e32 v203, 0xffff0000, v154
	v_lshlrev_b32_e32 v204, 16, v155
	v_and_b32_e32 v205, 0xffff0000, v155
	v_pk_add_f32 v[108:109], v[108:109], v[202:203]
	v_pk_add_f32 v[110:111], v[110:111], v[204:205]
	v_lshlrev_b32_e32 v202, 16, v156
	v_and_b32_e32 v203, 0xffff0000, v156
	v_lshlrev_b32_e32 v204, 16, v157
	v_and_b32_e32 v205, 0xffff0000, v157
	v_pk_add_f32 v[104:105], v[104:105], v[202:203]
	v_pk_add_f32 v[106:107], v[106:107], v[204:205]
	v_cvt_pk_bf16_f32 v154, v108, v109
	v_cvt_pk_bf16_f32 v155, v110, v111
	v_cvt_pk_bf16_f32 v156, v104, v105
	v_cvt_pk_bf16_f32 v157, v106, v107
	v_pk_mul_f32 v[138:139], v[108:109], v[108:109]
	global_store_dwordx4 v207, v[154:157], s[10:11]
	v_pk_fma_f32 v[138:139], v[110:111], v[110:111], v[138:139]
	v_pk_fma_f32 v[138:139], v[104:105], v[104:105], v[138:139]
	v_pk_fma_f32 v[138:139], v[106:107], v[106:107], v[138:139]
	v_lshlrev_b32_e32 v202, 16, v158
	v_and_b32_e32 v203, 0xffff0000, v158
	v_lshlrev_b32_e32 v204, 16, v159
	v_and_b32_e32 v205, 0xffff0000, v159
	v_pk_add_f32 v[100:101], v[100:101], v[202:203]
	v_pk_add_f32 v[102:103], v[102:103], v[204:205]
	v_lshlrev_b32_e32 v202, 16, v160
	v_and_b32_e32 v203, 0xffff0000, v160
	v_lshlrev_b32_e32 v204, 16, v161
	v_and_b32_e32 v205, 0xffff0000, v161
	v_pk_add_f32 v[96:97], v[96:97], v[202:203]
	v_pk_add_f32 v[98:99], v[98:99], v[204:205]
	v_cvt_pk_bf16_f32 v158, v100, v101
	v_cvt_pk_bf16_f32 v159, v102, v103
	v_cvt_pk_bf16_f32 v160, v96, v97
	v_cvt_pk_bf16_f32 v161, v98, v99
	v_pk_fma_f32 v[138:139], v[100:101], v[100:101], v[138:139]
	global_store_dwordx4 v207, v[158:161], s[10:11] offset:256
	v_pk_fma_f32 v[138:139], v[102:103], v[102:103], v[138:139]
	v_pk_fma_f32 v[138:139], v[96:97], v[96:97], v[138:139]
	v_pk_fma_f32 v[138:139], v[98:99], v[98:99], v[138:139]
	v_add_f32_e32 v214, v138, v139
	v_add_u32_e32 v207, 0x8000, v207
	v_mov_b32_e32 v215, v214
	s_nop 1
	v_permlane16_swap_b32_e32 v214, v215
	s_nop 0
	v_add_f32_e32 v214, v214, v215
	v_mov_b32_e32 v215, v214
	s_nop 1
	v_permlane32_swap_b32_e32 v214, v215
	s_nop 0
	v_add_f32_e32 v214, v214, v215
	s_and_saveexec_b64 s[28:29], s[4:5]
	global_store_dword v210, v214, s[16:17] offset:1024
	s_mov_b64 exec, s[28:29]
	s_waitcnt vmcnt(16)
	v_lshlrev_b32_e32 v202, 16, v162
	v_and_b32_e32 v203, 0xffff0000, v162
	v_lshlrev_b32_e32 v204, 16, v163
	v_and_b32_e32 v205, 0xffff0000, v163
	v_pk_add_f32 v[92:93], v[92:93], v[202:203]
	v_pk_add_f32 v[94:95], v[94:95], v[204:205]
	v_lshlrev_b32_e32 v202, 16, v164
	v_and_b32_e32 v203, 0xffff0000, v164
	v_lshlrev_b32_e32 v204, 16, v165
	v_and_b32_e32 v205, 0xffff0000, v165
	v_pk_add_f32 v[88:89], v[88:89], v[202:203]
	v_pk_add_f32 v[90:91], v[90:91], v[204:205]
	v_cvt_pk_bf16_f32 v162, v92, v93
	v_cvt_pk_bf16_f32 v163, v94, v95
	v_cvt_pk_bf16_f32 v164, v88, v89
	v_cvt_pk_bf16_f32 v165, v90, v91
	v_pk_mul_f32 v[138:139], v[92:93], v[92:93]
	global_store_dwordx4 v207, v[162:165], s[10:11]
	v_pk_fma_f32 v[138:139], v[94:95], v[94:95], v[138:139]
	v_pk_fma_f32 v[138:139], v[88:89], v[88:89], v[138:139]
	v_pk_fma_f32 v[138:139], v[90:91], v[90:91], v[138:139]
	v_lshlrev_b32_e32 v202, 16, v166
	v_and_b32_e32 v203, 0xffff0000, v166
	v_lshlrev_b32_e32 v204, 16, v167
	v_and_b32_e32 v205, 0xffff0000, v167
	v_pk_add_f32 v[84:85], v[84:85], v[202:203]
	v_pk_add_f32 v[86:87], v[86:87], v[204:205]
	v_lshlrev_b32_e32 v202, 16, v168
	v_and_b32_e32 v203, 0xffff0000, v168
	v_lshlrev_b32_e32 v204, 16, v169
	v_and_b32_e32 v205, 0xffff0000, v169
	v_pk_add_f32 v[80:81], v[80:81], v[202:203]
	v_pk_add_f32 v[82:83], v[82:83], v[204:205]
	v_cvt_pk_bf16_f32 v166, v84, v85
	v_cvt_pk_bf16_f32 v167, v86, v87
	v_cvt_pk_bf16_f32 v168, v80, v81
	v_cvt_pk_bf16_f32 v169, v82, v83
	v_pk_fma_f32 v[138:139], v[84:85], v[84:85], v[138:139]
	global_store_dwordx4 v207, v[166:169], s[10:11] offset:256
	v_pk_fma_f32 v[138:139], v[86:87], v[86:87], v[138:139]
	v_pk_fma_f32 v[138:139], v[80:81], v[80:81], v[138:139]
	v_pk_fma_f32 v[138:139], v[82:83], v[82:83], v[138:139]
	v_add_f32_e32 v214, v138, v139
	v_add_u32_e32 v207, 0x8000, v207
	v_mov_b32_e32 v215, v214
	s_nop 1
	v_permlane16_swap_b32_e32 v214, v215
	s_nop 0
	v_add_f32_e32 v214, v214, v215
	v_mov_b32_e32 v215, v214
	s_nop 1
	v_permlane32_swap_b32_e32 v214, v215
	s_nop 0
	v_add_f32_e32 v214, v214, v215
	s_and_saveexec_b64 s[28:29], s[4:5]
	global_store_dword v210, v214, s[16:17] offset:2048
	s_mov_b64 exec, s[28:29]
	s_waitcnt vmcnt(17)
	v_lshlrev_b32_e32 v202, 16, v170
	v_and_b32_e32 v203, 0xffff0000, v170
	v_lshlrev_b32_e32 v204, 16, v171
	v_and_b32_e32 v205, 0xffff0000, v171
	v_pk_add_f32 v[76:77], v[76:77], v[202:203]
	v_pk_add_f32 v[78:79], v[78:79], v[204:205]
	v_lshlrev_b32_e32 v202, 16, v172
	v_and_b32_e32 v203, 0xffff0000, v172
	v_lshlrev_b32_e32 v204, 16, v173
	v_and_b32_e32 v205, 0xffff0000, v173
	v_pk_add_f32 v[72:73], v[72:73], v[202:203]
	v_pk_add_f32 v[74:75], v[74:75], v[204:205]
	v_cvt_pk_bf16_f32 v170, v76, v77
	v_cvt_pk_bf16_f32 v171, v78, v79
	v_cvt_pk_bf16_f32 v172, v72, v73
	v_cvt_pk_bf16_f32 v173, v74, v75
	v_pk_mul_f32 v[138:139], v[76:77], v[76:77]
	global_store_dwordx4 v207, v[170:173], s[10:11]
	v_pk_fma_f32 v[138:139], v[78:79], v[78:79], v[138:139]
	v_pk_fma_f32 v[138:139], v[72:73], v[72:73], v[138:139]
	v_pk_fma_f32 v[138:139], v[74:75], v[74:75], v[138:139]
	v_lshlrev_b32_e32 v202, 16, v174
	v_and_b32_e32 v203, 0xffff0000, v174
	v_lshlrev_b32_e32 v204, 16, v175
	v_and_b32_e32 v205, 0xffff0000, v175
	v_pk_add_f32 v[68:69], v[68:69], v[202:203]
	v_pk_add_f32 v[70:71], v[70:71], v[204:205]
	v_lshlrev_b32_e32 v202, 16, v176
	v_and_b32_e32 v203, 0xffff0000, v176
	v_lshlrev_b32_e32 v204, 16, v177
	v_and_b32_e32 v205, 0xffff0000, v177
	v_pk_add_f32 v[64:65], v[64:65], v[202:203]
	v_pk_add_f32 v[66:67], v[66:67], v[204:205]
	v_cvt_pk_bf16_f32 v174, v68, v69
	v_cvt_pk_bf16_f32 v175, v70, v71
	v_cvt_pk_bf16_f32 v176, v64, v65
	v_cvt_pk_bf16_f32 v177, v66, v67
	v_pk_fma_f32 v[138:139], v[68:69], v[68:69], v[138:139]
	global_store_dwordx4 v207, v[174:177], s[10:11] offset:256
	v_pk_fma_f32 v[138:139], v[70:71], v[70:71], v[138:139]
	v_pk_fma_f32 v[138:139], v[64:65], v[64:65], v[138:139]
	v_pk_fma_f32 v[138:139], v[66:67], v[66:67], v[138:139]
	v_add_f32_e32 v214, v138, v139
	v_add_u32_e32 v207, 0x28000, v207
	v_mov_b32_e32 v215, v214
	s_nop 1
	v_permlane16_swap_b32_e32 v214, v215
	s_nop 0
	v_add_f32_e32 v214, v214, v215
	v_mov_b32_e32 v215, v214
	s_nop 1
	v_permlane32_swap_b32_e32 v214, v215
	s_nop 0
	v_add_f32_e32 v214, v214, v215
	s_and_saveexec_b64 s[28:29], s[4:5]
	global_store_dword v210, v214, s[16:17] offset:3072
	s_mov_b64 exec, s[28:29]
	v_add_u32_e32 v210, 0x2000, v210
	s_waitcnt vmcnt(18)
	v_lshlrev_b32_e32 v202, 16, v178
	v_and_b32_e32 v203, 0xffff0000, v178
	v_lshlrev_b32_e32 v204, 16, v179
	v_and_b32_e32 v205, 0xffff0000, v179
	v_pk_add_f32 v[60:61], v[60:61], v[202:203]
	v_pk_add_f32 v[62:63], v[62:63], v[204:205]
	v_lshlrev_b32_e32 v202, 16, v180
	v_and_b32_e32 v203, 0xffff0000, v180
	v_lshlrev_b32_e32 v204, 16, v181
	v_and_b32_e32 v205, 0xffff0000, v181
	v_pk_add_f32 v[56:57], v[56:57], v[202:203]
	v_pk_add_f32 v[58:59], v[58:59], v[204:205]
	v_cvt_pk_bf16_f32 v178, v60, v61
	v_cvt_pk_bf16_f32 v179, v62, v63
	v_cvt_pk_bf16_f32 v180, v56, v57
	v_cvt_pk_bf16_f32 v181, v58, v59
	v_pk_mul_f32 v[138:139], v[60:61], v[60:61]
	global_store_dwordx4 v207, v[178:181], s[10:11]
	v_pk_fma_f32 v[138:139], v[62:63], v[62:63], v[138:139]
	v_pk_fma_f32 v[138:139], v[56:57], v[56:57], v[138:139]
	v_pk_fma_f32 v[138:139], v[58:59], v[58:59], v[138:139]
	v_lshlrev_b32_e32 v202, 16, v182
	v_and_b32_e32 v203, 0xffff0000, v182
	v_lshlrev_b32_e32 v204, 16, v183
	v_and_b32_e32 v205, 0xffff0000, v183
	v_pk_add_f32 v[52:53], v[52:53], v[202:203]
	v_pk_add_f32 v[54:55], v[54:55], v[204:205]
	v_lshlrev_b32_e32 v202, 16, v184
	v_and_b32_e32 v203, 0xffff0000, v184
	v_lshlrev_b32_e32 v204, 16, v185
	v_and_b32_e32 v205, 0xffff0000, v185
	v_pk_add_f32 v[48:49], v[48:49], v[202:203]
	v_pk_add_f32 v[50:51], v[50:51], v[204:205]
	v_cvt_pk_bf16_f32 v182, v52, v53
	v_cvt_pk_bf16_f32 v183, v54, v55
	v_cvt_pk_bf16_f32 v184, v48, v49
	v_cvt_pk_bf16_f32 v185, v50, v51
	v_pk_fma_f32 v[138:139], v[52:53], v[52:53], v[138:139]
	global_store_dwordx4 v207, v[182:185], s[10:11] offset:256
	v_pk_fma_f32 v[138:139], v[54:55], v[54:55], v[138:139]
	v_pk_fma_f32 v[138:139], v[48:49], v[48:49], v[138:139]
	v_pk_fma_f32 v[138:139], v[50:51], v[50:51], v[138:139]
	v_add_f32_e32 v214, v138, v139
	v_add_u32_e32 v207, 0x8000, v207
	v_mov_b32_e32 v215, v214
	s_nop 1
	v_permlane16_swap_b32_e32 v214, v215
	s_nop 0
	v_add_f32_e32 v214, v214, v215
	v_mov_b32_e32 v215, v214
	s_nop 1
	v_permlane32_swap_b32_e32 v214, v215
	s_nop 0
	v_add_f32_e32 v214, v214, v215
	s_and_saveexec_b64 s[28:29], s[4:5]
	global_store_dword v210, v214, s[16:17]
	s_mov_b64 exec, s[28:29]
	s_waitcnt vmcnt(19)
	v_lshlrev_b32_e32 v202, 16, v186
	v_and_b32_e32 v203, 0xffff0000, v186
	v_lshlrev_b32_e32 v204, 16, v187
	v_and_b32_e32 v205, 0xffff0000, v187
	v_pk_add_f32 v[44:45], v[44:45], v[202:203]
	v_pk_add_f32 v[46:47], v[46:47], v[204:205]
	v_lshlrev_b32_e32 v202, 16, v188
	v_and_b32_e32 v203, 0xffff0000, v188
	v_lshlrev_b32_e32 v204, 16, v189
	v_and_b32_e32 v205, 0xffff0000, v189
	v_pk_add_f32 v[40:41], v[40:41], v[202:203]
	v_pk_add_f32 v[42:43], v[42:43], v[204:205]
	v_cvt_pk_bf16_f32 v186, v44, v45
	v_cvt_pk_bf16_f32 v187, v46, v47
	v_cvt_pk_bf16_f32 v188, v40, v41
	v_cvt_pk_bf16_f32 v189, v42, v43
	v_pk_mul_f32 v[138:139], v[44:45], v[44:45]
	global_store_dwordx4 v207, v[186:189], s[10:11]
	v_pk_fma_f32 v[138:139], v[46:47], v[46:47], v[138:139]
	v_pk_fma_f32 v[138:139], v[40:41], v[40:41], v[138:139]
	v_pk_fma_f32 v[138:139], v[42:43], v[42:43], v[138:139]
	v_lshlrev_b32_e32 v202, 16, v190
	v_and_b32_e32 v203, 0xffff0000, v190
	v_lshlrev_b32_e32 v204, 16, v191
	v_and_b32_e32 v205, 0xffff0000, v191
	v_pk_add_f32 v[36:37], v[36:37], v[202:203]
	v_pk_add_f32 v[38:39], v[38:39], v[204:205]
	v_lshlrev_b32_e32 v202, 16, v192
	v_and_b32_e32 v203, 0xffff0000, v192
	v_lshlrev_b32_e32 v204, 16, v193
	v_and_b32_e32 v205, 0xffff0000, v193
	v_pk_add_f32 v[32:33], v[32:33], v[202:203]
	v_pk_add_f32 v[34:35], v[34:35], v[204:205]
	v_cvt_pk_bf16_f32 v190, v36, v37
	v_cvt_pk_bf16_f32 v191, v38, v39
	v_cvt_pk_bf16_f32 v192, v32, v33
	v_cvt_pk_bf16_f32 v193, v34, v35
	v_pk_fma_f32 v[138:139], v[36:37], v[36:37], v[138:139]
	global_store_dwordx4 v207, v[190:193], s[10:11] offset:256
	v_pk_fma_f32 v[138:139], v[38:39], v[38:39], v[138:139]
	v_pk_fma_f32 v[138:139], v[32:33], v[32:33], v[138:139]
	v_pk_fma_f32 v[138:139], v[34:35], v[34:35], v[138:139]
	v_add_f32_e32 v214, v138, v139
	v_add_u32_e32 v207, 0x8000, v207
	v_mov_b32_e32 v215, v214
	s_nop 1
	v_permlane16_swap_b32_e32 v214, v215
	s_nop 0
	v_add_f32_e32 v214, v214, v215
	v_mov_b32_e32 v215, v214
	s_nop 1
	v_permlane32_swap_b32_e32 v214, v215
	s_nop 0
	v_add_f32_e32 v214, v214, v215
	s_and_saveexec_b64 s[28:29], s[4:5]
	global_store_dword v210, v214, s[16:17] offset:1024
	s_mov_b64 exec, s[28:29]
	s_waitcnt vmcnt(20)
	v_lshlrev_b32_e32 v202, 16, v194
	v_and_b32_e32 v203, 0xffff0000, v194
	v_lshlrev_b32_e32 v204, 16, v195
	v_and_b32_e32 v205, 0xffff0000, v195
	v_pk_add_f32 v[28:29], v[28:29], v[202:203]
	v_pk_add_f32 v[30:31], v[30:31], v[204:205]
	v_lshlrev_b32_e32 v202, 16, v196
	v_and_b32_e32 v203, 0xffff0000, v196
	v_lshlrev_b32_e32 v204, 16, v197
	v_and_b32_e32 v205, 0xffff0000, v197
	v_pk_add_f32 v[24:25], v[24:25], v[202:203]
	v_pk_add_f32 v[26:27], v[26:27], v[204:205]
	v_cvt_pk_bf16_f32 v194, v28, v29
	v_cvt_pk_bf16_f32 v195, v30, v31
	v_cvt_pk_bf16_f32 v196, v24, v25
	v_cvt_pk_bf16_f32 v197, v26, v27
	v_pk_mul_f32 v[138:139], v[28:29], v[28:29]
	global_store_dwordx4 v207, v[194:197], s[10:11]
	v_pk_fma_f32 v[138:139], v[30:31], v[30:31], v[138:139]
	v_pk_fma_f32 v[138:139], v[24:25], v[24:25], v[138:139]
	v_pk_fma_f32 v[138:139], v[26:27], v[26:27], v[138:139]
	v_lshlrev_b32_e32 v202, 16, v198
	v_and_b32_e32 v203, 0xffff0000, v198
	v_lshlrev_b32_e32 v204, 16, v199
	v_and_b32_e32 v205, 0xffff0000, v199
	v_pk_add_f32 v[20:21], v[20:21], v[202:203]
	v_pk_add_f32 v[22:23], v[22:23], v[204:205]
	v_lshlrev_b32_e32 v202, 16, v200
	v_and_b32_e32 v203, 0xffff0000, v200
	v_lshlrev_b32_e32 v204, 16, v201
	v_and_b32_e32 v205, 0xffff0000, v201
	v_pk_add_f32 v[16:17], v[16:17], v[202:203]
	v_pk_add_f32 v[18:19], v[18:19], v[204:205]
	v_cvt_pk_bf16_f32 v198, v20, v21
	v_cvt_pk_bf16_f32 v199, v22, v23
	v_cvt_pk_bf16_f32 v200, v16, v17
	v_cvt_pk_bf16_f32 v201, v18, v19
	v_pk_fma_f32 v[138:139], v[20:21], v[20:21], v[138:139]
	global_store_dwordx4 v207, v[198:201], s[10:11] offset:256
	v_pk_fma_f32 v[138:139], v[22:23], v[22:23], v[138:139]
	v_pk_fma_f32 v[138:139], v[16:17], v[16:17], v[138:139]
	v_pk_fma_f32 v[138:139], v[18:19], v[18:19], v[138:139]
	v_add_f32_e32 v214, v138, v139
	v_add_u32_e32 v207, 0x8000, v207
	v_mov_b32_e32 v215, v214
	s_nop 1
	v_permlane16_swap_b32_e32 v214, v215
	s_nop 0
	v_add_f32_e32 v214, v214, v215
	v_mov_b32_e32 v215, v214
	s_nop 1
	v_permlane32_swap_b32_e32 v214, v215
	s_nop 0
	v_add_f32_e32 v214, v214, v215
	s_and_saveexec_b64 s[28:29], s[4:5]
	global_store_dword v210, v214, s[16:17] offset:2048
	s_mov_b64 exec, s[28:29]
	s_waitcnt vmcnt(18)
	v_lshlrev_b32_e32 v202, 16, v146
	v_and_b32_e32 v203, 0xffff0000, v146
	v_lshlrev_b32_e32 v204, 16, v147
	v_and_b32_e32 v205, 0xffff0000, v147
	v_pk_add_f32 v[12:13], v[12:13], v[202:203]
	v_pk_add_f32 v[14:15], v[14:15], v[204:205]
	v_lshlrev_b32_e32 v202, 16, v148
	v_and_b32_e32 v203, 0xffff0000, v148
	v_lshlrev_b32_e32 v204, 16, v149
	v_and_b32_e32 v205, 0xffff0000, v149
	v_pk_add_f32 v[8:9], v[8:9], v[202:203]
	v_pk_add_f32 v[10:11], v[10:11], v[204:205]
	v_cvt_pk_bf16_f32 v146, v12, v13
	v_cvt_pk_bf16_f32 v147, v14, v15
	v_cvt_pk_bf16_f32 v148, v8, v9
	v_cvt_pk_bf16_f32 v149, v10, v11
	v_pk_mul_f32 v[138:139], v[12:13], v[12:13]
	global_store_dwordx4 v207, v[146:149], s[10:11]
	v_pk_fma_f32 v[138:139], v[14:15], v[14:15], v[138:139]
	v_pk_fma_f32 v[138:139], v[8:9], v[8:9], v[138:139]
	v_pk_fma_f32 v[138:139], v[10:11], v[10:11], v[138:139]
	v_lshlrev_b32_e32 v202, 16, v150
	v_and_b32_e32 v203, 0xffff0000, v150
	v_lshlrev_b32_e32 v204, 16, v151
	v_and_b32_e32 v205, 0xffff0000, v151
	v_pk_add_f32 v[4:5], v[4:5], v[202:203]
	v_pk_add_f32 v[6:7], v[6:7], v[204:205]
	v_lshlrev_b32_e32 v202, 16, v152
	v_and_b32_e32 v203, 0xffff0000, v152
	v_lshlrev_b32_e32 v204, 16, v153
	v_and_b32_e32 v205, 0xffff0000, v153
	v_pk_add_f32 v[0:1], v[0:1], v[202:203]
	v_pk_add_f32 v[2:3], v[2:3], v[204:205]
	v_cvt_pk_bf16_f32 v150, v4, v5
	v_cvt_pk_bf16_f32 v151, v6, v7
	v_cvt_pk_bf16_f32 v152, v0, v1
	v_cvt_pk_bf16_f32 v153, v2, v3
	v_pk_fma_f32 v[138:139], v[4:5], v[4:5], v[138:139]
	global_store_dwordx4 v207, v[150:153], s[10:11] offset:256
	v_pk_fma_f32 v[138:139], v[6:7], v[6:7], v[138:139]
	v_pk_fma_f32 v[138:139], v[0:1], v[0:1], v[138:139]
	v_pk_fma_f32 v[138:139], v[2:3], v[2:3], v[138:139]
	v_add_f32_e32 v214, v138, v139
	v_add_u32_e32 v207, 0x8000, v207
	v_mov_b32_e32 v215, v214
	s_nop 1
	v_permlane16_swap_b32_e32 v214, v215
	s_nop 0
	v_add_f32_e32 v214, v214, v215
	v_mov_b32_e32 v215, v214
	s_nop 1
	v_permlane32_swap_b32_e32 v214, v215
	s_nop 0
	v_add_f32_e32 v214, v214, v215
	s_and_saveexec_b64 s[28:29], s[4:5]
	global_store_dword v210, v214, s[16:17] offset:3072
	s_mov_b64 exec, s[28:29]
	s_branch .LBB0_768

.LBB0_823:
	s_add_u32 s26, s24, 0xfffc0080
	s_addc_u32 s27, s25, -1
	s_add_i32 s65, 0, 0x10000
	v_add_u32_e32 v154, s65, v143
	ds_read_b128 v[138:141], v154
	ds_read_b128 v[146:149], v154 offset:1024
	ds_read_b128 v[150:153], v154 offset:2048
	ds_read_b128 v[154:157], v154 offset:3072
	s_cmp_eq_u32 s51, 12
	s_cselect_b32 s29, s19, s27
	s_cselect_b32 s28, s38, s26
	s_cselect_b32 s27, s17, s50
	s_cselect_b32 s26, s39, s46
	s_add_i32 m0, s58, 0xc000
	ds_read_b128 v[158:161], v145
	ds_read_b128 v[162:165], v145 offset:1024
	ds_read_b128 v[166:169], v145 offset:2048
	ds_read_b128 v[170:173], v145 offset:3072
	ds_read_b128 v[174:177], v145 offset:4096
	ds_read_b128 v[178:181], v145 offset:5120
	ds_read_b128 v[182:185], v145 offset:6144
	ds_read_b128 v[186:189], v145 offset:7168
	global_load_lds_dwordx4 v134, s[24:25]
	s_add_i32 m0, s58, 0xe000
	s_nop 0
	global_load_lds_dwordx4 v136, s[24:25]
	s_waitcnt lgkmcnt(8)
	s_barrier
	s_waitcnt lgkmcnt(0)
	v_mfma_f32_16x16x32_bf16 v[124:127], v[138:141], v[158:161], v[124:127]
	v_mfma_f32_16x16x32_bf16 v[120:123], v[150:153], v[158:161], v[120:123]
	v_mfma_f32_16x16x32_bf16 v[108:111], v[138:141], v[166:169], v[108:111]
	v_mfma_f32_16x16x32_bf16 v[104:107], v[150:153], v[166:169], v[104:107]
	v_mfma_f32_16x16x32_bf16 v[92:95], v[138:141], v[174:177], v[92:95]
	v_mfma_f32_16x16x32_bf16 v[88:91], v[150:153], v[174:177], v[88:91]
	v_mfma_f32_16x16x32_bf16 v[76:79], v[138:141], v[182:185], v[76:79]
	v_mfma_f32_16x16x32_bf16 v[72:75], v[150:153], v[182:185], v[72:75]
	v_mfma_f32_16x16x32_bf16 v[124:127], v[146:149], v[162:165], v[124:127]
	v_mfma_f32_16x16x32_bf16 v[120:123], v[154:157], v[162:165], v[120:123]
	v_mfma_f32_16x16x32_bf16 v[108:111], v[146:149], v[170:173], v[108:111]
	v_mfma_f32_16x16x32_bf16 v[104:107], v[154:157], v[170:173], v[104:107]
	v_mfma_f32_16x16x32_bf16 v[92:95], v[146:149], v[178:181], v[92:95]
	v_mfma_f32_16x16x32_bf16 v[88:91], v[154:157], v[178:181], v[88:91]
	v_mfma_f32_16x16x32_bf16 v[76:79], v[146:149], v[186:189], v[76:79]
	v_mfma_f32_16x16x32_bf16 v[72:75], v[154:157], v[186:189], v[72:75]
	s_barrier
	s_add_i32 s68, 0, 0x14000
	s_add_i32 s65, s65, s57
	v_add_u32_e32 v202, s68, v143
	s_add_u32 s98, s26, s40
	s_addc_u32 s99, s27, s41
	s_mov_b32 m0, s65
	ds_read_b128 v[190:193], v202
	ds_read_b128 v[194:197], v202 offset:1024
	ds_read_b128 v[198:201], v202 offset:2048
	ds_read_b128 v[202:205], v202 offset:3072
	global_load_lds_dwordx4 v208, s[26:27]
	s_add_i32 m0, s65, 0x2000
	s_nop 0
	global_load_lds_dwordx4 v128, s[26:27]
	s_barrier
	s_waitcnt lgkmcnt(0)
	v_mfma_f32_16x16x32_bf16 v[116:119], v[190:193], v[158:161], v[116:119]
	v_mfma_f32_16x16x32_bf16 v[112:115], v[198:201], v[158:161], v[112:115]
	v_mfma_f32_16x16x32_bf16 v[100:103], v[190:193], v[166:169], v[100:103]
	v_mfma_f32_16x16x32_bf16 v[96:99], v[198:201], v[166:169], v[96:99]
	v_mfma_f32_16x16x32_bf16 v[84:87], v[190:193], v[174:177], v[84:87]
	v_mfma_f32_16x16x32_bf16 v[80:83], v[198:201], v[174:177], v[80:83]
	v_mfma_f32_16x16x32_bf16 v[68:71], v[190:193], v[182:185], v[68:71]
	v_mfma_f32_16x16x32_bf16 v[64:67], v[198:201], v[182:185], v[64:67]
	v_mfma_f32_16x16x32_bf16 v[116:119], v[194:197], v[162:165], v[116:119]
	v_mfma_f32_16x16x32_bf16 v[112:115], v[202:205], v[162:165], v[112:115]
	v_mfma_f32_16x16x32_bf16 v[100:103], v[194:197], v[170:173], v[100:103]
	v_mfma_f32_16x16x32_bf16 v[96:99], v[202:205], v[170:173], v[96:99]
	v_mfma_f32_16x16x32_bf16 v[84:87], v[194:197], v[178:181], v[84:87]
	v_mfma_f32_16x16x32_bf16 v[80:83], v[202:205], v[178:181], v[80:83]
	v_mfma_f32_16x16x32_bf16 v[68:71], v[194:197], v[186:189], v[68:71]
	v_mfma_f32_16x16x32_bf16 v[64:67], v[202:205], v[186:189], v[64:67]
	s_mov_b32 m0, s58
	s_add_u32 s100, s28, s40
	s_addc_u32 s101, s29, s41
	s_barrier
	ds_read_b128 v[158:161], v145 offset:16384
	ds_read_b128 v[162:165], v145 offset:17408
	ds_read_b128 v[166:169], v145 offset:18432
	ds_read_b128 v[170:173], v145 offset:19456
	ds_read_b128 v[174:177], v145 offset:20480
	ds_read_b128 v[178:181], v145 offset:21504
	ds_read_b128 v[182:185], v145 offset:22528
	ds_read_b128 v[186:189], v145 offset:23552
	global_load_lds_dwordx4 v132, s[28:29]
	s_mov_b32 m0, s59
	s_nop 0
	global_load_lds_dwordx4 v130, s[28:29]
	s_barrier
	s_waitcnt lgkmcnt(0)
	v_mfma_f32_16x16x32_bf16 v[60:63], v[138:141], v[158:161], v[60:63]
	v_mfma_f32_16x16x32_bf16 v[56:59], v[150:153], v[158:161], v[56:59]
	v_mfma_f32_16x16x32_bf16 v[44:47], v[138:141], v[166:169], v[44:47]
	v_mfma_f32_16x16x32_bf16 v[40:43], v[150:153], v[166:169], v[40:43]
	v_mfma_f32_16x16x32_bf16 v[28:31], v[138:141], v[174:177], v[28:31]
	v_mfma_f32_16x16x32_bf16 v[24:27], v[150:153], v[174:177], v[24:27]
	v_mfma_f32_16x16x32_bf16 v[12:15], v[138:141], v[182:185], v[12:15]
	v_mfma_f32_16x16x32_bf16 v[8:11], v[150:153], v[182:185], v[8:11]
	v_mfma_f32_16x16x32_bf16 v[60:63], v[146:149], v[162:165], v[60:63]
	v_mfma_f32_16x16x32_bf16 v[56:59], v[154:157], v[162:165], v[56:59]
	v_mfma_f32_16x16x32_bf16 v[44:47], v[146:149], v[170:173], v[44:47]
	v_mfma_f32_16x16x32_bf16 v[40:43], v[154:157], v[170:173], v[40:43]
	v_mfma_f32_16x16x32_bf16 v[28:31], v[146:149], v[178:181], v[28:31]
	v_mfma_f32_16x16x32_bf16 v[24:27], v[154:157], v[178:181], v[24:27]
	v_mfma_f32_16x16x32_bf16 v[12:15], v[146:149], v[186:189], v[12:15]
	v_mfma_f32_16x16x32_bf16 v[8:11], v[154:157], v[186:189], v[8:11]
	s_barrier
	s_add_u32 s66, s26, 0x40000
	s_addc_u32 s67, s27, 0
	s_add_i32 s65, s68, s57
	s_mov_b32 m0, s65
	s_nop 0
	global_load_lds_dwordx4 v208, s[66:67]
	s_add_i32 m0, s65, 0x2000
	s_nop 0
	global_load_lds_dwordx4 v128, s[66:67]
	s_waitcnt vmcnt(6)
	s_barrier
	v_mfma_f32_16x16x32_bf16 v[52:55], v[190:193], v[158:161], v[52:55]
	v_mfma_f32_16x16x32_bf16 v[48:51], v[198:201], v[158:161], v[48:51]
	v_mfma_f32_16x16x32_bf16 v[36:39], v[190:193], v[166:169], v[36:39]
	v_mfma_f32_16x16x32_bf16 v[32:35], v[198:201], v[166:169], v[32:35]
	v_mfma_f32_16x16x32_bf16 v[20:23], v[190:193], v[174:177], v[20:23]
	v_mfma_f32_16x16x32_bf16 v[16:19], v[198:201], v[174:177], v[16:19]
	v_mfma_f32_16x16x32_bf16 v[4:7], v[190:193], v[182:185], v[4:7]
	v_mfma_f32_16x16x32_bf16 v[0:3], v[198:201], v[182:185], v[0:3]
	v_mfma_f32_16x16x32_bf16 v[52:55], v[194:197], v[162:165], v[52:55]
	v_mfma_f32_16x16x32_bf16 v[48:51], v[202:205], v[162:165], v[48:51]
	v_mfma_f32_16x16x32_bf16 v[36:39], v[194:197], v[170:173], v[36:39]
	v_mfma_f32_16x16x32_bf16 v[32:35], v[202:205], v[170:173], v[32:35]
	v_mfma_f32_16x16x32_bf16 v[20:23], v[194:197], v[178:181], v[20:23]
	v_mfma_f32_16x16x32_bf16 v[16:19], v[202:205], v[178:181], v[16:19]
	v_mfma_f32_16x16x32_bf16 v[4:7], v[194:197], v[186:189], v[4:7]
	v_mfma_f32_16x16x32_bf16 v[0:3], v[202:205], v[186:189], v[0:3]
	s_add_i32 s65, 0, 0x18000
	v_add_u32_e32 v154, s65, v143
	s_barrier
	ds_read_b128 v[138:141], v154
	ds_read_b128 v[146:149], v154 offset:1024
	ds_read_b128 v[150:153], v154 offset:2048
	ds_read_b128 v[154:157], v154 offset:3072
	s_add_u32 s28, s28, 0x40000
	s_addc_u32 s29, s29, 0
	s_mov_b32 m0, s60
	ds_read_b128 v[158:161], v145 offset:32768
	ds_read_b128 v[162:165], v145 offset:33792
	ds_read_b128 v[166:169], v145 offset:34816
	ds_read_b128 v[170:173], v145 offset:35840
	ds_read_b128 v[174:177], v145 offset:36864
	ds_read_b128 v[178:181], v145 offset:37888
	ds_read_b128 v[182:185], v145 offset:38912
	ds_read_b128 v[186:189], v145 offset:39936
	global_load_lds_dwordx4 v132, s[28:29]
	s_mov_b32 m0, s61
	s_nop 0
	global_load_lds_dwordx4 v130, s[28:29]
	s_waitcnt lgkmcnt(8)
	s_barrier
	s_waitcnt lgkmcnt(0)
	v_mfma_f32_16x16x32_bf16 v[124:127], v[138:141], v[158:161], v[124:127]
	v_mfma_f32_16x16x32_bf16 v[120:123], v[150:153], v[158:161], v[120:123]
	v_mfma_f32_16x16x32_bf16 v[108:111], v[138:141], v[166:169], v[108:111]
	v_mfma_f32_16x16x32_bf16 v[104:107], v[150:153], v[166:169], v[104:107]
	v_mfma_f32_16x16x32_bf16 v[92:95], v[138:141], v[174:177], v[92:95]
	v_mfma_f32_16x16x32_bf16 v[88:91], v[150:153], v[174:177], v[88:91]
	v_mfma_f32_16x16x32_bf16 v[76:79], v[138:141], v[182:185], v[76:79]
	v_mfma_f32_16x16x32_bf16 v[72:75], v[150:153], v[182:185], v[72:75]
	v_mfma_f32_16x16x32_bf16 v[124:127], v[146:149], v[162:165], v[124:127]
	v_mfma_f32_16x16x32_bf16 v[120:123], v[154:157], v[162:165], v[120:123]
	v_mfma_f32_16x16x32_bf16 v[108:111], v[146:149], v[170:173], v[108:111]
	v_mfma_f32_16x16x32_bf16 v[104:107], v[154:157], v[170:173], v[104:107]
	v_mfma_f32_16x16x32_bf16 v[92:95], v[146:149], v[178:181], v[92:95]
	v_mfma_f32_16x16x32_bf16 v[88:91], v[154:157], v[178:181], v[88:91]
	v_mfma_f32_16x16x32_bf16 v[76:79], v[146:149], v[186:189], v[76:79]
	v_mfma_f32_16x16x32_bf16 v[72:75], v[154:157], v[186:189], v[72:75]
	s_barrier
	s_add_i32 s28, 0, 0x1c000
	s_add_i32 s29, s65, s57
	v_add_u32_e32 v202, s28, v143
	s_mov_b32 m0, s29
	ds_read_b128 v[190:193], v202
	ds_read_b128 v[194:197], v202 offset:1024
	ds_read_b128 v[198:201], v202 offset:2048
	ds_read_b128 v[202:205], v202 offset:3072
	global_load_lds_dwordx4 v208, s[98:99]
	s_add_i32 m0, s29, 0x2000
	s_nop 0
	global_load_lds_dwordx4 v128, s[98:99]
	s_barrier
	s_waitcnt lgkmcnt(0)
	v_mfma_f32_16x16x32_bf16 v[116:119], v[190:193], v[158:161], v[116:119]
	v_mfma_f32_16x16x32_bf16 v[112:115], v[198:201], v[158:161], v[112:115]
	v_mfma_f32_16x16x32_bf16 v[100:103], v[190:193], v[166:169], v[100:103]
	v_mfma_f32_16x16x32_bf16 v[96:99], v[198:201], v[166:169], v[96:99]
	v_mfma_f32_16x16x32_bf16 v[84:87], v[190:193], v[174:177], v[84:87]
	v_mfma_f32_16x16x32_bf16 v[80:83], v[198:201], v[174:177], v[80:83]
	v_mfma_f32_16x16x32_bf16 v[68:71], v[190:193], v[182:185], v[68:71]
	v_mfma_f32_16x16x32_bf16 v[64:67], v[198:201], v[182:185], v[64:67]
	v_mfma_f32_16x16x32_bf16 v[116:119], v[194:197], v[162:165], v[116:119]
	v_mfma_f32_16x16x32_bf16 v[112:115], v[202:205], v[162:165], v[112:115]
	v_mfma_f32_16x16x32_bf16 v[100:103], v[194:197], v[170:173], v[100:103]
	v_mfma_f32_16x16x32_bf16 v[96:99], v[202:205], v[170:173], v[96:99]
	v_mfma_f32_16x16x32_bf16 v[84:87], v[194:197], v[178:181], v[84:87]
	v_mfma_f32_16x16x32_bf16 v[80:83], v[202:205], v[178:181], v[80:83]
	v_mfma_f32_16x16x32_bf16 v[68:71], v[194:197], v[186:189], v[68:71]
	v_mfma_f32_16x16x32_bf16 v[64:67], v[202:205], v[186:189], v[64:67]
	s_mov_b32 m0, s62
	s_barrier
	ds_read_b128 v[158:161], v145 offset:49152
	ds_read_b128 v[162:165], v145 offset:50176
	ds_read_b128 v[166:169], v145 offset:51200
	ds_read_b128 v[170:173], v145 offset:52224
	ds_read_b128 v[174:177], v145 offset:53248
	ds_read_b128 v[178:181], v145 offset:54272
	ds_read_b128 v[182:185], v145 offset:55296
	ds_read_b128 v[186:189], v145 offset:56320
	global_load_lds_dwordx4 v132, s[100:101]
	s_mov_b32 m0, s63
	s_nop 0
	global_load_lds_dwordx4 v130, s[100:101]
	s_barrier
	s_waitcnt lgkmcnt(0)
	v_mfma_f32_16x16x32_bf16 v[60:63], v[138:141], v[158:161], v[60:63]
	v_mfma_f32_16x16x32_bf16 v[56:59], v[150:153], v[158:161], v[56:59]
	v_mfma_f32_16x16x32_bf16 v[44:47], v[138:141], v[166:169], v[44:47]
	v_mfma_f32_16x16x32_bf16 v[40:43], v[150:153], v[166:169], v[40:43]
	v_mfma_f32_16x16x32_bf16 v[28:31], v[138:141], v[174:177], v[28:31]
	v_mfma_f32_16x16x32_bf16 v[24:27], v[150:153], v[174:177], v[24:27]
	v_mfma_f32_16x16x32_bf16 v[12:15], v[138:141], v[182:185], v[12:15]
	v_mfma_f32_16x16x32_bf16 v[8:11], v[150:153], v[182:185], v[8:11]
	v_mfma_f32_16x16x32_bf16 v[60:63], v[146:149], v[162:165], v[60:63]
	v_mfma_f32_16x16x32_bf16 v[56:59], v[154:157], v[162:165], v[56:59]
	v_mfma_f32_16x16x32_bf16 v[44:47], v[146:149], v[170:173], v[44:47]
	v_mfma_f32_16x16x32_bf16 v[40:43], v[154:157], v[170:173], v[40:43]
	v_mfma_f32_16x16x32_bf16 v[28:31], v[146:149], v[178:181], v[28:31]
	v_mfma_f32_16x16x32_bf16 v[24:27], v[154:157], v[178:181], v[24:27]
	v_mfma_f32_16x16x32_bf16 v[12:15], v[146:149], v[186:189], v[12:15]
	v_mfma_f32_16x16x32_bf16 v[8:11], v[154:157], v[186:189], v[8:11]
	s_barrier
	s_add_u32 s26, s26, 0x40080
	s_addc_u32 s27, s27, 0
	s_add_i32 s28, s28, s57
	s_mov_b32 m0, s28
	s_nop 0
	global_load_lds_dwordx4 v208, s[26:27]
	s_add_i32 m0, s28, 0x2000
	s_nop 0
	global_load_lds_dwordx4 v128, s[26:27]
	s_waitcnt vmcnt(6)
	s_barrier
	v_mfma_f32_16x16x32_bf16 v[52:55], v[190:193], v[158:161], v[52:55]
	v_mfma_f32_16x16x32_bf16 v[48:51], v[198:201], v[158:161], v[48:51]
	v_mfma_f32_16x16x32_bf16 v[36:39], v[190:193], v[166:169], v[36:39]
	v_mfma_f32_16x16x32_bf16 v[32:35], v[198:201], v[166:169], v[32:35]
	v_mfma_f32_16x16x32_bf16 v[20:23], v[190:193], v[174:177], v[20:23]
	v_mfma_f32_16x16x32_bf16 v[16:19], v[198:201], v[174:177], v[16:19]
	v_mfma_f32_16x16x32_bf16 v[4:7], v[190:193], v[182:185], v[4:7]
	v_mfma_f32_16x16x32_bf16 v[0:3], v[198:201], v[182:185], v[0:3]
	v_mfma_f32_16x16x32_bf16 v[52:55], v[194:197], v[162:165], v[52:55]
	v_mfma_f32_16x16x32_bf16 v[48:51], v[202:205], v[162:165], v[48:51]
	v_mfma_f32_16x16x32_bf16 v[36:39], v[194:197], v[170:173], v[36:39]
	v_mfma_f32_16x16x32_bf16 v[32:35], v[202:205], v[170:173], v[32:35]
	v_mfma_f32_16x16x32_bf16 v[20:23], v[194:197], v[178:181], v[20:23]
	v_mfma_f32_16x16x32_bf16 v[16:19], v[202:205], v[178:181], v[16:19]
	v_mfma_f32_16x16x32_bf16 v[4:7], v[194:197], v[186:189], v[4:7]
	v_mfma_f32_16x16x32_bf16 v[0:3], v[202:205], v[186:189], v[0:3]
	s_add_i32 s51, s51, 2
	s_add_u32 s24, s24, 0x100
	s_addc_u32 s25, s25, 0
	s_add_u32 s46, s46, 0x100
	s_addc_u32 s50, s50, 0
	s_cmp_gt_u32 s51, 13
	s_barrier
	s_cbranch_scc0 .LBB0_823
	v_lshl_add_u32 v140, s35, 8, v142
	v_lshl_or_b32 v141, s34, 8, v144
	s_mov_b32 s34, s16
	s_mov_b32 s35, s18
	s_mov_b64 s[26:27], s[22:23]
	s_mov_b64 s[24:25], s[20:21]
	v_mbcnt_lo_u32_b32 v206, -1, 0
	v_mbcnt_hi_u32_b32 v206, -1, v206
	v_and_b32_e32 v206, 48, v206
	v_lshl_add_u32 v206, v140, 6, v206
	v_lshlrev_b32_e32 v207, 11, v140
	v_lshl_add_u32 v207, v141, 1, v207
	global_load_dwordx4 v[146:149], v206, s[14:15]
	global_load_dwordx4 v[150:153], v206, s[14:15] offset:1024
	global_load_dwordx4 v[154:157], v206, s[14:15] offset:2048
	global_load_dwordx4 v[158:161], v206, s[14:15] offset:3072
	v_add_u32_e32 v206, 0x2000, v206
	global_load_dwordx4 v[162:165], v206, s[14:15]
	global_load_dwordx4 v[166:169], v206, s[14:15] offset:1024
	global_load_dwordx4 v[170:173], v206, s[14:15] offset:2048
	global_load_dwordx4 v[174:177], v206, s[14:15] offset:3072
	s_waitcnt vmcnt(7)
	v_pk_add_f32 v[146:147], v[146:147], v[148:149]
	s_nop 0
	v_add_f32_e32 v214, v146, v147
	v_mov_b32_e32 v215, v214
	s_nop 1
	v_permlane16_swap_b32_e32 v214, v215
	s_nop 0
	v_add_f32_e32 v214, v214, v215
	v_mov_b32_e32 v215, v214
	s_nop 1
	v_permlane32_swap_b32_e32 v214, v215
	s_nop 0
	v_add_f32_e32 v214, v214, v215
	v_fmamk_f32 v214, v214, 0x3a800000, v248
	v_rsq_f32_e32 v178, v214
	s_nop 0
	v_pk_mul_f32 v[124:125], v[124:125], v[178:179] op_sel_hi:[1,0]
	v_pk_mul_f32 v[126:127], v[126:127], v[178:179] op_sel_hi:[1,0]
	v_pk_mul_f32 v[120:121], v[120:121], v[178:179] op_sel_hi:[1,0]
	v_pk_mul_f32 v[122:123], v[122:123], v[178:179] op_sel_hi:[1,0]
	v_cvt_pk_bf16_f32 v198, v124, v125
	v_cvt_pk_bf16_f32 v199, v126, v127
	v_cvt_pk_bf16_f32 v200, v120, v121
	v_cvt_pk_bf16_f32 v201, v122, v123
	global_store_dwordx4 v207, v[198:201], s[10:11]
	v_pk_mul_f32 v[116:117], v[116:117], v[178:179] op_sel_hi:[1,0]
	v_pk_mul_f32 v[118:119], v[118:119], v[178:179] op_sel_hi:[1,0]
	v_pk_mul_f32 v[112:113], v[112:113], v[178:179] op_sel_hi:[1,0]
	v_pk_mul_f32 v[114:115], v[114:115], v[178:179] op_sel_hi:[1,0]
	v_cvt_pk_bf16_f32 v202, v116, v117
	v_cvt_pk_bf16_f32 v203, v118, v119
	v_cvt_pk_bf16_f32 v204, v112, v113
	v_cvt_pk_bf16_f32 v205, v114, v115
	global_store_dwordx4 v207, v[202:205], s[10:11] offset:256
	v_add_u32_e32 v207, 0x8000, v207
	s_waitcnt vmcnt(8)
	v_pk_add_f32 v[150:151], v[150:151], v[152:153]
	s_nop 0
	v_add_f32_e32 v214, v150, v151
	v_mov_b32_e32 v215, v214
	s_nop 1
	v_permlane16_swap_b32_e32 v214, v215
	s_nop 0
	v_add_f32_e32 v214, v214, v215
	v_mov_b32_e32 v215, v214
	s_nop 1
	v_permlane32_swap_b32_e32 v214, v215
	s_nop 0
	v_add_f32_e32 v214, v214, v215
	v_fmamk_f32 v214, v214, 0x3a800000, v248
	v_rsq_f32_e32 v180, v214
	s_nop 0
	v_pk_mul_f32 v[108:109], v[108:109], v[180:181] op_sel_hi:[1,0]
	v_pk_mul_f32 v[110:111], v[110:111], v[180:181] op_sel_hi:[1,0]
	v_pk_mul_f32 v[104:105], v[104:105], v[180:181] op_sel_hi:[1,0]
	v_pk_mul_f32 v[106:107], v[106:107], v[180:181] op_sel_hi:[1,0]
	v_cvt_pk_bf16_f32 v198, v108, v109
	v_cvt_pk_bf16_f32 v199, v110, v111
	v_cvt_pk_bf16_f32 v200, v104, v105
	v_cvt_pk_bf16_f32 v201, v106, v107
	global_store_dwordx4 v207, v[198:201], s[10:11]
	v_pk_mul_f32 v[100:101], v[100:101], v[180:181] op_sel_hi:[1,0]
	v_pk_mul_f32 v[102:103], v[102:103], v[180:181] op_sel_hi:[1,0]
	v_pk_mul_f32 v[96:97], v[96:97], v[180:181] op_sel_hi:[1,0]
	v_pk_mul_f32 v[98:99], v[98:99], v[180:181] op_sel_hi:[1,0]
	v_cvt_pk_bf16_f32 v202, v100, v101
	v_cvt_pk_bf16_f32 v203, v102, v103
	v_cvt_pk_bf16_f32 v204, v96, v97
	v_cvt_pk_bf16_f32 v205, v98, v99
	global_store_dwordx4 v207, v[202:205], s[10:11] offset:256
	v_add_u32_e32 v207, 0x8000, v207
	s_waitcnt vmcnt(9)
	v_pk_add_f32 v[154:155], v[154:155], v[156:157]
	s_nop 0
	v_add_f32_e32 v214, v154, v155
	v_mov_b32_e32 v215, v214
	s_nop 1
	v_permlane16_swap_b32_e32 v214, v215
	s_nop 0
	v_add_f32_e32 v214, v214, v215
	v_mov_b32_e32 v215, v214
	s_nop 1
	v_permlane32_swap_b32_e32 v214, v215
	s_nop 0
	v_add_f32_e32 v214, v214, v215
	v_fmamk_f32 v214, v214, 0x3a800000, v248
	v_rsq_f32_e32 v182, v214
	s_nop 0
	v_pk_mul_f32 v[92:93], v[92:93], v[182:183] op_sel_hi:[1,0]
	v_pk_mul_f32 v[94:95], v[94:95], v[182:183] op_sel_hi:[1,0]
	v_pk_mul_f32 v[88:89], v[88:89], v[182:183] op_sel_hi:[1,0]
	v_pk_mul_f32 v[90:91], v[90:91], v[182:183] op_sel_hi:[1,0]
	v_cvt_pk_bf16_f32 v198, v92, v93
	v_cvt_pk_bf16_f32 v199, v94, v95
	v_cvt_pk_bf16_f32 v200, v88, v89
	v_cvt_pk_bf16_f32 v201, v90, v91
	global_store_dwordx4 v207, v[198:201], s[10:11]
	v_pk_mul_f32 v[84:85], v[84:85], v[182:183] op_sel_hi:[1,0]
	v_pk_mul_f32 v[86:87], v[86:87], v[182:183] op_sel_hi:[1,0]
	v_pk_mul_f32 v[80:81], v[80:81], v[182:183] op_sel_hi:[1,0]
	v_pk_mul_f32 v[82:83], v[82:83], v[182:183] op_sel_hi:[1,0]
	v_cvt_pk_bf16_f32 v202, v84, v85
	v_cvt_pk_bf16_f32 v203, v86, v87
	v_cvt_pk_bf16_f32 v204, v80, v81
	v_cvt_pk_bf16_f32 v205, v82, v83
	global_store_dwordx4 v207, v[202:205], s[10:11] offset:256
	v_add_u32_e32 v207, 0x8000, v207
	s_waitcnt vmcnt(10)
	v_pk_add_f32 v[158:159], v[158:159], v[160:161]
	s_nop 0
	v_add_f32_e32 v214, v158, v159
	v_mov_b32_e32 v215, v214
	s_nop 1
	v_permlane16_swap_b32_e32 v214, v215
	s_nop 0
	v_add_f32_e32 v214, v214, v215
	v_mov_b32_e32 v215, v214
	s_nop 1
	v_permlane32_swap_b32_e32 v214, v215
	s_nop 0
	v_add_f32_e32 v214, v214, v215
	v_fmamk_f32 v214, v214, 0x3a800000, v248
	v_rsq_f32_e32 v184, v214
	s_nop 0
	v_pk_mul_f32 v[76:77], v[76:77], v[184:185] op_sel_hi:[1,0]
	v_pk_mul_f32 v[78:79], v[78:79], v[184:185] op_sel_hi:[1,0]
	v_pk_mul_f32 v[72:73], v[72:73], v[184:185] op_sel_hi:[1,0]
	v_pk_mul_f32 v[74:75], v[74:75], v[184:185] op_sel_hi:[1,0]
	v_cvt_pk_bf16_f32 v198, v76, v77
	v_cvt_pk_bf16_f32 v199, v78, v79
	v_cvt_pk_bf16_f32 v200, v72, v73
	v_cvt_pk_bf16_f32 v201, v74, v75
	global_store_dwordx4 v207, v[198:201], s[10:11]
	v_pk_mul_f32 v[68:69], v[68:69], v[184:185] op_sel_hi:[1,0]
	v_pk_mul_f32 v[70:71], v[70:71], v[184:185] op_sel_hi:[1,0]
	v_pk_mul_f32 v[64:65], v[64:65], v[184:185] op_sel_hi:[1,0]
	v_pk_mul_f32 v[66:67], v[66:67], v[184:185] op_sel_hi:[1,0]
	v_cvt_pk_bf16_f32 v202, v68, v69
	v_cvt_pk_bf16_f32 v203, v70, v71
	v_cvt_pk_bf16_f32 v204, v64, v65
	v_cvt_pk_bf16_f32 v205, v66, v67
	global_store_dwordx4 v207, v[202:205], s[10:11] offset:256
	v_add_u32_e32 v207, 0x28000, v207
	s_waitcnt vmcnt(11)
	v_pk_add_f32 v[162:163], v[162:163], v[164:165]
	s_nop 0
	v_add_f32_e32 v214, v162, v163
	v_mov_b32_e32 v215, v214
	s_nop 1
	v_permlane16_swap_b32_e32 v214, v215
	s_nop 0
	v_add_f32_e32 v214, v214, v215
	v_mov_b32_e32 v215, v214
	s_nop 1
	v_permlane32_swap_b32_e32 v214, v215
	s_nop 0
	v_add_f32_e32 v214, v214, v215
	v_fmamk_f32 v214, v214, 0x3a800000, v248
	v_rsq_f32_e32 v186, v214
	s_nop 0
	v_pk_mul_f32 v[60:61], v[60:61], v[186:187] op_sel_hi:[1,0]
	v_pk_mul_f32 v[62:63], v[62:63], v[186:187] op_sel_hi:[1,0]
	v_pk_mul_f32 v[56:57], v[56:57], v[186:187] op_sel_hi:[1,0]
	v_pk_mul_f32 v[58:59], v[58:59], v[186:187] op_sel_hi:[1,0]
	v_cvt_pk_bf16_f32 v198, v60, v61
	v_cvt_pk_bf16_f32 v199, v62, v63
	v_cvt_pk_bf16_f32 v200, v56, v57
	v_cvt_pk_bf16_f32 v201, v58, v59
	global_store_dwordx4 v207, v[198:201], s[10:11]
	v_pk_mul_f32 v[52:53], v[52:53], v[186:187] op_sel_hi:[1,0]
	v_pk_mul_f32 v[54:55], v[54:55], v[186:187] op_sel_hi:[1,0]
	v_pk_mul_f32 v[48:49], v[48:49], v[186:187] op_sel_hi:[1,0]
	v_pk_mul_f32 v[50:51], v[50:51], v[186:187] op_sel_hi:[1,0]
	v_cvt_pk_bf16_f32 v202, v52, v53
	v_cvt_pk_bf16_f32 v203, v54, v55
	v_cvt_pk_bf16_f32 v204, v48, v49
	v_cvt_pk_bf16_f32 v205, v50, v51
	global_store_dwordx4 v207, v[202:205], s[10:11] offset:256
	v_add_u32_e32 v207, 0x8000, v207
	s_waitcnt vmcnt(12)
	v_pk_add_f32 v[166:167], v[166:167], v[168:169]
	s_nop 0
	v_add_f32_e32 v214, v166, v167
	v_mov_b32_e32 v215, v214
	s_nop 1
	v_permlane16_swap_b32_e32 v214, v215
	s_nop 0
	v_add_f32_e32 v214, v214, v215
	v_mov_b32_e32 v215, v214
	s_nop 1
	v_permlane32_swap_b32_e32 v214, v215
	s_nop 0
	v_add_f32_e32 v214, v214, v215
	v_fmamk_f32 v214, v214, 0x3a800000, v248
	v_rsq_f32_e32 v188, v214
	s_nop 0
	v_pk_mul_f32 v[44:45], v[44:45], v[188:189] op_sel_hi:[1,0]
	v_pk_mul_f32 v[46:47], v[46:47], v[188:189] op_sel_hi:[1,0]
	v_pk_mul_f32 v[40:41], v[40:41], v[188:189] op_sel_hi:[1,0]
	v_pk_mul_f32 v[42:43], v[42:43], v[188:189] op_sel_hi:[1,0]
	v_cvt_pk_bf16_f32 v198, v44, v45
	v_cvt_pk_bf16_f32 v199, v46, v47
	v_cvt_pk_bf16_f32 v200, v40, v41
	v_cvt_pk_bf16_f32 v201, v42, v43
	global_store_dwordx4 v207, v[198:201], s[10:11]
	v_pk_mul_f32 v[36:37], v[36:37], v[188:189] op_sel_hi:[1,0]
	v_pk_mul_f32 v[38:39], v[38:39], v[188:189] op_sel_hi:[1,0]
	v_pk_mul_f32 v[32:33], v[32:33], v[188:189] op_sel_hi:[1,0]
	v_pk_mul_f32 v[34:35], v[34:35], v[188:189] op_sel_hi:[1,0]
	v_cvt_pk_bf16_f32 v202, v36, v37
	v_cvt_pk_bf16_f32 v203, v38, v39
	v_cvt_pk_bf16_f32 v204, v32, v33
	v_cvt_pk_bf16_f32 v205, v34, v35
	global_store_dwordx4 v207, v[202:205], s[10:11] offset:256
	v_add_u32_e32 v207, 0x8000, v207
	s_waitcnt vmcnt(13)
	v_pk_add_f32 v[170:171], v[170:171], v[172:173]
	s_nop 0
	v_add_f32_e32 v214, v170, v171
	v_mov_b32_e32 v215, v214
	s_nop 1
	v_permlane16_swap_b32_e32 v214, v215
	s_nop 0
	v_add_f32_e32 v214, v214, v215
	v_mov_b32_e32 v215, v214
	s_nop 1
	v_permlane32_swap_b32_e32 v214, v215
	s_nop 0
	v_add_f32_e32 v214, v214, v215
	v_fmamk_f32 v214, v214, 0x3a800000, v248
	v_rsq_f32_e32 v190, v214
	s_nop 0
	v_pk_mul_f32 v[28:29], v[28:29], v[190:191] op_sel_hi:[1,0]
	v_pk_mul_f32 v[30:31], v[30:31], v[190:191] op_sel_hi:[1,0]
	v_pk_mul_f32 v[24:25], v[24:25], v[190:191] op_sel_hi:[1,0]
	v_pk_mul_f32 v[26:27], v[26:27], v[190:191] op_sel_hi:[1,0]
	v_cvt_pk_bf16_f32 v198, v28, v29
	v_cvt_pk_bf16_f32 v199, v30, v31
	v_cvt_pk_bf16_f32 v200, v24, v25
	v_cvt_pk_bf16_f32 v201, v26, v27
	global_store_dwordx4 v207, v[198:201], s[10:11]
	v_pk_mul_f32 v[20:21], v[20:21], v[190:191] op_sel_hi:[1,0]
	v_pk_mul_f32 v[22:23], v[22:23], v[190:191] op_sel_hi:[1,0]
	v_pk_mul_f32 v[16:17], v[16:17], v[190:191] op_sel_hi:[1,0]
	v_pk_mul_f32 v[18:19], v[18:19], v[190:191] op_sel_hi:[1,0]
	v_cvt_pk_bf16_f32 v202, v20, v21
	v_cvt_pk_bf16_f32 v203, v22, v23
	v_cvt_pk_bf16_f32 v204, v16, v17
	v_cvt_pk_bf16_f32 v205, v18, v19
	global_store_dwordx4 v207, v[202:205], s[10:11] offset:256
	v_add_u32_e32 v207, 0x8000, v207
	s_waitcnt vmcnt(14)
	v_pk_add_f32 v[174:175], v[174:175], v[176:177]
	s_nop 0
	v_add_f32_e32 v214, v174, v175
	v_mov_b32_e32 v215, v214
	s_nop 1
	v_permlane16_swap_b32_e32 v214, v215
	s_nop 0
	v_add_f32_e32 v214, v214, v215
	v_mov_b32_e32 v215, v214
	s_nop 1
	v_permlane32_swap_b32_e32 v214, v215
	s_nop 0
	v_add_f32_e32 v214, v214, v215
	v_fmamk_f32 v214, v214, 0x3a800000, v248
	v_rsq_f32_e32 v192, v214
	s_nop 0
	v_pk_mul_f32 v[12:13], v[12:13], v[192:193] op_sel_hi:[1,0]
	v_pk_mul_f32 v[14:15], v[14:15], v[192:193] op_sel_hi:[1,0]
	v_pk_mul_f32 v[8:9], v[8:9], v[192:193] op_sel_hi:[1,0]
	v_pk_mul_f32 v[10:11], v[10:11], v[192:193] op_sel_hi:[1,0]
	v_cvt_pk_bf16_f32 v198, v12, v13
	v_cvt_pk_bf16_f32 v199, v14, v15
	v_cvt_pk_bf16_f32 v200, v8, v9
	v_cvt_pk_bf16_f32 v201, v10, v11
	global_store_dwordx4 v207, v[198:201], s[10:11]
	v_pk_mul_f32 v[4:5], v[4:5], v[192:193] op_sel_hi:[1,0]
	v_pk_mul_f32 v[6:7], v[6:7], v[192:193] op_sel_hi:[1,0]
	v_pk_mul_f32 v[0:1], v[0:1], v[192:193] op_sel_hi:[1,0]
	v_pk_mul_f32 v[2:3], v[2:3], v[192:193] op_sel_hi:[1,0]
	v_cvt_pk_bf16_f32 v202, v4, v5
	v_cvt_pk_bf16_f32 v203, v6, v7
	v_cvt_pk_bf16_f32 v204, v0, v1
	v_cvt_pk_bf16_f32 v205, v2, v3
	global_store_dwordx4 v207, v[202:205], s[10:11] offset:256
	s_and_b64 vcc, exec, s[4:5]
	s_cbranch_vccz .LBB0_816
	s_waitcnt vmcnt(0)
	s_cmpk_gt_u32 s30, 0xff
	s_cbranch_scc1 .LBB0_827
	s_barrier

.LBB0_878:
	s_add_u32 s26, s24, 0xfffc0080
	s_addc_u32 s27, s25, -1
	s_add_i32 s65, 0, 0x10000
	v_add_u32_e32 v154, s65, v143
	ds_read_b128 v[138:141], v154
	ds_read_b128 v[146:149], v154 offset:1024
	ds_read_b128 v[150:153], v154 offset:2048
	ds_read_b128 v[154:157], v154 offset:3072
	s_cmp_eq_u32 s64, 12
	s_cselect_b32 s29, s19, s27
	s_cselect_b32 s28, s39, s26
	s_cselect_b32 s27, s17, s63
	s_cselect_b32 s26, s61, s62
	s_add_i32 m0, s50, 0xc000
	ds_read_b128 v[158:161], v145
	ds_read_b128 v[162:165], v145 offset:1024
	ds_read_b128 v[166:169], v145 offset:2048
	ds_read_b128 v[170:173], v145 offset:3072
	ds_read_b128 v[174:177], v145 offset:4096
	ds_read_b128 v[178:181], v145 offset:5120
	ds_read_b128 v[182:185], v145 offset:6144
	ds_read_b128 v[186:189], v145 offset:7168
	global_load_lds_dwordx4 v134, s[24:25]
	s_add_i32 m0, s50, 0xe000
	s_nop 0
	global_load_lds_dwordx4 v136, s[24:25]
	s_waitcnt lgkmcnt(8)
	s_barrier
	s_waitcnt lgkmcnt(0)
	v_mfma_f32_16x16x32_bf16 v[124:127], v[138:141], v[158:161], v[124:127]
	v_mfma_f32_16x16x32_bf16 v[120:123], v[150:153], v[158:161], v[120:123]
	v_mfma_f32_16x16x32_bf16 v[108:111], v[138:141], v[166:169], v[108:111]
	v_mfma_f32_16x16x32_bf16 v[104:107], v[150:153], v[166:169], v[104:107]
	v_mfma_f32_16x16x32_bf16 v[92:95], v[138:141], v[174:177], v[92:95]
	v_mfma_f32_16x16x32_bf16 v[88:91], v[150:153], v[174:177], v[88:91]
	v_mfma_f32_16x16x32_bf16 v[76:79], v[138:141], v[182:185], v[76:79]
	v_mfma_f32_16x16x32_bf16 v[72:75], v[150:153], v[182:185], v[72:75]
	v_mfma_f32_16x16x32_bf16 v[124:127], v[146:149], v[162:165], v[124:127]
	v_mfma_f32_16x16x32_bf16 v[120:123], v[154:157], v[162:165], v[120:123]
	v_mfma_f32_16x16x32_bf16 v[108:111], v[146:149], v[170:173], v[108:111]
	v_mfma_f32_16x16x32_bf16 v[104:107], v[154:157], v[170:173], v[104:107]
	v_mfma_f32_16x16x32_bf16 v[92:95], v[146:149], v[178:181], v[92:95]
	v_mfma_f32_16x16x32_bf16 v[88:91], v[154:157], v[178:181], v[88:91]
	v_mfma_f32_16x16x32_bf16 v[76:79], v[146:149], v[186:189], v[76:79]
	v_mfma_f32_16x16x32_bf16 v[72:75], v[154:157], v[186:189], v[72:75]
	s_barrier
	s_add_i32 s68, 0, 0x14000
	s_add_i32 s65, s65, s47
	v_add_u32_e32 v202, s68, v143
	s_add_u32 s98, s26, s40
	s_addc_u32 s99, s27, s41
	s_mov_b32 m0, s65
	ds_read_b128 v[190:193], v202
	ds_read_b128 v[194:197], v202 offset:1024
	ds_read_b128 v[198:201], v202 offset:2048
	ds_read_b128 v[202:205], v202 offset:3072
	global_load_lds_dwordx4 v208, s[26:27]
	s_add_i32 m0, s65, 0x2000
	s_nop 0
	global_load_lds_dwordx4 v128, s[26:27]
	s_barrier
	s_waitcnt lgkmcnt(0)
	v_mfma_f32_16x16x32_bf16 v[116:119], v[190:193], v[158:161], v[116:119]
	v_mfma_f32_16x16x32_bf16 v[112:115], v[198:201], v[158:161], v[112:115]
	v_mfma_f32_16x16x32_bf16 v[100:103], v[190:193], v[166:169], v[100:103]
	v_mfma_f32_16x16x32_bf16 v[96:99], v[198:201], v[166:169], v[96:99]
	v_mfma_f32_16x16x32_bf16 v[84:87], v[190:193], v[174:177], v[84:87]
	v_mfma_f32_16x16x32_bf16 v[80:83], v[198:201], v[174:177], v[80:83]
	v_mfma_f32_16x16x32_bf16 v[68:71], v[190:193], v[182:185], v[68:71]
	v_mfma_f32_16x16x32_bf16 v[64:67], v[198:201], v[182:185], v[64:67]
	v_mfma_f32_16x16x32_bf16 v[116:119], v[194:197], v[162:165], v[116:119]
	v_mfma_f32_16x16x32_bf16 v[112:115], v[202:205], v[162:165], v[112:115]
	v_mfma_f32_16x16x32_bf16 v[100:103], v[194:197], v[170:173], v[100:103]
	v_mfma_f32_16x16x32_bf16 v[96:99], v[202:205], v[170:173], v[96:99]
	v_mfma_f32_16x16x32_bf16 v[84:87], v[194:197], v[178:181], v[84:87]
	v_mfma_f32_16x16x32_bf16 v[80:83], v[202:205], v[178:181], v[80:83]
	v_mfma_f32_16x16x32_bf16 v[68:71], v[194:197], v[186:189], v[68:71]
	v_mfma_f32_16x16x32_bf16 v[64:67], v[202:205], v[186:189], v[64:67]
	s_mov_b32 m0, s50
	s_add_u32 s100, s28, s40
	s_addc_u32 s101, s29, s41
	s_barrier
	ds_read_b128 v[158:161], v145 offset:16384
	ds_read_b128 v[162:165], v145 offset:17408
	ds_read_b128 v[166:169], v145 offset:18432
	ds_read_b128 v[170:173], v145 offset:19456
	ds_read_b128 v[174:177], v145 offset:20480
	ds_read_b128 v[178:181], v145 offset:21504
	ds_read_b128 v[182:185], v145 offset:22528
	ds_read_b128 v[186:189], v145 offset:23552
	global_load_lds_dwordx4 v132, s[28:29]
	s_mov_b32 m0, s51
	s_nop 0
	global_load_lds_dwordx4 v130, s[28:29]
	s_barrier
	s_waitcnt lgkmcnt(0)
	v_mfma_f32_16x16x32_bf16 v[60:63], v[138:141], v[158:161], v[60:63]
	v_mfma_f32_16x16x32_bf16 v[56:59], v[150:153], v[158:161], v[56:59]
	v_mfma_f32_16x16x32_bf16 v[44:47], v[138:141], v[166:169], v[44:47]
	v_mfma_f32_16x16x32_bf16 v[40:43], v[150:153], v[166:169], v[40:43]
	v_mfma_f32_16x16x32_bf16 v[28:31], v[138:141], v[174:177], v[28:31]
	v_mfma_f32_16x16x32_bf16 v[24:27], v[150:153], v[174:177], v[24:27]
	v_mfma_f32_16x16x32_bf16 v[12:15], v[138:141], v[182:185], v[12:15]
	v_mfma_f32_16x16x32_bf16 v[8:11], v[150:153], v[182:185], v[8:11]
	v_mfma_f32_16x16x32_bf16 v[60:63], v[146:149], v[162:165], v[60:63]
	v_mfma_f32_16x16x32_bf16 v[56:59], v[154:157], v[162:165], v[56:59]
	v_mfma_f32_16x16x32_bf16 v[44:47], v[146:149], v[170:173], v[44:47]
	v_mfma_f32_16x16x32_bf16 v[40:43], v[154:157], v[170:173], v[40:43]
	v_mfma_f32_16x16x32_bf16 v[28:31], v[146:149], v[178:181], v[28:31]
	v_mfma_f32_16x16x32_bf16 v[24:27], v[154:157], v[178:181], v[24:27]
	v_mfma_f32_16x16x32_bf16 v[12:15], v[146:149], v[186:189], v[12:15]
	v_mfma_f32_16x16x32_bf16 v[8:11], v[154:157], v[186:189], v[8:11]
	s_barrier
	s_add_u32 s66, s26, 0x40000
	s_addc_u32 s67, s27, 0
	s_add_i32 s65, s68, s47
	s_mov_b32 m0, s65
	s_nop 0
	global_load_lds_dwordx4 v208, s[66:67]
	s_add_i32 m0, s65, 0x2000
	s_nop 0
	global_load_lds_dwordx4 v128, s[66:67]
	s_waitcnt vmcnt(6)
	s_barrier
	v_mfma_f32_16x16x32_bf16 v[52:55], v[190:193], v[158:161], v[52:55]
	v_mfma_f32_16x16x32_bf16 v[48:51], v[198:201], v[158:161], v[48:51]
	v_mfma_f32_16x16x32_bf16 v[36:39], v[190:193], v[166:169], v[36:39]
	v_mfma_f32_16x16x32_bf16 v[32:35], v[198:201], v[166:169], v[32:35]
	v_mfma_f32_16x16x32_bf16 v[20:23], v[190:193], v[174:177], v[20:23]
	v_mfma_f32_16x16x32_bf16 v[16:19], v[198:201], v[174:177], v[16:19]
	v_mfma_f32_16x16x32_bf16 v[4:7], v[190:193], v[182:185], v[4:7]
	v_mfma_f32_16x16x32_bf16 v[0:3], v[198:201], v[182:185], v[0:3]
	v_mfma_f32_16x16x32_bf16 v[52:55], v[194:197], v[162:165], v[52:55]
	v_mfma_f32_16x16x32_bf16 v[48:51], v[202:205], v[162:165], v[48:51]
	v_mfma_f32_16x16x32_bf16 v[36:39], v[194:197], v[170:173], v[36:39]
	v_mfma_f32_16x16x32_bf16 v[32:35], v[202:205], v[170:173], v[32:35]
	v_mfma_f32_16x16x32_bf16 v[20:23], v[194:197], v[178:181], v[20:23]
	v_mfma_f32_16x16x32_bf16 v[16:19], v[202:205], v[178:181], v[16:19]
	v_mfma_f32_16x16x32_bf16 v[4:7], v[194:197], v[186:189], v[4:7]
	v_mfma_f32_16x16x32_bf16 v[0:3], v[202:205], v[186:189], v[0:3]
	s_add_i32 s65, 0, 0x18000
	v_add_u32_e32 v154, s65, v143
	s_barrier
	ds_read_b128 v[138:141], v154
	ds_read_b128 v[146:149], v154 offset:1024
	ds_read_b128 v[150:153], v154 offset:2048
	ds_read_b128 v[154:157], v154 offset:3072
	s_add_u32 s28, s28, 0x40000
	s_addc_u32 s29, s29, 0
	s_mov_b32 m0, s53
	ds_read_b128 v[158:161], v145 offset:32768
	ds_read_b128 v[162:165], v145 offset:33792
	ds_read_b128 v[166:169], v145 offset:34816
	ds_read_b128 v[170:173], v145 offset:35840
	ds_read_b128 v[174:177], v145 offset:36864
	ds_read_b128 v[178:181], v145 offset:37888
	ds_read_b128 v[182:185], v145 offset:38912
	ds_read_b128 v[186:189], v145 offset:39936
	global_load_lds_dwordx4 v132, s[28:29]
	s_mov_b32 m0, s56
	s_nop 0
	global_load_lds_dwordx4 v130, s[28:29]
	s_waitcnt lgkmcnt(8)
	s_barrier
	s_waitcnt lgkmcnt(0)
	v_mfma_f32_16x16x32_bf16 v[124:127], v[138:141], v[158:161], v[124:127]
	v_mfma_f32_16x16x32_bf16 v[120:123], v[150:153], v[158:161], v[120:123]
	v_mfma_f32_16x16x32_bf16 v[108:111], v[138:141], v[166:169], v[108:111]
	v_mfma_f32_16x16x32_bf16 v[104:107], v[150:153], v[166:169], v[104:107]
	v_mfma_f32_16x16x32_bf16 v[92:95], v[138:141], v[174:177], v[92:95]
	v_mfma_f32_16x16x32_bf16 v[88:91], v[150:153], v[174:177], v[88:91]
	v_mfma_f32_16x16x32_bf16 v[76:79], v[138:141], v[182:185], v[76:79]
	v_mfma_f32_16x16x32_bf16 v[72:75], v[150:153], v[182:185], v[72:75]
	v_mfma_f32_16x16x32_bf16 v[124:127], v[146:149], v[162:165], v[124:127]
	v_mfma_f32_16x16x32_bf16 v[120:123], v[154:157], v[162:165], v[120:123]
	v_mfma_f32_16x16x32_bf16 v[108:111], v[146:149], v[170:173], v[108:111]
	v_mfma_f32_16x16x32_bf16 v[104:107], v[154:157], v[170:173], v[104:107]
	v_mfma_f32_16x16x32_bf16 v[92:95], v[146:149], v[178:181], v[92:95]
	v_mfma_f32_16x16x32_bf16 v[88:91], v[154:157], v[178:181], v[88:91]
	v_mfma_f32_16x16x32_bf16 v[76:79], v[146:149], v[186:189], v[76:79]
	v_mfma_f32_16x16x32_bf16 v[72:75], v[154:157], v[186:189], v[72:75]
	s_barrier
	s_add_i32 s28, 0, 0x1c000
	s_add_i32 s29, s65, s47
	v_add_u32_e32 v202, s28, v143
	s_mov_b32 m0, s29
	ds_read_b128 v[190:193], v202
	ds_read_b128 v[194:197], v202 offset:1024
	ds_read_b128 v[198:201], v202 offset:2048
	ds_read_b128 v[202:205], v202 offset:3072
	global_load_lds_dwordx4 v208, s[98:99]
	s_add_i32 m0, s29, 0x2000
	s_nop 0
	global_load_lds_dwordx4 v128, s[98:99]
	s_barrier
	s_waitcnt lgkmcnt(0)
	v_mfma_f32_16x16x32_bf16 v[116:119], v[190:193], v[158:161], v[116:119]
	v_mfma_f32_16x16x32_bf16 v[112:115], v[198:201], v[158:161], v[112:115]
	v_mfma_f32_16x16x32_bf16 v[100:103], v[190:193], v[166:169], v[100:103]
	v_mfma_f32_16x16x32_bf16 v[96:99], v[198:201], v[166:169], v[96:99]
	v_mfma_f32_16x16x32_bf16 v[84:87], v[190:193], v[174:177], v[84:87]
	v_mfma_f32_16x16x32_bf16 v[80:83], v[198:201], v[174:177], v[80:83]
	v_mfma_f32_16x16x32_bf16 v[68:71], v[190:193], v[182:185], v[68:71]
	v_mfma_f32_16x16x32_bf16 v[64:67], v[198:201], v[182:185], v[64:67]
	v_mfma_f32_16x16x32_bf16 v[116:119], v[194:197], v[162:165], v[116:119]
	v_mfma_f32_16x16x32_bf16 v[112:115], v[202:205], v[162:165], v[112:115]
	v_mfma_f32_16x16x32_bf16 v[100:103], v[194:197], v[170:173], v[100:103]
	v_mfma_f32_16x16x32_bf16 v[96:99], v[202:205], v[170:173], v[96:99]
	v_mfma_f32_16x16x32_bf16 v[84:87], v[194:197], v[178:181], v[84:87]
	v_mfma_f32_16x16x32_bf16 v[80:83], v[202:205], v[178:181], v[80:83]
	v_mfma_f32_16x16x32_bf16 v[68:71], v[194:197], v[186:189], v[68:71]
	v_mfma_f32_16x16x32_bf16 v[64:67], v[202:205], v[186:189], v[64:67]
	s_mov_b32 m0, s58
	s_barrier
	ds_read_b128 v[158:161], v145 offset:49152
	ds_read_b128 v[162:165], v145 offset:50176
	ds_read_b128 v[166:169], v145 offset:51200
	ds_read_b128 v[170:173], v145 offset:52224
	ds_read_b128 v[174:177], v145 offset:53248
	ds_read_b128 v[178:181], v145 offset:54272
	ds_read_b128 v[182:185], v145 offset:55296
	ds_read_b128 v[186:189], v145 offset:56320
	global_load_lds_dwordx4 v132, s[100:101]
	s_mov_b32 m0, s59
	s_nop 0
	global_load_lds_dwordx4 v130, s[100:101]
	s_barrier
	s_waitcnt lgkmcnt(0)
	v_mfma_f32_16x16x32_bf16 v[60:63], v[138:141], v[158:161], v[60:63]
	v_mfma_f32_16x16x32_bf16 v[56:59], v[150:153], v[158:161], v[56:59]
	v_mfma_f32_16x16x32_bf16 v[44:47], v[138:141], v[166:169], v[44:47]
	v_mfma_f32_16x16x32_bf16 v[40:43], v[150:153], v[166:169], v[40:43]
	v_mfma_f32_16x16x32_bf16 v[28:31], v[138:141], v[174:177], v[28:31]
	v_mfma_f32_16x16x32_bf16 v[24:27], v[150:153], v[174:177], v[24:27]
	v_mfma_f32_16x16x32_bf16 v[12:15], v[138:141], v[182:185], v[12:15]
	v_mfma_f32_16x16x32_bf16 v[8:11], v[150:153], v[182:185], v[8:11]
	v_mfma_f32_16x16x32_bf16 v[60:63], v[146:149], v[162:165], v[60:63]
	v_mfma_f32_16x16x32_bf16 v[56:59], v[154:157], v[162:165], v[56:59]
	v_mfma_f32_16x16x32_bf16 v[44:47], v[146:149], v[170:173], v[44:47]
	v_mfma_f32_16x16x32_bf16 v[40:43], v[154:157], v[170:173], v[40:43]
	v_mfma_f32_16x16x32_bf16 v[28:31], v[146:149], v[178:181], v[28:31]
	v_mfma_f32_16x16x32_bf16 v[24:27], v[154:157], v[178:181], v[24:27]
	v_mfma_f32_16x16x32_bf16 v[12:15], v[146:149], v[186:189], v[12:15]
	v_mfma_f32_16x16x32_bf16 v[8:11], v[154:157], v[186:189], v[8:11]
	s_barrier
	s_add_u32 s26, s26, 0x40080
	s_addc_u32 s27, s27, 0
	s_add_i32 s28, s28, s47
	s_mov_b32 m0, s28
	s_nop 0
	global_load_lds_dwordx4 v208, s[26:27]
	s_add_i32 m0, s28, 0x2000
	s_nop 0
	global_load_lds_dwordx4 v128, s[26:27]
	s_waitcnt vmcnt(6)
	s_barrier
	v_mfma_f32_16x16x32_bf16 v[52:55], v[190:193], v[158:161], v[52:55]
	v_mfma_f32_16x16x32_bf16 v[48:51], v[198:201], v[158:161], v[48:51]
	v_mfma_f32_16x16x32_bf16 v[36:39], v[190:193], v[166:169], v[36:39]
	v_mfma_f32_16x16x32_bf16 v[32:35], v[198:201], v[166:169], v[32:35]
	v_mfma_f32_16x16x32_bf16 v[20:23], v[190:193], v[174:177], v[20:23]
	v_mfma_f32_16x16x32_bf16 v[16:19], v[198:201], v[174:177], v[16:19]
	v_mfma_f32_16x16x32_bf16 v[4:7], v[190:193], v[182:185], v[4:7]
	v_mfma_f32_16x16x32_bf16 v[0:3], v[198:201], v[182:185], v[0:3]
	v_mfma_f32_16x16x32_bf16 v[52:55], v[194:197], v[162:165], v[52:55]
	v_mfma_f32_16x16x32_bf16 v[48:51], v[202:205], v[162:165], v[48:51]
	v_mfma_f32_16x16x32_bf16 v[36:39], v[194:197], v[170:173], v[36:39]
	v_mfma_f32_16x16x32_bf16 v[32:35], v[202:205], v[170:173], v[32:35]
	v_mfma_f32_16x16x32_bf16 v[20:23], v[194:197], v[178:181], v[20:23]
	v_mfma_f32_16x16x32_bf16 v[16:19], v[202:205], v[178:181], v[16:19]
	v_mfma_f32_16x16x32_bf16 v[4:7], v[194:197], v[186:189], v[4:7]
	v_mfma_f32_16x16x32_bf16 v[0:3], v[202:205], v[186:189], v[0:3]
	s_add_i32 s64, s64, 2
	s_add_u32 s24, s24, 0x100
	s_addc_u32 s25, s25, 0
	s_add_u32 s62, s62, 0x100
	s_addc_u32 s63, s63, 0
	s_cmp_gt_u32 s64, 13
	s_barrier
	s_cbranch_scc0 .LBB0_878
	v_lshl_add_u32 v140, s38, 8, v142
	v_lshl_or_b32 v141, s36, 8, v144
	s_lshl_b32 s24, s36, 2
	s_ashr_i32 s25, s24, 31
	s_lshl_b32 s36, s57, 2
	v_lshlrev_b32_e32 v206, 11, v140
	v_lshl_add_u32 v206, v141, 1, v206
	v_lshl_add_u32 v210, v140, 6, s36
	v_lshl_add_u32 v210, s24, 2, v210
	v_mov_b32_e32 v207, v206
	global_load_dwordx4 v[146:149], v206, s[8:9]
	global_load_dwordx4 v[150:153], v206, s[8:9] offset:256
	v_add_u32_e32 v206, 0x8000, v206
	global_load_dwordx4 v[154:157], v206, s[8:9]
	global_load_dwordx4 v[158:161], v206, s[8:9] offset:256
	v_add_u32_e32 v206, 0x8000, v206
	global_load_dwordx4 v[162:165], v206, s[8:9]
	global_load_dwordx4 v[166:169], v206, s[8:9] offset:256
	v_add_u32_e32 v206, 0x8000, v206
	global_load_dwordx4 v[170:173], v206, s[8:9]
	global_load_dwordx4 v[174:177], v206, s[8:9] offset:256
	v_add_u32_e32 v206, 0x28000, v206
	global_load_dwordx4 v[178:181], v206, s[8:9]
	global_load_dwordx4 v[182:185], v206, s[8:9] offset:256
	v_add_u32_e32 v206, 0x8000, v206
	global_load_dwordx4 v[186:189], v206, s[8:9]
	global_load_dwordx4 v[190:193], v206, s[8:9] offset:256
	v_add_u32_e32 v206, 0x8000, v206
	global_load_dwordx4 v[194:197], v206, s[8:9]
	global_load_dwordx4 v[198:201], v206, s[8:9] offset:256
	v_add_u32_e32 v206, 0x8000, v206
	s_waitcnt vmcnt(12)
	v_lshlrev_b32_e32 v202, 16, v146
	v_and_b32_e32 v203, 0xffff0000, v146
	v_lshlrev_b32_e32 v204, 16, v147
	v_and_b32_e32 v205, 0xffff0000, v147
	v_pk_add_f32 v[124:125], v[124:125], v[202:203]
	v_pk_add_f32 v[126:127], v[126:127], v[204:205]
	v_lshlrev_b32_e32 v202, 16, v148
	v_and_b32_e32 v203, 0xffff0000, v148
	v_lshlrev_b32_e32 v204, 16, v149
	v_and_b32_e32 v205, 0xffff0000, v149
	v_pk_add_f32 v[120:121], v[120:121], v[202:203]
	v_pk_add_f32 v[122:123], v[122:123], v[204:205]
	v_cvt_pk_bf16_f32 v146, v124, v125
	v_cvt_pk_bf16_f32 v147, v126, v127
	v_cvt_pk_bf16_f32 v148, v120, v121
	v_cvt_pk_bf16_f32 v149, v122, v123
	v_pk_mul_f32 v[138:139], v[124:125], v[124:125]
	global_store_dwordx4 v207, v[146:149], s[8:9]
	v_pk_fma_f32 v[138:139], v[126:127], v[126:127], v[138:139]
	v_pk_fma_f32 v[138:139], v[120:121], v[120:121], v[138:139]
	v_pk_fma_f32 v[138:139], v[122:123], v[122:123], v[138:139]
	v_lshlrev_b32_e32 v202, 16, v150
	v_and_b32_e32 v203, 0xffff0000, v150
	v_lshlrev_b32_e32 v204, 16, v151
	v_and_b32_e32 v205, 0xffff0000, v151
	v_pk_add_f32 v[116:117], v[116:117], v[202:203]
	v_pk_add_f32 v[118:119], v[118:119], v[204:205]
	v_lshlrev_b32_e32 v202, 16, v152
	v_and_b32_e32 v203, 0xffff0000, v152
	v_lshlrev_b32_e32 v204, 16, v153
	v_and_b32_e32 v205, 0xffff0000, v153
	v_pk_add_f32 v[112:113], v[112:113], v[202:203]
	v_pk_add_f32 v[114:115], v[114:115], v[204:205]
	v_cvt_pk_bf16_f32 v150, v116, v117
	v_cvt_pk_bf16_f32 v151, v118, v119
	v_cvt_pk_bf16_f32 v152, v112, v113
	v_cvt_pk_bf16_f32 v153, v114, v115
	v_pk_fma_f32 v[138:139], v[116:117], v[116:117], v[138:139]
	global_store_dwordx4 v207, v[150:153], s[8:9] offset:256
	v_pk_fma_f32 v[138:139], v[118:119], v[118:119], v[138:139]
	v_pk_fma_f32 v[138:139], v[112:113], v[112:113], v[138:139]
	v_pk_fma_f32 v[138:139], v[114:115], v[114:115], v[138:139]
	v_add_f32_e32 v214, v138, v139
	v_add_u32_e32 v207, 0x8000, v207
	v_mov_b32_e32 v215, v214
	s_nop 1
	v_permlane16_swap_b32_e32 v214, v215
	s_nop 0
	v_add_f32_e32 v214, v214, v215
	v_mov_b32_e32 v215, v214
	s_nop 1
	v_permlane32_swap_b32_e32 v214, v215
	s_nop 0
	v_add_f32_e32 v214, v214, v215
	s_and_saveexec_b64 s[26:27], s[4:5]
	global_store_dword v210, v214, s[14:15]
	s_mov_b64 exec, s[26:27]
	global_load_dwordx4 v[146:149], v206, s[8:9]
	global_load_dwordx4 v[150:153], v206, s[8:9] offset:256
	s_waitcnt vmcnt(15)
	v_lshlrev_b32_e32 v202, 16, v154
	v_and_b32_e32 v203, 0xffff0000, v154
	v_lshlrev_b32_e32 v204, 16, v155
	v_and_b32_e32 v205, 0xffff0000, v155
	v_pk_add_f32 v[108:109], v[108:109], v[202:203]
	v_pk_add_f32 v[110:111], v[110:111], v[204:205]
	v_lshlrev_b32_e32 v202, 16, v156
	v_and_b32_e32 v203, 0xffff0000, v156
	v_lshlrev_b32_e32 v204, 16, v157
	v_and_b32_e32 v205, 0xffff0000, v157
	v_pk_add_f32 v[104:105], v[104:105], v[202:203]
	v_pk_add_f32 v[106:107], v[106:107], v[204:205]
	v_cvt_pk_bf16_f32 v154, v108, v109
	v_cvt_pk_bf16_f32 v155, v110, v111
	v_cvt_pk_bf16_f32 v156, v104, v105
	v_cvt_pk_bf16_f32 v157, v106, v107
	v_pk_mul_f32 v[138:139], v[108:109], v[108:109]
	global_store_dwordx4 v207, v[154:157], s[8:9]
	v_pk_fma_f32 v[138:139], v[110:111], v[110:111], v[138:139]
	v_pk_fma_f32 v[138:139], v[104:105], v[104:105], v[138:139]
	v_pk_fma_f32 v[138:139], v[106:107], v[106:107], v[138:139]
	v_lshlrev_b32_e32 v202, 16, v158
	v_and_b32_e32 v203, 0xffff0000, v158
	v_lshlrev_b32_e32 v204, 16, v159
	v_and_b32_e32 v205, 0xffff0000, v159
	v_pk_add_f32 v[100:101], v[100:101], v[202:203]
	v_pk_add_f32 v[102:103], v[102:103], v[204:205]
	v_lshlrev_b32_e32 v202, 16, v160
	v_and_b32_e32 v203, 0xffff0000, v160
	v_lshlrev_b32_e32 v204, 16, v161
	v_and_b32_e32 v205, 0xffff0000, v161
	v_pk_add_f32 v[96:97], v[96:97], v[202:203]
	v_pk_add_f32 v[98:99], v[98:99], v[204:205]
	v_cvt_pk_bf16_f32 v158, v100, v101
	v_cvt_pk_bf16_f32 v159, v102, v103
	v_cvt_pk_bf16_f32 v160, v96, v97
	v_cvt_pk_bf16_f32 v161, v98, v99
	v_pk_fma_f32 v[138:139], v[100:101], v[100:101], v[138:139]
	global_store_dwordx4 v207, v[158:161], s[8:9] offset:256
	v_pk_fma_f32 v[138:139], v[102:103], v[102:103], v[138:139]
	v_pk_fma_f32 v[138:139], v[96:97], v[96:97], v[138:139]
	v_pk_fma_f32 v[138:139], v[98:99], v[98:99], v[138:139]
	v_add_f32_e32 v214, v138, v139
	v_add_u32_e32 v207, 0x8000, v207
	v_mov_b32_e32 v215, v214
	s_nop 1
	v_permlane16_swap_b32_e32 v214, v215
	s_nop 0
	v_add_f32_e32 v214, v214, v215
	v_mov_b32_e32 v215, v214
	s_nop 1
	v_permlane32_swap_b32_e32 v214, v215
	s_nop 0
	v_add_f32_e32 v214, v214, v215
	s_and_saveexec_b64 s[26:27], s[4:5]
	global_store_dword v210, v214, s[14:15] offset:1024
	s_mov_b64 exec, s[26:27]
	s_waitcnt vmcnt(16)
	v_lshlrev_b32_e32 v202, 16, v162
	v_and_b32_e32 v203, 0xffff0000, v162
	v_lshlrev_b32_e32 v204, 16, v163
	v_and_b32_e32 v205, 0xffff0000, v163
	v_pk_add_f32 v[92:93], v[92:93], v[202:203]
	v_pk_add_f32 v[94:95], v[94:95], v[204:205]
	v_lshlrev_b32_e32 v202, 16, v164
	v_and_b32_e32 v203, 0xffff0000, v164
	v_lshlrev_b32_e32 v204, 16, v165
	v_and_b32_e32 v205, 0xffff0000, v165
	v_pk_add_f32 v[88:89], v[88:89], v[202:203]
	v_pk_add_f32 v[90:91], v[90:91], v[204:205]
	v_cvt_pk_bf16_f32 v162, v92, v93
	v_cvt_pk_bf16_f32 v163, v94, v95
	v_cvt_pk_bf16_f32 v164, v88, v89
	v_cvt_pk_bf16_f32 v165, v90, v91
	v_pk_mul_f32 v[138:139], v[92:93], v[92:93]
	global_store_dwordx4 v207, v[162:165], s[8:9]
	v_pk_fma_f32 v[138:139], v[94:95], v[94:95], v[138:139]
	v_pk_fma_f32 v[138:139], v[88:89], v[88:89], v[138:139]
	v_pk_fma_f32 v[138:139], v[90:91], v[90:91], v[138:139]
	v_lshlrev_b32_e32 v202, 16, v166
	v_and_b32_e32 v203, 0xffff0000, v166
	v_lshlrev_b32_e32 v204, 16, v167
	v_and_b32_e32 v205, 0xffff0000, v167
	v_pk_add_f32 v[84:85], v[84:85], v[202:203]
	v_pk_add_f32 v[86:87], v[86:87], v[204:205]
	v_lshlrev_b32_e32 v202, 16, v168
	v_and_b32_e32 v203, 0xffff0000, v168
	v_lshlrev_b32_e32 v204, 16, v169
	v_and_b32_e32 v205, 0xffff0000, v169
	v_pk_add_f32 v[80:81], v[80:81], v[202:203]
	v_pk_add_f32 v[82:83], v[82:83], v[204:205]
	v_cvt_pk_bf16_f32 v166, v84, v85
	v_cvt_pk_bf16_f32 v167, v86, v87
	v_cvt_pk_bf16_f32 v168, v80, v81
	v_cvt_pk_bf16_f32 v169, v82, v83
	v_pk_fma_f32 v[138:139], v[84:85], v[84:85], v[138:139]
	global_store_dwordx4 v207, v[166:169], s[8:9] offset:256
	v_pk_fma_f32 v[138:139], v[86:87], v[86:87], v[138:139]
	v_pk_fma_f32 v[138:139], v[80:81], v[80:81], v[138:139]
	v_pk_fma_f32 v[138:139], v[82:83], v[82:83], v[138:139]
	v_add_f32_e32 v214, v138, v139
	v_add_u32_e32 v207, 0x8000, v207
	v_mov_b32_e32 v215, v214
	s_nop 1
	v_permlane16_swap_b32_e32 v214, v215
	s_nop 0
	v_add_f32_e32 v214, v214, v215
	v_mov_b32_e32 v215, v214
	s_nop 1
	v_permlane32_swap_b32_e32 v214, v215
	s_nop 0
	v_add_f32_e32 v214, v214, v215
	s_and_saveexec_b64 s[26:27], s[4:5]
	global_store_dword v210, v214, s[14:15] offset:2048
	s_mov_b64 exec, s[26:27]
	s_waitcnt vmcnt(17)
	v_lshlrev_b32_e32 v202, 16, v170
	v_and_b32_e32 v203, 0xffff0000, v170
	v_lshlrev_b32_e32 v204, 16, v171
	v_and_b32_e32 v205, 0xffff0000, v171
	v_pk_add_f32 v[76:77], v[76:77], v[202:203]
	v_pk_add_f32 v[78:79], v[78:79], v[204:205]
	v_lshlrev_b32_e32 v202, 16, v172
	v_and_b32_e32 v203, 0xffff0000, v172
	v_lshlrev_b32_e32 v204, 16, v173
	v_and_b32_e32 v205, 0xffff0000, v173
	v_pk_add_f32 v[72:73], v[72:73], v[202:203]
	v_pk_add_f32 v[74:75], v[74:75], v[204:205]
	v_cvt_pk_bf16_f32 v170, v76, v77
	v_cvt_pk_bf16_f32 v171, v78, v79
	v_cvt_pk_bf16_f32 v172, v72, v73
	v_cvt_pk_bf16_f32 v173, v74, v75
	v_pk_mul_f32 v[138:139], v[76:77], v[76:77]
	global_store_dwordx4 v207, v[170:173], s[8:9]
	v_pk_fma_f32 v[138:139], v[78:79], v[78:79], v[138:139]
	v_pk_fma_f32 v[138:139], v[72:73], v[72:73], v[138:139]
	v_pk_fma_f32 v[138:139], v[74:75], v[74:75], v[138:139]
	v_lshlrev_b32_e32 v202, 16, v174
	v_and_b32_e32 v203, 0xffff0000, v174
	v_lshlrev_b32_e32 v204, 16, v175
	v_and_b32_e32 v205, 0xffff0000, v175
	v_pk_add_f32 v[68:69], v[68:69], v[202:203]
	v_pk_add_f32 v[70:71], v[70:71], v[204:205]
	v_lshlrev_b32_e32 v202, 16, v176
	v_and_b32_e32 v203, 0xffff0000, v176
	v_lshlrev_b32_e32 v204, 16, v177
	v_and_b32_e32 v205, 0xffff0000, v177
	v_pk_add_f32 v[64:65], v[64:65], v[202:203]
	v_pk_add_f32 v[66:67], v[66:67], v[204:205]
	v_cvt_pk_bf16_f32 v174, v68, v69
	v_cvt_pk_bf16_f32 v175, v70, v71
	v_cvt_pk_bf16_f32 v176, v64, v65
	v_cvt_pk_bf16_f32 v177, v66, v67
	v_pk_fma_f32 v[138:139], v[68:69], v[68:69], v[138:139]
	global_store_dwordx4 v207, v[174:177], s[8:9] offset:256
	v_pk_fma_f32 v[138:139], v[70:71], v[70:71], v[138:139]
	v_pk_fma_f32 v[138:139], v[64:65], v[64:65], v[138:139]
	v_pk_fma_f32 v[138:139], v[66:67], v[66:67], v[138:139]
	v_add_f32_e32 v214, v138, v139
	v_add_u32_e32 v207, 0x28000, v207
	v_mov_b32_e32 v215, v214
	s_nop 1
	v_permlane16_swap_b32_e32 v214, v215
	s_nop 0
	v_add_f32_e32 v214, v214, v215
	v_mov_b32_e32 v215, v214
	s_nop 1
	v_permlane32_swap_b32_e32 v214, v215
	s_nop 0
	v_add_f32_e32 v214, v214, v215
	s_and_saveexec_b64 s[26:27], s[4:5]
	global_store_dword v210, v214, s[14:15] offset:3072
	s_mov_b64 exec, s[26:27]
	v_add_u32_e32 v210, 0x2000, v210
	s_waitcnt vmcnt(18)
	v_lshlrev_b32_e32 v202, 16, v178
	v_and_b32_e32 v203, 0xffff0000, v178
	v_lshlrev_b32_e32 v204, 16, v179
	v_and_b32_e32 v205, 0xffff0000, v179
	v_pk_add_f32 v[60:61], v[60:61], v[202:203]
	v_pk_add_f32 v[62:63], v[62:63], v[204:205]
	v_lshlrev_b32_e32 v202, 16, v180
	v_and_b32_e32 v203, 0xffff0000, v180
	v_lshlrev_b32_e32 v204, 16, v181
	v_and_b32_e32 v205, 0xffff0000, v181
	v_pk_add_f32 v[56:57], v[56:57], v[202:203]
	v_pk_add_f32 v[58:59], v[58:59], v[204:205]
	v_cvt_pk_bf16_f32 v178, v60, v61
	v_cvt_pk_bf16_f32 v179, v62, v63
	v_cvt_pk_bf16_f32 v180, v56, v57
	v_cvt_pk_bf16_f32 v181, v58, v59
	v_pk_mul_f32 v[138:139], v[60:61], v[60:61]
	global_store_dwordx4 v207, v[178:181], s[8:9]
	v_pk_fma_f32 v[138:139], v[62:63], v[62:63], v[138:139]
	v_pk_fma_f32 v[138:139], v[56:57], v[56:57], v[138:139]
	v_pk_fma_f32 v[138:139], v[58:59], v[58:59], v[138:139]
	v_lshlrev_b32_e32 v202, 16, v182
	v_and_b32_e32 v203, 0xffff0000, v182
	v_lshlrev_b32_e32 v204, 16, v183
	v_and_b32_e32 v205, 0xffff0000, v183
	v_pk_add_f32 v[52:53], v[52:53], v[202:203]
	v_pk_add_f32 v[54:55], v[54:55], v[204:205]
	v_lshlrev_b32_e32 v202, 16, v184
	v_and_b32_e32 v203, 0xffff0000, v184
	v_lshlrev_b32_e32 v204, 16, v185
	v_and_b32_e32 v205, 0xffff0000, v185
	v_pk_add_f32 v[48:49], v[48:49], v[202:203]
	v_pk_add_f32 v[50:51], v[50:51], v[204:205]
	v_cvt_pk_bf16_f32 v182, v52, v53
	v_cvt_pk_bf16_f32 v183, v54, v55
	v_cvt_pk_bf16_f32 v184, v48, v49
	v_cvt_pk_bf16_f32 v185, v50, v51
	v_pk_fma_f32 v[138:139], v[52:53], v[52:53], v[138:139]
	global_store_dwordx4 v207, v[182:185], s[8:9] offset:256
	v_pk_fma_f32 v[138:139], v[54:55], v[54:55], v[138:139]
	v_pk_fma_f32 v[138:139], v[48:49], v[48:49], v[138:139]
	v_pk_fma_f32 v[138:139], v[50:51], v[50:51], v[138:139]
	v_add_f32_e32 v214, v138, v139
	v_add_u32_e32 v207, 0x8000, v207
	v_mov_b32_e32 v215, v214
	s_nop 1
	v_permlane16_swap_b32_e32 v214, v215
	s_nop 0
	v_add_f32_e32 v214, v214, v215
	v_mov_b32_e32 v215, v214
	s_nop 1
	v_permlane32_swap_b32_e32 v214, v215
	s_nop 0
	v_add_f32_e32 v214, v214, v215
	s_and_saveexec_b64 s[26:27], s[4:5]
	global_store_dword v210, v214, s[14:15]
	s_mov_b64 exec, s[26:27]
	s_waitcnt vmcnt(19)
	v_lshlrev_b32_e32 v202, 16, v186
	v_and_b32_e32 v203, 0xffff0000, v186
	v_lshlrev_b32_e32 v204, 16, v187
	v_and_b32_e32 v205, 0xffff0000, v187
	v_pk_add_f32 v[44:45], v[44:45], v[202:203]
	v_pk_add_f32 v[46:47], v[46:47], v[204:205]
	v_lshlrev_b32_e32 v202, 16, v188
	v_and_b32_e32 v203, 0xffff0000, v188
	v_lshlrev_b32_e32 v204, 16, v189
	v_and_b32_e32 v205, 0xffff0000, v189
	v_pk_add_f32 v[40:41], v[40:41], v[202:203]
	v_pk_add_f32 v[42:43], v[42:43], v[204:205]
	v_cvt_pk_bf16_f32 v186, v44, v45
	v_cvt_pk_bf16_f32 v187, v46, v47
	v_cvt_pk_bf16_f32 v188, v40, v41
	v_cvt_pk_bf16_f32 v189, v42, v43
	v_pk_mul_f32 v[138:139], v[44:45], v[44:45]
	global_store_dwordx4 v207, v[186:189], s[8:9]
	v_pk_fma_f32 v[138:139], v[46:47], v[46:47], v[138:139]
	v_pk_fma_f32 v[138:139], v[40:41], v[40:41], v[138:139]
	v_pk_fma_f32 v[138:139], v[42:43], v[42:43], v[138:139]
	v_lshlrev_b32_e32 v202, 16, v190
	v_and_b32_e32 v203, 0xffff0000, v190
	v_lshlrev_b32_e32 v204, 16, v191
	v_and_b32_e32 v205, 0xffff0000, v191
	v_pk_add_f32 v[36:37], v[36:37], v[202:203]
	v_pk_add_f32 v[38:39], v[38:39], v[204:205]
	v_lshlrev_b32_e32 v202, 16, v192
	v_and_b32_e32 v203, 0xffff0000, v192
	v_lshlrev_b32_e32 v204, 16, v193
	v_and_b32_e32 v205, 0xffff0000, v193
	v_pk_add_f32 v[32:33], v[32:33], v[202:203]
	v_pk_add_f32 v[34:35], v[34:35], v[204:205]
	v_cvt_pk_bf16_f32 v190, v36, v37
	v_cvt_pk_bf16_f32 v191, v38, v39
	v_cvt_pk_bf16_f32 v192, v32, v33
	v_cvt_pk_bf16_f32 v193, v34, v35
	v_pk_fma_f32 v[138:139], v[36:37], v[36:37], v[138:139]
	global_store_dwordx4 v207, v[190:193], s[8:9] offset:256
	v_pk_fma_f32 v[138:139], v[38:39], v[38:39], v[138:139]
	v_pk_fma_f32 v[138:139], v[32:33], v[32:33], v[138:139]
	v_pk_fma_f32 v[138:139], v[34:35], v[34:35], v[138:139]
	v_add_f32_e32 v214, v138, v139
	v_add_u32_e32 v207, 0x8000, v207
	v_mov_b32_e32 v215, v214
	s_nop 1
	v_permlane16_swap_b32_e32 v214, v215
	s_nop 0
	v_add_f32_e32 v214, v214, v215
	v_mov_b32_e32 v215, v214
	s_nop 1
	v_permlane32_swap_b32_e32 v214, v215
	s_nop 0
	v_add_f32_e32 v214, v214, v215
	s_and_saveexec_b64 s[26:27], s[4:5]
	global_store_dword v210, v214, s[14:15] offset:1024
	s_mov_b64 exec, s[26:27]
	s_waitcnt vmcnt(20)
	v_lshlrev_b32_e32 v202, 16, v194
	v_and_b32_e32 v203, 0xffff0000, v194
	v_lshlrev_b32_e32 v204, 16, v195
	v_and_b32_e32 v205, 0xffff0000, v195
	v_pk_add_f32 v[28:29], v[28:29], v[202:203]
	v_pk_add_f32 v[30:31], v[30:31], v[204:205]
	v_lshlrev_b32_e32 v202, 16, v196
	v_and_b32_e32 v203, 0xffff0000, v196
	v_lshlrev_b32_e32 v204, 16, v197
	v_and_b32_e32 v205, 0xffff0000, v197
	v_pk_add_f32 v[24:25], v[24:25], v[202:203]
	v_pk_add_f32 v[26:27], v[26:27], v[204:205]
	v_cvt_pk_bf16_f32 v194, v28, v29
	v_cvt_pk_bf16_f32 v195, v30, v31
	v_cvt_pk_bf16_f32 v196, v24, v25
	v_cvt_pk_bf16_f32 v197, v26, v27
	v_pk_mul_f32 v[138:139], v[28:29], v[28:29]
	global_store_dwordx4 v207, v[194:197], s[8:9]
	v_pk_fma_f32 v[138:139], v[30:31], v[30:31], v[138:139]
	v_pk_fma_f32 v[138:139], v[24:25], v[24:25], v[138:139]
	v_pk_fma_f32 v[138:139], v[26:27], v[26:27], v[138:139]
	v_lshlrev_b32_e32 v202, 16, v198
	v_and_b32_e32 v203, 0xffff0000, v198
	v_lshlrev_b32_e32 v204, 16, v199
	v_and_b32_e32 v205, 0xffff0000, v199
	v_pk_add_f32 v[20:21], v[20:21], v[202:203]
	v_pk_add_f32 v[22:23], v[22:23], v[204:205]
	v_lshlrev_b32_e32 v202, 16, v200
	v_and_b32_e32 v203, 0xffff0000, v200
	v_lshlrev_b32_e32 v204, 16, v201
	v_and_b32_e32 v205, 0xffff0000, v201
	v_pk_add_f32 v[16:17], v[16:17], v[202:203]
	v_pk_add_f32 v[18:19], v[18:19], v[204:205]
	v_cvt_pk_bf16_f32 v198, v20, v21
	v_cvt_pk_bf16_f32 v199, v22, v23
	v_cvt_pk_bf16_f32 v200, v16, v17
	v_cvt_pk_bf16_f32 v201, v18, v19
	v_pk_fma_f32 v[138:139], v[20:21], v[20:21], v[138:139]
	global_store_dwordx4 v207, v[198:201], s[8:9] offset:256
	v_pk_fma_f32 v[138:139], v[22:23], v[22:23], v[138:139]
	v_pk_fma_f32 v[138:139], v[16:17], v[16:17], v[138:139]
	v_pk_fma_f32 v[138:139], v[18:19], v[18:19], v[138:139]
	v_add_f32_e32 v214, v138, v139
	v_add_u32_e32 v207, 0x8000, v207
	v_mov_b32_e32 v215, v214
	s_nop 1
	v_permlane16_swap_b32_e32 v214, v215
	s_nop 0
	v_add_f32_e32 v214, v214, v215
	v_mov_b32_e32 v215, v214
	s_nop 1
	v_permlane32_swap_b32_e32 v214, v215
	s_nop 0
	v_add_f32_e32 v214, v214, v215
	s_and_saveexec_b64 s[26:27], s[4:5]
	global_store_dword v210, v214, s[14:15] offset:2048
	s_mov_b64 exec, s[26:27]
	s_waitcnt vmcnt(18)
	v_lshlrev_b32_e32 v202, 16, v146
	v_and_b32_e32 v203, 0xffff0000, v146
	v_lshlrev_b32_e32 v204, 16, v147
	v_and_b32_e32 v205, 0xffff0000, v147
	v_pk_add_f32 v[12:13], v[12:13], v[202:203]
	v_pk_add_f32 v[14:15], v[14:15], v[204:205]
	v_lshlrev_b32_e32 v202, 16, v148
	v_and_b32_e32 v203, 0xffff0000, v148
	v_lshlrev_b32_e32 v204, 16, v149
	v_and_b32_e32 v205, 0xffff0000, v149
	v_pk_add_f32 v[8:9], v[8:9], v[202:203]
	v_pk_add_f32 v[10:11], v[10:11], v[204:205]
	v_cvt_pk_bf16_f32 v146, v12, v13
	v_cvt_pk_bf16_f32 v147, v14, v15
	v_cvt_pk_bf16_f32 v148, v8, v9
	v_cvt_pk_bf16_f32 v149, v10, v11
	v_pk_mul_f32 v[138:139], v[12:13], v[12:13]
	global_store_dwordx4 v207, v[146:149], s[8:9]
	v_pk_fma_f32 v[138:139], v[14:15], v[14:15], v[138:139]
	v_pk_fma_f32 v[138:139], v[8:9], v[8:9], v[138:139]
	v_pk_fma_f32 v[138:139], v[10:11], v[10:11], v[138:139]
	v_lshlrev_b32_e32 v202, 16, v150
	v_and_b32_e32 v203, 0xffff0000, v150
	v_lshlrev_b32_e32 v204, 16, v151
	v_and_b32_e32 v205, 0xffff0000, v151
	v_pk_add_f32 v[4:5], v[4:5], v[202:203]
	v_pk_add_f32 v[6:7], v[6:7], v[204:205]
	v_lshlrev_b32_e32 v202, 16, v152
	v_and_b32_e32 v203, 0xffff0000, v152
	v_lshlrev_b32_e32 v204, 16, v153
	v_and_b32_e32 v205, 0xffff0000, v153
	v_pk_add_f32 v[0:1], v[0:1], v[202:203]
	v_pk_add_f32 v[2:3], v[2:3], v[204:205]
	v_cvt_pk_bf16_f32 v150, v4, v5
	v_cvt_pk_bf16_f32 v151, v6, v7
	v_cvt_pk_bf16_f32 v152, v0, v1
	v_cvt_pk_bf16_f32 v153, v2, v3
	v_pk_fma_f32 v[138:139], v[4:5], v[4:5], v[138:139]
	global_store_dwordx4 v207, v[150:153], s[8:9] offset:256
	v_pk_fma_f32 v[138:139], v[6:7], v[6:7], v[138:139]
	v_pk_fma_f32 v[138:139], v[0:1], v[0:1], v[138:139]
	v_pk_fma_f32 v[138:139], v[2:3], v[2:3], v[138:139]
	v_add_f32_e32 v214, v138, v139
	v_add_u32_e32 v207, 0x8000, v207
	v_mov_b32_e32 v215, v214
	s_nop 1
	v_permlane16_swap_b32_e32 v214, v215
	s_nop 0
	v_add_f32_e32 v214, v214, v215
	v_mov_b32_e32 v215, v214
	s_nop 1
	v_permlane32_swap_b32_e32 v214, v215
	s_nop 0
	v_add_f32_e32 v214, v214, v215
	s_and_saveexec_b64 s[26:27], s[4:5]
	global_store_dword v210, v214, s[14:15] offset:3072
	s_mov_b64 exec, s[26:27]
	s_branch .LBB0_870

.LBB0_921:
	s_add_u32 s8, s6, 0xfffe0080
	s_addc_u32 s9, s7, -1
	s_add_i32 s84, 0, 0x10000
	v_add_u32_e32 v140, s84, v253
	ds_read_b128 v[128:131], v140
	ds_read_b128 v[132:135], v140 offset:1024
	ds_read_b128 v[136:139], v140 offset:2048
	ds_read_b128 v[140:143], v140 offset:3072
	s_cmp_eq_u32 s73, 12
	s_cselect_b32 s11, s15, s9
	s_cselect_b32 s10, s39, s8
	s_cselect_b32 s9, s65, vcc_hi
	s_cselect_b32 s8, s67, vcc_lo
	s_add_i32 m0, s46, 0xc000
	ds_read_b128 v[144:147], v251
	ds_read_b128 v[148:151], v251 offset:1024
	ds_read_b128 v[152:155], v251 offset:2048
	ds_read_b128 v[156:159], v251 offset:3072
	ds_read_b128 v[160:163], v251 offset:4096
	ds_read_b128 v[164:167], v251 offset:5120
	ds_read_b128 v[168:171], v251 offset:6144
	ds_read_b128 v[172:175], v251 offset:7168
	global_load_lds_dwordx4 v220, s[6:7]
	s_add_i32 m0, s46, 0xe000
	s_nop 0
	global_load_lds_dwordx4 v222, s[6:7]
	s_waitcnt lgkmcnt(8)
	s_barrier
	s_waitcnt lgkmcnt(0)
	v_mfma_f32_16x16x32_bf16 v[124:127], v[128:131], v[144:147], v[124:127]
	v_mfma_f32_16x16x32_bf16 v[120:123], v[136:139], v[144:147], v[120:123]
	v_mfma_f32_16x16x32_bf16 v[92:95], v[128:131], v[152:155], v[92:95]
	v_mfma_f32_16x16x32_bf16 v[44:47], v[136:139], v[152:155], v[44:47]
	v_mfma_f32_16x16x32_bf16 v[84:87], v[128:131], v[160:163], v[84:87]
	v_mfma_f32_16x16x32_bf16 v[40:43], v[136:139], v[160:163], v[40:43]
	v_mfma_f32_16x16x32_bf16 v[76:79], v[128:131], v[168:171], v[76:79]
	v_mfma_f32_16x16x32_bf16 v[36:39], v[136:139], v[168:171], v[36:39]
	v_mfma_f32_16x16x32_bf16 v[124:127], v[132:135], v[148:151], v[124:127]
	v_mfma_f32_16x16x32_bf16 v[120:123], v[140:143], v[148:151], v[120:123]
	v_mfma_f32_16x16x32_bf16 v[92:95], v[132:135], v[156:159], v[92:95]
	v_mfma_f32_16x16x32_bf16 v[44:47], v[140:143], v[156:159], v[44:47]
	v_mfma_f32_16x16x32_bf16 v[84:87], v[132:135], v[164:167], v[84:87]
	v_mfma_f32_16x16x32_bf16 v[40:43], v[140:143], v[164:167], v[40:43]
	v_mfma_f32_16x16x32_bf16 v[76:79], v[132:135], v[172:175], v[76:79]
	v_mfma_f32_16x16x32_bf16 v[36:39], v[140:143], v[172:175], v[36:39]
	s_barrier
	s_add_i32 s86, 0, 0x14000
	s_add_i32 s84, s84, s88
	v_add_u32_e32 v188, s86, v253
	s_add_u32 s98, s8, s40
	s_addc_u32 s99, s9, s41
	s_mov_b32 m0, s84
	ds_read_b128 v[176:179], v188
	ds_read_b128 v[180:183], v188 offset:1024
	ds_read_b128 v[184:187], v188 offset:2048
	ds_read_b128 v[188:191], v188 offset:3072
	global_load_lds_dwordx4 v208, s[8:9]
	s_add_i32 m0, s84, 0x2000
	s_nop 0
	global_load_lds_dwordx4 v214, s[8:9]
	s_barrier
	s_waitcnt lgkmcnt(0)
	v_mfma_f32_16x16x32_bf16 v[116:119], v[176:179], v[144:147], v[116:119]
	v_mfma_f32_16x16x32_bf16 v[112:115], v[184:187], v[144:147], v[112:115]
	v_mfma_f32_16x16x32_bf16 v[88:91], v[176:179], v[152:155], v[88:91]
	v_mfma_f32_16x16x32_bf16 v[32:35], v[184:187], v[152:155], v[32:35]
	v_mfma_f32_16x16x32_bf16 v[80:83], v[176:179], v[160:163], v[80:83]
	v_mfma_f32_16x16x32_bf16 v[28:31], v[184:187], v[160:163], v[28:31]
	v_mfma_f32_16x16x32_bf16 v[72:75], v[176:179], v[168:171], v[72:75]
	v_mfma_f32_16x16x32_bf16 v[24:27], v[184:187], v[168:171], v[24:27]
	v_mfma_f32_16x16x32_bf16 v[116:119], v[180:183], v[148:151], v[116:119]
	v_mfma_f32_16x16x32_bf16 v[112:115], v[188:191], v[148:151], v[112:115]
	v_mfma_f32_16x16x32_bf16 v[88:91], v[180:183], v[156:159], v[88:91]
	v_mfma_f32_16x16x32_bf16 v[32:35], v[188:191], v[156:159], v[32:35]
	v_mfma_f32_16x16x32_bf16 v[80:83], v[180:183], v[164:167], v[80:83]
	v_mfma_f32_16x16x32_bf16 v[28:31], v[188:191], v[164:167], v[28:31]
	v_mfma_f32_16x16x32_bf16 v[72:75], v[180:183], v[172:175], v[72:75]
	v_mfma_f32_16x16x32_bf16 v[24:27], v[188:191], v[172:175], v[24:27]
	s_mov_b32 m0, s46
	s_add_u32 s100, s10, s40
	s_addc_u32 s101, s11, s41
	s_barrier
	ds_read_b128 v[144:147], v251 offset:16384
	ds_read_b128 v[148:151], v251 offset:17408
	ds_read_b128 v[152:155], v251 offset:18432
	ds_read_b128 v[156:159], v251 offset:19456
	ds_read_b128 v[160:163], v251 offset:20480
	ds_read_b128 v[164:167], v251 offset:21504
	ds_read_b128 v[168:171], v251 offset:22528
	ds_read_b128 v[172:175], v251 offset:23552
	global_load_lds_dwordx4 v218, s[10:11]
	s_mov_b32 m0, s50
	s_nop 0
	global_load_lds_dwordx4 v216, s[10:11]
	s_barrier
	s_waitcnt lgkmcnt(0)
	v_mfma_f32_16x16x32_bf16 v[68:71], v[128:131], v[144:147], v[68:71]
	v_mfma_f32_16x16x32_bf16 v[20:23], v[136:139], v[144:147], v[20:23]
	v_mfma_f32_16x16x32_bf16 v[64:67], v[128:131], v[152:155], v[64:67]
	v_mfma_f32_16x16x32_bf16 v[16:19], v[136:139], v[152:155], v[16:19]
	v_mfma_f32_16x16x32_bf16 v[60:63], v[128:131], v[160:163], v[60:63]
	v_mfma_f32_16x16x32_bf16 v[12:15], v[136:139], v[160:163], v[12:15]
	v_mfma_f32_16x16x32_bf16 v[108:111], v[128:131], v[168:171], v[108:111]
	v_mfma_f32_16x16x32_bf16 v[104:107], v[136:139], v[168:171], v[104:107]
	v_mfma_f32_16x16x32_bf16 v[68:71], v[132:135], v[148:151], v[68:71]
	v_mfma_f32_16x16x32_bf16 v[20:23], v[140:143], v[148:151], v[20:23]
	v_mfma_f32_16x16x32_bf16 v[64:67], v[132:135], v[156:159], v[64:67]
	v_mfma_f32_16x16x32_bf16 v[16:19], v[140:143], v[156:159], v[16:19]
	v_mfma_f32_16x16x32_bf16 v[60:63], v[132:135], v[164:167], v[60:63]
	v_mfma_f32_16x16x32_bf16 v[12:15], v[140:143], v[164:167], v[12:15]
	v_mfma_f32_16x16x32_bf16 v[108:111], v[132:135], v[172:175], v[108:111]
	v_mfma_f32_16x16x32_bf16 v[104:107], v[140:143], v[172:175], v[104:107]
	s_barrier
	s_add_u32 s84, s8, 0x40000
	s_addc_u32 s85, s9, 0
	s_add_i32 s86, s86, s88
	s_mov_b32 m0, s86
	s_nop 0
	global_load_lds_dwordx4 v208, s[84:85]
	s_add_i32 m0, s86, 0x2000
	s_nop 0
	global_load_lds_dwordx4 v214, s[84:85]
	s_waitcnt vmcnt(6)
	s_barrier
	v_mfma_f32_16x16x32_bf16 v[56:59], v[176:179], v[144:147], v[56:59]
	v_mfma_f32_16x16x32_bf16 v[8:11], v[184:187], v[144:147], v[8:11]
	v_mfma_f32_16x16x32_bf16 v[52:55], v[176:179], v[152:155], v[52:55]
	v_mfma_f32_16x16x32_bf16 v[4:7], v[184:187], v[152:155], v[4:7]
	v_mfma_f32_16x16x32_bf16 v[48:51], v[176:179], v[160:163], v[48:51]
	v_mfma_f32_16x16x32_bf16 v[0:3], v[184:187], v[160:163], v[0:3]
	v_mfma_f32_16x16x32_bf16 v[100:103], v[176:179], v[168:171], v[100:103]
	v_mfma_f32_16x16x32_bf16 v[96:99], v[184:187], v[168:171], v[96:99]
	v_mfma_f32_16x16x32_bf16 v[56:59], v[180:183], v[148:151], v[56:59]
	v_mfma_f32_16x16x32_bf16 v[8:11], v[188:191], v[148:151], v[8:11]
	v_mfma_f32_16x16x32_bf16 v[52:55], v[180:183], v[156:159], v[52:55]
	v_mfma_f32_16x16x32_bf16 v[4:7], v[188:191], v[156:159], v[4:7]
	v_mfma_f32_16x16x32_bf16 v[48:51], v[180:183], v[164:167], v[48:51]
	v_mfma_f32_16x16x32_bf16 v[0:3], v[188:191], v[164:167], v[0:3]
	v_mfma_f32_16x16x32_bf16 v[100:103], v[180:183], v[172:175], v[100:103]
	v_mfma_f32_16x16x32_bf16 v[96:99], v[188:191], v[172:175], v[96:99]
	s_add_i32 s84, 0, 0x18000
	v_add_u32_e32 v140, s84, v253
	s_barrier
	ds_read_b128 v[128:131], v140
	ds_read_b128 v[132:135], v140 offset:1024
	ds_read_b128 v[136:139], v140 offset:2048
	ds_read_b128 v[140:143], v140 offset:3072
	s_add_u32 s10, s10, 0x20000
	s_addc_u32 s11, s11, 0
	s_mov_b32 m0, s51
	ds_read_b128 v[144:147], v251 offset:32768
	ds_read_b128 v[148:151], v251 offset:33792
	ds_read_b128 v[152:155], v251 offset:34816
	ds_read_b128 v[156:159], v251 offset:35840
	ds_read_b128 v[160:163], v251 offset:36864
	ds_read_b128 v[164:167], v251 offset:37888
	ds_read_b128 v[168:171], v251 offset:38912
	ds_read_b128 v[172:175], v251 offset:39936
	global_load_lds_dwordx4 v218, s[10:11]
	s_mov_b32 m0, s34
	s_nop 0
	global_load_lds_dwordx4 v216, s[10:11]
	s_waitcnt lgkmcnt(8)
	s_barrier
	s_waitcnt lgkmcnt(0)
	v_mfma_f32_16x16x32_bf16 v[124:127], v[128:131], v[144:147], v[124:127]
	v_mfma_f32_16x16x32_bf16 v[120:123], v[136:139], v[144:147], v[120:123]
	v_mfma_f32_16x16x32_bf16 v[92:95], v[128:131], v[152:155], v[92:95]
	v_mfma_f32_16x16x32_bf16 v[44:47], v[136:139], v[152:155], v[44:47]
	v_mfma_f32_16x16x32_bf16 v[84:87], v[128:131], v[160:163], v[84:87]
	v_mfma_f32_16x16x32_bf16 v[40:43], v[136:139], v[160:163], v[40:43]
	v_mfma_f32_16x16x32_bf16 v[76:79], v[128:131], v[168:171], v[76:79]
	v_mfma_f32_16x16x32_bf16 v[36:39], v[136:139], v[168:171], v[36:39]
	v_mfma_f32_16x16x32_bf16 v[124:127], v[132:135], v[148:151], v[124:127]
	v_mfma_f32_16x16x32_bf16 v[120:123], v[140:143], v[148:151], v[120:123]
	v_mfma_f32_16x16x32_bf16 v[92:95], v[132:135], v[156:159], v[92:95]
	v_mfma_f32_16x16x32_bf16 v[44:47], v[140:143], v[156:159], v[44:47]
	v_mfma_f32_16x16x32_bf16 v[84:87], v[132:135], v[164:167], v[84:87]
	v_mfma_f32_16x16x32_bf16 v[40:43], v[140:143], v[164:167], v[40:43]
	v_mfma_f32_16x16x32_bf16 v[76:79], v[132:135], v[172:175], v[76:79]
	v_mfma_f32_16x16x32_bf16 v[36:39], v[140:143], v[172:175], v[36:39]
	s_barrier
	s_add_i32 s10, 0, 0x1c000
	s_add_i32 s11, s84, s88
	v_add_u32_e32 v188, s10, v253
	s_mov_b32 m0, s11
	ds_read_b128 v[176:179], v188
	ds_read_b128 v[180:183], v188 offset:1024
	ds_read_b128 v[184:187], v188 offset:2048
	ds_read_b128 v[188:191], v188 offset:3072
	global_load_lds_dwordx4 v208, s[98:99]
	s_add_i32 m0, s11, 0x2000
	s_nop 0
	global_load_lds_dwordx4 v214, s[98:99]
	s_barrier
	s_waitcnt lgkmcnt(0)
	v_mfma_f32_16x16x32_bf16 v[116:119], v[176:179], v[144:147], v[116:119]
	v_mfma_f32_16x16x32_bf16 v[112:115], v[184:187], v[144:147], v[112:115]
	v_mfma_f32_16x16x32_bf16 v[88:91], v[176:179], v[152:155], v[88:91]
	v_mfma_f32_16x16x32_bf16 v[32:35], v[184:187], v[152:155], v[32:35]
	v_mfma_f32_16x16x32_bf16 v[80:83], v[176:179], v[160:163], v[80:83]
	v_mfma_f32_16x16x32_bf16 v[28:31], v[184:187], v[160:163], v[28:31]
	v_mfma_f32_16x16x32_bf16 v[72:75], v[176:179], v[168:171], v[72:75]
	v_mfma_f32_16x16x32_bf16 v[24:27], v[184:187], v[168:171], v[24:27]
	v_mfma_f32_16x16x32_bf16 v[116:119], v[180:183], v[148:151], v[116:119]
	v_mfma_f32_16x16x32_bf16 v[112:115], v[188:191], v[148:151], v[112:115]
	v_mfma_f32_16x16x32_bf16 v[88:91], v[180:183], v[156:159], v[88:91]
	v_mfma_f32_16x16x32_bf16 v[32:35], v[188:191], v[156:159], v[32:35]
	v_mfma_f32_16x16x32_bf16 v[80:83], v[180:183], v[164:167], v[80:83]
	v_mfma_f32_16x16x32_bf16 v[28:31], v[188:191], v[164:167], v[28:31]
	v_mfma_f32_16x16x32_bf16 v[72:75], v[180:183], v[172:175], v[72:75]
	v_mfma_f32_16x16x32_bf16 v[24:27], v[188:191], v[172:175], v[24:27]
	s_mov_b32 m0, s92
	s_barrier
	ds_read_b128 v[144:147], v251 offset:49152
	ds_read_b128 v[148:151], v251 offset:50176
	ds_read_b128 v[152:155], v251 offset:51200
	ds_read_b128 v[156:159], v251 offset:52224
	ds_read_b128 v[160:163], v251 offset:53248
	ds_read_b128 v[164:167], v251 offset:54272
	ds_read_b128 v[168:171], v251 offset:55296
	ds_read_b128 v[172:175], v251 offset:56320
	global_load_lds_dwordx4 v218, s[100:101]
	s_mov_b32 m0, s93
	s_nop 0
	global_load_lds_dwordx4 v216, s[100:101]
	s_barrier
	s_waitcnt lgkmcnt(0)
	v_mfma_f32_16x16x32_bf16 v[68:71], v[128:131], v[144:147], v[68:71]
	v_mfma_f32_16x16x32_bf16 v[20:23], v[136:139], v[144:147], v[20:23]
	v_mfma_f32_16x16x32_bf16 v[64:67], v[128:131], v[152:155], v[64:67]
	v_mfma_f32_16x16x32_bf16 v[16:19], v[136:139], v[152:155], v[16:19]
	v_mfma_f32_16x16x32_bf16 v[60:63], v[128:131], v[160:163], v[60:63]
	v_mfma_f32_16x16x32_bf16 v[12:15], v[136:139], v[160:163], v[12:15]
	v_mfma_f32_16x16x32_bf16 v[108:111], v[128:131], v[168:171], v[108:111]
	v_mfma_f32_16x16x32_bf16 v[104:107], v[136:139], v[168:171], v[104:107]
	v_mfma_f32_16x16x32_bf16 v[68:71], v[132:135], v[148:151], v[68:71]
	v_mfma_f32_16x16x32_bf16 v[20:23], v[140:143], v[148:151], v[20:23]
	v_mfma_f32_16x16x32_bf16 v[64:67], v[132:135], v[156:159], v[64:67]
	v_mfma_f32_16x16x32_bf16 v[16:19], v[140:143], v[156:159], v[16:19]
	v_mfma_f32_16x16x32_bf16 v[60:63], v[132:135], v[164:167], v[60:63]
	v_mfma_f32_16x16x32_bf16 v[12:15], v[140:143], v[164:167], v[12:15]
	v_mfma_f32_16x16x32_bf16 v[108:111], v[132:135], v[172:175], v[108:111]
	v_mfma_f32_16x16x32_bf16 v[104:107], v[140:143], v[172:175], v[104:107]
	s_barrier
	s_add_u32 s8, s8, 0x40080
	s_addc_u32 s9, s9, 0
	s_add_i32 s10, s10, s88
	s_mov_b32 m0, s10
	s_nop 0
	global_load_lds_dwordx4 v208, s[8:9]
	s_add_i32 m0, s10, 0x2000
	s_nop 0
	global_load_lds_dwordx4 v214, s[8:9]
	s_waitcnt vmcnt(6)
	s_barrier
	v_mfma_f32_16x16x32_bf16 v[56:59], v[176:179], v[144:147], v[56:59]
	v_mfma_f32_16x16x32_bf16 v[8:11], v[184:187], v[144:147], v[8:11]
	v_mfma_f32_16x16x32_bf16 v[52:55], v[176:179], v[152:155], v[52:55]
	v_mfma_f32_16x16x32_bf16 v[4:7], v[184:187], v[152:155], v[4:7]
	v_mfma_f32_16x16x32_bf16 v[48:51], v[176:179], v[160:163], v[48:51]
	v_mfma_f32_16x16x32_bf16 v[0:3], v[184:187], v[160:163], v[0:3]
	v_mfma_f32_16x16x32_bf16 v[100:103], v[176:179], v[168:171], v[100:103]
	v_mfma_f32_16x16x32_bf16 v[96:99], v[184:187], v[168:171], v[96:99]
	v_mfma_f32_16x16x32_bf16 v[56:59], v[180:183], v[148:151], v[56:59]
	v_mfma_f32_16x16x32_bf16 v[8:11], v[188:191], v[148:151], v[8:11]
	v_mfma_f32_16x16x32_bf16 v[52:55], v[180:183], v[156:159], v[52:55]
	v_mfma_f32_16x16x32_bf16 v[4:7], v[188:191], v[156:159], v[4:7]
	v_mfma_f32_16x16x32_bf16 v[48:51], v[180:183], v[164:167], v[48:51]
	v_mfma_f32_16x16x32_bf16 v[0:3], v[188:191], v[164:167], v[0:3]
	v_mfma_f32_16x16x32_bf16 v[100:103], v[180:183], v[172:175], v[100:103]
	v_mfma_f32_16x16x32_bf16 v[96:99], v[188:191], v[172:175], v[96:99]
	s_add_i32 s73, s73, 2
	s_add_u32 s6, s6, 0x100
	s_addc_u32 s7, s7, 0
	s_add_u32 vcc_lo, vcc_lo, 0x100
	s_addc_u32 vcc_hi, vcc_hi, 0
	s_cmp_gt_u32 s73, 13
	s_barrier
	s_cbranch_scc0 .LBB0_921
	s_lshl_b32 s6, s38, 8
	v_mov_b32_e32 v250, v210
	v_mov_b32_e32 v254, v249
	s_add_i32 s6, s6, s90
	v_mov_b64_e32 v[242:243], s[44:45]
	v_add_u32_e32 v234, s6, v254
	v_ashrrev_i32_e32 v235, 31, v234
	v_mbcnt_lo_u32_b32 v212, -1, 0
	v_mbcnt_hi_u32_b32 v212, -1, v212
	v_lshlrev_b32_e32 v244, 6, v234
	v_and_b32_e32 v212, 48, v212
	v_add_u32_e32 v212, v244, v212
	v_add_u32_e32 v213, 0x1000, v212
	v_add_u32_e32 v245, 0x1000, v244
	global_load_dwordx4 v[192:195], v212, s[20:21]
	global_load_dwordx4 v[196:199], v212, s[20:21] offset:1024
	global_load_dwordx4 v[200:203], v213, s[20:21] offset:2048
	global_load_dwordx4 v[204:207], v213, s[20:21] offset:3072
	global_load_dwordx4 v[160:163], v244, s[20:21] offset:2096
	global_load_dwordx4 v[164:167], v244, s[20:21] offset:2080
	global_load_dwordx4 v[176:179], v244, s[20:21] offset:2064
	global_load_dwordx4 v[180:183], v244, s[20:21] offset:2048
	global_load_dwordx4 v[168:171], v244, s[20:21] offset:3120
	global_load_dwordx4 v[172:175], v244, s[20:21] offset:3104
	global_load_dwordx4 v[184:187], v244, s[20:21] offset:3088
	global_load_dwordx4 v[188:191], v244, s[20:21] offset:3072
	global_load_dwordx4 v[144:147], v245, s[20:21] offset:48
	global_load_dwordx4 v[148:151], v245, s[20:21] offset:32
	global_load_dwordx4 v[152:155], v245, s[20:21] offset:16
	global_load_dwordx4 v[156:159], v245, s[20:21]
	global_load_dwordx4 v[128:131], v245, s[20:21] offset:1072
	global_load_dwordx4 v[132:135], v245, s[20:21] offset:1056
	global_load_dwordx4 v[136:139], v245, s[20:21] offset:1040
	global_load_dwordx4 v[140:143], v245, s[20:21] offset:1024
	v_add_u32_e32 v236, 16, v234
	v_ashrrev_i32_e32 v237, 31, v236
	v_add_u32_e32 v238, 32, v234
	v_ashrrev_i32_e32 v239, 31, v238
	v_add_u32_e32 v232, 48, v234
	v_ashrrev_i32_e32 v233, 31, v232
	v_add_u32_e32 v230, 64, v234
	v_ashrrev_i32_e32 v231, 31, v230
	v_add_u32_e32 v228, 0x50, v234
	v_ashrrev_i32_e32 v229, 31, v228
	v_add_u32_e32 v224, 0x60, v234
	v_ashrrev_i32_e32 v225, 31, v224
	v_add_u32_e32 v226, 0x70, v234
	v_ashrrev_i32_e32 v227, 31, v226
	s_lshl_b32 s14, s14, 7
	s_or_b32 s14, s14, s35
	s_waitcnt vmcnt(16)
	v_pk_add_f32 v[192:193], v[192:193], v[194:195]
	s_nop 0
	v_add_f32_e32 v246, v192, v193
	v_mov_b32_e32 v247, v246
	s_nop 1
	v_permlane16_swap_b32_e32 v246, v247
	s_nop 0
	v_add_f32_e32 v246, v246, v247
	v_mov_b32_e32 v247, v246
	s_nop 1
	v_permlane32_swap_b32_e32 v246, v247
	s_nop 0
	v_add_f32_e32 v193, v246, v247
	v_pk_add_f32 v[196:197], v[196:197], v[198:199]
	s_nop 0
	v_add_f32_e32 v246, v196, v197
	v_mov_b32_e32 v247, v246
	s_nop 1
	v_permlane16_swap_b32_e32 v246, v247
	s_nop 0
	v_add_f32_e32 v246, v246, v247
	v_mov_b32_e32 v247, v246
	s_nop 1
	v_permlane32_swap_b32_e32 v246, v247
	s_nop 0
	v_add_f32_e32 v192, v246, v247
	v_pk_add_f32 v[200:201], v[200:201], v[202:203]
	s_nop 0
	v_add_f32_e32 v246, v200, v201
	v_mov_b32_e32 v247, v246
	s_nop 1
	v_permlane16_swap_b32_e32 v246, v247
	s_nop 0
	v_add_f32_e32 v246, v246, v247
	v_mov_b32_e32 v247, v246
	s_nop 1
	v_permlane32_swap_b32_e32 v246, v247
	s_nop 0
	v_add_f32_e32 v197, v246, v247
	v_pk_add_f32 v[204:205], v[204:205], v[206:207]
	s_nop 0
	v_add_f32_e32 v246, v204, v205
	v_mov_b32_e32 v247, v246
	s_nop 1
	v_permlane16_swap_b32_e32 v246, v247
	s_nop 0
	v_add_f32_e32 v246, v246, v247
	v_mov_b32_e32 v247, v246
	s_nop 1
	v_permlane32_swap_b32_e32 v246, v247
	s_nop 0
	v_add_f32_e32 v196, v246, v247
	s_nop 0
	v_pk_fma_f32 v[240:241], v[192:193], s[42:43], v[242:243] op_sel_hi:[1,0,0]
	v_pk_fma_f32 v[202:203], v[196:197], s[42:43], v[242:243] op_sel_hi:[1,0,0]
	v_cmp_gt_f32_e64 s[6:7], s97, v240
	v_cmp_gt_f32_e32 vcc, s97, v241
	s_waitcnt vmcnt(0)
	v_lshl_add_u32 v192, v250, 3, s14
	v_add_u32_e32 v193, -14, v254
	v_cmp_gt_f32_e64 s[8:9], s97, v203
	v_cmp_gt_f32_e64 s[10:11], s97, v202
	v_cmp_lt_u32_e64 s[14:15], -13, v193
	v_ashrrev_i32_e32 v193, 31, v192
	s_and_saveexec_b64 s[86:87], s[14:15]
	s_xor_b64 s[14:15], exec, s[86:87]
	s_or_saveexec_b64 s[14:15], s[14:15]
	v_mul_f32_e32 v194, 0x4b800000, v241
	v_cndmask_b32_e32 v194, v241, v194, vcc
	v_rsq_f32_e32 v194, v194
	s_nop 0
	v_mul_f32_e32 v195, 0x45800000, v194
	v_cndmask_b32_e32 v204, v194, v195, vcc
	v_pk_mul_f32 v[196:197], v[118:119], v[204:205] op_sel_hi:[1,0]
	v_mul_f32_e32 v118, 0x4b800000, v202
	v_cndmask_b32_e64 v118, v202, v118, s[10:11]
	v_rsq_f32_e32 v118, v118
	v_pk_mul_f32 v[200:201], v[116:117], v[204:205] op_sel_hi:[1,0]
	v_pk_mul_f32 v[194:195], v[126:127], v[204:205] op_sel_hi:[1,0]
	v_pk_mul_f32 v[198:199], v[124:125], v[204:205] op_sel_hi:[1,0]
	v_mul_f32_e32 v116, 0x45800000, v118
	v_cndmask_b32_e64 v116, v118, v116, s[10:11]
	v_pk_mul_f32 v[122:123], v[122:123], v[204:205] op_sel_hi:[1,0]
	v_pk_mul_f32 v[120:121], v[120:121], v[204:205] op_sel_hi:[1,0]
	v_pk_mul_f32 v[114:115], v[114:115], v[204:205] op_sel_hi:[1,0]
	v_pk_mul_f32 v[112:113], v[112:113], v[204:205] op_sel_hi:[1,0]
	v_pk_mul_f32 v[110:111], v[110:111], v[116:117] op_sel_hi:[1,0]
	v_pk_mul_f32 v[108:109], v[108:109], v[116:117] op_sel_hi:[1,0]
	v_pk_mul_f32 v[106:107], v[106:107], v[116:117] op_sel_hi:[1,0]
	v_pk_mul_f32 v[104:105], v[104:105], v[116:117] op_sel_hi:[1,0]
	v_pk_mul_f32 v[102:103], v[102:103], v[116:117] op_sel_hi:[1,0]
	v_pk_mul_f32 v[100:101], v[100:101], v[116:117] op_sel_hi:[1,0]
	v_pk_mul_f32 v[98:99], v[98:99], v[116:117] op_sel_hi:[1,0]
	v_pk_mul_f32 v[96:97], v[96:97], v[116:117] op_sel_hi:[1,0]
	s_xor_b64 exec, exec, s[14:15]
	s_cbranch_execz .LBB0_917
	v_add_u32_e32 v116, -12, v254
	v_cmp_gt_i32_e64 s[10:11], 2, v254
	s_lshl_b32 s38, s38, 3
	s_add_i32 s38, s38, s91
	v_cndmask_b32_e64 v116, v116, v254, s[10:11]
	v_add_u32_e32 v126, s38, v116
	v_mov_b64_e32 v[124:125], s[22:23]
	s_movk_i32 s38, 0x5800
	v_mad_i64_i32 v[124:125], s[38:39], v126, s38, v[124:125]
	v_cndmask_b32_e64 v119, v111, v195, s[10:11]
	v_cndmask_b32_e64 v118, v110, v194, s[10:11]
	v_cndmask_b32_e64 v117, v109, v199, s[10:11]
	v_cndmask_b32_e64 v116, v108, v198, s[10:11]
	v_lshl_add_u64 v[124:125], v[192:193], 2, v[124:125]
	s_mov_b64 s[38:39], 0x2c00
	global_store_dwordx4 v[124:125], v[116:119], off
	v_lshl_add_u64 v[126:127], v[124:125], 0, s[38:39]
	s_movk_i32 s38, 0x2000
	v_cndmask_b32_e64 v119, v107, v123, s[10:11]
	v_cndmask_b32_e64 v118, v106, v122, s[10:11]
	v_cndmask_b32_e64 v117, v105, v121, s[10:11]
	v_cndmask_b32_e64 v116, v104, v120, s[10:11]
	global_store_dwordx4 v[124:125], v[116:119], off offset:16
	v_add_co_u32_e32 v124, vcc, s38, v124
	s_nop 0
	v_cndmask_b32_e64 v119, v103, v197, s[10:11]
	v_cndmask_b32_e64 v118, v102, v196, s[10:11]
	v_cndmask_b32_e64 v117, v101, v201, s[10:11]
	v_cndmask_b32_e64 v116, v100, v200, s[10:11]
	v_addc_co_u32_e32 v125, vcc, 0, v125, vcc
	global_store_dwordx4 v[124:125], v[116:119], off offset:3072
	s_nop 1
	v_cndmask_b32_e64 v119, v99, v115, s[10:11]
	v_cndmask_b32_e64 v118, v98, v114, s[10:11]
	v_cndmask_b32_e64 v117, v97, v113, s[10:11]
	v_cndmask_b32_e64 v116, v96, v112, s[10:11]
	global_store_dwordx4 v[126:127], v[116:119], off offset:16
	s_branch .LBB0_917

.LBB0_998:
	s_add_u32 s20, s10, 0x100
	s_addc_u32 s21, s11, 0
	s_add_i32 s60, 0, 0x10000
	v_add_u32_e32 v142, s60, v145
	ds_read_b128 v[138:141], v142
	ds_read_b128 v[148:151], v142 offset:1024
	ds_read_b128 v[152:155], v142 offset:2048
	ds_read_b128 v[156:159], v142 offset:3072
	s_cmp_eq_u32 s59, 40
	s_cselect_b32 s25, s7, s21
	s_cselect_b32 s24, s6, s20
	s_cselect_b32 s23, s9, s58
	s_cselect_b32 s22, s8, s57
	v_lshl_add_u64 v[142:143], s[10:11], 0, v[134:135]
	s_add_i32 m0, s34, 0xc000
	ds_read_b128 v[160:163], v147
	ds_read_b128 v[164:167], v147 offset:1024
	ds_read_b128 v[168:171], v147 offset:2048
	ds_read_b128 v[172:175], v147 offset:3072
	ds_read_b128 v[176:179], v147 offset:4096
	ds_read_b128 v[180:183], v147 offset:5120
	ds_read_b128 v[184:187], v147 offset:6144
	ds_read_b128 v[188:191], v147 offset:7168
	global_load_lds_dwordx4 v[142:143], off
	v_lshl_add_u64 v[142:143], s[10:11], 0, v[136:137]
	s_add_i32 m0, s34, 0xe000
	s_nop 0
	global_load_lds_dwordx4 v[142:143], off
	s_waitcnt lgkmcnt(8)
	s_barrier
	s_waitcnt lgkmcnt(0)
	v_mfma_f32_16x16x32_bf16 v[124:127], v[138:141], v[160:163], v[124:127]
	v_mfma_f32_16x16x32_bf16 v[120:123], v[152:155], v[160:163], v[120:123]
	v_mfma_f32_16x16x32_bf16 v[108:111], v[138:141], v[168:171], v[108:111]
	v_mfma_f32_16x16x32_bf16 v[104:107], v[152:155], v[168:171], v[104:107]
	v_mfma_f32_16x16x32_bf16 v[92:95], v[138:141], v[176:179], v[92:95]
	v_mfma_f32_16x16x32_bf16 v[88:91], v[152:155], v[176:179], v[88:91]
	v_mfma_f32_16x16x32_bf16 v[76:79], v[138:141], v[184:187], v[76:79]
	v_mfma_f32_16x16x32_bf16 v[72:75], v[152:155], v[184:187], v[72:75]
	v_mfma_f32_16x16x32_bf16 v[124:127], v[148:151], v[164:167], v[124:127]
	v_mfma_f32_16x16x32_bf16 v[120:123], v[156:159], v[164:167], v[120:123]
	v_mfma_f32_16x16x32_bf16 v[108:111], v[148:151], v[172:175], v[108:111]
	v_mfma_f32_16x16x32_bf16 v[104:107], v[156:159], v[172:175], v[104:107]
	v_mfma_f32_16x16x32_bf16 v[92:95], v[148:151], v[180:183], v[92:95]
	v_mfma_f32_16x16x32_bf16 v[88:91], v[156:159], v[180:183], v[88:91]
	v_mfma_f32_16x16x32_bf16 v[76:79], v[148:151], v[188:191], v[76:79]
	v_mfma_f32_16x16x32_bf16 v[72:75], v[156:159], v[188:191], v[72:75]
	s_barrier
	s_add_i32 s61, 0, 0x14000
	v_add_u32_e32 v142, s61, v145
	s_add_i32 s10, s60, s27
	ds_read_b128 v[192:195], v142
	ds_read_b128 v[196:199], v142 offset:1024
	ds_read_b128 v[200:203], v142 offset:2048
	ds_read_b128 v[204:207], v142 offset:3072
	s_add_u32 s98, s22, s40
	s_addc_u32 s99, s23, s41
	s_mov_b32 m0, s10
	s_nop 0
	global_load_lds_dwordx4 v208, s[22:23]
	s_add_i32 m0, s10, 0x2000
	s_nop 0
	global_load_lds_dwordx4 v128, s[22:23]
	s_barrier
	s_waitcnt lgkmcnt(0)
	v_mfma_f32_16x16x32_bf16 v[116:119], v[192:195], v[160:163], v[116:119]
	v_mfma_f32_16x16x32_bf16 v[112:115], v[200:203], v[160:163], v[112:115]
	v_mfma_f32_16x16x32_bf16 v[100:103], v[192:195], v[168:171], v[100:103]
	v_mfma_f32_16x16x32_bf16 v[96:99], v[200:203], v[168:171], v[96:99]
	v_mfma_f32_16x16x32_bf16 v[84:87], v[192:195], v[176:179], v[84:87]
	v_mfma_f32_16x16x32_bf16 v[80:83], v[200:203], v[176:179], v[80:83]
	v_mfma_f32_16x16x32_bf16 v[68:71], v[192:195], v[184:187], v[68:71]
	v_mfma_f32_16x16x32_bf16 v[64:67], v[200:203], v[184:187], v[64:67]
	v_mfma_f32_16x16x32_bf16 v[116:119], v[196:199], v[164:167], v[116:119]
	v_mfma_f32_16x16x32_bf16 v[112:115], v[204:207], v[164:167], v[112:115]
	v_mfma_f32_16x16x32_bf16 v[100:103], v[196:199], v[172:175], v[100:103]
	v_mfma_f32_16x16x32_bf16 v[96:99], v[204:207], v[172:175], v[96:99]
	v_mfma_f32_16x16x32_bf16 v[84:87], v[196:199], v[180:183], v[84:87]
	v_mfma_f32_16x16x32_bf16 v[80:83], v[204:207], v[180:183], v[80:83]
	v_mfma_f32_16x16x32_bf16 v[68:71], v[196:199], v[188:191], v[68:71]
	v_mfma_f32_16x16x32_bf16 v[64:67], v[204:207], v[188:191], v[64:67]
	s_mov_b32 m0, s34
	s_add_u32 s100, s24, s40
	s_addc_u32 s101, s25, s41
	s_barrier
	ds_read_b128 v[160:163], v147 offset:16384
	ds_read_b128 v[164:167], v147 offset:17408
	ds_read_b128 v[168:171], v147 offset:18432
	ds_read_b128 v[172:175], v147 offset:19456
	ds_read_b128 v[176:179], v147 offset:20480
	ds_read_b128 v[180:183], v147 offset:21504
	ds_read_b128 v[184:187], v147 offset:22528
	ds_read_b128 v[188:191], v147 offset:23552
	global_load_lds_dwordx4 v132, s[24:25]
	s_mov_b32 m0, s35
	s_nop 0
	global_load_lds_dwordx4 v130, s[24:25]
	s_barrier
	s_waitcnt lgkmcnt(0)
	v_mfma_f32_16x16x32_bf16 v[60:63], v[138:141], v[160:163], v[60:63]
	v_mfma_f32_16x16x32_bf16 v[56:59], v[152:155], v[160:163], v[56:59]
	v_mfma_f32_16x16x32_bf16 v[44:47], v[138:141], v[168:171], v[44:47]
	v_mfma_f32_16x16x32_bf16 v[40:43], v[152:155], v[168:171], v[40:43]
	v_mfma_f32_16x16x32_bf16 v[28:31], v[138:141], v[176:179], v[28:31]
	v_mfma_f32_16x16x32_bf16 v[24:27], v[152:155], v[176:179], v[24:27]
	v_mfma_f32_16x16x32_bf16 v[12:15], v[138:141], v[184:187], v[12:15]
	v_mfma_f32_16x16x32_bf16 v[8:11], v[152:155], v[184:187], v[8:11]
	v_mfma_f32_16x16x32_bf16 v[60:63], v[148:151], v[164:167], v[60:63]
	v_mfma_f32_16x16x32_bf16 v[56:59], v[156:159], v[164:167], v[56:59]
	v_mfma_f32_16x16x32_bf16 v[44:47], v[148:151], v[172:175], v[44:47]
	v_mfma_f32_16x16x32_bf16 v[40:43], v[156:159], v[172:175], v[40:43]
	v_mfma_f32_16x16x32_bf16 v[28:31], v[148:151], v[180:183], v[28:31]
	v_mfma_f32_16x16x32_bf16 v[24:27], v[156:159], v[180:183], v[24:27]
	v_mfma_f32_16x16x32_bf16 v[12:15], v[148:151], v[188:191], v[12:15]
	v_mfma_f32_16x16x32_bf16 v[8:11], v[156:159], v[188:191], v[8:11]
	s_barrier
	s_add_u32 s10, s22, 0xb0000
	s_addc_u32 s11, s23, 0
	s_add_i32 s60, s61, s27
	s_mov_b32 m0, s60
	s_nop 0
	global_load_lds_dwordx4 v208, s[10:11]
	s_add_i32 m0, s60, 0x2000
	s_nop 0
	global_load_lds_dwordx4 v128, s[10:11]
	s_waitcnt vmcnt(6)
	s_barrier
	v_mfma_f32_16x16x32_bf16 v[52:55], v[192:195], v[160:163], v[52:55]
	v_mfma_f32_16x16x32_bf16 v[48:51], v[200:203], v[160:163], v[48:51]
	v_mfma_f32_16x16x32_bf16 v[36:39], v[192:195], v[168:171], v[36:39]
	v_mfma_f32_16x16x32_bf16 v[32:35], v[200:203], v[168:171], v[32:35]
	v_mfma_f32_16x16x32_bf16 v[20:23], v[192:195], v[176:179], v[20:23]
	v_mfma_f32_16x16x32_bf16 v[16:19], v[200:203], v[176:179], v[16:19]
	v_mfma_f32_16x16x32_bf16 v[4:7], v[192:195], v[184:187], v[4:7]
	v_mfma_f32_16x16x32_bf16 v[0:3], v[200:203], v[184:187], v[0:3]
	v_mfma_f32_16x16x32_bf16 v[52:55], v[196:199], v[164:167], v[52:55]
	v_mfma_f32_16x16x32_bf16 v[48:51], v[204:207], v[164:167], v[48:51]
	v_mfma_f32_16x16x32_bf16 v[36:39], v[196:199], v[172:175], v[36:39]
	v_mfma_f32_16x16x32_bf16 v[32:35], v[204:207], v[172:175], v[32:35]
	v_mfma_f32_16x16x32_bf16 v[20:23], v[196:199], v[180:183], v[20:23]
	v_mfma_f32_16x16x32_bf16 v[16:19], v[204:207], v[180:183], v[16:19]
	v_mfma_f32_16x16x32_bf16 v[4:7], v[196:199], v[188:191], v[4:7]
	v_mfma_f32_16x16x32_bf16 v[0:3], v[204:207], v[188:191], v[0:3]
	s_add_i32 s60, 0, 0x18000
	v_add_u32_e32 v156, s60, v145
	s_barrier
	ds_read_b128 v[138:141], v156
	ds_read_b128 v[148:151], v156 offset:1024
	ds_read_b128 v[152:155], v156 offset:2048
	ds_read_b128 v[156:159], v156 offset:3072
	s_add_u32 s10, s24, 0xb0000
	s_addc_u32 s11, s25, 0
	s_mov_b32 m0, s36
	ds_read_b128 v[160:163], v147 offset:32768
	ds_read_b128 v[164:167], v147 offset:33792
	ds_read_b128 v[168:171], v147 offset:34816
	ds_read_b128 v[172:175], v147 offset:35840
	ds_read_b128 v[176:179], v147 offset:36864
	ds_read_b128 v[180:183], v147 offset:37888
	ds_read_b128 v[184:187], v147 offset:38912
	ds_read_b128 v[188:191], v147 offset:39936
	global_load_lds_dwordx4 v132, s[10:11]
	s_mov_b32 m0, s46
	s_nop 0
	global_load_lds_dwordx4 v130, s[10:11]
	s_waitcnt lgkmcnt(8)
	s_barrier
	s_waitcnt lgkmcnt(0)
	v_mfma_f32_16x16x32_bf16 v[124:127], v[138:141], v[160:163], v[124:127]
	v_mfma_f32_16x16x32_bf16 v[120:123], v[152:155], v[160:163], v[120:123]
	v_mfma_f32_16x16x32_bf16 v[108:111], v[138:141], v[168:171], v[108:111]
	v_mfma_f32_16x16x32_bf16 v[104:107], v[152:155], v[168:171], v[104:107]
	v_mfma_f32_16x16x32_bf16 v[92:95], v[138:141], v[176:179], v[92:95]
	v_mfma_f32_16x16x32_bf16 v[88:91], v[152:155], v[176:179], v[88:91]
	v_mfma_f32_16x16x32_bf16 v[76:79], v[138:141], v[184:187], v[76:79]
	v_mfma_f32_16x16x32_bf16 v[72:75], v[152:155], v[184:187], v[72:75]
	v_mfma_f32_16x16x32_bf16 v[124:127], v[148:151], v[164:167], v[124:127]
	v_mfma_f32_16x16x32_bf16 v[120:123], v[156:159], v[164:167], v[120:123]
	v_mfma_f32_16x16x32_bf16 v[108:111], v[148:151], v[172:175], v[108:111]
	v_mfma_f32_16x16x32_bf16 v[104:107], v[156:159], v[172:175], v[104:107]
	v_mfma_f32_16x16x32_bf16 v[92:95], v[148:151], v[180:183], v[92:95]
	v_mfma_f32_16x16x32_bf16 v[88:91], v[156:159], v[180:183], v[88:91]
	v_mfma_f32_16x16x32_bf16 v[76:79], v[148:151], v[188:191], v[76:79]
	v_mfma_f32_16x16x32_bf16 v[72:75], v[156:159], v[188:191], v[72:75]
	s_barrier
	s_add_i32 s24, 0, 0x1c000
	s_add_i32 s10, s60, s27
	v_add_u32_e32 v204, s24, v145
	s_mov_b32 m0, s10
	ds_read_b128 v[192:195], v204
	ds_read_b128 v[196:199], v204 offset:1024
	ds_read_b128 v[200:203], v204 offset:2048
	ds_read_b128 v[204:207], v204 offset:3072
	global_load_lds_dwordx4 v208, s[98:99]
	s_add_i32 m0, s10, 0x2000
	s_nop 0
	global_load_lds_dwordx4 v128, s[98:99]
	s_barrier
	s_waitcnt lgkmcnt(0)
	v_mfma_f32_16x16x32_bf16 v[116:119], v[192:195], v[160:163], v[116:119]
	v_mfma_f32_16x16x32_bf16 v[112:115], v[200:203], v[160:163], v[112:115]
	v_mfma_f32_16x16x32_bf16 v[100:103], v[192:195], v[168:171], v[100:103]
	v_mfma_f32_16x16x32_bf16 v[96:99], v[200:203], v[168:171], v[96:99]
	v_mfma_f32_16x16x32_bf16 v[84:87], v[192:195], v[176:179], v[84:87]
	v_mfma_f32_16x16x32_bf16 v[80:83], v[200:203], v[176:179], v[80:83]
	v_mfma_f32_16x16x32_bf16 v[68:71], v[192:195], v[184:187], v[68:71]
	v_mfma_f32_16x16x32_bf16 v[64:67], v[200:203], v[184:187], v[64:67]
	v_mfma_f32_16x16x32_bf16 v[116:119], v[196:199], v[164:167], v[116:119]
	v_mfma_f32_16x16x32_bf16 v[112:115], v[204:207], v[164:167], v[112:115]
	v_mfma_f32_16x16x32_bf16 v[100:103], v[196:199], v[172:175], v[100:103]
	v_mfma_f32_16x16x32_bf16 v[96:99], v[204:207], v[172:175], v[96:99]
	v_mfma_f32_16x16x32_bf16 v[84:87], v[196:199], v[180:183], v[84:87]
	v_mfma_f32_16x16x32_bf16 v[80:83], v[204:207], v[180:183], v[80:83]
	v_mfma_f32_16x16x32_bf16 v[68:71], v[196:199], v[188:191], v[68:71]
	v_mfma_f32_16x16x32_bf16 v[64:67], v[204:207], v[188:191], v[64:67]
	s_mov_b32 m0, s50
	s_barrier
	ds_read_b128 v[160:163], v147 offset:49152
	ds_read_b128 v[164:167], v147 offset:50176
	ds_read_b128 v[168:171], v147 offset:51200
	ds_read_b128 v[172:175], v147 offset:52224
	ds_read_b128 v[176:179], v147 offset:53248
	ds_read_b128 v[180:183], v147 offset:54272
	ds_read_b128 v[184:187], v147 offset:55296
	ds_read_b128 v[188:191], v147 offset:56320
	global_load_lds_dwordx4 v132, s[100:101]
	s_mov_b32 m0, s51
	s_nop 0
	global_load_lds_dwordx4 v130, s[100:101]
	s_barrier
	s_waitcnt lgkmcnt(0)
	v_mfma_f32_16x16x32_bf16 v[60:63], v[138:141], v[160:163], v[60:63]
	v_mfma_f32_16x16x32_bf16 v[56:59], v[152:155], v[160:163], v[56:59]
	v_mfma_f32_16x16x32_bf16 v[44:47], v[138:141], v[168:171], v[44:47]
	v_mfma_f32_16x16x32_bf16 v[40:43], v[152:155], v[168:171], v[40:43]
	v_mfma_f32_16x16x32_bf16 v[28:31], v[138:141], v[176:179], v[28:31]
	v_mfma_f32_16x16x32_bf16 v[24:27], v[152:155], v[176:179], v[24:27]
	v_mfma_f32_16x16x32_bf16 v[12:15], v[138:141], v[184:187], v[12:15]
	v_mfma_f32_16x16x32_bf16 v[8:11], v[152:155], v[184:187], v[8:11]
	v_mfma_f32_16x16x32_bf16 v[60:63], v[148:151], v[164:167], v[60:63]
	v_mfma_f32_16x16x32_bf16 v[56:59], v[156:159], v[164:167], v[56:59]
	v_mfma_f32_16x16x32_bf16 v[44:47], v[148:151], v[172:175], v[44:47]
	v_mfma_f32_16x16x32_bf16 v[40:43], v[156:159], v[172:175], v[40:43]
	v_mfma_f32_16x16x32_bf16 v[28:31], v[148:151], v[180:183], v[28:31]
	v_mfma_f32_16x16x32_bf16 v[24:27], v[156:159], v[180:183], v[24:27]
	v_mfma_f32_16x16x32_bf16 v[12:15], v[148:151], v[188:191], v[12:15]
	v_mfma_f32_16x16x32_bf16 v[8:11], v[156:159], v[188:191], v[8:11]
	s_barrier
	s_add_u32 s10, s22, 0xb0080
	s_addc_u32 s11, s23, 0
	s_add_i32 s22, s24, s27
	s_mov_b32 m0, s22
	s_nop 0
	global_load_lds_dwordx4 v208, s[10:11]
	s_add_i32 m0, s22, 0x2000
	s_nop 0
	global_load_lds_dwordx4 v128, s[10:11]
	s_waitcnt vmcnt(6)
	s_barrier
	v_mfma_f32_16x16x32_bf16 v[52:55], v[192:195], v[160:163], v[52:55]
	v_mfma_f32_16x16x32_bf16 v[48:51], v[200:203], v[160:163], v[48:51]
	v_mfma_f32_16x16x32_bf16 v[36:39], v[192:195], v[168:171], v[36:39]
	v_mfma_f32_16x16x32_bf16 v[32:35], v[200:203], v[168:171], v[32:35]
	v_mfma_f32_16x16x32_bf16 v[20:23], v[192:195], v[176:179], v[20:23]
	v_mfma_f32_16x16x32_bf16 v[16:19], v[200:203], v[176:179], v[16:19]
	v_mfma_f32_16x16x32_bf16 v[4:7], v[192:195], v[184:187], v[4:7]
	v_mfma_f32_16x16x32_bf16 v[0:3], v[200:203], v[184:187], v[0:3]
	v_mfma_f32_16x16x32_bf16 v[52:55], v[196:199], v[164:167], v[52:55]
	v_mfma_f32_16x16x32_bf16 v[48:51], v[204:207], v[164:167], v[48:51]
	v_mfma_f32_16x16x32_bf16 v[36:39], v[196:199], v[172:175], v[36:39]
	v_mfma_f32_16x16x32_bf16 v[32:35], v[204:207], v[172:175], v[32:35]
	v_mfma_f32_16x16x32_bf16 v[20:23], v[196:199], v[180:183], v[20:23]
	v_mfma_f32_16x16x32_bf16 v[16:19], v[204:207], v[180:183], v[16:19]
	v_mfma_f32_16x16x32_bf16 v[4:7], v[196:199], v[188:191], v[4:7]
	v_mfma_f32_16x16x32_bf16 v[0:3], v[204:207], v[188:191], v[0:3]
	s_add_i32 s59, s59, 2
	s_add_u32 s57, s57, 0x100
	s_addc_u32 s58, s58, 0
	s_cmp_gt_u32 s59, 41
	s_mov_b64 s[10:11], s[20:21]
	s_barrier
	s_cbranch_scc0 .LBB0_998
	v_lshl_add_u32 v142, s39, 8, v144
	v_lshl_or_b32 v143, s38, 8, v146
	s_and_b64 vcc, exec, s[4:5]
	s_mov_b32 s38, s53
	s_mov_b32 s39, s56
	s_mov_b64 s[20:21], s[8:9]
	s_mov_b64 s[10:11], s[6:7]
	v_lshl_add_u32 v210, v142, 10, v143
	v_lshlrev_b32_e32 v211, 2, v210
	v_lshlrev_b32_e32 v210, 1, v210
	global_load_dwordx4 v[148:151], v210, s[14:15]
	global_load_dwordx4 v[152:155], v210, s[14:15] offset:256
	v_add_u32_e32 v210, 0x8000, v210
	global_load_dwordx4 v[156:159], v210, s[14:15]
	global_load_dwordx4 v[160:163], v210, s[14:15] offset:256
	v_add_u32_e32 v210, 0x8000, v210
	global_load_dwordx4 v[164:167], v210, s[14:15]
	global_load_dwordx4 v[168:171], v210, s[14:15] offset:256
	v_add_u32_e32 v210, 0x8000, v210
	global_load_dwordx4 v[172:175], v210, s[14:15]
	global_load_dwordx4 v[176:179], v210, s[14:15] offset:256
	v_add_u32_e32 v210, 0x28000, v210
	global_load_dwordx4 v[180:183], v210, s[14:15]
	global_load_dwordx4 v[184:187], v210, s[14:15] offset:256
	v_add_u32_e32 v210, 0x8000, v210
	global_load_dwordx4 v[188:191], v210, s[14:15]
	global_load_dwordx4 v[192:195], v210, s[14:15] offset:256
	v_add_u32_e32 v210, 0x8000, v210
	global_load_dwordx4 v[196:199], v210, s[14:15]
	global_load_dwordx4 v[200:203], v210, s[14:15] offset:256
	v_add_u32_e32 v210, 0x8000, v210
	s_waitcnt vmcnt(12)
	v_lshlrev_b32_e32 v204, 16, v148
	v_and_b32_e32 v205, 0xffff0000, v148
	v_lshlrev_b32_e32 v206, 16, v149
	v_and_b32_e32 v207, 0xffff0000, v149
	v_pk_add_f32 v[124:125], v[124:125], v[204:205]
	v_pk_add_f32 v[126:127], v[126:127], v[206:207]
	v_lshlrev_b32_e32 v204, 16, v150
	v_and_b32_e32 v205, 0xffff0000, v150
	v_lshlrev_b32_e32 v206, 16, v151
	v_and_b32_e32 v207, 0xffff0000, v151
	v_pk_add_f32 v[120:121], v[120:121], v[204:205]
	v_pk_add_f32 v[122:123], v[122:123], v[206:207]
	global_store_dwordx4 v211, v[124:127], s[16:17]
	global_store_dwordx4 v211, v[120:123], s[16:17] offset:16
	v_lshlrev_b32_e32 v204, 16, v152
	v_and_b32_e32 v205, 0xffff0000, v152
	v_lshlrev_b32_e32 v206, 16, v153
	v_and_b32_e32 v207, 0xffff0000, v153
	v_pk_add_f32 v[116:117], v[116:117], v[204:205]
	v_pk_add_f32 v[118:119], v[118:119], v[206:207]
	v_lshlrev_b32_e32 v204, 16, v154
	v_and_b32_e32 v205, 0xffff0000, v154
	v_lshlrev_b32_e32 v206, 16, v155
	v_and_b32_e32 v207, 0xffff0000, v155
	v_pk_add_f32 v[112:113], v[112:113], v[204:205]
	v_pk_add_f32 v[114:115], v[114:115], v[206:207]
	global_store_dwordx4 v211, v[116:119], s[16:17] offset:512
	global_store_dwordx4 v211, v[112:115], s[16:17] offset:528
	v_add_u32_e32 v211, 0x10000, v211
	global_load_dwordx4 v[148:151], v210, s[14:15]
	global_load_dwordx4 v[152:155], v210, s[14:15] offset:256
	s_waitcnt vmcnt(16)
	v_lshlrev_b32_e32 v204, 16, v156
	v_and_b32_e32 v205, 0xffff0000, v156
	v_lshlrev_b32_e32 v206, 16, v157
	v_and_b32_e32 v207, 0xffff0000, v157
	v_pk_add_f32 v[108:109], v[108:109], v[204:205]
	v_pk_add_f32 v[110:111], v[110:111], v[206:207]
	v_lshlrev_b32_e32 v204, 16, v158
	v_and_b32_e32 v205, 0xffff0000, v158
	v_lshlrev_b32_e32 v206, 16, v159
	v_and_b32_e32 v207, 0xffff0000, v159
	v_pk_add_f32 v[104:105], v[104:105], v[204:205]
	v_pk_add_f32 v[106:107], v[106:107], v[206:207]
	global_store_dwordx4 v211, v[108:111], s[16:17]
	global_store_dwordx4 v211, v[104:107], s[16:17] offset:16
	v_lshlrev_b32_e32 v204, 16, v160
	v_and_b32_e32 v205, 0xffff0000, v160
	v_lshlrev_b32_e32 v206, 16, v161
	v_and_b32_e32 v207, 0xffff0000, v161
	v_pk_add_f32 v[100:101], v[100:101], v[204:205]
	v_pk_add_f32 v[102:103], v[102:103], v[206:207]
	v_lshlrev_b32_e32 v204, 16, v162
	v_and_b32_e32 v205, 0xffff0000, v162
	v_lshlrev_b32_e32 v206, 16, v163
	v_and_b32_e32 v207, 0xffff0000, v163
	v_pk_add_f32 v[96:97], v[96:97], v[204:205]
	v_pk_add_f32 v[98:99], v[98:99], v[206:207]
	global_store_dwordx4 v211, v[100:103], s[16:17] offset:512
	global_store_dwordx4 v211, v[96:99], s[16:17] offset:528
	v_add_u32_e32 v211, 0x10000, v211
	s_waitcnt vmcnt(18)
	v_lshlrev_b32_e32 v204, 16, v164
	v_and_b32_e32 v205, 0xffff0000, v164
	v_lshlrev_b32_e32 v206, 16, v165
	v_and_b32_e32 v207, 0xffff0000, v165
	v_pk_add_f32 v[92:93], v[92:93], v[204:205]
	v_pk_add_f32 v[94:95], v[94:95], v[206:207]
	v_lshlrev_b32_e32 v204, 16, v166
	v_and_b32_e32 v205, 0xffff0000, v166
	v_lshlrev_b32_e32 v206, 16, v167
	v_and_b32_e32 v207, 0xffff0000, v167
	v_pk_add_f32 v[88:89], v[88:89], v[204:205]
	v_pk_add_f32 v[90:91], v[90:91], v[206:207]
	global_store_dwordx4 v211, v[92:95], s[16:17]
	global_store_dwordx4 v211, v[88:91], s[16:17] offset:16
	v_lshlrev_b32_e32 v204, 16, v168
	v_and_b32_e32 v205, 0xffff0000, v168
	v_lshlrev_b32_e32 v206, 16, v169
	v_and_b32_e32 v207, 0xffff0000, v169
	v_pk_add_f32 v[84:85], v[84:85], v[204:205]
	v_pk_add_f32 v[86:87], v[86:87], v[206:207]
	v_lshlrev_b32_e32 v204, 16, v170
	v_and_b32_e32 v205, 0xffff0000, v170
	v_lshlrev_b32_e32 v206, 16, v171
	v_and_b32_e32 v207, 0xffff0000, v171
	v_pk_add_f32 v[80:81], v[80:81], v[204:205]
	v_pk_add_f32 v[82:83], v[82:83], v[206:207]
	global_store_dwordx4 v211, v[84:87], s[16:17] offset:512
	global_store_dwordx4 v211, v[80:83], s[16:17] offset:528
	v_add_u32_e32 v211, 0x10000, v211
	s_waitcnt vmcnt(20)
	v_lshlrev_b32_e32 v204, 16, v172
	v_and_b32_e32 v205, 0xffff0000, v172
	v_lshlrev_b32_e32 v206, 16, v173
	v_and_b32_e32 v207, 0xffff0000, v173
	v_pk_add_f32 v[76:77], v[76:77], v[204:205]
	v_pk_add_f32 v[78:79], v[78:79], v[206:207]
	v_lshlrev_b32_e32 v204, 16, v174
	v_and_b32_e32 v205, 0xffff0000, v174
	v_lshlrev_b32_e32 v206, 16, v175
	v_and_b32_e32 v207, 0xffff0000, v175
	v_pk_add_f32 v[72:73], v[72:73], v[204:205]
	v_pk_add_f32 v[74:75], v[74:75], v[206:207]
	global_store_dwordx4 v211, v[76:79], s[16:17]
	global_store_dwordx4 v211, v[72:75], s[16:17] offset:16
	v_lshlrev_b32_e32 v204, 16, v176
	v_and_b32_e32 v205, 0xffff0000, v176
	v_lshlrev_b32_e32 v206, 16, v177
	v_and_b32_e32 v207, 0xffff0000, v177
	v_pk_add_f32 v[68:69], v[68:69], v[204:205]
	v_pk_add_f32 v[70:71], v[70:71], v[206:207]
	v_lshlrev_b32_e32 v204, 16, v178
	v_and_b32_e32 v205, 0xffff0000, v178
	v_lshlrev_b32_e32 v206, 16, v179
	v_and_b32_e32 v207, 0xffff0000, v179
	v_pk_add_f32 v[64:65], v[64:65], v[204:205]
	v_pk_add_f32 v[66:67], v[66:67], v[206:207]
	global_store_dwordx4 v211, v[68:71], s[16:17] offset:512
	global_store_dwordx4 v211, v[64:67], s[16:17] offset:528
	v_add_u32_e32 v211, 0x50000, v211
	s_waitcnt vmcnt(22)
	v_lshlrev_b32_e32 v204, 16, v180
	v_and_b32_e32 v205, 0xffff0000, v180
	v_lshlrev_b32_e32 v206, 16, v181
	v_and_b32_e32 v207, 0xffff0000, v181
	v_pk_add_f32 v[60:61], v[60:61], v[204:205]
	v_pk_add_f32 v[62:63], v[62:63], v[206:207]
	v_lshlrev_b32_e32 v204, 16, v182
	v_and_b32_e32 v205, 0xffff0000, v182
	v_lshlrev_b32_e32 v206, 16, v183
	v_and_b32_e32 v207, 0xffff0000, v183
	v_pk_add_f32 v[56:57], v[56:57], v[204:205]
	v_pk_add_f32 v[58:59], v[58:59], v[206:207]
	global_store_dwordx4 v211, v[60:63], s[16:17]
	global_store_dwordx4 v211, v[56:59], s[16:17] offset:16
	v_lshlrev_b32_e32 v204, 16, v184
	v_and_b32_e32 v205, 0xffff0000, v184
	v_lshlrev_b32_e32 v206, 16, v185
	v_and_b32_e32 v207, 0xffff0000, v185
	v_pk_add_f32 v[52:53], v[52:53], v[204:205]
	v_pk_add_f32 v[54:55], v[54:55], v[206:207]
	v_lshlrev_b32_e32 v204, 16, v186
	v_and_b32_e32 v205, 0xffff0000, v186
	v_lshlrev_b32_e32 v206, 16, v187
	v_and_b32_e32 v207, 0xffff0000, v187
	v_pk_add_f32 v[48:49], v[48:49], v[204:205]
	v_pk_add_f32 v[50:51], v[50:51], v[206:207]
	global_store_dwordx4 v211, v[52:55], s[16:17] offset:512
	global_store_dwordx4 v211, v[48:51], s[16:17] offset:528
	v_add_u32_e32 v211, 0x10000, v211
	s_waitcnt vmcnt(24)
	v_lshlrev_b32_e32 v204, 16, v188
	v_and_b32_e32 v205, 0xffff0000, v188
	v_lshlrev_b32_e32 v206, 16, v189
	v_and_b32_e32 v207, 0xffff0000, v189
	v_pk_add_f32 v[44:45], v[44:45], v[204:205]
	v_pk_add_f32 v[46:47], v[46:47], v[206:207]
	v_lshlrev_b32_e32 v204, 16, v190
	v_and_b32_e32 v205, 0xffff0000, v190
	v_lshlrev_b32_e32 v206, 16, v191
	v_and_b32_e32 v207, 0xffff0000, v191
	v_pk_add_f32 v[40:41], v[40:41], v[204:205]
	v_pk_add_f32 v[42:43], v[42:43], v[206:207]
	global_store_dwordx4 v211, v[44:47], s[16:17]
	global_store_dwordx4 v211, v[40:43], s[16:17] offset:16
	v_lshlrev_b32_e32 v204, 16, v192
	v_and_b32_e32 v205, 0xffff0000, v192
	v_lshlrev_b32_e32 v206, 16, v193
	v_and_b32_e32 v207, 0xffff0000, v193
	v_pk_add_f32 v[36:37], v[36:37], v[204:205]
	v_pk_add_f32 v[38:39], v[38:39], v[206:207]
	v_lshlrev_b32_e32 v204, 16, v194
	v_and_b32_e32 v205, 0xffff0000, v194
	v_lshlrev_b32_e32 v206, 16, v195
	v_and_b32_e32 v207, 0xffff0000, v195
	v_pk_add_f32 v[32:33], v[32:33], v[204:205]
	v_pk_add_f32 v[34:35], v[34:35], v[206:207]
	global_store_dwordx4 v211, v[36:39], s[16:17] offset:512
	global_store_dwordx4 v211, v[32:35], s[16:17] offset:528
	v_add_u32_e32 v211, 0x10000, v211
	s_waitcnt vmcnt(26)
	v_lshlrev_b32_e32 v204, 16, v196
	v_and_b32_e32 v205, 0xffff0000, v196
	v_lshlrev_b32_e32 v206, 16, v197
	v_and_b32_e32 v207, 0xffff0000, v197
	v_pk_add_f32 v[28:29], v[28:29], v[204:205]
	v_pk_add_f32 v[30:31], v[30:31], v[206:207]
	v_lshlrev_b32_e32 v204, 16, v198
	v_and_b32_e32 v205, 0xffff0000, v198
	v_lshlrev_b32_e32 v206, 16, v199
	v_and_b32_e32 v207, 0xffff0000, v199
	v_pk_add_f32 v[24:25], v[24:25], v[204:205]
	v_pk_add_f32 v[26:27], v[26:27], v[206:207]
	global_store_dwordx4 v211, v[28:31], s[16:17]
	global_store_dwordx4 v211, v[24:27], s[16:17] offset:16
	v_lshlrev_b32_e32 v204, 16, v200
	v_and_b32_e32 v205, 0xffff0000, v200
	v_lshlrev_b32_e32 v206, 16, v201
	v_and_b32_e32 v207, 0xffff0000, v201
	v_pk_add_f32 v[20:21], v[20:21], v[204:205]
	v_pk_add_f32 v[22:23], v[22:23], v[206:207]
	v_lshlrev_b32_e32 v204, 16, v202
	v_and_b32_e32 v205, 0xffff0000, v202
	v_lshlrev_b32_e32 v206, 16, v203
	v_and_b32_e32 v207, 0xffff0000, v203
	v_pk_add_f32 v[16:17], v[16:17], v[204:205]
	v_pk_add_f32 v[18:19], v[18:19], v[206:207]
	global_store_dwordx4 v211, v[20:23], s[16:17] offset:512
	global_store_dwordx4 v211, v[16:19], s[16:17] offset:528
	v_add_u32_e32 v211, 0x10000, v211
	s_waitcnt vmcnt(24)
	v_lshlrev_b32_e32 v204, 16, v148
	v_and_b32_e32 v205, 0xffff0000, v148
	v_lshlrev_b32_e32 v206, 16, v149
	v_and_b32_e32 v207, 0xffff0000, v149
	v_pk_add_f32 v[12:13], v[12:13], v[204:205]
	v_pk_add_f32 v[14:15], v[14:15], v[206:207]
	v_lshlrev_b32_e32 v204, 16, v150
	v_and_b32_e32 v205, 0xffff0000, v150
	v_lshlrev_b32_e32 v206, 16, v151
	v_and_b32_e32 v207, 0xffff0000, v151
	v_pk_add_f32 v[8:9], v[8:9], v[204:205]
	v_pk_add_f32 v[10:11], v[10:11], v[206:207]
	global_store_dwordx4 v211, v[12:15], s[16:17]
	global_store_dwordx4 v211, v[8:11], s[16:17] offset:16
	v_lshlrev_b32_e32 v204, 16, v152
	v_and_b32_e32 v205, 0xffff0000, v152
	v_lshlrev_b32_e32 v206, 16, v153
	v_and_b32_e32 v207, 0xffff0000, v153
	v_pk_add_f32 v[4:5], v[4:5], v[204:205]
	v_pk_add_f32 v[6:7], v[6:7], v[206:207]
	v_lshlrev_b32_e32 v204, 16, v154
	v_and_b32_e32 v205, 0xffff0000, v154
	v_lshlrev_b32_e32 v206, 16, v155
	v_and_b32_e32 v207, 0xffff0000, v155
	v_pk_add_f32 v[0:1], v[0:1], v[204:205]
	v_pk_add_f32 v[2:3], v[2:3], v[206:207]
	global_store_dwordx4 v211, v[4:7], s[16:17] offset:512
	global_store_dwordx4 v211, v[0:3], s[16:17] offset:528
	v_add_u32_e32 v211, 0x10000, v211
	s_cbranch_vccz .LBB0_987
	s_waitcnt vmcnt(0)
	s_cmpk_gt_u32 s26, 0xff
	s_cbranch_scc1 .LBB0_1002
	s_barrier

.LBB0_1021:
	s_add_u32 s22, s20, 0x100
	s_addc_u32 s23, s21, 0
	s_add_i32 s62, 0, 0x10000
	v_add_u32_e32 v154, s62, v143
	ds_read_b128 v[138:141], v154
	ds_read_b128 v[146:149], v154 offset:1024
	ds_read_b128 v[150:153], v154 offset:2048
	ds_read_b128 v[154:157], v154 offset:3072
	s_cmp_eq_u32 s61, 40
	s_cselect_b32 s27, s9, s23
	s_cselect_b32 s26, s8, s22
	s_cselect_b32 s25, s11, s60
	s_cselect_b32 s24, s10, s39
	v_lshl_add_u64 v[190:191], s[20:21], 0, v[134:135]
	s_add_i32 m0, s46, 0xc000
	ds_read_b128 v[158:161], v145
	ds_read_b128 v[162:165], v145 offset:1024
	ds_read_b128 v[166:169], v145 offset:2048
	ds_read_b128 v[170:173], v145 offset:3072
	ds_read_b128 v[174:177], v145 offset:4096
	ds_read_b128 v[178:181], v145 offset:5120
	ds_read_b128 v[182:185], v145 offset:6144
	ds_read_b128 v[186:189], v145 offset:7168
	global_load_lds_dwordx4 v[190:191], off
	v_lshl_add_u64 v[190:191], s[20:21], 0, v[136:137]
	s_add_i32 m0, s46, 0xe000
	s_nop 0
	global_load_lds_dwordx4 v[190:191], off
	s_waitcnt lgkmcnt(8)
	s_barrier
	s_waitcnt lgkmcnt(0)
	v_mfma_f32_16x16x32_bf16 v[124:127], v[138:141], v[158:161], v[124:127]
	v_mfma_f32_16x16x32_bf16 v[120:123], v[150:153], v[158:161], v[120:123]
	v_mfma_f32_16x16x32_bf16 v[108:111], v[138:141], v[166:169], v[108:111]
	v_mfma_f32_16x16x32_bf16 v[104:107], v[150:153], v[166:169], v[104:107]
	v_mfma_f32_16x16x32_bf16 v[92:95], v[138:141], v[174:177], v[92:95]
	v_mfma_f32_16x16x32_bf16 v[88:91], v[150:153], v[174:177], v[88:91]
	v_mfma_f32_16x16x32_bf16 v[76:79], v[138:141], v[182:185], v[76:79]
	v_mfma_f32_16x16x32_bf16 v[72:75], v[150:153], v[182:185], v[72:75]
	v_mfma_f32_16x16x32_bf16 v[124:127], v[146:149], v[162:165], v[124:127]
	v_mfma_f32_16x16x32_bf16 v[120:123], v[154:157], v[162:165], v[120:123]
	v_mfma_f32_16x16x32_bf16 v[108:111], v[146:149], v[170:173], v[108:111]
	v_mfma_f32_16x16x32_bf16 v[104:107], v[154:157], v[170:173], v[104:107]
	v_mfma_f32_16x16x32_bf16 v[92:95], v[146:149], v[178:181], v[92:95]
	v_mfma_f32_16x16x32_bf16 v[88:91], v[154:157], v[178:181], v[88:91]
	v_mfma_f32_16x16x32_bf16 v[76:79], v[146:149], v[186:189], v[76:79]
	v_mfma_f32_16x16x32_bf16 v[72:75], v[154:157], v[186:189], v[72:75]
	s_barrier
	s_add_i32 s63, 0, 0x14000
	s_add_i32 s20, s62, s35
	v_add_u32_e32 v202, s63, v143
	s_add_u32 s98, s24, s40
	s_addc_u32 s99, s25, s41
	s_mov_b32 m0, s20
	ds_read_b128 v[190:193], v202
	ds_read_b128 v[194:197], v202 offset:1024
	ds_read_b128 v[198:201], v202 offset:2048
	ds_read_b128 v[202:205], v202 offset:3072
	global_load_lds_dwordx4 v208, s[24:25]
	s_add_i32 m0, s20, 0x2000
	s_nop 0
	global_load_lds_dwordx4 v128, s[24:25]
	s_barrier
	s_waitcnt lgkmcnt(0)
	v_mfma_f32_16x16x32_bf16 v[116:119], v[190:193], v[158:161], v[116:119]
	v_mfma_f32_16x16x32_bf16 v[112:115], v[198:201], v[158:161], v[112:115]
	v_mfma_f32_16x16x32_bf16 v[100:103], v[190:193], v[166:169], v[100:103]
	v_mfma_f32_16x16x32_bf16 v[96:99], v[198:201], v[166:169], v[96:99]
	v_mfma_f32_16x16x32_bf16 v[84:87], v[190:193], v[174:177], v[84:87]
	v_mfma_f32_16x16x32_bf16 v[80:83], v[198:201], v[174:177], v[80:83]
	v_mfma_f32_16x16x32_bf16 v[68:71], v[190:193], v[182:185], v[68:71]
	v_mfma_f32_16x16x32_bf16 v[64:67], v[198:201], v[182:185], v[64:67]
	v_mfma_f32_16x16x32_bf16 v[116:119], v[194:197], v[162:165], v[116:119]
	v_mfma_f32_16x16x32_bf16 v[112:115], v[202:205], v[162:165], v[112:115]
	v_mfma_f32_16x16x32_bf16 v[100:103], v[194:197], v[170:173], v[100:103]
	v_mfma_f32_16x16x32_bf16 v[96:99], v[202:205], v[170:173], v[96:99]
	v_mfma_f32_16x16x32_bf16 v[84:87], v[194:197], v[178:181], v[84:87]
	v_mfma_f32_16x16x32_bf16 v[80:83], v[202:205], v[178:181], v[80:83]
	v_mfma_f32_16x16x32_bf16 v[68:71], v[194:197], v[186:189], v[68:71]
	v_mfma_f32_16x16x32_bf16 v[64:67], v[202:205], v[186:189], v[64:67]
	s_mov_b32 m0, s46
	s_add_u32 s100, s26, s40
	s_addc_u32 s101, s27, s41
	s_barrier
	ds_read_b128 v[158:161], v145 offset:16384
	ds_read_b128 v[162:165], v145 offset:17408
	ds_read_b128 v[166:169], v145 offset:18432
	ds_read_b128 v[170:173], v145 offset:19456
	ds_read_b128 v[174:177], v145 offset:20480
	ds_read_b128 v[178:181], v145 offset:21504
	ds_read_b128 v[182:185], v145 offset:22528
	ds_read_b128 v[186:189], v145 offset:23552
	global_load_lds_dwordx4 v132, s[26:27]
	s_mov_b32 m0, s47
	s_nop 0
	global_load_lds_dwordx4 v130, s[26:27]
	s_barrier
	s_waitcnt lgkmcnt(0)
	v_mfma_f32_16x16x32_bf16 v[60:63], v[138:141], v[158:161], v[60:63]
	v_mfma_f32_16x16x32_bf16 v[56:59], v[150:153], v[158:161], v[56:59]
	v_mfma_f32_16x16x32_bf16 v[44:47], v[138:141], v[166:169], v[44:47]
	v_mfma_f32_16x16x32_bf16 v[40:43], v[150:153], v[166:169], v[40:43]
	v_mfma_f32_16x16x32_bf16 v[28:31], v[138:141], v[174:177], v[28:31]
	v_mfma_f32_16x16x32_bf16 v[24:27], v[150:153], v[174:177], v[24:27]
	v_mfma_f32_16x16x32_bf16 v[12:15], v[138:141], v[182:185], v[12:15]
	v_mfma_f32_16x16x32_bf16 v[8:11], v[150:153], v[182:185], v[8:11]
	v_mfma_f32_16x16x32_bf16 v[60:63], v[146:149], v[162:165], v[60:63]
	v_mfma_f32_16x16x32_bf16 v[56:59], v[154:157], v[162:165], v[56:59]
	v_mfma_f32_16x16x32_bf16 v[44:47], v[146:149], v[170:173], v[44:47]
	v_mfma_f32_16x16x32_bf16 v[40:43], v[154:157], v[170:173], v[40:43]
	v_mfma_f32_16x16x32_bf16 v[28:31], v[146:149], v[178:181], v[28:31]
	v_mfma_f32_16x16x32_bf16 v[24:27], v[154:157], v[178:181], v[24:27]
	v_mfma_f32_16x16x32_bf16 v[12:15], v[146:149], v[186:189], v[12:15]
	v_mfma_f32_16x16x32_bf16 v[8:11], v[154:157], v[186:189], v[8:11]
	s_barrier
	s_add_u32 s20, s24, 0xb0000
	s_addc_u32 s21, s25, 0
	s_add_i32 s62, s63, s35
	s_mov_b32 m0, s62
	s_nop 0
	global_load_lds_dwordx4 v208, s[20:21]
	s_add_i32 m0, s62, 0x2000
	s_nop 0
	global_load_lds_dwordx4 v128, s[20:21]
	s_waitcnt vmcnt(6)
	s_barrier
	v_mfma_f32_16x16x32_bf16 v[52:55], v[190:193], v[158:161], v[52:55]
	v_mfma_f32_16x16x32_bf16 v[48:51], v[198:201], v[158:161], v[48:51]
	v_mfma_f32_16x16x32_bf16 v[36:39], v[190:193], v[166:169], v[36:39]
	v_mfma_f32_16x16x32_bf16 v[32:35], v[198:201], v[166:169], v[32:35]
	v_mfma_f32_16x16x32_bf16 v[20:23], v[190:193], v[174:177], v[20:23]
	v_mfma_f32_16x16x32_bf16 v[16:19], v[198:201], v[174:177], v[16:19]
	v_mfma_f32_16x16x32_bf16 v[4:7], v[190:193], v[182:185], v[4:7]
	v_mfma_f32_16x16x32_bf16 v[0:3], v[198:201], v[182:185], v[0:3]
	v_mfma_f32_16x16x32_bf16 v[52:55], v[194:197], v[162:165], v[52:55]
	v_mfma_f32_16x16x32_bf16 v[48:51], v[202:205], v[162:165], v[48:51]
	v_mfma_f32_16x16x32_bf16 v[36:39], v[194:197], v[170:173], v[36:39]
	v_mfma_f32_16x16x32_bf16 v[32:35], v[202:205], v[170:173], v[32:35]
	v_mfma_f32_16x16x32_bf16 v[20:23], v[194:197], v[178:181], v[20:23]
	v_mfma_f32_16x16x32_bf16 v[16:19], v[202:205], v[178:181], v[16:19]
	v_mfma_f32_16x16x32_bf16 v[4:7], v[194:197], v[186:189], v[4:7]
	v_mfma_f32_16x16x32_bf16 v[0:3], v[202:205], v[186:189], v[0:3]
	s_add_i32 s62, 0, 0x18000
	v_add_u32_e32 v154, s62, v143
	s_barrier
	ds_read_b128 v[138:141], v154
	ds_read_b128 v[146:149], v154 offset:1024
	ds_read_b128 v[150:153], v154 offset:2048
	ds_read_b128 v[154:157], v154 offset:3072
	s_add_u32 s20, s26, 0xb0000
	s_addc_u32 s21, s27, 0
	s_mov_b32 m0, s50
	ds_read_b128 v[158:161], v145 offset:32768
	ds_read_b128 v[162:165], v145 offset:33792
	ds_read_b128 v[166:169], v145 offset:34816
	ds_read_b128 v[170:173], v145 offset:35840
	ds_read_b128 v[174:177], v145 offset:36864
	ds_read_b128 v[178:181], v145 offset:37888
	ds_read_b128 v[182:185], v145 offset:38912
	ds_read_b128 v[186:189], v145 offset:39936
	global_load_lds_dwordx4 v132, s[20:21]
	s_mov_b32 m0, s51
	s_nop 0
	global_load_lds_dwordx4 v130, s[20:21]
	s_waitcnt lgkmcnt(8)
	s_barrier
	s_waitcnt lgkmcnt(0)
	v_mfma_f32_16x16x32_bf16 v[124:127], v[138:141], v[158:161], v[124:127]
	v_mfma_f32_16x16x32_bf16 v[120:123], v[150:153], v[158:161], v[120:123]
	v_mfma_f32_16x16x32_bf16 v[108:111], v[138:141], v[166:169], v[108:111]
	v_mfma_f32_16x16x32_bf16 v[104:107], v[150:153], v[166:169], v[104:107]
	v_mfma_f32_16x16x32_bf16 v[92:95], v[138:141], v[174:177], v[92:95]
	v_mfma_f32_16x16x32_bf16 v[88:91], v[150:153], v[174:177], v[88:91]
	v_mfma_f32_16x16x32_bf16 v[76:79], v[138:141], v[182:185], v[76:79]
	v_mfma_f32_16x16x32_bf16 v[72:75], v[150:153], v[182:185], v[72:75]
	v_mfma_f32_16x16x32_bf16 v[124:127], v[146:149], v[162:165], v[124:127]
	v_mfma_f32_16x16x32_bf16 v[120:123], v[154:157], v[162:165], v[120:123]
	v_mfma_f32_16x16x32_bf16 v[108:111], v[146:149], v[170:173], v[108:111]
	v_mfma_f32_16x16x32_bf16 v[104:107], v[154:157], v[170:173], v[104:107]
	v_mfma_f32_16x16x32_bf16 v[92:95], v[146:149], v[178:181], v[92:95]
	v_mfma_f32_16x16x32_bf16 v[88:91], v[154:157], v[178:181], v[88:91]
	v_mfma_f32_16x16x32_bf16 v[76:79], v[146:149], v[186:189], v[76:79]
	v_mfma_f32_16x16x32_bf16 v[72:75], v[154:157], v[186:189], v[72:75]
	s_barrier
	s_add_i32 s26, 0, 0x1c000
	s_add_i32 s20, s62, s35
	v_add_u32_e32 v202, s26, v143
	s_mov_b32 m0, s20
	ds_read_b128 v[190:193], v202
	ds_read_b128 v[194:197], v202 offset:1024
	ds_read_b128 v[198:201], v202 offset:2048
	ds_read_b128 v[202:205], v202 offset:3072
	global_load_lds_dwordx4 v208, s[98:99]
	s_add_i32 m0, s20, 0x2000
	s_nop 0
	global_load_lds_dwordx4 v128, s[98:99]
	s_barrier
	s_waitcnt lgkmcnt(0)
	v_mfma_f32_16x16x32_bf16 v[116:119], v[190:193], v[158:161], v[116:119]
	v_mfma_f32_16x16x32_bf16 v[112:115], v[198:201], v[158:161], v[112:115]
	v_mfma_f32_16x16x32_bf16 v[100:103], v[190:193], v[166:169], v[100:103]
	v_mfma_f32_16x16x32_bf16 v[96:99], v[198:201], v[166:169], v[96:99]
	v_mfma_f32_16x16x32_bf16 v[84:87], v[190:193], v[174:177], v[84:87]
	v_mfma_f32_16x16x32_bf16 v[80:83], v[198:201], v[174:177], v[80:83]
	v_mfma_f32_16x16x32_bf16 v[68:71], v[190:193], v[182:185], v[68:71]
	v_mfma_f32_16x16x32_bf16 v[64:67], v[198:201], v[182:185], v[64:67]
	v_mfma_f32_16x16x32_bf16 v[116:119], v[194:197], v[162:165], v[116:119]
	v_mfma_f32_16x16x32_bf16 v[112:115], v[202:205], v[162:165], v[112:115]
	v_mfma_f32_16x16x32_bf16 v[100:103], v[194:197], v[170:173], v[100:103]
	v_mfma_f32_16x16x32_bf16 v[96:99], v[202:205], v[170:173], v[96:99]
	v_mfma_f32_16x16x32_bf16 v[84:87], v[194:197], v[178:181], v[84:87]
	v_mfma_f32_16x16x32_bf16 v[80:83], v[202:205], v[178:181], v[80:83]
	v_mfma_f32_16x16x32_bf16 v[68:71], v[194:197], v[186:189], v[68:71]
	v_mfma_f32_16x16x32_bf16 v[64:67], v[202:205], v[186:189], v[64:67]
	s_mov_b32 m0, s53
	s_barrier
	ds_read_b128 v[158:161], v145 offset:49152
	ds_read_b128 v[162:165], v145 offset:50176
	ds_read_b128 v[166:169], v145 offset:51200
	ds_read_b128 v[170:173], v145 offset:52224
	ds_read_b128 v[174:177], v145 offset:53248
	ds_read_b128 v[178:181], v145 offset:54272
	ds_read_b128 v[182:185], v145 offset:55296
	ds_read_b128 v[186:189], v145 offset:56320
	global_load_lds_dwordx4 v132, s[100:101]
	s_mov_b32 m0, s56
	s_nop 0
	global_load_lds_dwordx4 v130, s[100:101]
	s_barrier
	s_waitcnt lgkmcnt(0)
	v_mfma_f32_16x16x32_bf16 v[60:63], v[138:141], v[158:161], v[60:63]
	v_mfma_f32_16x16x32_bf16 v[56:59], v[150:153], v[158:161], v[56:59]
	v_mfma_f32_16x16x32_bf16 v[44:47], v[138:141], v[166:169], v[44:47]
	v_mfma_f32_16x16x32_bf16 v[40:43], v[150:153], v[166:169], v[40:43]
	v_mfma_f32_16x16x32_bf16 v[28:31], v[138:141], v[174:177], v[28:31]
	v_mfma_f32_16x16x32_bf16 v[24:27], v[150:153], v[174:177], v[24:27]
	v_mfma_f32_16x16x32_bf16 v[12:15], v[138:141], v[182:185], v[12:15]
	v_mfma_f32_16x16x32_bf16 v[8:11], v[150:153], v[182:185], v[8:11]
	v_mfma_f32_16x16x32_bf16 v[60:63], v[146:149], v[162:165], v[60:63]
	v_mfma_f32_16x16x32_bf16 v[56:59], v[154:157], v[162:165], v[56:59]
	v_mfma_f32_16x16x32_bf16 v[44:47], v[146:149], v[170:173], v[44:47]
	v_mfma_f32_16x16x32_bf16 v[40:43], v[154:157], v[170:173], v[40:43]
	v_mfma_f32_16x16x32_bf16 v[28:31], v[146:149], v[178:181], v[28:31]
	v_mfma_f32_16x16x32_bf16 v[24:27], v[154:157], v[178:181], v[24:27]
	v_mfma_f32_16x16x32_bf16 v[12:15], v[146:149], v[186:189], v[12:15]
	v_mfma_f32_16x16x32_bf16 v[8:11], v[154:157], v[186:189], v[8:11]
	s_barrier
	s_add_u32 s20, s24, 0xb0080
	s_addc_u32 s21, s25, 0
	s_add_i32 s24, s26, s35
	s_mov_b32 m0, s24
	s_nop 0
	global_load_lds_dwordx4 v208, s[20:21]
	s_add_i32 m0, s24, 0x2000
	s_nop 0
	global_load_lds_dwordx4 v128, s[20:21]
	s_waitcnt vmcnt(6)
	s_barrier
	v_mfma_f32_16x16x32_bf16 v[52:55], v[190:193], v[158:161], v[52:55]
	v_mfma_f32_16x16x32_bf16 v[48:51], v[198:201], v[158:161], v[48:51]
	v_mfma_f32_16x16x32_bf16 v[36:39], v[190:193], v[166:169], v[36:39]
	v_mfma_f32_16x16x32_bf16 v[32:35], v[198:201], v[166:169], v[32:35]
	v_mfma_f32_16x16x32_bf16 v[20:23], v[190:193], v[174:177], v[20:23]
	v_mfma_f32_16x16x32_bf16 v[16:19], v[198:201], v[174:177], v[16:19]
	v_mfma_f32_16x16x32_bf16 v[4:7], v[190:193], v[182:185], v[4:7]
	v_mfma_f32_16x16x32_bf16 v[0:3], v[198:201], v[182:185], v[0:3]
	v_mfma_f32_16x16x32_bf16 v[52:55], v[194:197], v[162:165], v[52:55]
	v_mfma_f32_16x16x32_bf16 v[48:51], v[202:205], v[162:165], v[48:51]
	v_mfma_f32_16x16x32_bf16 v[36:39], v[194:197], v[170:173], v[36:39]
	v_mfma_f32_16x16x32_bf16 v[32:35], v[202:205], v[170:173], v[32:35]
	v_mfma_f32_16x16x32_bf16 v[20:23], v[194:197], v[178:181], v[20:23]
	v_mfma_f32_16x16x32_bf16 v[16:19], v[202:205], v[178:181], v[16:19]
	v_mfma_f32_16x16x32_bf16 v[4:7], v[194:197], v[186:189], v[4:7]
	v_mfma_f32_16x16x32_bf16 v[0:3], v[202:205], v[186:189], v[0:3]
	s_add_i32 s61, s61, 2
	s_add_u32 s39, s39, 0x100
	s_addc_u32 s60, s60, 0
	s_cmp_gt_u32 s61, 41
	s_mov_b64 s[20:21], s[22:23]
	s_barrier
	s_cbranch_scc0 .LBB0_1021
	v_lshl_add_u32 v140, s38, 8, v142
	v_lshl_or_b32 v141, s36, 8, v144
	s_lshl_b32 s20, s36, 2
	s_ashr_i32 s21, s20, 31
	s_lshl_b32 s36, s52, 2
	v_lshlrev_b32_e32 v206, 11, v140
	v_lshl_add_u32 v206, v141, 1, v206
	v_lshl_add_u32 v210, v140, 6, s36
	v_lshl_add_u32 v210, s20, 2, v210
	v_mov_b32_e32 v207, v206
	global_load_dwordx4 v[146:149], v206, s[14:15]
	global_load_dwordx4 v[150:153], v206, s[14:15] offset:256
	v_add_u32_e32 v206, 0x8000, v206
	global_load_dwordx4 v[154:157], v206, s[14:15]
	global_load_dwordx4 v[158:161], v206, s[14:15] offset:256
	v_add_u32_e32 v206, 0x8000, v206
	global_load_dwordx4 v[162:165], v206, s[14:15]
	global_load_dwordx4 v[166:169], v206, s[14:15] offset:256
	v_add_u32_e32 v206, 0x8000, v206
	global_load_dwordx4 v[170:173], v206, s[14:15]
	global_load_dwordx4 v[174:177], v206, s[14:15] offset:256
	v_add_u32_e32 v206, 0x28000, v206
	global_load_dwordx4 v[178:181], v206, s[14:15]
	global_load_dwordx4 v[182:185], v206, s[14:15] offset:256
	v_add_u32_e32 v206, 0x8000, v206
	global_load_dwordx4 v[186:189], v206, s[14:15]
	global_load_dwordx4 v[190:193], v206, s[14:15] offset:256
	v_add_u32_e32 v206, 0x8000, v206
	global_load_dwordx4 v[194:197], v206, s[14:15]
	global_load_dwordx4 v[198:201], v206, s[14:15] offset:256
	v_add_u32_e32 v206, 0x8000, v206
	s_waitcnt vmcnt(12)
	v_lshlrev_b32_e32 v202, 16, v146
	v_and_b32_e32 v203, 0xffff0000, v146
	v_lshlrev_b32_e32 v204, 16, v147
	v_and_b32_e32 v205, 0xffff0000, v147
	v_pk_add_f32 v[124:125], v[124:125], v[202:203]
	v_pk_add_f32 v[126:127], v[126:127], v[204:205]
	v_lshlrev_b32_e32 v202, 16, v148
	v_and_b32_e32 v203, 0xffff0000, v148
	v_lshlrev_b32_e32 v204, 16, v149
	v_and_b32_e32 v205, 0xffff0000, v149
	v_pk_add_f32 v[120:121], v[120:121], v[202:203]
	v_pk_add_f32 v[122:123], v[122:123], v[204:205]
	v_cvt_pk_bf16_f32 v146, v124, v125
	v_cvt_pk_bf16_f32 v147, v126, v127
	v_cvt_pk_bf16_f32 v148, v120, v121
	v_cvt_pk_bf16_f32 v149, v122, v123
	v_pk_mul_f32 v[138:139], v[124:125], v[124:125]
	global_store_dwordx4 v207, v[146:149], s[14:15]
	v_pk_fma_f32 v[138:139], v[126:127], v[126:127], v[138:139]
	v_pk_fma_f32 v[138:139], v[120:121], v[120:121], v[138:139]
	v_pk_fma_f32 v[138:139], v[122:123], v[122:123], v[138:139]
	v_lshlrev_b32_e32 v202, 16, v150
	v_and_b32_e32 v203, 0xffff0000, v150
	v_lshlrev_b32_e32 v204, 16, v151
	v_and_b32_e32 v205, 0xffff0000, v151
	v_pk_add_f32 v[116:117], v[116:117], v[202:203]
	v_pk_add_f32 v[118:119], v[118:119], v[204:205]
	v_lshlrev_b32_e32 v202, 16, v152
	v_and_b32_e32 v203, 0xffff0000, v152
	v_lshlrev_b32_e32 v204, 16, v153
	v_and_b32_e32 v205, 0xffff0000, v153
	v_pk_add_f32 v[112:113], v[112:113], v[202:203]
	v_pk_add_f32 v[114:115], v[114:115], v[204:205]
	v_cvt_pk_bf16_f32 v150, v116, v117
	v_cvt_pk_bf16_f32 v151, v118, v119
	v_cvt_pk_bf16_f32 v152, v112, v113
	v_cvt_pk_bf16_f32 v153, v114, v115
	v_pk_fma_f32 v[138:139], v[116:117], v[116:117], v[138:139]
	global_store_dwordx4 v207, v[150:153], s[14:15] offset:256
	v_pk_fma_f32 v[138:139], v[118:119], v[118:119], v[138:139]
	v_pk_fma_f32 v[138:139], v[112:113], v[112:113], v[138:139]
	v_pk_fma_f32 v[138:139], v[114:115], v[114:115], v[138:139]
	v_add_f32_e32 v214, v138, v139
	v_add_u32_e32 v207, 0x8000, v207
	v_mov_b32_e32 v215, v214
	s_nop 1
	v_permlane16_swap_b32_e32 v214, v215
	s_nop 0
	v_add_f32_e32 v214, v214, v215
	v_mov_b32_e32 v215, v214
	s_nop 1
	v_permlane32_swap_b32_e32 v214, v215
	s_nop 0
	v_add_f32_e32 v214, v214, v215
	s_and_saveexec_b64 s[22:23], s[4:5]
	global_store_dword v210, v214, s[16:17]
	s_mov_b64 exec, s[22:23]
	global_load_dwordx4 v[146:149], v206, s[14:15]
	global_load_dwordx4 v[150:153], v206, s[14:15] offset:256
	s_waitcnt vmcnt(15)
	v_lshlrev_b32_e32 v202, 16, v154
	v_and_b32_e32 v203, 0xffff0000, v154
	v_lshlrev_b32_e32 v204, 16, v155
	v_and_b32_e32 v205, 0xffff0000, v155
	v_pk_add_f32 v[108:109], v[108:109], v[202:203]
	v_pk_add_f32 v[110:111], v[110:111], v[204:205]
	v_lshlrev_b32_e32 v202, 16, v156
	v_and_b32_e32 v203, 0xffff0000, v156
	v_lshlrev_b32_e32 v204, 16, v157
	v_and_b32_e32 v205, 0xffff0000, v157
	v_pk_add_f32 v[104:105], v[104:105], v[202:203]
	v_pk_add_f32 v[106:107], v[106:107], v[204:205]
	v_cvt_pk_bf16_f32 v154, v108, v109
	v_cvt_pk_bf16_f32 v155, v110, v111
	v_cvt_pk_bf16_f32 v156, v104, v105
	v_cvt_pk_bf16_f32 v157, v106, v107
	v_pk_mul_f32 v[138:139], v[108:109], v[108:109]
	global_store_dwordx4 v207, v[154:157], s[14:15]
	v_pk_fma_f32 v[138:139], v[110:111], v[110:111], v[138:139]
	v_pk_fma_f32 v[138:139], v[104:105], v[104:105], v[138:139]
	v_pk_fma_f32 v[138:139], v[106:107], v[106:107], v[138:139]
	v_lshlrev_b32_e32 v202, 16, v158
	v_and_b32_e32 v203, 0xffff0000, v158
	v_lshlrev_b32_e32 v204, 16, v159
	v_and_b32_e32 v205, 0xffff0000, v159
	v_pk_add_f32 v[100:101], v[100:101], v[202:203]
	v_pk_add_f32 v[102:103], v[102:103], v[204:205]
	v_lshlrev_b32_e32 v202, 16, v160
	v_and_b32_e32 v203, 0xffff0000, v160
	v_lshlrev_b32_e32 v204, 16, v161
	v_and_b32_e32 v205, 0xffff0000, v161
	v_pk_add_f32 v[96:97], v[96:97], v[202:203]
	v_pk_add_f32 v[98:99], v[98:99], v[204:205]
	v_cvt_pk_bf16_f32 v158, v100, v101
	v_cvt_pk_bf16_f32 v159, v102, v103
	v_cvt_pk_bf16_f32 v160, v96, v97
	v_cvt_pk_bf16_f32 v161, v98, v99
	v_pk_fma_f32 v[138:139], v[100:101], v[100:101], v[138:139]
	global_store_dwordx4 v207, v[158:161], s[14:15] offset:256
	v_pk_fma_f32 v[138:139], v[102:103], v[102:103], v[138:139]
	v_pk_fma_f32 v[138:139], v[96:97], v[96:97], v[138:139]
	v_pk_fma_f32 v[138:139], v[98:99], v[98:99], v[138:139]
	v_add_f32_e32 v214, v138, v139
	v_add_u32_e32 v207, 0x8000, v207
	v_mov_b32_e32 v215, v214
	s_nop 1
	v_permlane16_swap_b32_e32 v214, v215
	s_nop 0
	v_add_f32_e32 v214, v214, v215
	v_mov_b32_e32 v215, v214
	s_nop 1
	v_permlane32_swap_b32_e32 v214, v215
	s_nop 0
	v_add_f32_e32 v214, v214, v215
	s_and_saveexec_b64 s[22:23], s[4:5]
	global_store_dword v210, v214, s[16:17] offset:1024
	s_mov_b64 exec, s[22:23]
	s_waitcnt vmcnt(16)
	v_lshlrev_b32_e32 v202, 16, v162
	v_and_b32_e32 v203, 0xffff0000, v162
	v_lshlrev_b32_e32 v204, 16, v163
	v_and_b32_e32 v205, 0xffff0000, v163
	v_pk_add_f32 v[92:93], v[92:93], v[202:203]
	v_pk_add_f32 v[94:95], v[94:95], v[204:205]
	v_lshlrev_b32_e32 v202, 16, v164
	v_and_b32_e32 v203, 0xffff0000, v164
	v_lshlrev_b32_e32 v204, 16, v165
	v_and_b32_e32 v205, 0xffff0000, v165
	v_pk_add_f32 v[88:89], v[88:89], v[202:203]
	v_pk_add_f32 v[90:91], v[90:91], v[204:205]
	v_cvt_pk_bf16_f32 v162, v92, v93
	v_cvt_pk_bf16_f32 v163, v94, v95
	v_cvt_pk_bf16_f32 v164, v88, v89
	v_cvt_pk_bf16_f32 v165, v90, v91
	v_pk_mul_f32 v[138:139], v[92:93], v[92:93]
	global_store_dwordx4 v207, v[162:165], s[14:15]
	v_pk_fma_f32 v[138:139], v[94:95], v[94:95], v[138:139]
	v_pk_fma_f32 v[138:139], v[88:89], v[88:89], v[138:139]
	v_pk_fma_f32 v[138:139], v[90:91], v[90:91], v[138:139]
	v_lshlrev_b32_e32 v202, 16, v166
	v_and_b32_e32 v203, 0xffff0000, v166
	v_lshlrev_b32_e32 v204, 16, v167
	v_and_b32_e32 v205, 0xffff0000, v167
	v_pk_add_f32 v[84:85], v[84:85], v[202:203]
	v_pk_add_f32 v[86:87], v[86:87], v[204:205]
	v_lshlrev_b32_e32 v202, 16, v168
	v_and_b32_e32 v203, 0xffff0000, v168
	v_lshlrev_b32_e32 v204, 16, v169
	v_and_b32_e32 v205, 0xffff0000, v169
	v_pk_add_f32 v[80:81], v[80:81], v[202:203]
	v_pk_add_f32 v[82:83], v[82:83], v[204:205]
	v_cvt_pk_bf16_f32 v166, v84, v85
	v_cvt_pk_bf16_f32 v167, v86, v87
	v_cvt_pk_bf16_f32 v168, v80, v81
	v_cvt_pk_bf16_f32 v169, v82, v83
	v_pk_fma_f32 v[138:139], v[84:85], v[84:85], v[138:139]
	global_store_dwordx4 v207, v[166:169], s[14:15] offset:256
	v_pk_fma_f32 v[138:139], v[86:87], v[86:87], v[138:139]
	v_pk_fma_f32 v[138:139], v[80:81], v[80:81], v[138:139]
	v_pk_fma_f32 v[138:139], v[82:83], v[82:83], v[138:139]
	v_add_f32_e32 v214, v138, v139
	v_add_u32_e32 v207, 0x8000, v207
	v_mov_b32_e32 v215, v214
	s_nop 1
	v_permlane16_swap_b32_e32 v214, v215
	s_nop 0
	v_add_f32_e32 v214, v214, v215
	v_mov_b32_e32 v215, v214
	s_nop 1
	v_permlane32_swap_b32_e32 v214, v215
	s_nop 0
	v_add_f32_e32 v214, v214, v215
	s_and_saveexec_b64 s[22:23], s[4:5]
	global_store_dword v210, v214, s[16:17] offset:2048
	s_mov_b64 exec, s[22:23]
	s_waitcnt vmcnt(17)
	v_lshlrev_b32_e32 v202, 16, v170
	v_and_b32_e32 v203, 0xffff0000, v170
	v_lshlrev_b32_e32 v204, 16, v171
	v_and_b32_e32 v205, 0xffff0000, v171
	v_pk_add_f32 v[76:77], v[76:77], v[202:203]
	v_pk_add_f32 v[78:79], v[78:79], v[204:205]
	v_lshlrev_b32_e32 v202, 16, v172
	v_and_b32_e32 v203, 0xffff0000, v172
	v_lshlrev_b32_e32 v204, 16, v173
	v_and_b32_e32 v205, 0xffff0000, v173
	v_pk_add_f32 v[72:73], v[72:73], v[202:203]
	v_pk_add_f32 v[74:75], v[74:75], v[204:205]
	v_cvt_pk_bf16_f32 v170, v76, v77
	v_cvt_pk_bf16_f32 v171, v78, v79
	v_cvt_pk_bf16_f32 v172, v72, v73
	v_cvt_pk_bf16_f32 v173, v74, v75
	v_pk_mul_f32 v[138:139], v[76:77], v[76:77]
	global_store_dwordx4 v207, v[170:173], s[14:15]
	v_pk_fma_f32 v[138:139], v[78:79], v[78:79], v[138:139]
	v_pk_fma_f32 v[138:139], v[72:73], v[72:73], v[138:139]
	v_pk_fma_f32 v[138:139], v[74:75], v[74:75], v[138:139]
	v_lshlrev_b32_e32 v202, 16, v174
	v_and_b32_e32 v203, 0xffff0000, v174
	v_lshlrev_b32_e32 v204, 16, v175
	v_and_b32_e32 v205, 0xffff0000, v175
	v_pk_add_f32 v[68:69], v[68:69], v[202:203]
	v_pk_add_f32 v[70:71], v[70:71], v[204:205]
	v_lshlrev_b32_e32 v202, 16, v176
	v_and_b32_e32 v203, 0xffff0000, v176
	v_lshlrev_b32_e32 v204, 16, v177
	v_and_b32_e32 v205, 0xffff0000, v177
	v_pk_add_f32 v[64:65], v[64:65], v[202:203]
	v_pk_add_f32 v[66:67], v[66:67], v[204:205]
	v_cvt_pk_bf16_f32 v174, v68, v69
	v_cvt_pk_bf16_f32 v175, v70, v71
	v_cvt_pk_bf16_f32 v176, v64, v65
	v_cvt_pk_bf16_f32 v177, v66, v67
	v_pk_fma_f32 v[138:139], v[68:69], v[68:69], v[138:139]
	global_store_dwordx4 v207, v[174:177], s[14:15] offset:256
	v_pk_fma_f32 v[138:139], v[70:71], v[70:71], v[138:139]
	v_pk_fma_f32 v[138:139], v[64:65], v[64:65], v[138:139]
	v_pk_fma_f32 v[138:139], v[66:67], v[66:67], v[138:139]
	v_add_f32_e32 v214, v138, v139
	v_add_u32_e32 v207, 0x28000, v207
	v_mov_b32_e32 v215, v214
	s_nop 1
	v_permlane16_swap_b32_e32 v214, v215
	s_nop 0
	v_add_f32_e32 v214, v214, v215
	v_mov_b32_e32 v215, v214
	s_nop 1
	v_permlane32_swap_b32_e32 v214, v215
	s_nop 0
	v_add_f32_e32 v214, v214, v215
	s_and_saveexec_b64 s[22:23], s[4:5]
	global_store_dword v210, v214, s[16:17] offset:3072
	s_mov_b64 exec, s[22:23]
	v_add_u32_e32 v210, 0x2000, v210
	s_waitcnt vmcnt(18)
	v_lshlrev_b32_e32 v202, 16, v178
	v_and_b32_e32 v203, 0xffff0000, v178
	v_lshlrev_b32_e32 v204, 16, v179
	v_and_b32_e32 v205, 0xffff0000, v179
	v_pk_add_f32 v[60:61], v[60:61], v[202:203]
	v_pk_add_f32 v[62:63], v[62:63], v[204:205]
	v_lshlrev_b32_e32 v202, 16, v180
	v_and_b32_e32 v203, 0xffff0000, v180
	v_lshlrev_b32_e32 v204, 16, v181
	v_and_b32_e32 v205, 0xffff0000, v181
	v_pk_add_f32 v[56:57], v[56:57], v[202:203]
	v_pk_add_f32 v[58:59], v[58:59], v[204:205]
	v_cvt_pk_bf16_f32 v178, v60, v61
	v_cvt_pk_bf16_f32 v179, v62, v63
	v_cvt_pk_bf16_f32 v180, v56, v57
	v_cvt_pk_bf16_f32 v181, v58, v59
	v_pk_mul_f32 v[138:139], v[60:61], v[60:61]
	global_store_dwordx4 v207, v[178:181], s[14:15]
	v_pk_fma_f32 v[138:139], v[62:63], v[62:63], v[138:139]
	v_pk_fma_f32 v[138:139], v[56:57], v[56:57], v[138:139]
	v_pk_fma_f32 v[138:139], v[58:59], v[58:59], v[138:139]
	v_lshlrev_b32_e32 v202, 16, v182
	v_and_b32_e32 v203, 0xffff0000, v182
	v_lshlrev_b32_e32 v204, 16, v183
	v_and_b32_e32 v205, 0xffff0000, v183
	v_pk_add_f32 v[52:53], v[52:53], v[202:203]
	v_pk_add_f32 v[54:55], v[54:55], v[204:205]
	v_lshlrev_b32_e32 v202, 16, v184
	v_and_b32_e32 v203, 0xffff0000, v184
	v_lshlrev_b32_e32 v204, 16, v185
	v_and_b32_e32 v205, 0xffff0000, v185
	v_pk_add_f32 v[48:49], v[48:49], v[202:203]
	v_pk_add_f32 v[50:51], v[50:51], v[204:205]
	v_cvt_pk_bf16_f32 v182, v52, v53
	v_cvt_pk_bf16_f32 v183, v54, v55
	v_cvt_pk_bf16_f32 v184, v48, v49
	v_cvt_pk_bf16_f32 v185, v50, v51
	v_pk_fma_f32 v[138:139], v[52:53], v[52:53], v[138:139]
	global_store_dwordx4 v207, v[182:185], s[14:15] offset:256
	v_pk_fma_f32 v[138:139], v[54:55], v[54:55], v[138:139]
	v_pk_fma_f32 v[138:139], v[48:49], v[48:49], v[138:139]
	v_pk_fma_f32 v[138:139], v[50:51], v[50:51], v[138:139]
	v_add_f32_e32 v214, v138, v139
	v_add_u32_e32 v207, 0x8000, v207
	v_mov_b32_e32 v215, v214
	s_nop 1
	v_permlane16_swap_b32_e32 v214, v215
	s_nop 0
	v_add_f32_e32 v214, v214, v215
	v_mov_b32_e32 v215, v214
	s_nop 1
	v_permlane32_swap_b32_e32 v214, v215
	s_nop 0
	v_add_f32_e32 v214, v214, v215
	s_and_saveexec_b64 s[22:23], s[4:5]
	global_store_dword v210, v214, s[16:17]
	s_mov_b64 exec, s[22:23]
	s_waitcnt vmcnt(19)
	v_lshlrev_b32_e32 v202, 16, v186
	v_and_b32_e32 v203, 0xffff0000, v186
	v_lshlrev_b32_e32 v204, 16, v187
	v_and_b32_e32 v205, 0xffff0000, v187
	v_pk_add_f32 v[44:45], v[44:45], v[202:203]
	v_pk_add_f32 v[46:47], v[46:47], v[204:205]
	v_lshlrev_b32_e32 v202, 16, v188
	v_and_b32_e32 v203, 0xffff0000, v188
	v_lshlrev_b32_e32 v204, 16, v189
	v_and_b32_e32 v205, 0xffff0000, v189
	v_pk_add_f32 v[40:41], v[40:41], v[202:203]
	v_pk_add_f32 v[42:43], v[42:43], v[204:205]
	v_cvt_pk_bf16_f32 v186, v44, v45
	v_cvt_pk_bf16_f32 v187, v46, v47
	v_cvt_pk_bf16_f32 v188, v40, v41
	v_cvt_pk_bf16_f32 v189, v42, v43
	v_pk_mul_f32 v[138:139], v[44:45], v[44:45]
	global_store_dwordx4 v207, v[186:189], s[14:15]
	v_pk_fma_f32 v[138:139], v[46:47], v[46:47], v[138:139]
	v_pk_fma_f32 v[138:139], v[40:41], v[40:41], v[138:139]
	v_pk_fma_f32 v[138:139], v[42:43], v[42:43], v[138:139]
	v_lshlrev_b32_e32 v202, 16, v190
	v_and_b32_e32 v203, 0xffff0000, v190
	v_lshlrev_b32_e32 v204, 16, v191
	v_and_b32_e32 v205, 0xffff0000, v191
	v_pk_add_f32 v[36:37], v[36:37], v[202:203]
	v_pk_add_f32 v[38:39], v[38:39], v[204:205]
	v_lshlrev_b32_e32 v202, 16, v192
	v_and_b32_e32 v203, 0xffff0000, v192
	v_lshlrev_b32_e32 v204, 16, v193
	v_and_b32_e32 v205, 0xffff0000, v193
	v_pk_add_f32 v[32:33], v[32:33], v[202:203]
	v_pk_add_f32 v[34:35], v[34:35], v[204:205]
	v_cvt_pk_bf16_f32 v190, v36, v37
	v_cvt_pk_bf16_f32 v191, v38, v39
	v_cvt_pk_bf16_f32 v192, v32, v33
	v_cvt_pk_bf16_f32 v193, v34, v35
	v_pk_fma_f32 v[138:139], v[36:37], v[36:37], v[138:139]
	global_store_dwordx4 v207, v[190:193], s[14:15] offset:256
	v_pk_fma_f32 v[138:139], v[38:39], v[38:39], v[138:139]
	v_pk_fma_f32 v[138:139], v[32:33], v[32:33], v[138:139]
	v_pk_fma_f32 v[138:139], v[34:35], v[34:35], v[138:139]
	v_add_f32_e32 v214, v138, v139
	v_add_u32_e32 v207, 0x8000, v207
	v_mov_b32_e32 v215, v214
	s_nop 1
	v_permlane16_swap_b32_e32 v214, v215
	s_nop 0
	v_add_f32_e32 v214, v214, v215
	v_mov_b32_e32 v215, v214
	s_nop 1
	v_permlane32_swap_b32_e32 v214, v215
	s_nop 0
	v_add_f32_e32 v214, v214, v215
	s_and_saveexec_b64 s[22:23], s[4:5]
	global_store_dword v210, v214, s[16:17] offset:1024
	s_mov_b64 exec, s[22:23]
	s_waitcnt vmcnt(20)
	v_lshlrev_b32_e32 v202, 16, v194
	v_and_b32_e32 v203, 0xffff0000, v194
	v_lshlrev_b32_e32 v204, 16, v195
	v_and_b32_e32 v205, 0xffff0000, v195
	v_pk_add_f32 v[28:29], v[28:29], v[202:203]
	v_pk_add_f32 v[30:31], v[30:31], v[204:205]
	v_lshlrev_b32_e32 v202, 16, v196
	v_and_b32_e32 v203, 0xffff0000, v196
	v_lshlrev_b32_e32 v204, 16, v197
	v_and_b32_e32 v205, 0xffff0000, v197
	v_pk_add_f32 v[24:25], v[24:25], v[202:203]
	v_pk_add_f32 v[26:27], v[26:27], v[204:205]
	v_cvt_pk_bf16_f32 v194, v28, v29
	v_cvt_pk_bf16_f32 v195, v30, v31
	v_cvt_pk_bf16_f32 v196, v24, v25
	v_cvt_pk_bf16_f32 v197, v26, v27
	v_pk_mul_f32 v[138:139], v[28:29], v[28:29]
	global_store_dwordx4 v207, v[194:197], s[14:15]
	v_pk_fma_f32 v[138:139], v[30:31], v[30:31], v[138:139]
	v_pk_fma_f32 v[138:139], v[24:25], v[24:25], v[138:139]
	v_pk_fma_f32 v[138:139], v[26:27], v[26:27], v[138:139]
	v_lshlrev_b32_e32 v202, 16, v198
	v_and_b32_e32 v203, 0xffff0000, v198
	v_lshlrev_b32_e32 v204, 16, v199
	v_and_b32_e32 v205, 0xffff0000, v199
	v_pk_add_f32 v[20:21], v[20:21], v[202:203]
	v_pk_add_f32 v[22:23], v[22:23], v[204:205]
	v_lshlrev_b32_e32 v202, 16, v200
	v_and_b32_e32 v203, 0xffff0000, v200
	v_lshlrev_b32_e32 v204, 16, v201
	v_and_b32_e32 v205, 0xffff0000, v201
	v_pk_add_f32 v[16:17], v[16:17], v[202:203]
	v_pk_add_f32 v[18:19], v[18:19], v[204:205]
	v_cvt_pk_bf16_f32 v198, v20, v21
	v_cvt_pk_bf16_f32 v199, v22, v23
	v_cvt_pk_bf16_f32 v200, v16, v17
	v_cvt_pk_bf16_f32 v201, v18, v19
	v_pk_fma_f32 v[138:139], v[20:21], v[20:21], v[138:139]
	global_store_dwordx4 v207, v[198:201], s[14:15] offset:256
	v_pk_fma_f32 v[138:139], v[22:23], v[22:23], v[138:139]
	v_pk_fma_f32 v[138:139], v[16:17], v[16:17], v[138:139]
	v_pk_fma_f32 v[138:139], v[18:19], v[18:19], v[138:139]
	v_add_f32_e32 v214, v138, v139
	v_add_u32_e32 v207, 0x8000, v207
	v_mov_b32_e32 v215, v214
	s_nop 1
	v_permlane16_swap_b32_e32 v214, v215
	s_nop 0
	v_add_f32_e32 v214, v214, v215
	v_mov_b32_e32 v215, v214
	s_nop 1
	v_permlane32_swap_b32_e32 v214, v215
	s_nop 0
	v_add_f32_e32 v214, v214, v215
	s_and_saveexec_b64 s[22:23], s[4:5]
	global_store_dword v210, v214, s[16:17] offset:2048
	s_mov_b64 exec, s[22:23]
	s_waitcnt vmcnt(18)
	v_lshlrev_b32_e32 v202, 16, v146
	v_and_b32_e32 v203, 0xffff0000, v146
	v_lshlrev_b32_e32 v204, 16, v147
	v_and_b32_e32 v205, 0xffff0000, v147
	v_pk_add_f32 v[12:13], v[12:13], v[202:203]
	v_pk_add_f32 v[14:15], v[14:15], v[204:205]
	v_lshlrev_b32_e32 v202, 16, v148
	v_and_b32_e32 v203, 0xffff0000, v148
	v_lshlrev_b32_e32 v204, 16, v149
	v_and_b32_e32 v205, 0xffff0000, v149
	v_pk_add_f32 v[8:9], v[8:9], v[202:203]
	v_pk_add_f32 v[10:11], v[10:11], v[204:205]
	v_cvt_pk_bf16_f32 v146, v12, v13
	v_cvt_pk_bf16_f32 v147, v14, v15
	v_cvt_pk_bf16_f32 v148, v8, v9
	v_cvt_pk_bf16_f32 v149, v10, v11
	v_pk_mul_f32 v[138:139], v[12:13], v[12:13]
	global_store_dwordx4 v207, v[146:149], s[14:15]
	v_pk_fma_f32 v[138:139], v[14:15], v[14:15], v[138:139]
	v_pk_fma_f32 v[138:139], v[8:9], v[8:9], v[138:139]
	v_pk_fma_f32 v[138:139], v[10:11], v[10:11], v[138:139]
	v_lshlrev_b32_e32 v202, 16, v150
	v_and_b32_e32 v203, 0xffff0000, v150
	v_lshlrev_b32_e32 v204, 16, v151
	v_and_b32_e32 v205, 0xffff0000, v151
	v_pk_add_f32 v[4:5], v[4:5], v[202:203]
	v_pk_add_f32 v[6:7], v[6:7], v[204:205]
	v_lshlrev_b32_e32 v202, 16, v152
	v_and_b32_e32 v203, 0xffff0000, v152
	v_lshlrev_b32_e32 v204, 16, v153
	v_and_b32_e32 v205, 0xffff0000, v153
	v_pk_add_f32 v[0:1], v[0:1], v[202:203]
	v_pk_add_f32 v[2:3], v[2:3], v[204:205]
	v_cvt_pk_bf16_f32 v150, v4, v5
	v_cvt_pk_bf16_f32 v151, v6, v7
	v_cvt_pk_bf16_f32 v152, v0, v1
	v_cvt_pk_bf16_f32 v153, v2, v3
	v_pk_fma_f32 v[138:139], v[4:5], v[4:5], v[138:139]
	global_store_dwordx4 v207, v[150:153], s[14:15] offset:256
	v_pk_fma_f32 v[138:139], v[6:7], v[6:7], v[138:139]
	v_pk_fma_f32 v[138:139], v[0:1], v[0:1], v[138:139]
	v_pk_fma_f32 v[138:139], v[2:3], v[2:3], v[138:139]
	v_add_f32_e32 v214, v138, v139
	v_add_u32_e32 v207, 0x8000, v207
	v_mov_b32_e32 v215, v214
	s_nop 1
	v_permlane16_swap_b32_e32 v214, v215
	s_nop 0
	v_add_f32_e32 v214, v214, v215
	v_mov_b32_e32 v215, v214
	s_nop 1
	v_permlane32_swap_b32_e32 v214, v215
	s_nop 0
	v_add_f32_e32 v214, v214, v215
	s_and_saveexec_b64 s[22:23], s[4:5]
	global_store_dword v210, v214, s[16:17] offset:3072
	s_mov_b64 exec, s[22:23]
	s_branch .LBB0_1009
